# stack1g + merged vmcnt/lgkmcnt waits into a single s_waitcnt at each GEMM super-phase
# baseline (speedup 1.0000x reference)
; #define PG8_STAGE(bufoff, gbase, voff) do { _Pragma("unroll") for (int _i = 0; _i < 2; ++_i) \
;         __builtin_amdgcn_global_load_lds((const unsigned*)((const char*)(gbase) + (voff)[_i]), (PG8_LAS unsigned*)(lds + (bufoff) + ldsw + _i * 8192), 16, 0, 0); } while (0)
; #define PG8_LDA(dst, b, h) do { _Pragma("unroll") for (int m = 0; m < 4; ++m) _Pragma("unroll") for (int k = 0; k < 2; ++k) dst[m][k] = *(const PG8_LAS bf16x8*)(lds + PG8_SA(b, h) + aoff + m * 2048 + k * 1024); } while (0)
; #define PG8_LDB(dst, b, h) do { _Pragma("unroll") for (int n = 0; n < 2; ++n) _Pragma("unroll") for (int k = 0; k < 2; ++k) dst[n][k] = *(const PG8_LAS bf16x8*)(lds + PG8_SB(b, h) + boff + n * 2048 + k * 1024); } while (0)
; #define PG8_MMA(ai, bj, At, Bt) do { __builtin_amdgcn_s_setprio(1); _Pragma("unroll") for (int m = 0; m < 4; ++m) _Pragma("unroll") for (int n = 0; n < 2; ++n) _Pragma("unroll") for (int k = 0; k < 2; ++k) \
;         acc[ai][bj][m][n] = __builtin_amdgcn_mfma_f32_16x16x32_bf16(Bt[n][k], At[m][k], acc[ai][bj][m][n], 0, 0, 0); __builtin_amdgcn_s_setprio(0); } while (0)
; #define PG8_WAIT_V(n) asm volatile("s_waitcnt vmcnt(" #n ")" ::: "memory")
; #define PG8_WAIT_L(n) asm volatile("s_waitcnt lgkmcnt(" #n ")" ::: "memory")
; template <class Epi, class Sched, bool ALIGN_EPI = false, bool SP2 = false>
; __device__ __forceinline__ void gemm_phase(PG8_LAS unsigned char* lds, const Gemm g, const Sched& S, const Epi& E) {
;     ...
;             const bool last = (t == nt - 2);
;             const char* a1 = cA + (size_t)(t + 1) * kstep;
;             const char* a2 = last ? nA : cA + (size_t)(t + 2) * kstep; const char* b2 = last ? nB : cB + (size_t)(t + 2) * kstep;
;             const char* a3 = a2 + kstep; const char* b3 = b2 + kstep;
;             if (last && has_next) S.a_ready(nxt);
;             if constexpr (SP2) {
;             PG8_LDB(B0, 0, 0); PG8_LDB(B1, 0, 1); PG8_SCHED; PG8_LDA(At, 0, 0); PG8_STAGE(PG8_SA(1, 1), a1 + hstep, voffA);
;             PG8_WAIT_V(8); PG8_WAIT_L(0); PG8_BAR; PG8_MMA(0, 0, At, B0); PG8_MMA(0, 1, At, B1); PG8_BAR; PG8_SCHED;
;             PG8_LDA(At, 0, 1); PG8_STAGE(PG8_SB(0, 0), b2, voffB); PG8_STAGE(PG8_SB(0, 1), b2 + hstep, voffB); PG8_STAGE(PG8_SA(0, 0), a2, voffA);
;             PG8_WAIT_V(8); PG8_WAIT_L(0); PG8_BAR; PG8_MMA(1, 0, At, B0); PG8_MMA(1, 1, At, B1); PG8_BAR; PG8_SCHED;
.LBB0_304:
	v_add_u32_e32 v166, s54, v169
	v_add_u32_e32 v168, s55, v169
	ds_read_b128 v[162:165], v166
	ds_read_b128 v[182:185], v166 offset:1024
	ds_read_b128 v[186:189], v166 offset:2048
	ds_read_b128 v[190:193], v166 offset:3072
	ds_read_b128 v[194:197], v168
	ds_read_b128 v[198:201], v168 offset:1024
	ds_read_b128 v[202:205], v168 offset:2048
	ds_read_b128 v[206:209], v168 offset:3072
	s_cmp_eq_u32 s53, s10
	v_lshl_add_u64 v[172:173], v[160:161], 0, s[22:23]
	s_cselect_b64 vcc, -1, 0
	s_add_i32 s10, s10, 2
	v_cndmask_b32_e32 v173, v173, v153, vcc
	v_cndmask_b32_e32 v172, v172, v152, vcc
	v_cndmask_b32_e32 v245, v159, v155, vcc
	v_cndmask_b32_e32 v244, v158, v154, vcc
	s_mov_b32 m0, s56
	v_lshl_add_u64 v[246:247], v[160:161], 0, v[148:149]
	ds_read_b128 v[210:213], v179
	ds_read_b128 v[216:219], v179 offset:1024
	ds_read_b128 v[220:223], v179 offset:2048
	ds_read_b128 v[224:227], v179 offset:3072
	ds_read_b128 v[228:231], v179 offset:4096
	ds_read_b128 v[232:235], v179 offset:5120
	ds_read_b128 v[236:239], v179 offset:6144
	ds_read_b128 v[240:243], v179 offset:7168
	global_load_lds_dwordx4 v[246:247], off
	s_mov_b32 m0, s57
	v_lshl_add_u64 v[246:247], v[160:161], 0, v[146:147]
	global_load_lds_dwordx4 v[246:247], off
	s_waitcnt vmcnt(8) lgkmcnt(0)
	s_setprio 1
	s_barrier
	v_mfma_f32_16x16x32_bf16 v[124:127], v[162:165], v[210:213], v[124:127]
	v_mfma_f32_16x16x32_bf16 v[116:119], v[186:189], v[210:213], v[116:119]
	v_mfma_f32_16x16x32_bf16 v[108:111], v[162:165], v[220:223], v[108:111]
	v_mfma_f32_16x16x32_bf16 v[100:103], v[186:189], v[220:223], v[100:103]
	v_mfma_f32_16x16x32_bf16 v[92:95], v[162:165], v[228:231], v[92:95]
	v_mfma_f32_16x16x32_bf16 v[84:87], v[186:189], v[228:231], v[84:87]
	v_mfma_f32_16x16x32_bf16 v[76:79], v[162:165], v[236:239], v[76:79]
	v_mfma_f32_16x16x32_bf16 v[68:71], v[186:189], v[236:239], v[68:71]
	v_mfma_f32_16x16x32_bf16 v[124:127], v[182:185], v[216:219], v[124:127]
	v_mfma_f32_16x16x32_bf16 v[116:119], v[190:193], v[216:219], v[116:119]
	v_mfma_f32_16x16x32_bf16 v[108:111], v[182:185], v[224:227], v[108:111]
	v_mfma_f32_16x16x32_bf16 v[100:103], v[190:193], v[224:227], v[100:103]
	v_mfma_f32_16x16x32_bf16 v[92:95], v[182:185], v[232:235], v[92:95]
	v_mfma_f32_16x16x32_bf16 v[84:87], v[190:193], v[232:235], v[84:87]
	v_mfma_f32_16x16x32_bf16 v[76:79], v[182:185], v[240:243], v[76:79]
	v_mfma_f32_16x16x32_bf16 v[68:71], v[190:193], v[240:243], v[68:71]
	v_mfma_f32_16x16x32_bf16 v[120:123], v[194:197], v[210:213], v[120:123]
	v_mfma_f32_16x16x32_bf16 v[112:115], v[202:205], v[210:213], v[112:115]
	v_mfma_f32_16x16x32_bf16 v[104:107], v[194:197], v[220:223], v[104:107]
	v_mfma_f32_16x16x32_bf16 v[96:99], v[202:205], v[220:223], v[96:99]
	v_mfma_f32_16x16x32_bf16 v[88:91], v[194:197], v[228:231], v[88:91]
	v_mfma_f32_16x16x32_bf16 v[80:83], v[202:205], v[228:231], v[80:83]
	v_mfma_f32_16x16x32_bf16 v[72:75], v[194:197], v[236:239], v[72:75]
	v_mfma_f32_16x16x32_bf16 v[64:67], v[202:205], v[236:239], v[64:67]
	v_mfma_f32_16x16x32_bf16 v[120:123], v[198:201], v[216:219], v[120:123]
	v_mfma_f32_16x16x32_bf16 v[112:115], v[206:209], v[216:219], v[112:115]
	v_mfma_f32_16x16x32_bf16 v[104:107], v[198:201], v[224:227], v[104:107]
	v_mfma_f32_16x16x32_bf16 v[96:99], v[206:209], v[224:227], v[96:99]
	v_mfma_f32_16x16x32_bf16 v[88:91], v[198:201], v[232:235], v[88:91]
	v_mfma_f32_16x16x32_bf16 v[80:83], v[206:209], v[232:235], v[80:83]
	v_mfma_f32_16x16x32_bf16 v[72:75], v[198:201], v[240:243], v[72:75]
	v_mfma_f32_16x16x32_bf16 v[64:67], v[206:209], v[240:243], v[64:67]
	s_setprio 0
	s_barrier
	s_mov_b32 m0, s60
	v_lshl_add_u64 v[246:247], v[244:245], 0, v[138:139]
	ds_read_b128 v[210:213], v179 offset:16384
	ds_read_b128 v[216:219], v179 offset:17408
	ds_read_b128 v[220:223], v179 offset:18432
	ds_read_b128 v[224:227], v179 offset:19456
	ds_read_b128 v[228:231], v179 offset:20480
	ds_read_b128 v[232:235], v179 offset:21504
	ds_read_b128 v[236:239], v179 offset:22528
	ds_read_b128 v[240:243], v179 offset:23552
	global_load_lds_dwordx4 v[246:247], off
	v_lshl_add_u64 v[248:249], v[244:245], 0, v[134:135]
	s_mov_b32 m0, s61
	v_lshl_add_u64 v[244:245], v[244:245], 0, s[14:15]
	global_load_lds_dwordx4 v[248:249], off
	v_lshl_add_u64 v[250:251], v[244:245], 0, v[138:139]
	s_mov_b32 m0, s62
	v_lshl_add_u64 v[244:245], v[244:245], 0, v[134:135]
	global_load_lds_dwordx4 v[250:251], off
	s_add_i32 m0, s62, 0x2000
	v_lshl_add_u64 v[252:253], v[172:173], 0, v[140:141]
	global_load_lds_dwordx4 v[244:245], off
	s_mov_b32 m0, s46
	v_lshl_add_u64 v[214:215], v[172:173], 0, v[136:137]
	global_load_lds_dwordx4 v[252:253], off
	s_mov_b32 m0, s47
	s_nop 0
	global_load_lds_dwordx4 v[214:215], off
	s_waitcnt vmcnt(8) lgkmcnt(0)
	s_setprio 1
	s_barrier
; #define PG8_STAGE(bufoff, gbase, voff) do { _Pragma("unroll") for (int _i = 0; _i < 2; ++_i) \
;         __builtin_amdgcn_global_load_lds((const unsigned*)((const char*)(gbase) + (voff)[_i]), (PG8_LAS unsigned*)(lds + (bufoff) + ldsw + _i * 8192), 16, 0, 0); } while (0)
; #define PG8_LDA(dst, b, h) do { _Pragma("unroll") for (int m = 0; m < 4; ++m) _Pragma("unroll") for (int k = 0; k < 2; ++k) dst[m][k] = *(const PG8_LAS bf16x8*)(lds + PG8_SA(b, h) + aoff + m * 2048 + k * 1024); } while (0)
; #define PG8_LDB(dst, b, h) do { _Pragma("unroll") for (int n = 0; n < 2; ++n) _Pragma("unroll") for (int k = 0; k < 2; ++k) dst[n][k] = *(const PG8_LAS bf16x8*)(lds + PG8_SB(b, h) + boff + n * 2048 + k * 1024); } while (0)
; #define PG8_MMA(ai, bj, At, Bt) do { __builtin_amdgcn_s_setprio(1); _Pragma("unroll") for (int m = 0; m < 4; ++m) _Pragma("unroll") for (int n = 0; n < 2; ++n) _Pragma("unroll") for (int k = 0; k < 2; ++k) \
;         acc[ai][bj][m][n] = __builtin_amdgcn_mfma_f32_16x16x32_bf16(Bt[n][k], At[m][k], acc[ai][bj][m][n], 0, 0, 0); __builtin_amdgcn_s_setprio(0); } while (0)
; #define PG8_WAIT_V(n) asm volatile("s_waitcnt vmcnt(" #n ")" ::: "memory")
; #define PG8_WAIT_L(n) asm volatile("s_waitcnt lgkmcnt(" #n ")" ::: "memory")
; #define PG8_BAR __builtin_amdgcn_s_barrier()
; #define PG8_SCHED __builtin_amdgcn_sched_barrier(0)
; template <class Epi, class Sched, bool ALIGN_EPI = false, bool SP2 = false>
; __device__ __forceinline__ void gemm_phase(PG8_LAS unsigned char* lds, const Gemm g, const Sched& S, const Epi& E) {
;     ...
;             PG8_WAIT_V(8); PG8_WAIT_L(0); PG8_BAR; PG8_MMA(1, 0, At, B0); PG8_MMA(1, 1, At, B1); PG8_BAR; PG8_SCHED;
;             PG8_LDB(B0, 1, 0); PG8_LDB(B1, 1, 1); PG8_SCHED; PG8_LDA(At, 1, 0); PG8_STAGE(PG8_SA(0, 1), a2 + hstep, voffA);
;             PG8_WAIT_V(8); PG8_WAIT_L(0); PG8_BAR; PG8_MMA(0, 0, At, B0); PG8_MMA(0, 1, At, B1); PG8_BAR; PG8_SCHED;
	v_mfma_f32_16x16x32_bf16 v[60:63], v[162:165], v[210:213], v[60:63]
	v_mfma_f32_16x16x32_bf16 v[52:55], v[186:189], v[210:213], v[52:55]
	v_mfma_f32_16x16x32_bf16 v[44:47], v[162:165], v[220:223], v[44:47]
	v_mfma_f32_16x16x32_bf16 v[36:39], v[186:189], v[220:223], v[36:39]
	v_mfma_f32_16x16x32_bf16 v[28:31], v[162:165], v[228:231], v[28:31]
	v_mfma_f32_16x16x32_bf16 v[20:23], v[186:189], v[228:231], v[20:23]
	v_mfma_f32_16x16x32_bf16 v[12:15], v[162:165], v[236:239], v[12:15]
	v_mfma_f32_16x16x32_bf16 v[4:7], v[186:189], v[236:239], v[4:7]
	v_mfma_f32_16x16x32_bf16 v[60:63], v[182:185], v[216:219], v[60:63]
	v_mfma_f32_16x16x32_bf16 v[52:55], v[190:193], v[216:219], v[52:55]
	v_mfma_f32_16x16x32_bf16 v[44:47], v[182:185], v[224:227], v[44:47]
	v_mfma_f32_16x16x32_bf16 v[36:39], v[190:193], v[224:227], v[36:39]
	v_mfma_f32_16x16x32_bf16 v[28:31], v[182:185], v[232:235], v[28:31]
	v_mfma_f32_16x16x32_bf16 v[20:23], v[190:193], v[232:235], v[20:23]
	v_mfma_f32_16x16x32_bf16 v[12:15], v[182:185], v[240:243], v[12:15]
	v_mfma_f32_16x16x32_bf16 v[4:7], v[190:193], v[240:243], v[4:7]
	v_mfma_f32_16x16x32_bf16 v[56:59], v[194:197], v[210:213], v[56:59]
	v_mfma_f32_16x16x32_bf16 v[48:51], v[202:205], v[210:213], v[48:51]
	v_mfma_f32_16x16x32_bf16 v[40:43], v[194:197], v[220:223], v[40:43]
	v_mfma_f32_16x16x32_bf16 v[32:35], v[202:205], v[220:223], v[32:35]
	v_mfma_f32_16x16x32_bf16 v[24:27], v[194:197], v[228:231], v[24:27]
	v_mfma_f32_16x16x32_bf16 v[16:19], v[202:205], v[228:231], v[16:19]
	v_mfma_f32_16x16x32_bf16 v[8:11], v[194:197], v[236:239], v[8:11]
	v_mfma_f32_16x16x32_bf16 v[0:3], v[202:205], v[236:239], v[0:3]
	v_mfma_f32_16x16x32_bf16 v[56:59], v[198:201], v[216:219], v[56:59]
	v_mfma_f32_16x16x32_bf16 v[48:51], v[206:209], v[216:219], v[48:51]
	v_mfma_f32_16x16x32_bf16 v[40:43], v[198:201], v[224:227], v[40:43]
	v_mfma_f32_16x16x32_bf16 v[32:35], v[206:209], v[224:227], v[32:35]
	v_mfma_f32_16x16x32_bf16 v[24:27], v[198:201], v[232:235], v[24:27]
	v_mfma_f32_16x16x32_bf16 v[16:19], v[206:209], v[232:235], v[16:19]
	v_mfma_f32_16x16x32_bf16 v[8:11], v[198:201], v[240:243], v[8:11]
	v_mfma_f32_16x16x32_bf16 v[0:3], v[206:209], v[240:243], v[0:3]
	s_setprio 0
	s_barrier
	s_add_i32 s11, 0, 0x18000
	v_add_u32_e32 v166, s11, v169
	s_add_i32 s13, 0, 0x1c000
	ds_read_b128 v[162:165], v166
	ds_read_b128 v[182:185], v166 offset:1024
	ds_read_b128 v[186:189], v166 offset:2048
	ds_read_b128 v[190:193], v166 offset:3072
	v_add_u32_e32 v166, s13, v169
	ds_read_b128 v[194:197], v166
	ds_read_b128 v[198:201], v166 offset:1024
	ds_read_b128 v[202:205], v166 offset:2048
	ds_read_b128 v[206:209], v166 offset:3072
	v_lshl_add_u64 v[172:173], v[172:173], 0, s[14:15]
	s_mov_b32 m0, s48
	v_lshl_add_u64 v[170:171], v[172:173], 0, v[140:141]
	ds_read_b128 v[210:213], v179 offset:32768
	ds_read_b128 v[216:219], v179 offset:33792
	ds_read_b128 v[220:223], v179 offset:34816
	ds_read_b128 v[224:227], v179 offset:35840
	ds_read_b128 v[228:231], v179 offset:36864
	ds_read_b128 v[232:235], v179 offset:37888
	ds_read_b128 v[236:239], v179 offset:38912
	ds_read_b128 v[240:243], v179 offset:39936
	global_load_lds_dwordx4 v[170:171], off
	s_mov_b32 m0, s49
	v_lshl_add_u64 v[170:171], v[172:173], 0, v[136:137]
	global_load_lds_dwordx4 v[170:171], off
	s_waitcnt vmcnt(8) lgkmcnt(0)
	s_setprio 1
	s_barrier
	v_mfma_f32_16x16x32_bf16 v[124:127], v[162:165], v[210:213], v[124:127]
	v_mfma_f32_16x16x32_bf16 v[116:119], v[186:189], v[210:213], v[116:119]
	v_mfma_f32_16x16x32_bf16 v[108:111], v[162:165], v[220:223], v[108:111]
	v_mfma_f32_16x16x32_bf16 v[100:103], v[186:189], v[220:223], v[100:103]
	v_mfma_f32_16x16x32_bf16 v[92:95], v[162:165], v[228:231], v[92:95]
	v_mfma_f32_16x16x32_bf16 v[84:87], v[186:189], v[228:231], v[84:87]
	v_mfma_f32_16x16x32_bf16 v[76:79], v[162:165], v[236:239], v[76:79]
	v_mfma_f32_16x16x32_bf16 v[68:71], v[186:189], v[236:239], v[68:71]
	v_mfma_f32_16x16x32_bf16 v[124:127], v[182:185], v[216:219], v[124:127]
	v_mfma_f32_16x16x32_bf16 v[116:119], v[190:193], v[216:219], v[116:119]
	v_mfma_f32_16x16x32_bf16 v[108:111], v[182:185], v[224:227], v[108:111]
	v_mfma_f32_16x16x32_bf16 v[100:103], v[190:193], v[224:227], v[100:103]
	v_mfma_f32_16x16x32_bf16 v[92:95], v[182:185], v[232:235], v[92:95]
	v_mfma_f32_16x16x32_bf16 v[84:87], v[190:193], v[232:235], v[84:87]
	v_mfma_f32_16x16x32_bf16 v[76:79], v[182:185], v[240:243], v[76:79]
	v_mfma_f32_16x16x32_bf16 v[68:71], v[190:193], v[240:243], v[68:71]
	v_mfma_f32_16x16x32_bf16 v[120:123], v[194:197], v[210:213], v[120:123]
	v_mfma_f32_16x16x32_bf16 v[112:115], v[202:205], v[210:213], v[112:115]
	v_mfma_f32_16x16x32_bf16 v[104:107], v[194:197], v[220:223], v[104:107]
	v_mfma_f32_16x16x32_bf16 v[96:99], v[202:205], v[220:223], v[96:99]
	v_mfma_f32_16x16x32_bf16 v[88:91], v[194:197], v[228:231], v[88:91]
	v_mfma_f32_16x16x32_bf16 v[80:83], v[202:205], v[228:231], v[80:83]
	v_mfma_f32_16x16x32_bf16 v[72:75], v[194:197], v[236:239], v[72:75]
	v_mfma_f32_16x16x32_bf16 v[64:67], v[202:205], v[236:239], v[64:67]
	v_mfma_f32_16x16x32_bf16 v[120:123], v[198:201], v[216:219], v[120:123]
	v_mfma_f32_16x16x32_bf16 v[112:115], v[206:209], v[216:219], v[112:115]
	v_mfma_f32_16x16x32_bf16 v[104:107], v[198:201], v[224:227], v[104:107]
	v_mfma_f32_16x16x32_bf16 v[96:99], v[206:209], v[224:227], v[96:99]
	v_mfma_f32_16x16x32_bf16 v[88:91], v[198:201], v[232:235], v[88:91]
	v_mfma_f32_16x16x32_bf16 v[80:83], v[206:209], v[232:235], v[80:83]
	v_mfma_f32_16x16x32_bf16 v[72:75], v[198:201], v[240:243], v[72:75]
	v_mfma_f32_16x16x32_bf16 v[64:67], v[206:209], v[240:243], v[64:67]
	s_setprio 0
	s_barrier
; #define PG8_STAGE(bufoff, gbase, voff) do { _Pragma("unroll") for (int _i = 0; _i < 2; ++_i) \
;         __builtin_amdgcn_global_load_lds((const unsigned*)((const char*)(gbase) + (voff)[_i]), (PG8_LAS unsigned*)(lds + (bufoff) + ldsw + _i * 8192), 16, 0, 0); } while (0)
; #define PG8_LDA(dst, b, h) do { _Pragma("unroll") for (int m = 0; m < 4; ++m) _Pragma("unroll") for (int k = 0; k < 2; ++k) dst[m][k] = *(const PG8_LAS bf16x8*)(lds + PG8_SA(b, h) + aoff + m * 2048 + k * 1024); } while (0)
; #define PG8_MMA(ai, bj, At, Bt) do { __builtin_amdgcn_s_setprio(1); _Pragma("unroll") for (int m = 0; m < 4; ++m) _Pragma("unroll") for (int n = 0; n < 2; ++n) _Pragma("unroll") for (int k = 0; k < 2; ++k) \
;         acc[ai][bj][m][n] = __builtin_amdgcn_mfma_f32_16x16x32_bf16(Bt[n][k], At[m][k], acc[ai][bj][m][n], 0, 0, 0); __builtin_amdgcn_s_setprio(0); } while (0)
; #define PG8_WAIT_V(n) asm volatile("s_waitcnt vmcnt(" #n ")" ::: "memory")
; #define PG8_WAIT_L(n) asm volatile("s_waitcnt lgkmcnt(" #n ")" ::: "memory")
; #define PG8_BAR __builtin_amdgcn_s_barrier()
; #define PG8_SCHED __builtin_amdgcn_sched_barrier(0)
; template <class Epi, class Sched, bool ALIGN_EPI = false, bool SP2 = false>
; __device__ __forceinline__ void gemm_phase(PG8_LAS unsigned char* lds, const Gemm g, const Sched& S, const Epi& E) {
;     ...
;             PG8_LDA(At, 1, 1); PG8_STAGE(PG8_SB(1, 0), b3, voffB); PG8_STAGE(PG8_SB(1, 1), b3 + hstep, voffB); PG8_STAGE(PG8_SA(1, 0), a3, voffA);
;             PG8_WAIT_V(8); PG8_WAIT_L(0); PG8_BAR; PG8_MMA(1, 0, At, B0); PG8_MMA(1, 1, At, B1); PG8_BAR; PG8_SCHED;
	s_add_i32 s11, s11, s29
	v_lshl_add_u64 v[170:171], v[246:247], 0, s[22:23]
	s_mov_b32 m0, s11
	ds_read_b128 v[210:213], v179 offset:49152
	ds_read_b128 v[216:219], v179 offset:50176
	ds_read_b128 v[220:223], v179 offset:51200
	ds_read_b128 v[224:227], v179 offset:52224
	ds_read_b128 v[228:231], v179 offset:53248
	ds_read_b128 v[232:235], v179 offset:54272
	ds_read_b128 v[236:239], v179 offset:55296
	ds_read_b128 v[240:243], v179 offset:56320
	global_load_lds_dwordx4 v[170:171], off
	v_lshl_add_u64 v[170:171], v[248:249], 0, s[22:23]
	s_add_i32 m0, s11, 0x2000
	s_add_i32 s11, s13, s29
	global_load_lds_dwordx4 v[170:171], off
	s_mov_b32 m0, s11
	v_lshl_add_u64 v[170:171], v[250:251], 0, s[22:23]
	global_load_lds_dwordx4 v[170:171], off
	s_add_i32 m0, s11, 0x2000
	v_lshl_add_u64 v[170:171], v[244:245], 0, s[22:23]
	global_load_lds_dwordx4 v[170:171], off
	s_mov_b32 m0, s50
	v_lshl_add_u64 v[170:171], v[252:253], 0, s[22:23]
	global_load_lds_dwordx4 v[170:171], off
	s_mov_b32 m0, s51
	v_lshl_add_u64 v[170:171], v[214:215], 0, s[22:23]
	global_load_lds_dwordx4 v[170:171], off
	s_waitcnt vmcnt(8) lgkmcnt(0)
	s_setprio 1
	s_barrier
	v_mfma_f32_16x16x32_bf16 v[60:63], v[162:165], v[210:213], v[60:63]
	v_mfma_f32_16x16x32_bf16 v[52:55], v[186:189], v[210:213], v[52:55]
	v_mfma_f32_16x16x32_bf16 v[44:47], v[162:165], v[220:223], v[44:47]
	v_mfma_f32_16x16x32_bf16 v[36:39], v[186:189], v[220:223], v[36:39]
	v_mfma_f32_16x16x32_bf16 v[28:31], v[162:165], v[228:231], v[28:31]
	v_mfma_f32_16x16x32_bf16 v[20:23], v[186:189], v[228:231], v[20:23]
	v_mfma_f32_16x16x32_bf16 v[12:15], v[162:165], v[236:239], v[12:15]
	v_mfma_f32_16x16x32_bf16 v[4:7], v[186:189], v[236:239], v[4:7]
	v_mfma_f32_16x16x32_bf16 v[60:63], v[182:185], v[216:219], v[60:63]
	v_mfma_f32_16x16x32_bf16 v[52:55], v[190:193], v[216:219], v[52:55]
	v_mfma_f32_16x16x32_bf16 v[44:47], v[182:185], v[224:227], v[44:47]
	v_mfma_f32_16x16x32_bf16 v[36:39], v[190:193], v[224:227], v[36:39]
	v_mfma_f32_16x16x32_bf16 v[28:31], v[182:185], v[232:235], v[28:31]
	v_mfma_f32_16x16x32_bf16 v[20:23], v[190:193], v[232:235], v[20:23]
	v_mfma_f32_16x16x32_bf16 v[12:15], v[182:185], v[240:243], v[12:15]
	v_mfma_f32_16x16x32_bf16 v[4:7], v[190:193], v[240:243], v[4:7]
	v_mfma_f32_16x16x32_bf16 v[56:59], v[194:197], v[210:213], v[56:59]
	v_mfma_f32_16x16x32_bf16 v[48:51], v[202:205], v[210:213], v[48:51]
	v_mfma_f32_16x16x32_bf16 v[40:43], v[194:197], v[220:223], v[40:43]
	v_mfma_f32_16x16x32_bf16 v[32:35], v[202:205], v[220:223], v[32:35]
	v_mfma_f32_16x16x32_bf16 v[24:27], v[194:197], v[228:231], v[24:27]
	v_mfma_f32_16x16x32_bf16 v[16:19], v[202:205], v[228:231], v[16:19]
	v_mfma_f32_16x16x32_bf16 v[8:11], v[194:197], v[236:239], v[8:11]
	v_mfma_f32_16x16x32_bf16 v[0:3], v[202:205], v[236:239], v[0:3]
	v_mfma_f32_16x16x32_bf16 v[56:59], v[198:201], v[216:219], v[56:59]
	v_mfma_f32_16x16x32_bf16 v[48:51], v[206:209], v[216:219], v[48:51]
	v_mfma_f32_16x16x32_bf16 v[40:43], v[198:201], v[224:227], v[40:43]
	v_mfma_f32_16x16x32_bf16 v[32:35], v[206:209], v[224:227], v[32:35]
	v_mfma_f32_16x16x32_bf16 v[24:27], v[198:201], v[232:235], v[24:27]
	v_mfma_f32_16x16x32_bf16 v[16:19], v[206:209], v[232:235], v[16:19]
	v_mfma_f32_16x16x32_bf16 v[8:11], v[198:201], v[240:243], v[8:11]
	v_mfma_f32_16x16x32_bf16 v[0:3], v[206:209], v[240:243], v[0:3]
	s_setprio 0
	s_barrier
	v_lshl_add_u64 v[158:159], v[158:159], 0, s[26:27]
	s_cmp_ge_i32 s10, s52
	v_lshl_add_u64 v[160:161], v[160:161], 0, s[26:27]
	s_cbranch_scc0 .LBB0_304

; #define PG8_STAGE(bufoff, gbase, voff) do { _Pragma("unroll") for (int _i = 0; _i < 2; ++_i) \
;         __builtin_amdgcn_global_load_lds((const unsigned*)((const char*)(gbase) + (voff)[_i]), (PG8_LAS unsigned*)(lds + (bufoff) + ldsw + _i * 8192), 16, 0, 0); } while (0)
; #define PG8_LDA(dst, b, h) do { _Pragma("unroll") for (int m = 0; m < 4; ++m) _Pragma("unroll") for (int k = 0; k < 2; ++k) dst[m][k] = *(const PG8_LAS bf16x8*)(lds + PG8_SA(b, h) + aoff + m * 2048 + k * 1024); } while (0)
; #define PG8_LDB(dst, b, h) do { _Pragma("unroll") for (int n = 0; n < 2; ++n) _Pragma("unroll") for (int k = 0; k < 2; ++k) dst[n][k] = *(const PG8_LAS bf16x8*)(lds + PG8_SB(b, h) + boff + n * 2048 + k * 1024); } while (0)
; #define PG8_MMA(ai, bj, At, Bt) do { __builtin_amdgcn_s_setprio(1); _Pragma("unroll") for (int m = 0; m < 4; ++m) _Pragma("unroll") for (int n = 0; n < 2; ++n) _Pragma("unroll") for (int k = 0; k < 2; ++k) \
;         acc[ai][bj][m][n] = __builtin_amdgcn_mfma_f32_16x16x32_bf16(Bt[n][k], At[m][k], acc[ai][bj][m][n], 0, 0, 0); __builtin_amdgcn_s_setprio(0); } while (0)
; #define PG8_WAIT_V(n) asm volatile("s_waitcnt vmcnt(" #n ")" ::: "memory")
; #define PG8_WAIT_L(n) asm volatile("s_waitcnt lgkmcnt(" #n ")" ::: "memory")
; template <class Epi, class Sched, bool ALIGN_EPI = false, bool SP2 = false>
; __device__ __forceinline__ void gemm_phase(PG8_LAS unsigned char* lds, const Gemm g, const Sched& S, const Epi& E) {
;     ...
;             const bool last = (t == nt - 2);
;             const char* a1 = cA + (size_t)(t + 1) * kstep;
;             const char* a2 = last ? nA : cA + (size_t)(t + 2) * kstep; const char* b2 = last ? nB : cB + (size_t)(t + 2) * kstep;
;             const char* a3 = a2 + kstep; const char* b3 = b2 + kstep;
;             if (last && has_next) S.a_ready(nxt);
;             if constexpr (SP2) {
;             PG8_LDB(B0, 0, 0); PG8_LDB(B1, 0, 1); PG8_SCHED; PG8_LDA(At, 0, 0); PG8_STAGE(PG8_SA(1, 1), a1 + hstep, voffA);
;             PG8_WAIT_V(8); PG8_WAIT_L(0); PG8_BAR; PG8_MMA(0, 0, At, B0); PG8_MMA(0, 1, At, B1); PG8_BAR; PG8_SCHED;
;             PG8_LDA(At, 0, 1); PG8_STAGE(PG8_SB(0, 0), b2, voffB); PG8_STAGE(PG8_SB(0, 1), b2 + hstep, voffB); PG8_STAGE(PG8_SA(0, 0), a2, voffA);
;             PG8_WAIT_V(8); PG8_WAIT_L(0); PG8_BAR; PG8_MMA(1, 0, At, B0); PG8_MMA(1, 1, At, B1); PG8_BAR; PG8_SCHED;
.LBB0_371:
	v_add_u32_e32 v148, s54, v201
	v_add_u32_e32 v190, s55, v201
	ds_read_b128 v[136:139], v148
	ds_read_b128 v[140:143], v148 offset:1024
	ds_read_b128 v[144:147], v148 offset:2048
	ds_read_b128 v[148:151], v148 offset:3072
	ds_read_b128 v[152:155], v190
	ds_read_b128 v[182:185], v190 offset:1024
	ds_read_b128 v[186:189], v190 offset:2048
	ds_read_b128 v[190:193], v190 offset:3072
	s_cmp_eq_u32 s48, s12
	v_lshl_add_u64 v[194:195], v[134:135], 0, s[22:23]
	s_cselect_b64 vcc, -1, 0
	s_add_i32 s12, s12, 2
	v_cndmask_b32_e32 v199, v195, v179, vcc
	v_cndmask_b32_e32 v198, v194, v178, vcc
	v_cndmask_b32_e32 v215, v133, v181, vcc
	v_cndmask_b32_e32 v214, v132, v180, vcc
	s_mov_b32 m0, s56
	v_lshl_add_u64 v[236:237], v[134:135], 0, v[174:175]
	ds_read_b128 v[194:197], v203
	ds_read_b128 v[206:209], v203 offset:1024
	ds_read_b128 v[210:213], v203 offset:2048
	ds_read_b128 v[216:219], v203 offset:3072
	ds_read_b128 v[220:223], v203 offset:4096
	ds_read_b128 v[224:227], v203 offset:5120
	ds_read_b128 v[228:231], v203 offset:6144
	ds_read_b128 v[232:235], v203 offset:7168
	global_load_lds_dwordx4 v[236:237], off
	s_mov_b32 m0, s57
	v_lshl_add_u64 v[236:237], v[134:135], 0, v[172:173]
	global_load_lds_dwordx4 v[236:237], off
	s_waitcnt vmcnt(8) lgkmcnt(0)
	s_setprio 1
	s_barrier
	v_mfma_f32_16x16x32_bf16 v[124:127], v[136:139], v[194:197], v[124:127]
	v_mfma_f32_16x16x32_bf16 v[128:131], v[144:147], v[194:197], v[128:131]
	v_mfma_f32_16x16x32_bf16 v[112:115], v[136:139], v[210:213], v[112:115]
	v_mfma_f32_16x16x32_bf16 v[108:111], v[144:147], v[210:213], v[108:111]
	v_mfma_f32_16x16x32_bf16 v[96:99], v[136:139], v[220:223], v[96:99]
	v_mfma_f32_16x16x32_bf16 v[92:95], v[144:147], v[220:223], v[92:95]
	v_mfma_f32_16x16x32_bf16 v[80:83], v[136:139], v[228:231], v[80:83]
	v_mfma_f32_16x16x32_bf16 v[76:79], v[144:147], v[228:231], v[76:79]
	v_mfma_f32_16x16x32_bf16 v[124:127], v[140:143], v[206:209], v[124:127]
	v_mfma_f32_16x16x32_bf16 v[128:131], v[148:151], v[206:209], v[128:131]
	v_mfma_f32_16x16x32_bf16 v[112:115], v[140:143], v[216:219], v[112:115]
	v_mfma_f32_16x16x32_bf16 v[108:111], v[148:151], v[216:219], v[108:111]
	v_mfma_f32_16x16x32_bf16 v[96:99], v[140:143], v[224:227], v[96:99]
	v_mfma_f32_16x16x32_bf16 v[92:95], v[148:151], v[224:227], v[92:95]
	v_mfma_f32_16x16x32_bf16 v[80:83], v[140:143], v[232:235], v[80:83]
	v_mfma_f32_16x16x32_bf16 v[76:79], v[148:151], v[232:235], v[76:79]
	v_mfma_f32_16x16x32_bf16 v[120:123], v[152:155], v[194:197], v[120:123]
	v_mfma_f32_16x16x32_bf16 v[116:119], v[186:189], v[194:197], v[116:119]
	v_mfma_f32_16x16x32_bf16 v[104:107], v[152:155], v[210:213], v[104:107]
	v_mfma_f32_16x16x32_bf16 v[100:103], v[186:189], v[210:213], v[100:103]
	v_mfma_f32_16x16x32_bf16 v[88:91], v[152:155], v[220:223], v[88:91]
	v_mfma_f32_16x16x32_bf16 v[84:87], v[186:189], v[220:223], v[84:87]
	v_mfma_f32_16x16x32_bf16 v[72:75], v[152:155], v[228:231], v[72:75]
	v_mfma_f32_16x16x32_bf16 v[68:71], v[186:189], v[228:231], v[68:71]
	v_mfma_f32_16x16x32_bf16 v[120:123], v[182:185], v[206:209], v[120:123]
	v_mfma_f32_16x16x32_bf16 v[116:119], v[190:193], v[206:209], v[116:119]
	v_mfma_f32_16x16x32_bf16 v[104:107], v[182:185], v[216:219], v[104:107]
	v_mfma_f32_16x16x32_bf16 v[100:103], v[190:193], v[216:219], v[100:103]
	v_mfma_f32_16x16x32_bf16 v[88:91], v[182:185], v[224:227], v[88:91]
	v_mfma_f32_16x16x32_bf16 v[84:87], v[190:193], v[224:227], v[84:87]
	v_mfma_f32_16x16x32_bf16 v[72:75], v[182:185], v[232:235], v[72:75]
	v_mfma_f32_16x16x32_bf16 v[68:71], v[190:193], v[232:235], v[68:71]
	s_setprio 0
	s_barrier
	s_mov_b32 m0, s58
	v_lshl_add_u64 v[236:237], v[214:215], 0, v[166:167]
	ds_read_b128 v[194:197], v203 offset:16384
	ds_read_b128 v[206:209], v203 offset:17408
	ds_read_b128 v[210:213], v203 offset:18432
	ds_read_b128 v[216:219], v203 offset:19456
	ds_read_b128 v[220:223], v203 offset:20480
	ds_read_b128 v[224:227], v203 offset:21504
	ds_read_b128 v[228:231], v203 offset:22528
	ds_read_b128 v[232:235], v203 offset:23552
	global_load_lds_dwordx4 v[236:237], off
	v_lshl_add_u64 v[238:239], v[214:215], 0, v[170:171]
	s_mov_b32 m0, s59
	v_lshl_add_u64 v[214:215], v[214:215], 0, s[14:15]
	s_add_i32 s13, s55, s30
	global_load_lds_dwordx4 v[238:239], off
	v_lshl_add_u64 v[240:241], v[214:215], 0, v[166:167]
	s_mov_b32 m0, s13
	v_lshl_add_u64 v[214:215], v[214:215], 0, v[170:171]
	global_load_lds_dwordx4 v[240:241], off
	s_add_i32 m0, s13, 0x2000
	v_lshl_add_u64 v[242:243], v[198:199], 0, v[164:165]
	global_load_lds_dwordx4 v[214:215], off
	s_mov_b32 m0, s31
	v_lshl_add_u64 v[244:245], v[198:199], 0, v[168:169]
	global_load_lds_dwordx4 v[242:243], off
	s_mov_b32 m0, s34
	s_nop 0
	global_load_lds_dwordx4 v[244:245], off
	s_waitcnt vmcnt(8) lgkmcnt(0)
	s_setprio 1
	s_barrier
; #define PG8_STAGE(bufoff, gbase, voff) do { _Pragma("unroll") for (int _i = 0; _i < 2; ++_i) \
;         __builtin_amdgcn_global_load_lds((const unsigned*)((const char*)(gbase) + (voff)[_i]), (PG8_LAS unsigned*)(lds + (bufoff) + ldsw + _i * 8192), 16, 0, 0); } while (0)
; #define PG8_LDA(dst, b, h) do { _Pragma("unroll") for (int m = 0; m < 4; ++m) _Pragma("unroll") for (int k = 0; k < 2; ++k) dst[m][k] = *(const PG8_LAS bf16x8*)(lds + PG8_SA(b, h) + aoff + m * 2048 + k * 1024); } while (0)
; #define PG8_LDB(dst, b, h) do { _Pragma("unroll") for (int n = 0; n < 2; ++n) _Pragma("unroll") for (int k = 0; k < 2; ++k) dst[n][k] = *(const PG8_LAS bf16x8*)(lds + PG8_SB(b, h) + boff + n * 2048 + k * 1024); } while (0)
; #define PG8_MMA(ai, bj, At, Bt) do { __builtin_amdgcn_s_setprio(1); _Pragma("unroll") for (int m = 0; m < 4; ++m) _Pragma("unroll") for (int n = 0; n < 2; ++n) _Pragma("unroll") for (int k = 0; k < 2; ++k) \
;         acc[ai][bj][m][n] = __builtin_amdgcn_mfma_f32_16x16x32_bf16(Bt[n][k], At[m][k], acc[ai][bj][m][n], 0, 0, 0); __builtin_amdgcn_s_setprio(0); } while (0)
; #define PG8_WAIT_V(n) asm volatile("s_waitcnt vmcnt(" #n ")" ::: "memory")
; #define PG8_WAIT_L(n) asm volatile("s_waitcnt lgkmcnt(" #n ")" ::: "memory")
; #define PG8_BAR __builtin_amdgcn_s_barrier()
; #define PG8_SCHED __builtin_amdgcn_sched_barrier(0)
; template <class Epi, class Sched, bool ALIGN_EPI = false, bool SP2 = false>
; __device__ __forceinline__ void gemm_phase(PG8_LAS unsigned char* lds, const Gemm g, const Sched& S, const Epi& E) {
;     ...
;             PG8_WAIT_V(8); PG8_WAIT_L(0); PG8_BAR; PG8_MMA(1, 0, At, B0); PG8_MMA(1, 1, At, B1); PG8_BAR; PG8_SCHED;
;             PG8_LDB(B0, 1, 0); PG8_LDB(B1, 1, 1); PG8_SCHED; PG8_LDA(At, 1, 0); PG8_STAGE(PG8_SA(0, 1), a2 + hstep, voffA);
;             PG8_WAIT_V(8); PG8_WAIT_L(0); PG8_BAR; PG8_MMA(0, 0, At, B0); PG8_MMA(0, 1, At, B1); PG8_BAR; PG8_SCHED;
	v_mfma_f32_16x16x32_bf16 v[64:67], v[136:139], v[194:197], v[64:67]
	v_mfma_f32_16x16x32_bf16 v[60:63], v[144:147], v[194:197], v[60:63]
	v_mfma_f32_16x16x32_bf16 v[48:51], v[136:139], v[210:213], v[48:51]
	v_mfma_f32_16x16x32_bf16 v[44:47], v[144:147], v[210:213], v[44:47]
	v_mfma_f32_16x16x32_bf16 v[32:35], v[136:139], v[220:223], v[32:35]
	v_mfma_f32_16x16x32_bf16 v[28:31], v[144:147], v[220:223], v[28:31]
	v_mfma_f32_16x16x32_bf16 v[16:19], v[136:139], v[228:231], v[16:19]
	v_mfma_f32_16x16x32_bf16 v[12:15], v[144:147], v[228:231], v[12:15]
	v_mfma_f32_16x16x32_bf16 v[64:67], v[140:143], v[206:209], v[64:67]
	v_mfma_f32_16x16x32_bf16 v[60:63], v[148:151], v[206:209], v[60:63]
	v_mfma_f32_16x16x32_bf16 v[48:51], v[140:143], v[216:219], v[48:51]
	v_mfma_f32_16x16x32_bf16 v[44:47], v[148:151], v[216:219], v[44:47]
	v_mfma_f32_16x16x32_bf16 v[32:35], v[140:143], v[224:227], v[32:35]
	v_mfma_f32_16x16x32_bf16 v[28:31], v[148:151], v[224:227], v[28:31]
	v_mfma_f32_16x16x32_bf16 v[16:19], v[140:143], v[232:235], v[16:19]
	v_mfma_f32_16x16x32_bf16 v[12:15], v[148:151], v[232:235], v[12:15]
	v_mfma_f32_16x16x32_bf16 v[56:59], v[152:155], v[194:197], v[56:59]
	v_mfma_f32_16x16x32_bf16 v[52:55], v[186:189], v[194:197], v[52:55]
	v_mfma_f32_16x16x32_bf16 v[40:43], v[152:155], v[210:213], v[40:43]
	v_mfma_f32_16x16x32_bf16 v[36:39], v[186:189], v[210:213], v[36:39]
	v_mfma_f32_16x16x32_bf16 v[24:27], v[152:155], v[220:223], v[24:27]
	v_mfma_f32_16x16x32_bf16 v[20:23], v[186:189], v[220:223], v[20:23]
	v_mfma_f32_16x16x32_bf16 v[8:11], v[152:155], v[228:231], v[8:11]
	v_mfma_f32_16x16x32_bf16 v[4:7], v[186:189], v[228:231], v[4:7]
	v_mfma_f32_16x16x32_bf16 v[56:59], v[182:185], v[206:209], v[56:59]
	v_mfma_f32_16x16x32_bf16 v[52:55], v[190:193], v[206:209], v[52:55]
	v_mfma_f32_16x16x32_bf16 v[40:43], v[182:185], v[216:219], v[40:43]
	v_mfma_f32_16x16x32_bf16 v[36:39], v[190:193], v[216:219], v[36:39]
	v_mfma_f32_16x16x32_bf16 v[24:27], v[182:185], v[224:227], v[24:27]
	v_mfma_f32_16x16x32_bf16 v[20:23], v[190:193], v[224:227], v[20:23]
	v_mfma_f32_16x16x32_bf16 v[8:11], v[182:185], v[232:235], v[8:11]
	v_mfma_f32_16x16x32_bf16 v[4:7], v[190:193], v[232:235], v[4:7]
	s_setprio 0
	s_barrier
	s_add_i32 s13, 0, 0x18000
	s_add_i32 s29, 0, 0x1c000
	v_add_u32_e32 v148, s13, v201
	v_add_u32_e32 v190, s29, v201
	ds_read_b128 v[136:139], v148
	ds_read_b128 v[140:143], v148 offset:1024
	ds_read_b128 v[144:147], v148 offset:2048
	ds_read_b128 v[148:151], v148 offset:3072
	ds_read_b128 v[152:155], v190
	ds_read_b128 v[182:185], v190 offset:1024
	ds_read_b128 v[186:189], v190 offset:2048
	ds_read_b128 v[190:193], v190 offset:3072
	v_lshl_add_u64 v[198:199], v[198:199], 0, s[14:15]
	s_mov_b32 m0, s35
	v_lshl_add_u64 v[246:247], v[198:199], 0, v[164:165]
	ds_read_b128 v[194:197], v203 offset:32768
	ds_read_b128 v[206:209], v203 offset:33792
	ds_read_b128 v[210:213], v203 offset:34816
	ds_read_b128 v[216:219], v203 offset:35840
	ds_read_b128 v[220:223], v203 offset:36864
	ds_read_b128 v[224:227], v203 offset:37888
	ds_read_b128 v[228:231], v203 offset:38912
	ds_read_b128 v[232:235], v203 offset:39936
	global_load_lds_dwordx4 v[246:247], off
	s_mov_b32 m0, s36
	v_lshl_add_u64 v[198:199], v[198:199], 0, v[168:169]
	global_load_lds_dwordx4 v[198:199], off
	s_waitcnt vmcnt(8) lgkmcnt(0)
	s_setprio 1
	s_barrier
	v_mfma_f32_16x16x32_bf16 v[124:127], v[136:139], v[194:197], v[124:127]
	v_mfma_f32_16x16x32_bf16 v[128:131], v[144:147], v[194:197], v[128:131]
	v_mfma_f32_16x16x32_bf16 v[112:115], v[136:139], v[210:213], v[112:115]
	v_mfma_f32_16x16x32_bf16 v[108:111], v[144:147], v[210:213], v[108:111]
	v_mfma_f32_16x16x32_bf16 v[96:99], v[136:139], v[220:223], v[96:99]
	v_mfma_f32_16x16x32_bf16 v[92:95], v[144:147], v[220:223], v[92:95]
	v_mfma_f32_16x16x32_bf16 v[80:83], v[136:139], v[228:231], v[80:83]
	v_mfma_f32_16x16x32_bf16 v[76:79], v[144:147], v[228:231], v[76:79]
	v_mfma_f32_16x16x32_bf16 v[124:127], v[140:143], v[206:209], v[124:127]
	v_mfma_f32_16x16x32_bf16 v[128:131], v[148:151], v[206:209], v[128:131]
	v_mfma_f32_16x16x32_bf16 v[112:115], v[140:143], v[216:219], v[112:115]
	v_mfma_f32_16x16x32_bf16 v[108:111], v[148:151], v[216:219], v[108:111]
	v_mfma_f32_16x16x32_bf16 v[96:99], v[140:143], v[224:227], v[96:99]
	v_mfma_f32_16x16x32_bf16 v[92:95], v[148:151], v[224:227], v[92:95]
	v_mfma_f32_16x16x32_bf16 v[80:83], v[140:143], v[232:235], v[80:83]
	v_mfma_f32_16x16x32_bf16 v[76:79], v[148:151], v[232:235], v[76:79]
	v_mfma_f32_16x16x32_bf16 v[120:123], v[152:155], v[194:197], v[120:123]
	v_mfma_f32_16x16x32_bf16 v[116:119], v[186:189], v[194:197], v[116:119]
	v_mfma_f32_16x16x32_bf16 v[104:107], v[152:155], v[210:213], v[104:107]
	v_mfma_f32_16x16x32_bf16 v[100:103], v[186:189], v[210:213], v[100:103]
	v_mfma_f32_16x16x32_bf16 v[88:91], v[152:155], v[220:223], v[88:91]
	v_mfma_f32_16x16x32_bf16 v[84:87], v[186:189], v[220:223], v[84:87]
	v_mfma_f32_16x16x32_bf16 v[72:75], v[152:155], v[228:231], v[72:75]
	v_mfma_f32_16x16x32_bf16 v[68:71], v[186:189], v[228:231], v[68:71]
	v_mfma_f32_16x16x32_bf16 v[120:123], v[182:185], v[206:209], v[120:123]
	v_mfma_f32_16x16x32_bf16 v[116:119], v[190:193], v[206:209], v[116:119]
	v_mfma_f32_16x16x32_bf16 v[104:107], v[182:185], v[216:219], v[104:107]
	v_mfma_f32_16x16x32_bf16 v[100:103], v[190:193], v[216:219], v[100:103]
	v_mfma_f32_16x16x32_bf16 v[88:91], v[182:185], v[224:227], v[88:91]
	v_mfma_f32_16x16x32_bf16 v[84:87], v[190:193], v[224:227], v[84:87]
	v_mfma_f32_16x16x32_bf16 v[72:75], v[182:185], v[232:235], v[72:75]
	v_mfma_f32_16x16x32_bf16 v[68:71], v[190:193], v[232:235], v[68:71]
	s_setprio 0
	s_barrier
; #define PG8_STAGE(bufoff, gbase, voff) do { _Pragma("unroll") for (int _i = 0; _i < 2; ++_i) \
;         __builtin_amdgcn_global_load_lds((const unsigned*)((const char*)(gbase) + (voff)[_i]), (PG8_LAS unsigned*)(lds + (bufoff) + ldsw + _i * 8192), 16, 0, 0); } while (0)
; #define PG8_LDA(dst, b, h) do { _Pragma("unroll") for (int m = 0; m < 4; ++m) _Pragma("unroll") for (int k = 0; k < 2; ++k) dst[m][k] = *(const PG8_LAS bf16x8*)(lds + PG8_SA(b, h) + aoff + m * 2048 + k * 1024); } while (0)
; #define PG8_MMA(ai, bj, At, Bt) do { __builtin_amdgcn_s_setprio(1); _Pragma("unroll") for (int m = 0; m < 4; ++m) _Pragma("unroll") for (int n = 0; n < 2; ++n) _Pragma("unroll") for (int k = 0; k < 2; ++k) \
;         acc[ai][bj][m][n] = __builtin_amdgcn_mfma_f32_16x16x32_bf16(Bt[n][k], At[m][k], acc[ai][bj][m][n], 0, 0, 0); __builtin_amdgcn_s_setprio(0); } while (0)
; #define PG8_WAIT_V(n) asm volatile("s_waitcnt vmcnt(" #n ")" ::: "memory")
; #define PG8_WAIT_L(n) asm volatile("s_waitcnt lgkmcnt(" #n ")" ::: "memory")
; #define PG8_BAR __builtin_amdgcn_s_barrier()
; #define PG8_SCHED __builtin_amdgcn_sched_barrier(0)
; template <class Epi, class Sched, bool ALIGN_EPI = false, bool SP2 = false>
; __device__ __forceinline__ void gemm_phase(PG8_LAS unsigned char* lds, const Gemm g, const Sched& S, const Epi& E) {
;     ...
;             PG8_LDA(At, 1, 1); PG8_STAGE(PG8_SB(1, 0), b3, voffB); PG8_STAGE(PG8_SB(1, 1), b3 + hstep, voffB); PG8_STAGE(PG8_SA(1, 0), a3, voffA);
;             PG8_WAIT_V(8); PG8_WAIT_L(0); PG8_BAR; PG8_MMA(1, 0, At, B0); PG8_MMA(1, 1, At, B1); PG8_BAR; PG8_SCHED;
	s_add_i32 s13, s13, s30
	v_lshl_add_u64 v[198:199], v[236:237], 0, s[22:23]
	s_mov_b32 m0, s13
	ds_read_b128 v[194:197], v203 offset:49152
	ds_read_b128 v[206:209], v203 offset:50176
	ds_read_b128 v[210:213], v203 offset:51200
	ds_read_b128 v[216:219], v203 offset:52224
	ds_read_b128 v[220:223], v203 offset:53248
	ds_read_b128 v[224:227], v203 offset:54272
	ds_read_b128 v[228:231], v203 offset:55296
	ds_read_b128 v[232:235], v203 offset:56320
	global_load_lds_dwordx4 v[198:199], off
	v_lshl_add_u64 v[198:199], v[238:239], 0, s[22:23]
	s_add_i32 m0, s13, 0x2000
	s_add_i32 s13, s29, s30
	global_load_lds_dwordx4 v[198:199], off
	s_mov_b32 m0, s13
	v_lshl_add_u64 v[198:199], v[240:241], 0, s[22:23]
	global_load_lds_dwordx4 v[198:199], off
	s_add_i32 m0, s13, 0x2000
	v_lshl_add_u64 v[198:199], v[214:215], 0, s[22:23]
	global_load_lds_dwordx4 v[198:199], off
	s_mov_b32 m0, s37
	v_lshl_add_u64 v[198:199], v[242:243], 0, s[22:23]
	global_load_lds_dwordx4 v[198:199], off
	s_mov_b32 m0, s41
	v_lshl_add_u64 v[198:199], v[244:245], 0, s[22:23]
	global_load_lds_dwordx4 v[198:199], off
	s_waitcnt vmcnt(8) lgkmcnt(0)
	s_setprio 1
	s_barrier
	v_mfma_f32_16x16x32_bf16 v[64:67], v[136:139], v[194:197], v[64:67]
	v_mfma_f32_16x16x32_bf16 v[60:63], v[144:147], v[194:197], v[60:63]
	v_mfma_f32_16x16x32_bf16 v[48:51], v[136:139], v[210:213], v[48:51]
	v_mfma_f32_16x16x32_bf16 v[44:47], v[144:147], v[210:213], v[44:47]
	v_mfma_f32_16x16x32_bf16 v[32:35], v[136:139], v[220:223], v[32:35]
	v_mfma_f32_16x16x32_bf16 v[28:31], v[144:147], v[220:223], v[28:31]
	v_mfma_f32_16x16x32_bf16 v[16:19], v[136:139], v[228:231], v[16:19]
	v_mfma_f32_16x16x32_bf16 v[12:15], v[144:147], v[228:231], v[12:15]
	v_mfma_f32_16x16x32_bf16 v[64:67], v[140:143], v[206:209], v[64:67]
	v_mfma_f32_16x16x32_bf16 v[60:63], v[148:151], v[206:209], v[60:63]
	v_mfma_f32_16x16x32_bf16 v[48:51], v[140:143], v[216:219], v[48:51]
	v_mfma_f32_16x16x32_bf16 v[44:47], v[148:151], v[216:219], v[44:47]
	v_mfma_f32_16x16x32_bf16 v[32:35], v[140:143], v[224:227], v[32:35]
	v_mfma_f32_16x16x32_bf16 v[28:31], v[148:151], v[224:227], v[28:31]
	v_mfma_f32_16x16x32_bf16 v[16:19], v[140:143], v[232:235], v[16:19]
	v_mfma_f32_16x16x32_bf16 v[12:15], v[148:151], v[232:235], v[12:15]
	v_mfma_f32_16x16x32_bf16 v[56:59], v[152:155], v[194:197], v[56:59]
	v_mfma_f32_16x16x32_bf16 v[52:55], v[186:189], v[194:197], v[52:55]
	v_mfma_f32_16x16x32_bf16 v[40:43], v[152:155], v[210:213], v[40:43]
	v_mfma_f32_16x16x32_bf16 v[36:39], v[186:189], v[210:213], v[36:39]
	v_mfma_f32_16x16x32_bf16 v[24:27], v[152:155], v[220:223], v[24:27]
	v_mfma_f32_16x16x32_bf16 v[20:23], v[186:189], v[220:223], v[20:23]
	v_mfma_f32_16x16x32_bf16 v[8:11], v[152:155], v[228:231], v[8:11]
	v_mfma_f32_16x16x32_bf16 v[4:7], v[186:189], v[228:231], v[4:7]
	v_mfma_f32_16x16x32_bf16 v[56:59], v[182:185], v[206:209], v[56:59]
	v_mfma_f32_16x16x32_bf16 v[52:55], v[190:193], v[206:209], v[52:55]
	v_mfma_f32_16x16x32_bf16 v[40:43], v[182:185], v[216:219], v[40:43]
	v_mfma_f32_16x16x32_bf16 v[36:39], v[190:193], v[216:219], v[36:39]
	v_mfma_f32_16x16x32_bf16 v[24:27], v[182:185], v[224:227], v[24:27]
	v_mfma_f32_16x16x32_bf16 v[20:23], v[190:193], v[224:227], v[20:23]
	v_mfma_f32_16x16x32_bf16 v[8:11], v[182:185], v[232:235], v[8:11]
	v_mfma_f32_16x16x32_bf16 v[4:7], v[190:193], v[232:235], v[4:7]
	s_setprio 0
	s_barrier
	v_lshl_add_u64 v[132:133], v[132:133], 0, s[26:27]
	s_cmp_ge_i32 s12, s47
	v_lshl_add_u64 v[134:135], v[134:135], 0, s[26:27]
	s_cbranch_scc0 .LBB0_371

; #define PG8_STAGE(bufoff, gbase, voff) do { _Pragma("unroll") for (int _i = 0; _i < 2; ++_i) \
;         __builtin_amdgcn_global_load_lds((const unsigned*)((const char*)(gbase) + (voff)[_i]), (PG8_LAS unsigned*)(lds + (bufoff) + ldsw + _i * 8192), 16, 0, 0); } while (0)
; #define PG8_LDA(dst, b, h) do { _Pragma("unroll") for (int m = 0; m < 4; ++m) _Pragma("unroll") for (int k = 0; k < 2; ++k) dst[m][k] = *(const PG8_LAS bf16x8*)(lds + PG8_SA(b, h) + aoff + m * 2048 + k * 1024); } while (0)
; #define PG8_LDB(dst, b, h) do { _Pragma("unroll") for (int n = 0; n < 2; ++n) _Pragma("unroll") for (int k = 0; k < 2; ++k) dst[n][k] = *(const PG8_LAS bf16x8*)(lds + PG8_SB(b, h) + boff + n * 2048 + k * 1024); } while (0)
; #define PG8_MMA(ai, bj, At, Bt) do { __builtin_amdgcn_s_setprio(1); _Pragma("unroll") for (int m = 0; m < 4; ++m) _Pragma("unroll") for (int n = 0; n < 2; ++n) _Pragma("unroll") for (int k = 0; k < 2; ++k) \
;         acc[ai][bj][m][n] = __builtin_amdgcn_mfma_f32_16x16x32_bf16(Bt[n][k], At[m][k], acc[ai][bj][m][n], 0, 0, 0); __builtin_amdgcn_s_setprio(0); } while (0)
; #define PG8_WAIT_V(n) asm volatile("s_waitcnt vmcnt(" #n ")" ::: "memory")
; #define PG8_WAIT_L(n) asm volatile("s_waitcnt lgkmcnt(" #n ")" ::: "memory")
; template <class Epi, class Sched, bool ALIGN_EPI = false, bool SP2 = false>
; __device__ __forceinline__ void gemm_phase(PG8_LAS unsigned char* lds, const Gemm g, const Sched& S, const Epi& E) {
;     ...
;             const bool last = (t == nt - 2);
;             const char* a1 = cA + (size_t)(t + 1) * kstep;
;             const char* a2 = last ? nA : cA + (size_t)(t + 2) * kstep; const char* b2 = last ? nB : cB + (size_t)(t + 2) * kstep;
;             const char* a3 = a2 + kstep; const char* b3 = b2 + kstep;
;             if (last && has_next) S.a_ready(nxt);
;             if constexpr (SP2) {
;             PG8_LDB(B0, 0, 0); PG8_LDB(B1, 0, 1); PG8_SCHED; PG8_LDA(At, 0, 0); PG8_STAGE(PG8_SA(1, 1), a1 + hstep, voffA);
;             PG8_WAIT_V(8); PG8_WAIT_L(0); PG8_BAR; PG8_MMA(0, 0, At, B0); PG8_MMA(0, 1, At, B1); PG8_BAR; PG8_SCHED;
;             PG8_LDA(At, 0, 1); PG8_STAGE(PG8_SB(0, 0), b2, voffB); PG8_STAGE(PG8_SB(0, 1), b2 + hstep, voffB); PG8_STAGE(PG8_SA(0, 0), a2, voffA);
;             PG8_WAIT_V(8); PG8_WAIT_L(0); PG8_BAR; PG8_MMA(1, 0, At, B0); PG8_MMA(1, 1, At, B1); PG8_BAR; PG8_SCHED;
.LBB0_454:
	v_add_u32_e32 v165, s69, v171
	v_add_u32_e32 v167, s70, v171
	ds_read_b128 v[132:135], v165
	ds_read_b128 v[136:139], v165 offset:1024
	ds_read_b128 v[176:179], v165 offset:2048
	ds_read_b128 v[180:183], v165 offset:3072
	ds_read_b128 v[184:187], v167
	ds_read_b128 v[188:191], v167 offset:1024
	ds_read_b128 v[192:195], v167 offset:2048
	ds_read_b128 v[196:199], v167 offset:3072
	s_cmp_eq_u32 s62, s12
	v_lshl_add_u64 v[200:201], v[130:131], 0, s[24:25]
	s_cselect_b64 vcc, -1, 0
	s_add_i32 s12, s12, 2
	v_cndmask_b32_e32 v209, v201, v173, vcc
	v_cndmask_b32_e32 v208, v200, v172, vcc
	v_cndmask_b32_e32 v213, v129, v175, vcc
	v_cndmask_b32_e32 v212, v128, v174, vcc
	v_lshl_add_u64 v[214:215], v[130:131], 0, v[160:161]
	s_add_i32 m0, s41, 0xc000
	ds_read_b128 v[200:203], v216
	ds_read_b128 v[204:207], v216 offset:1024
	ds_read_b128 v[218:221], v216 offset:2048
	ds_read_b128 v[222:225], v216 offset:3072
	ds_read_b128 v[226:229], v216 offset:4096
	ds_read_b128 v[230:233], v216 offset:5120
	ds_read_b128 v[234:237], v216 offset:6144
	ds_read_b128 v[238:241], v216 offset:7168
	global_load_lds_dwordx4 v[214:215], off
	s_add_i32 m0, s41, 0xe000
	v_lshl_add_u64 v[214:215], v[130:131], 0, v[158:159]
	global_load_lds_dwordx4 v[214:215], off
	s_waitcnt vmcnt(8) lgkmcnt(0)
	s_setprio 1
	s_barrier
	v_mfma_f32_16x16x32_bf16 v[124:127], v[132:135], v[200:203], v[124:127]
	v_mfma_f32_16x16x32_bf16 v[120:123], v[176:179], v[200:203], v[120:123]
	v_mfma_f32_16x16x32_bf16 v[108:111], v[132:135], v[218:221], v[108:111]
	v_mfma_f32_16x16x32_bf16 v[104:107], v[176:179], v[218:221], v[104:107]
	v_mfma_f32_16x16x32_bf16 v[92:95], v[132:135], v[226:229], v[92:95]
	v_mfma_f32_16x16x32_bf16 v[88:91], v[176:179], v[226:229], v[88:91]
	v_mfma_f32_16x16x32_bf16 v[76:79], v[132:135], v[234:237], v[76:79]
	v_mfma_f32_16x16x32_bf16 v[72:75], v[176:179], v[234:237], v[72:75]
	v_mfma_f32_16x16x32_bf16 v[124:127], v[136:139], v[204:207], v[124:127]
	v_mfma_f32_16x16x32_bf16 v[120:123], v[180:183], v[204:207], v[120:123]
	v_mfma_f32_16x16x32_bf16 v[108:111], v[136:139], v[222:225], v[108:111]
	v_mfma_f32_16x16x32_bf16 v[104:107], v[180:183], v[222:225], v[104:107]
	v_mfma_f32_16x16x32_bf16 v[92:95], v[136:139], v[230:233], v[92:95]
	v_mfma_f32_16x16x32_bf16 v[88:91], v[180:183], v[230:233], v[88:91]
	v_mfma_f32_16x16x32_bf16 v[76:79], v[136:139], v[238:241], v[76:79]
	v_mfma_f32_16x16x32_bf16 v[72:75], v[180:183], v[238:241], v[72:75]
	s_cmp_gt_u32 s75, 3
	s_cbranch_scc1 .Lie_skipk0
	v_mfma_f32_16x16x32_bf16 v[116:119], v[184:187], v[200:203], v[116:119]
	v_mfma_f32_16x16x32_bf16 v[112:115], v[192:195], v[200:203], v[112:115]
	v_mfma_f32_16x16x32_bf16 v[100:103], v[184:187], v[218:221], v[100:103]
	v_mfma_f32_16x16x32_bf16 v[96:99], v[192:195], v[218:221], v[96:99]
	v_mfma_f32_16x16x32_bf16 v[84:87], v[184:187], v[226:229], v[84:87]
	v_mfma_f32_16x16x32_bf16 v[80:83], v[192:195], v[226:229], v[80:83]
	v_mfma_f32_16x16x32_bf16 v[68:71], v[184:187], v[234:237], v[68:71]
	v_mfma_f32_16x16x32_bf16 v[64:67], v[192:195], v[234:237], v[64:67]
	v_mfma_f32_16x16x32_bf16 v[116:119], v[188:191], v[204:207], v[116:119]
	v_mfma_f32_16x16x32_bf16 v[112:115], v[196:199], v[204:207], v[112:115]
	v_mfma_f32_16x16x32_bf16 v[100:103], v[188:191], v[222:225], v[100:103]
	v_mfma_f32_16x16x32_bf16 v[96:99], v[196:199], v[222:225], v[96:99]
	v_mfma_f32_16x16x32_bf16 v[84:87], v[188:191], v[230:233], v[84:87]
	v_mfma_f32_16x16x32_bf16 v[80:83], v[196:199], v[230:233], v[80:83]
	v_mfma_f32_16x16x32_bf16 v[68:71], v[188:191], v[238:241], v[68:71]
	v_mfma_f32_16x16x32_bf16 v[64:67], v[196:199], v[238:241], v[64:67]
.Lie_skipk0:
	s_setprio 0
	s_barrier
	s_add_i32 s13, s69, s37
	v_lshl_add_u64 v[214:215], v[212:213], 0, v[146:147]
	s_mov_b32 m0, s13
	ds_read_b128 v[200:203], v216 offset:16384
	ds_read_b128 v[204:207], v216 offset:17408
	ds_read_b128 v[218:221], v216 offset:18432
	ds_read_b128 v[222:225], v216 offset:19456
	ds_read_b128 v[226:229], v216 offset:20480
	ds_read_b128 v[230:233], v216 offset:21504
	ds_read_b128 v[234:237], v216 offset:22528
	ds_read_b128 v[238:241], v216 offset:23552
	global_load_lds_dwordx4 v[214:215], off
	v_lshl_add_u64 v[242:243], v[212:213], 0, v[150:151]
	s_add_i32 m0, s13, 0x2000
	v_lshl_add_u64 v[212:213], v[212:213], 0, s[16:17]
	s_add_i32 s13, s70, s37
	global_load_lds_dwordx4 v[242:243], off
	v_lshl_add_u64 v[244:245], v[212:213], 0, v[146:147]
	s_mov_b32 m0, s13
	v_lshl_add_u64 v[212:213], v[212:213], 0, v[150:151]
	global_load_lds_dwordx4 v[244:245], off
	s_add_i32 m0, s13, 0x2000
	v_lshl_add_u64 v[246:247], v[208:209], 0, v[144:145]
	global_load_lds_dwordx4 v[212:213], off
	s_mov_b32 m0, s41
	v_lshl_add_u64 v[248:249], v[208:209], 0, v[148:149]
	global_load_lds_dwordx4 v[246:247], off
	s_mov_b32 m0, s50
	s_nop 0
	global_load_lds_dwordx4 v[248:249], off
	s_waitcnt vmcnt(8) lgkmcnt(0)
	s_setprio 1
	s_barrier
	v_mfma_f32_16x16x32_bf16 v[60:63], v[132:135], v[200:203], v[60:63]
	v_mfma_f32_16x16x32_bf16 v[56:59], v[176:179], v[200:203], v[56:59]
	v_mfma_f32_16x16x32_bf16 v[44:47], v[132:135], v[218:221], v[44:47]
	v_mfma_f32_16x16x32_bf16 v[40:43], v[176:179], v[218:221], v[40:43]
	v_mfma_f32_16x16x32_bf16 v[28:31], v[132:135], v[226:229], v[28:31]
	v_mfma_f32_16x16x32_bf16 v[24:27], v[176:179], v[226:229], v[24:27]
	v_mfma_f32_16x16x32_bf16 v[12:15], v[132:135], v[234:237], v[12:15]
	v_mfma_f32_16x16x32_bf16 v[8:11], v[176:179], v[234:237], v[8:11]
	v_mfma_f32_16x16x32_bf16 v[60:63], v[136:139], v[204:207], v[60:63]
	v_mfma_f32_16x16x32_bf16 v[56:59], v[180:183], v[204:207], v[56:59]
	v_mfma_f32_16x16x32_bf16 v[44:47], v[136:139], v[222:225], v[44:47]
	v_mfma_f32_16x16x32_bf16 v[40:43], v[180:183], v[222:225], v[40:43]
	v_mfma_f32_16x16x32_bf16 v[28:31], v[136:139], v[230:233], v[28:31]
	v_mfma_f32_16x16x32_bf16 v[24:27], v[180:183], v[230:233], v[24:27]
	v_mfma_f32_16x16x32_bf16 v[12:15], v[136:139], v[238:241], v[12:15]
	v_mfma_f32_16x16x32_bf16 v[8:11], v[180:183], v[238:241], v[8:11]
	s_cmp_gt_u32 s75, 3
	s_cbranch_scc1 .Lie_skipk1
; #define PG8_STAGE(bufoff, gbase, voff) do { _Pragma("unroll") for (int _i = 0; _i < 2; ++_i) \
;         __builtin_amdgcn_global_load_lds((const unsigned*)((const char*)(gbase) + (voff)[_i]), (PG8_LAS unsigned*)(lds + (bufoff) + ldsw + _i * 8192), 16, 0, 0); } while (0)
; #define PG8_LDA(dst, b, h) do { _Pragma("unroll") for (int m = 0; m < 4; ++m) _Pragma("unroll") for (int k = 0; k < 2; ++k) dst[m][k] = *(const PG8_LAS bf16x8*)(lds + PG8_SA(b, h) + aoff + m * 2048 + k * 1024); } while (0)
; #define PG8_LDB(dst, b, h) do { _Pragma("unroll") for (int n = 0; n < 2; ++n) _Pragma("unroll") for (int k = 0; k < 2; ++k) dst[n][k] = *(const PG8_LAS bf16x8*)(lds + PG8_SB(b, h) + boff + n * 2048 + k * 1024); } while (0)
; #define PG8_MMA(ai, bj, At, Bt) do { __builtin_amdgcn_s_setprio(1); _Pragma("unroll") for (int m = 0; m < 4; ++m) _Pragma("unroll") for (int n = 0; n < 2; ++n) _Pragma("unroll") for (int k = 0; k < 2; ++k) \
;         acc[ai][bj][m][n] = __builtin_amdgcn_mfma_f32_16x16x32_bf16(Bt[n][k], At[m][k], acc[ai][bj][m][n], 0, 0, 0); __builtin_amdgcn_s_setprio(0); } while (0)
; #define PG8_WAIT_V(n) asm volatile("s_waitcnt vmcnt(" #n ")" ::: "memory")
; #define PG8_WAIT_L(n) asm volatile("s_waitcnt lgkmcnt(" #n ")" ::: "memory")
; #define PG8_BAR __builtin_amdgcn_s_barrier()
; #define PG8_SCHED __builtin_amdgcn_sched_barrier(0)
; template <class Epi, class Sched, bool ALIGN_EPI = false, bool SP2 = false>
; __device__ __forceinline__ void gemm_phase(PG8_LAS unsigned char* lds, const Gemm g, const Sched& S, const Epi& E) {
;     ...
;             PG8_WAIT_V(8); PG8_WAIT_L(0); PG8_BAR; PG8_MMA(1, 0, At, B0); PG8_MMA(1, 1, At, B1); PG8_BAR; PG8_SCHED;
;             PG8_LDB(B0, 1, 0); PG8_LDB(B1, 1, 1); PG8_SCHED; PG8_LDA(At, 1, 0); PG8_STAGE(PG8_SA(0, 1), a2 + hstep, voffA);
;             PG8_WAIT_V(8); PG8_WAIT_L(0); PG8_BAR; PG8_MMA(0, 0, At, B0); PG8_MMA(0, 1, At, B1); PG8_BAR; PG8_SCHED;
	v_mfma_f32_16x16x32_bf16 v[52:55], v[184:187], v[200:203], v[52:55]
	v_mfma_f32_16x16x32_bf16 v[48:51], v[192:195], v[200:203], v[48:51]
	v_mfma_f32_16x16x32_bf16 v[36:39], v[184:187], v[218:221], v[36:39]
	v_mfma_f32_16x16x32_bf16 v[32:35], v[192:195], v[218:221], v[32:35]
	v_mfma_f32_16x16x32_bf16 v[20:23], v[184:187], v[226:229], v[20:23]
	v_mfma_f32_16x16x32_bf16 v[16:19], v[192:195], v[226:229], v[16:19]
	v_mfma_f32_16x16x32_bf16 v[4:7], v[184:187], v[234:237], v[4:7]
	v_mfma_f32_16x16x32_bf16 v[0:3], v[192:195], v[234:237], v[0:3]
	v_mfma_f32_16x16x32_bf16 v[52:55], v[188:191], v[204:207], v[52:55]
	v_mfma_f32_16x16x32_bf16 v[48:51], v[196:199], v[204:207], v[48:51]
	v_mfma_f32_16x16x32_bf16 v[36:39], v[188:191], v[222:225], v[36:39]
	v_mfma_f32_16x16x32_bf16 v[32:35], v[196:199], v[222:225], v[32:35]
	v_mfma_f32_16x16x32_bf16 v[20:23], v[188:191], v[230:233], v[20:23]
	v_mfma_f32_16x16x32_bf16 v[16:19], v[196:199], v[230:233], v[16:19]
	v_mfma_f32_16x16x32_bf16 v[4:7], v[188:191], v[238:241], v[4:7]
	v_mfma_f32_16x16x32_bf16 v[0:3], v[196:199], v[238:241], v[0:3]
.Lie_skipk1:
	s_setprio 0
	s_barrier
	s_add_i32 s13, 0, 0x18000
	v_add_u32_e32 v165, s13, v171
	s_add_i32 s15, 0, 0x1c000
	ds_read_b128 v[132:135], v165
	ds_read_b128 v[136:139], v165 offset:1024
	ds_read_b128 v[176:179], v165 offset:2048
	ds_read_b128 v[180:183], v165 offset:3072
	v_add_u32_e32 v165, s15, v171
	ds_read_b128 v[184:187], v165
	ds_read_b128 v[188:191], v165 offset:1024
	ds_read_b128 v[192:195], v165 offset:2048
	ds_read_b128 v[196:199], v165 offset:3072
	v_lshl_add_u64 v[208:209], v[208:209], 0, s[16:17]
	s_mov_b32 m0, s52
	v_lshl_add_u64 v[250:251], v[208:209], 0, v[144:145]
	ds_read_b128 v[200:203], v216 offset:32768
	ds_read_b128 v[204:207], v216 offset:33792
	ds_read_b128 v[218:221], v216 offset:34816
	ds_read_b128 v[222:225], v216 offset:35840
	ds_read_b128 v[226:229], v216 offset:36864
	ds_read_b128 v[230:233], v216 offset:37888
	ds_read_b128 v[234:237], v216 offset:38912
	ds_read_b128 v[238:241], v216 offset:39936
	global_load_lds_dwordx4 v[250:251], off
	s_mov_b32 m0, s53
	v_lshl_add_u64 v[208:209], v[208:209], 0, v[148:149]
	global_load_lds_dwordx4 v[208:209], off
	s_waitcnt vmcnt(8) lgkmcnt(0)
	s_setprio 1
	s_barrier
	v_mfma_f32_16x16x32_bf16 v[124:127], v[132:135], v[200:203], v[124:127]
	v_mfma_f32_16x16x32_bf16 v[120:123], v[176:179], v[200:203], v[120:123]
	v_mfma_f32_16x16x32_bf16 v[108:111], v[132:135], v[218:221], v[108:111]
	v_mfma_f32_16x16x32_bf16 v[104:107], v[176:179], v[218:221], v[104:107]
	v_mfma_f32_16x16x32_bf16 v[92:95], v[132:135], v[226:229], v[92:95]
	v_mfma_f32_16x16x32_bf16 v[88:91], v[176:179], v[226:229], v[88:91]
	v_mfma_f32_16x16x32_bf16 v[76:79], v[132:135], v[234:237], v[76:79]
	v_mfma_f32_16x16x32_bf16 v[72:75], v[176:179], v[234:237], v[72:75]
	v_mfma_f32_16x16x32_bf16 v[124:127], v[136:139], v[204:207], v[124:127]
	v_mfma_f32_16x16x32_bf16 v[120:123], v[180:183], v[204:207], v[120:123]
	v_mfma_f32_16x16x32_bf16 v[108:111], v[136:139], v[222:225], v[108:111]
	v_mfma_f32_16x16x32_bf16 v[104:107], v[180:183], v[222:225], v[104:107]
	v_mfma_f32_16x16x32_bf16 v[92:95], v[136:139], v[230:233], v[92:95]
	v_mfma_f32_16x16x32_bf16 v[88:91], v[180:183], v[230:233], v[88:91]
	v_mfma_f32_16x16x32_bf16 v[76:79], v[136:139], v[238:241], v[76:79]
	v_mfma_f32_16x16x32_bf16 v[72:75], v[180:183], v[238:241], v[72:75]
	s_cmp_gt_u32 s75, 3
	s_cbranch_scc1 .Lie_skipk2
	v_mfma_f32_16x16x32_bf16 v[116:119], v[184:187], v[200:203], v[116:119]
	v_mfma_f32_16x16x32_bf16 v[112:115], v[192:195], v[200:203], v[112:115]
	v_mfma_f32_16x16x32_bf16 v[100:103], v[184:187], v[218:221], v[100:103]
	v_mfma_f32_16x16x32_bf16 v[96:99], v[192:195], v[218:221], v[96:99]
	v_mfma_f32_16x16x32_bf16 v[84:87], v[184:187], v[226:229], v[84:87]
	v_mfma_f32_16x16x32_bf16 v[80:83], v[192:195], v[226:229], v[80:83]
	v_mfma_f32_16x16x32_bf16 v[68:71], v[184:187], v[234:237], v[68:71]
	v_mfma_f32_16x16x32_bf16 v[64:67], v[192:195], v[234:237], v[64:67]
	v_mfma_f32_16x16x32_bf16 v[116:119], v[188:191], v[204:207], v[116:119]
	v_mfma_f32_16x16x32_bf16 v[112:115], v[196:199], v[204:207], v[112:115]
	v_mfma_f32_16x16x32_bf16 v[100:103], v[188:191], v[222:225], v[100:103]
	v_mfma_f32_16x16x32_bf16 v[96:99], v[196:199], v[222:225], v[96:99]
	v_mfma_f32_16x16x32_bf16 v[84:87], v[188:191], v[230:233], v[84:87]
	v_mfma_f32_16x16x32_bf16 v[80:83], v[196:199], v[230:233], v[80:83]
	v_mfma_f32_16x16x32_bf16 v[68:71], v[188:191], v[238:241], v[68:71]
	v_mfma_f32_16x16x32_bf16 v[64:67], v[196:199], v[238:241], v[64:67]
; #define PG8_STAGE(bufoff, gbase, voff) do { _Pragma("unroll") for (int _i = 0; _i < 2; ++_i) \
;         __builtin_amdgcn_global_load_lds((const unsigned*)((const char*)(gbase) + (voff)[_i]), (PG8_LAS unsigned*)(lds + (bufoff) + ldsw + _i * 8192), 16, 0, 0); } while (0)
; #define PG8_LDA(dst, b, h) do { _Pragma("unroll") for (int m = 0; m < 4; ++m) _Pragma("unroll") for (int k = 0; k < 2; ++k) dst[m][k] = *(const PG8_LAS bf16x8*)(lds + PG8_SA(b, h) + aoff + m * 2048 + k * 1024); } while (0)
; #define PG8_MMA(ai, bj, At, Bt) do { __builtin_amdgcn_s_setprio(1); _Pragma("unroll") for (int m = 0; m < 4; ++m) _Pragma("unroll") for (int n = 0; n < 2; ++n) _Pragma("unroll") for (int k = 0; k < 2; ++k) \
;         acc[ai][bj][m][n] = __builtin_amdgcn_mfma_f32_16x16x32_bf16(Bt[n][k], At[m][k], acc[ai][bj][m][n], 0, 0, 0); __builtin_amdgcn_s_setprio(0); } while (0)
; #define PG8_WAIT_V(n) asm volatile("s_waitcnt vmcnt(" #n ")" ::: "memory")
; #define PG8_WAIT_L(n) asm volatile("s_waitcnt lgkmcnt(" #n ")" ::: "memory")
; #define PG8_BAR __builtin_amdgcn_s_barrier()
; #define PG8_SCHED __builtin_amdgcn_sched_barrier(0)
; template <class Epi, class Sched, bool ALIGN_EPI = false, bool SP2 = false>
; __device__ __forceinline__ void gemm_phase(PG8_LAS unsigned char* lds, const Gemm g, const Sched& S, const Epi& E) {
;     ...
;             PG8_LDA(At, 1, 1); PG8_STAGE(PG8_SB(1, 0), b3, voffB); PG8_STAGE(PG8_SB(1, 1), b3 + hstep, voffB); PG8_STAGE(PG8_SA(1, 0), a3, voffA);
;             PG8_WAIT_V(8); PG8_WAIT_L(0); PG8_BAR; PG8_MMA(1, 0, At, B0); PG8_MMA(1, 1, At, B1); PG8_BAR; PG8_SCHED;
.Lie_skipk2:
	s_setprio 0
	s_barrier
	s_add_i32 s13, s13, s37
	v_lshl_add_u64 v[208:209], v[214:215], 0, s[24:25]
	s_mov_b32 m0, s13
	ds_read_b128 v[200:203], v216 offset:49152
	ds_read_b128 v[204:207], v216 offset:50176
	ds_read_b128 v[218:221], v216 offset:51200
	ds_read_b128 v[222:225], v216 offset:52224
	ds_read_b128 v[226:229], v216 offset:53248
	ds_read_b128 v[230:233], v216 offset:54272
	ds_read_b128 v[234:237], v216 offset:55296
	ds_read_b128 v[238:241], v216 offset:56320
	global_load_lds_dwordx4 v[208:209], off
	v_lshl_add_u64 v[208:209], v[242:243], 0, s[24:25]
	s_add_i32 m0, s13, 0x2000
	s_add_i32 s13, s15, s37
	global_load_lds_dwordx4 v[208:209], off
	s_mov_b32 m0, s13
	v_lshl_add_u64 v[208:209], v[244:245], 0, s[24:25]
	global_load_lds_dwordx4 v[208:209], off
	s_add_i32 m0, s13, 0x2000
	v_lshl_add_u64 v[208:209], v[212:213], 0, s[24:25]
	global_load_lds_dwordx4 v[208:209], off
	s_mov_b32 m0, s56
	v_lshl_add_u64 v[208:209], v[246:247], 0, s[24:25]
	global_load_lds_dwordx4 v[208:209], off
	s_mov_b32 m0, s57
	v_lshl_add_u64 v[208:209], v[248:249], 0, s[24:25]
	global_load_lds_dwordx4 v[208:209], off
	s_waitcnt vmcnt(8) lgkmcnt(0)
	s_setprio 1
	s_barrier
	v_mfma_f32_16x16x32_bf16 v[60:63], v[132:135], v[200:203], v[60:63]
	v_mfma_f32_16x16x32_bf16 v[56:59], v[176:179], v[200:203], v[56:59]
	v_mfma_f32_16x16x32_bf16 v[44:47], v[132:135], v[218:221], v[44:47]
	v_mfma_f32_16x16x32_bf16 v[40:43], v[176:179], v[218:221], v[40:43]
	v_mfma_f32_16x16x32_bf16 v[28:31], v[132:135], v[226:229], v[28:31]
	v_mfma_f32_16x16x32_bf16 v[24:27], v[176:179], v[226:229], v[24:27]
	v_mfma_f32_16x16x32_bf16 v[12:15], v[132:135], v[234:237], v[12:15]
	v_mfma_f32_16x16x32_bf16 v[8:11], v[176:179], v[234:237], v[8:11]
	v_mfma_f32_16x16x32_bf16 v[60:63], v[136:139], v[204:207], v[60:63]
	v_mfma_f32_16x16x32_bf16 v[56:59], v[180:183], v[204:207], v[56:59]
	v_mfma_f32_16x16x32_bf16 v[44:47], v[136:139], v[222:225], v[44:47]
	v_mfma_f32_16x16x32_bf16 v[40:43], v[180:183], v[222:225], v[40:43]
	v_mfma_f32_16x16x32_bf16 v[28:31], v[136:139], v[230:233], v[28:31]
	v_mfma_f32_16x16x32_bf16 v[24:27], v[180:183], v[230:233], v[24:27]
	v_mfma_f32_16x16x32_bf16 v[12:15], v[136:139], v[238:241], v[12:15]
	v_mfma_f32_16x16x32_bf16 v[8:11], v[180:183], v[238:241], v[8:11]
	s_cmp_gt_u32 s75, 3
	s_cbranch_scc1 .Lie_skipk3
	v_mfma_f32_16x16x32_bf16 v[52:55], v[184:187], v[200:203], v[52:55]
	v_mfma_f32_16x16x32_bf16 v[48:51], v[192:195], v[200:203], v[48:51]
	v_mfma_f32_16x16x32_bf16 v[36:39], v[184:187], v[218:221], v[36:39]
	v_mfma_f32_16x16x32_bf16 v[32:35], v[192:195], v[218:221], v[32:35]
	v_mfma_f32_16x16x32_bf16 v[20:23], v[184:187], v[226:229], v[20:23]
	v_mfma_f32_16x16x32_bf16 v[16:19], v[192:195], v[226:229], v[16:19]
	v_mfma_f32_16x16x32_bf16 v[4:7], v[184:187], v[234:237], v[4:7]
	v_mfma_f32_16x16x32_bf16 v[0:3], v[192:195], v[234:237], v[0:3]
	v_mfma_f32_16x16x32_bf16 v[52:55], v[188:191], v[204:207], v[52:55]
	v_mfma_f32_16x16x32_bf16 v[48:51], v[196:199], v[204:207], v[48:51]
	v_mfma_f32_16x16x32_bf16 v[36:39], v[188:191], v[222:225], v[36:39]
	v_mfma_f32_16x16x32_bf16 v[32:35], v[196:199], v[222:225], v[32:35]
	v_mfma_f32_16x16x32_bf16 v[20:23], v[188:191], v[230:233], v[20:23]
	v_mfma_f32_16x16x32_bf16 v[16:19], v[196:199], v[230:233], v[16:19]
	v_mfma_f32_16x16x32_bf16 v[4:7], v[188:191], v[238:241], v[4:7]
	v_mfma_f32_16x16x32_bf16 v[0:3], v[196:199], v[238:241], v[0:3]

; #define PG8_STAGE(bufoff, gbase, voff) do { _Pragma("unroll") for (int _i = 0; _i < 2; ++_i) \
;         __builtin_amdgcn_global_load_lds((const unsigned*)((const char*)(gbase) + (voff)[_i]), (PG8_LAS unsigned*)(lds + (bufoff) + ldsw + _i * 8192), 16, 0, 0); } while (0)
; #define PG8_LDA(dst, b, h) do { _Pragma("unroll") for (int m = 0; m < 4; ++m) _Pragma("unroll") for (int k = 0; k < 2; ++k) dst[m][k] = *(const PG8_LAS bf16x8*)(lds + PG8_SA(b, h) + aoff + m * 2048 + k * 1024); } while (0)
; #define PG8_LDB(dst, b, h) do { _Pragma("unroll") for (int n = 0; n < 2; ++n) _Pragma("unroll") for (int k = 0; k < 2; ++k) dst[n][k] = *(const PG8_LAS bf16x8*)(lds + PG8_SB(b, h) + boff + n * 2048 + k * 1024); } while (0)
; #define PG8_MMA(ai, bj, At, Bt) do { __builtin_amdgcn_s_setprio(1); _Pragma("unroll") for (int m = 0; m < 4; ++m) _Pragma("unroll") for (int n = 0; n < 2; ++n) _Pragma("unroll") for (int k = 0; k < 2; ++k) \
;         acc[ai][bj][m][n] = __builtin_amdgcn_mfma_f32_16x16x32_bf16(Bt[n][k], At[m][k], acc[ai][bj][m][n], 0, 0, 0); __builtin_amdgcn_s_setprio(0); } while (0)
; #define PG8_WAIT_V(n) asm volatile("s_waitcnt vmcnt(" #n ")" ::: "memory")
; #define PG8_WAIT_L(n) asm volatile("s_waitcnt lgkmcnt(" #n ")" ::: "memory")
; template <class Epi, class Sched, bool ALIGN_EPI = false, bool SP2 = false>
; __device__ __forceinline__ void gemm_phase(PG8_LAS unsigned char* lds, const Gemm g, const Sched& S, const Epi& E) {
;     ...
;             const bool last = (t == nt - 2);
;             const char* a1 = cA + (size_t)(t + 1) * kstep;
;             const char* a2 = last ? nA : cA + (size_t)(t + 2) * kstep; const char* b2 = last ? nB : cB + (size_t)(t + 2) * kstep;
;             const char* a3 = a2 + kstep; const char* b3 = b2 + kstep;
;             if (last && has_next) S.a_ready(nxt);
;             if constexpr (SP2) {
;             PG8_LDB(B0, 0, 0); PG8_LDB(B1, 0, 1); PG8_SCHED; PG8_LDA(At, 0, 0); PG8_STAGE(PG8_SA(1, 1), a1 + hstep, voffA);
;             PG8_WAIT_V(8); PG8_WAIT_L(0); PG8_BAR; PG8_MMA(0, 0, At, B0); PG8_MMA(0, 1, At, B1); PG8_BAR; PG8_SCHED;
;             PG8_LDA(At, 0, 1); PG8_STAGE(PG8_SB(0, 0), b2, voffB); PG8_STAGE(PG8_SB(0, 1), b2 + hstep, voffB); PG8_STAGE(PG8_SA(0, 0), a2, voffA);
;             PG8_WAIT_V(8); PG8_WAIT_L(0); PG8_BAR; PG8_MMA(1, 0, At, B0); PG8_MMA(1, 1, At, B1); PG8_BAR; PG8_SCHED;
.LBB0_635:
	v_add_u32_e32 v144, s64, v209
	v_add_u32_e32 v194, s65, v209
	ds_read_b128 v[92:95], v144
	ds_read_b128 v[128:131], v144 offset:1024
	ds_read_b128 v[132:135], v144 offset:2048
	ds_read_b128 v[144:147], v144 offset:3072
	ds_read_b128 v[148:151], v194
	ds_read_b128 v[152:155], v194 offset:1024
	ds_read_b128 v[190:193], v194 offset:2048
	ds_read_b128 v[194:197], v194 offset:3072
	s_cmp_eq_u32 s58, s10
	v_lshl_add_u64 v[198:199], v[90:91], 0, s[24:25]
	s_cselect_b64 vcc, -1, 0
	s_add_i32 s10, s10, 2
	v_cndmask_b32_e32 v207, v199, v187, vcc
	v_cndmask_b32_e32 v206, v198, v186, vcc
	v_cndmask_b32_e32 v215, v89, v189, vcc
	v_cndmask_b32_e32 v214, v88, v188, vcc
	v_lshl_add_u64 v[238:239], v[90:91], 0, v[180:181]
	s_add_i32 m0, s41, 0xc000
	ds_read_b128 v[198:201], v216
	ds_read_b128 v[202:205], v216 offset:1024
	ds_read_b128 v[210:213], v216 offset:2048
	ds_read_b128 v[218:221], v216 offset:3072
	ds_read_b128 v[222:225], v216 offset:4096
	ds_read_b128 v[226:229], v216 offset:5120
	ds_read_b128 v[230:233], v216 offset:6144
	ds_read_b128 v[234:237], v216 offset:7168
	global_load_lds_dwordx4 v[238:239], off
	s_add_i32 m0, s41, 0xe000
	v_lshl_add_u64 v[238:239], v[90:91], 0, v[178:179]
	global_load_lds_dwordx4 v[238:239], off
	s_waitcnt vmcnt(8) lgkmcnt(0)
	s_setprio 1
	s_barrier
	v_mfma_f32_16x16x32_bf16 v[140:143], v[92:95], v[198:201], v[140:143]
	v_mfma_f32_16x16x32_bf16 v[136:139], v[132:135], v[198:201], v[136:139]
	v_mfma_f32_16x16x32_bf16 v[116:119], v[92:95], v[210:213], v[116:119]
	v_mfma_f32_16x16x32_bf16 v[112:115], v[132:135], v[210:213], v[112:115]
	v_mfma_f32_16x16x32_bf16 v[100:103], v[92:95], v[222:225], v[100:103]
	v_mfma_f32_16x16x32_bf16 v[96:99], v[132:135], v[222:225], v[96:99]
	v_mfma_f32_16x16x32_bf16 v[76:79], v[92:95], v[230:233], v[76:79]
	v_mfma_f32_16x16x32_bf16 v[72:75], v[132:135], v[230:233], v[72:75]
	v_mfma_f32_16x16x32_bf16 v[140:143], v[128:131], v[202:205], v[140:143]
	v_mfma_f32_16x16x32_bf16 v[136:139], v[144:147], v[202:205], v[136:139]
	v_mfma_f32_16x16x32_bf16 v[116:119], v[128:131], v[218:221], v[116:119]
	v_mfma_f32_16x16x32_bf16 v[112:115], v[144:147], v[218:221], v[112:115]
	v_mfma_f32_16x16x32_bf16 v[100:103], v[128:131], v[226:229], v[100:103]
	v_mfma_f32_16x16x32_bf16 v[96:99], v[144:147], v[226:229], v[96:99]
	v_mfma_f32_16x16x32_bf16 v[76:79], v[128:131], v[234:237], v[76:79]
	v_mfma_f32_16x16x32_bf16 v[72:75], v[144:147], v[234:237], v[72:75]
	v_mfma_f32_16x16x32_bf16 v[124:127], v[148:151], v[198:201], v[124:127]
	v_mfma_f32_16x16x32_bf16 v[120:123], v[190:193], v[198:201], v[120:123]
	v_mfma_f32_16x16x32_bf16 v[108:111], v[148:151], v[210:213], v[108:111]
	v_mfma_f32_16x16x32_bf16 v[104:107], v[190:193], v[210:213], v[104:107]
	v_mfma_f32_16x16x32_bf16 v[84:87], v[148:151], v[222:225], v[84:87]
	v_mfma_f32_16x16x32_bf16 v[80:83], v[190:193], v[222:225], v[80:83]
	v_mfma_f32_16x16x32_bf16 v[68:71], v[148:151], v[230:233], v[68:71]
	v_mfma_f32_16x16x32_bf16 v[64:67], v[190:193], v[230:233], v[64:67]
	v_mfma_f32_16x16x32_bf16 v[124:127], v[152:155], v[202:205], v[124:127]
	v_mfma_f32_16x16x32_bf16 v[120:123], v[194:197], v[202:205], v[120:123]
	v_mfma_f32_16x16x32_bf16 v[108:111], v[152:155], v[218:221], v[108:111]
	v_mfma_f32_16x16x32_bf16 v[104:107], v[194:197], v[218:221], v[104:107]
	v_mfma_f32_16x16x32_bf16 v[84:87], v[152:155], v[226:229], v[84:87]
	v_mfma_f32_16x16x32_bf16 v[80:83], v[194:197], v[226:229], v[80:83]
	v_mfma_f32_16x16x32_bf16 v[68:71], v[152:155], v[234:237], v[68:71]
	v_mfma_f32_16x16x32_bf16 v[64:67], v[194:197], v[234:237], v[64:67]
	s_setprio 0
	s_barrier
	s_add_i32 s11, s64, s35
	v_lshl_add_u64 v[238:239], v[214:215], 0, v[168:169]
	s_mov_b32 m0, s11
	ds_read_b128 v[198:201], v216 offset:16384
	ds_read_b128 v[202:205], v216 offset:17408
	ds_read_b128 v[210:213], v216 offset:18432
	ds_read_b128 v[218:221], v216 offset:19456
	ds_read_b128 v[222:225], v216 offset:20480
	ds_read_b128 v[226:229], v216 offset:21504
	ds_read_b128 v[230:233], v216 offset:22528
	ds_read_b128 v[234:237], v216 offset:23552
	global_load_lds_dwordx4 v[238:239], off
	v_lshl_add_u64 v[240:241], v[214:215], 0, v[172:173]
	s_add_i32 m0, s11, 0x2000
	v_lshl_add_u64 v[214:215], v[214:215], 0, s[18:19]
	s_add_i32 s11, s65, s35
	global_load_lds_dwordx4 v[240:241], off
	v_lshl_add_u64 v[242:243], v[214:215], 0, v[168:169]
	s_mov_b32 m0, s11
	v_lshl_add_u64 v[214:215], v[214:215], 0, v[172:173]
	global_load_lds_dwordx4 v[242:243], off
	s_add_i32 m0, s11, 0x2000
	v_lshl_add_u64 v[244:245], v[206:207], 0, v[166:167]
	global_load_lds_dwordx4 v[214:215], off
	s_mov_b32 m0, s41
	v_lshl_add_u64 v[246:247], v[206:207], 0, v[170:171]
	global_load_lds_dwordx4 v[244:245], off
	s_mov_b32 m0, s50
	s_nop 0
	global_load_lds_dwordx4 v[246:247], off
	s_waitcnt vmcnt(8) lgkmcnt(0)
	s_setprio 1
	s_barrier
; #define PG8_STAGE(bufoff, gbase, voff) do { _Pragma("unroll") for (int _i = 0; _i < 2; ++_i) \
;         __builtin_amdgcn_global_load_lds((const unsigned*)((const char*)(gbase) + (voff)[_i]), (PG8_LAS unsigned*)(lds + (bufoff) + ldsw + _i * 8192), 16, 0, 0); } while (0)
; #define PG8_LDA(dst, b, h) do { _Pragma("unroll") for (int m = 0; m < 4; ++m) _Pragma("unroll") for (int k = 0; k < 2; ++k) dst[m][k] = *(const PG8_LAS bf16x8*)(lds + PG8_SA(b, h) + aoff + m * 2048 + k * 1024); } while (0)
; #define PG8_LDB(dst, b, h) do { _Pragma("unroll") for (int n = 0; n < 2; ++n) _Pragma("unroll") for (int k = 0; k < 2; ++k) dst[n][k] = *(const PG8_LAS bf16x8*)(lds + PG8_SB(b, h) + boff + n * 2048 + k * 1024); } while (0)
; #define PG8_MMA(ai, bj, At, Bt) do { __builtin_amdgcn_s_setprio(1); _Pragma("unroll") for (int m = 0; m < 4; ++m) _Pragma("unroll") for (int n = 0; n < 2; ++n) _Pragma("unroll") for (int k = 0; k < 2; ++k) \
;         acc[ai][bj][m][n] = __builtin_amdgcn_mfma_f32_16x16x32_bf16(Bt[n][k], At[m][k], acc[ai][bj][m][n], 0, 0, 0); __builtin_amdgcn_s_setprio(0); } while (0)
; #define PG8_WAIT_V(n) asm volatile("s_waitcnt vmcnt(" #n ")" ::: "memory")
; #define PG8_WAIT_L(n) asm volatile("s_waitcnt lgkmcnt(" #n ")" ::: "memory")
; #define PG8_BAR __builtin_amdgcn_s_barrier()
; #define PG8_SCHED __builtin_amdgcn_sched_barrier(0)
; template <class Epi, class Sched, bool ALIGN_EPI = false, bool SP2 = false>
; __device__ __forceinline__ void gemm_phase(PG8_LAS unsigned char* lds, const Gemm g, const Sched& S, const Epi& E) {
;     ...
;             PG8_WAIT_V(8); PG8_WAIT_L(0); PG8_BAR; PG8_MMA(1, 0, At, B0); PG8_MMA(1, 1, At, B1); PG8_BAR; PG8_SCHED;
;             PG8_LDB(B0, 1, 0); PG8_LDB(B1, 1, 1); PG8_SCHED; PG8_LDA(At, 1, 0); PG8_STAGE(PG8_SA(0, 1), a2 + hstep, voffA);
;             PG8_WAIT_V(8); PG8_WAIT_L(0); PG8_BAR; PG8_MMA(0, 0, At, B0); PG8_MMA(0, 1, At, B1); PG8_BAR; PG8_SCHED;
	v_mfma_f32_16x16x32_bf16 v[60:63], v[92:95], v[198:201], v[60:63]
	v_mfma_f32_16x16x32_bf16 v[56:59], v[132:135], v[198:201], v[56:59]
	v_mfma_f32_16x16x32_bf16 v[44:47], v[92:95], v[210:213], v[44:47]
	v_mfma_f32_16x16x32_bf16 v[40:43], v[132:135], v[210:213], v[40:43]
	v_mfma_f32_16x16x32_bf16 v[28:31], v[92:95], v[222:225], v[28:31]
	v_mfma_f32_16x16x32_bf16 v[24:27], v[132:135], v[222:225], v[24:27]
	v_mfma_f32_16x16x32_bf16 v[12:15], v[92:95], v[230:233], v[12:15]
	v_mfma_f32_16x16x32_bf16 v[8:11], v[132:135], v[230:233], v[8:11]
	v_mfma_f32_16x16x32_bf16 v[60:63], v[128:131], v[202:205], v[60:63]
	v_mfma_f32_16x16x32_bf16 v[56:59], v[144:147], v[202:205], v[56:59]
	v_mfma_f32_16x16x32_bf16 v[44:47], v[128:131], v[218:221], v[44:47]
	v_mfma_f32_16x16x32_bf16 v[40:43], v[144:147], v[218:221], v[40:43]
	v_mfma_f32_16x16x32_bf16 v[28:31], v[128:131], v[226:229], v[28:31]
	v_mfma_f32_16x16x32_bf16 v[24:27], v[144:147], v[226:229], v[24:27]
	v_mfma_f32_16x16x32_bf16 v[12:15], v[128:131], v[234:237], v[12:15]
	v_mfma_f32_16x16x32_bf16 v[8:11], v[144:147], v[234:237], v[8:11]
	v_mfma_f32_16x16x32_bf16 v[52:55], v[148:151], v[198:201], v[52:55]
	v_mfma_f32_16x16x32_bf16 v[48:51], v[190:193], v[198:201], v[48:51]
	v_mfma_f32_16x16x32_bf16 v[36:39], v[148:151], v[210:213], v[36:39]
	v_mfma_f32_16x16x32_bf16 v[32:35], v[190:193], v[210:213], v[32:35]
	v_mfma_f32_16x16x32_bf16 v[20:23], v[148:151], v[222:225], v[20:23]
	v_mfma_f32_16x16x32_bf16 v[16:19], v[190:193], v[222:225], v[16:19]
	v_mfma_f32_16x16x32_bf16 v[4:7], v[148:151], v[230:233], v[4:7]
	v_mfma_f32_16x16x32_bf16 v[0:3], v[190:193], v[230:233], v[0:3]
	v_mfma_f32_16x16x32_bf16 v[52:55], v[152:155], v[202:205], v[52:55]
	v_mfma_f32_16x16x32_bf16 v[48:51], v[194:197], v[202:205], v[48:51]
	v_mfma_f32_16x16x32_bf16 v[36:39], v[152:155], v[218:221], v[36:39]
	v_mfma_f32_16x16x32_bf16 v[32:35], v[194:197], v[218:221], v[32:35]
	v_mfma_f32_16x16x32_bf16 v[20:23], v[152:155], v[226:229], v[20:23]
	v_mfma_f32_16x16x32_bf16 v[16:19], v[194:197], v[226:229], v[16:19]
	v_mfma_f32_16x16x32_bf16 v[4:7], v[152:155], v[234:237], v[4:7]
	v_mfma_f32_16x16x32_bf16 v[0:3], v[194:197], v[234:237], v[0:3]
	s_setprio 0
	s_barrier
	s_add_i32 s11, 0, 0x18000
	s_add_i32 s14, 0, 0x1c000
	v_add_u32_e32 v144, s11, v209
	v_add_u32_e32 v194, s14, v209
	ds_read_b128 v[92:95], v144
	ds_read_b128 v[128:131], v144 offset:1024
	ds_read_b128 v[132:135], v144 offset:2048
	ds_read_b128 v[144:147], v144 offset:3072
	ds_read_b128 v[148:151], v194
	ds_read_b128 v[152:155], v194 offset:1024
	ds_read_b128 v[190:193], v194 offset:2048
	ds_read_b128 v[194:197], v194 offset:3072
	v_lshl_add_u64 v[206:207], v[206:207], 0, s[18:19]
	s_mov_b32 m0, s51
	v_lshl_add_u64 v[248:249], v[206:207], 0, v[166:167]
	ds_read_b128 v[198:201], v216 offset:32768
	ds_read_b128 v[202:205], v216 offset:33792
	ds_read_b128 v[210:213], v216 offset:34816
	ds_read_b128 v[218:221], v216 offset:35840
	ds_read_b128 v[222:225], v216 offset:36864
	ds_read_b128 v[226:229], v216 offset:37888
	ds_read_b128 v[230:233], v216 offset:38912
	ds_read_b128 v[234:237], v216 offset:39936
	global_load_lds_dwordx4 v[248:249], off
	s_mov_b32 m0, s52
	v_lshl_add_u64 v[206:207], v[206:207], 0, v[170:171]
	global_load_lds_dwordx4 v[206:207], off
	s_waitcnt vmcnt(8) lgkmcnt(0)
	s_setprio 1
	s_barrier
	v_mfma_f32_16x16x32_bf16 v[140:143], v[92:95], v[198:201], v[140:143]
	v_mfma_f32_16x16x32_bf16 v[136:139], v[132:135], v[198:201], v[136:139]
	v_mfma_f32_16x16x32_bf16 v[116:119], v[92:95], v[210:213], v[116:119]
	v_mfma_f32_16x16x32_bf16 v[112:115], v[132:135], v[210:213], v[112:115]
	v_mfma_f32_16x16x32_bf16 v[100:103], v[92:95], v[222:225], v[100:103]
	v_mfma_f32_16x16x32_bf16 v[96:99], v[132:135], v[222:225], v[96:99]
	v_mfma_f32_16x16x32_bf16 v[76:79], v[92:95], v[230:233], v[76:79]
	v_mfma_f32_16x16x32_bf16 v[72:75], v[132:135], v[230:233], v[72:75]
	v_mfma_f32_16x16x32_bf16 v[140:143], v[128:131], v[202:205], v[140:143]
	v_mfma_f32_16x16x32_bf16 v[136:139], v[144:147], v[202:205], v[136:139]
	v_mfma_f32_16x16x32_bf16 v[116:119], v[128:131], v[218:221], v[116:119]
	v_mfma_f32_16x16x32_bf16 v[112:115], v[144:147], v[218:221], v[112:115]
	v_mfma_f32_16x16x32_bf16 v[100:103], v[128:131], v[226:229], v[100:103]
	v_mfma_f32_16x16x32_bf16 v[96:99], v[144:147], v[226:229], v[96:99]
	v_mfma_f32_16x16x32_bf16 v[76:79], v[128:131], v[234:237], v[76:79]
	v_mfma_f32_16x16x32_bf16 v[72:75], v[144:147], v[234:237], v[72:75]
	v_mfma_f32_16x16x32_bf16 v[124:127], v[148:151], v[198:201], v[124:127]
	v_mfma_f32_16x16x32_bf16 v[120:123], v[190:193], v[198:201], v[120:123]
	v_mfma_f32_16x16x32_bf16 v[108:111], v[148:151], v[210:213], v[108:111]
	v_mfma_f32_16x16x32_bf16 v[104:107], v[190:193], v[210:213], v[104:107]
	v_mfma_f32_16x16x32_bf16 v[84:87], v[148:151], v[222:225], v[84:87]
	v_mfma_f32_16x16x32_bf16 v[80:83], v[190:193], v[222:225], v[80:83]
	v_mfma_f32_16x16x32_bf16 v[68:71], v[148:151], v[230:233], v[68:71]
	v_mfma_f32_16x16x32_bf16 v[64:67], v[190:193], v[230:233], v[64:67]
	v_mfma_f32_16x16x32_bf16 v[124:127], v[152:155], v[202:205], v[124:127]
	v_mfma_f32_16x16x32_bf16 v[120:123], v[194:197], v[202:205], v[120:123]
	v_mfma_f32_16x16x32_bf16 v[108:111], v[152:155], v[218:221], v[108:111]
	v_mfma_f32_16x16x32_bf16 v[104:107], v[194:197], v[218:221], v[104:107]
	v_mfma_f32_16x16x32_bf16 v[84:87], v[152:155], v[226:229], v[84:87]
	v_mfma_f32_16x16x32_bf16 v[80:83], v[194:197], v[226:229], v[80:83]
	v_mfma_f32_16x16x32_bf16 v[68:71], v[152:155], v[234:237], v[68:71]
	v_mfma_f32_16x16x32_bf16 v[64:67], v[194:197], v[234:237], v[64:67]
	s_setprio 0
	s_barrier
; #define PG8_STAGE(bufoff, gbase, voff) do { _Pragma("unroll") for (int _i = 0; _i < 2; ++_i) \
;         __builtin_amdgcn_global_load_lds((const unsigned*)((const char*)(gbase) + (voff)[_i]), (PG8_LAS unsigned*)(lds + (bufoff) + ldsw + _i * 8192), 16, 0, 0); } while (0)
; #define PG8_LDA(dst, b, h) do { _Pragma("unroll") for (int m = 0; m < 4; ++m) _Pragma("unroll") for (int k = 0; k < 2; ++k) dst[m][k] = *(const PG8_LAS bf16x8*)(lds + PG8_SA(b, h) + aoff + m * 2048 + k * 1024); } while (0)
; #define PG8_MMA(ai, bj, At, Bt) do { __builtin_amdgcn_s_setprio(1); _Pragma("unroll") for (int m = 0; m < 4; ++m) _Pragma("unroll") for (int n = 0; n < 2; ++n) _Pragma("unroll") for (int k = 0; k < 2; ++k) \
;         acc[ai][bj][m][n] = __builtin_amdgcn_mfma_f32_16x16x32_bf16(Bt[n][k], At[m][k], acc[ai][bj][m][n], 0, 0, 0); __builtin_amdgcn_s_setprio(0); } while (0)
; #define PG8_WAIT_V(n) asm volatile("s_waitcnt vmcnt(" #n ")" ::: "memory")
; #define PG8_WAIT_L(n) asm volatile("s_waitcnt lgkmcnt(" #n ")" ::: "memory")
; #define PG8_BAR __builtin_amdgcn_s_barrier()
; #define PG8_SCHED __builtin_amdgcn_sched_barrier(0)
; template <class Epi, class Sched, bool ALIGN_EPI = false, bool SP2 = false>
; __device__ __forceinline__ void gemm_phase(PG8_LAS unsigned char* lds, const Gemm g, const Sched& S, const Epi& E) {
;     ...
;             PG8_LDA(At, 1, 1); PG8_STAGE(PG8_SB(1, 0), b3, voffB); PG8_STAGE(PG8_SB(1, 1), b3 + hstep, voffB); PG8_STAGE(PG8_SA(1, 0), a3, voffA);
;             PG8_WAIT_V(8); PG8_WAIT_L(0); PG8_BAR; PG8_MMA(1, 0, At, B0); PG8_MMA(1, 1, At, B1); PG8_BAR; PG8_SCHED;
	s_add_i32 s11, s11, s35
	v_lshl_add_u64 v[206:207], v[238:239], 0, s[24:25]
	s_mov_b32 m0, s11
	ds_read_b128 v[198:201], v216 offset:49152
	ds_read_b128 v[202:205], v216 offset:50176
	ds_read_b128 v[210:213], v216 offset:51200
	ds_read_b128 v[218:221], v216 offset:52224
	ds_read_b128 v[222:225], v216 offset:53248
	ds_read_b128 v[226:229], v216 offset:54272
	ds_read_b128 v[230:233], v216 offset:55296
	ds_read_b128 v[234:237], v216 offset:56320
	global_load_lds_dwordx4 v[206:207], off
	v_lshl_add_u64 v[206:207], v[240:241], 0, s[24:25]
	s_add_i32 m0, s11, 0x2000
	s_add_i32 s11, s14, s35
	global_load_lds_dwordx4 v[206:207], off
	s_mov_b32 m0, s11
	v_lshl_add_u64 v[206:207], v[242:243], 0, s[24:25]
	global_load_lds_dwordx4 v[206:207], off
	s_add_i32 m0, s11, 0x2000
	v_lshl_add_u64 v[206:207], v[214:215], 0, s[24:25]
	global_load_lds_dwordx4 v[206:207], off
	s_mov_b32 m0, s54
	v_lshl_add_u64 v[206:207], v[244:245], 0, s[24:25]
	global_load_lds_dwordx4 v[206:207], off
	s_mov_b32 m0, s55
	v_lshl_add_u64 v[206:207], v[246:247], 0, s[24:25]
	global_load_lds_dwordx4 v[206:207], off
	s_waitcnt vmcnt(8) lgkmcnt(0)
	s_setprio 1
	s_barrier
	v_mfma_f32_16x16x32_bf16 v[60:63], v[92:95], v[198:201], v[60:63]
	v_mfma_f32_16x16x32_bf16 v[56:59], v[132:135], v[198:201], v[56:59]
	v_mfma_f32_16x16x32_bf16 v[44:47], v[92:95], v[210:213], v[44:47]
	v_mfma_f32_16x16x32_bf16 v[40:43], v[132:135], v[210:213], v[40:43]
	v_mfma_f32_16x16x32_bf16 v[28:31], v[92:95], v[222:225], v[28:31]
	v_mfma_f32_16x16x32_bf16 v[24:27], v[132:135], v[222:225], v[24:27]
	v_mfma_f32_16x16x32_bf16 v[12:15], v[92:95], v[230:233], v[12:15]
	v_mfma_f32_16x16x32_bf16 v[8:11], v[132:135], v[230:233], v[8:11]
	v_mfma_f32_16x16x32_bf16 v[60:63], v[128:131], v[202:205], v[60:63]
	v_mfma_f32_16x16x32_bf16 v[56:59], v[144:147], v[202:205], v[56:59]
	v_mfma_f32_16x16x32_bf16 v[44:47], v[128:131], v[218:221], v[44:47]
	v_mfma_f32_16x16x32_bf16 v[40:43], v[144:147], v[218:221], v[40:43]
	v_mfma_f32_16x16x32_bf16 v[28:31], v[128:131], v[226:229], v[28:31]
	v_mfma_f32_16x16x32_bf16 v[24:27], v[144:147], v[226:229], v[24:27]
	v_mfma_f32_16x16x32_bf16 v[12:15], v[128:131], v[234:237], v[12:15]
	v_mfma_f32_16x16x32_bf16 v[8:11], v[144:147], v[234:237], v[8:11]
	v_mfma_f32_16x16x32_bf16 v[52:55], v[148:151], v[198:201], v[52:55]
	v_mfma_f32_16x16x32_bf16 v[48:51], v[190:193], v[198:201], v[48:51]
	v_mfma_f32_16x16x32_bf16 v[36:39], v[148:151], v[210:213], v[36:39]
	v_mfma_f32_16x16x32_bf16 v[32:35], v[190:193], v[210:213], v[32:35]
	v_mfma_f32_16x16x32_bf16 v[20:23], v[148:151], v[222:225], v[20:23]
	v_mfma_f32_16x16x32_bf16 v[16:19], v[190:193], v[222:225], v[16:19]
	v_mfma_f32_16x16x32_bf16 v[4:7], v[148:151], v[230:233], v[4:7]
	v_mfma_f32_16x16x32_bf16 v[0:3], v[190:193], v[230:233], v[0:3]
	v_mfma_f32_16x16x32_bf16 v[52:55], v[152:155], v[202:205], v[52:55]
	v_mfma_f32_16x16x32_bf16 v[48:51], v[194:197], v[202:205], v[48:51]
	v_mfma_f32_16x16x32_bf16 v[36:39], v[152:155], v[218:221], v[36:39]
	v_mfma_f32_16x16x32_bf16 v[32:35], v[194:197], v[218:221], v[32:35]
	v_mfma_f32_16x16x32_bf16 v[20:23], v[152:155], v[226:229], v[20:23]
	v_mfma_f32_16x16x32_bf16 v[16:19], v[194:197], v[226:229], v[16:19]
	v_mfma_f32_16x16x32_bf16 v[4:7], v[152:155], v[234:237], v[4:7]
	v_mfma_f32_16x16x32_bf16 v[0:3], v[194:197], v[234:237], v[0:3]
	s_setprio 0
	s_barrier
	v_lshl_add_u64 v[88:89], v[88:89], 0, s[30:31]
	s_cmp_ge_i32 s10, s57
	v_lshl_add_u64 v[90:91], v[90:91], 0, s[30:31]
	s_cbranch_scc0 .LBB0_635

; #define PG8_STAGE(bufoff, gbase, voff) do { _Pragma("unroll") for (int _i = 0; _i < 2; ++_i) \
;         __builtin_amdgcn_global_load_lds((const unsigned*)((const char*)(gbase) + (voff)[_i]), (PG8_LAS unsigned*)(lds + (bufoff) + ldsw + _i * 8192), 16, 0, 0); } while (0)
; #define PG8_LDA(dst, b, h) do { _Pragma("unroll") for (int m = 0; m < 4; ++m) _Pragma("unroll") for (int k = 0; k < 2; ++k) dst[m][k] = *(const PG8_LAS bf16x8*)(lds + PG8_SA(b, h) + aoff + m * 2048 + k * 1024); } while (0)
; #define PG8_LDB(dst, b, h) do { _Pragma("unroll") for (int n = 0; n < 2; ++n) _Pragma("unroll") for (int k = 0; k < 2; ++k) dst[n][k] = *(const PG8_LAS bf16x8*)(lds + PG8_SB(b, h) + boff + n * 2048 + k * 1024); } while (0)
; #define PG8_MMA(ai, bj, At, Bt) do { __builtin_amdgcn_s_setprio(1); _Pragma("unroll") for (int m = 0; m < 4; ++m) _Pragma("unroll") for (int n = 0; n < 2; ++n) _Pragma("unroll") for (int k = 0; k < 2; ++k) \
;         acc[ai][bj][m][n] = __builtin_amdgcn_mfma_f32_16x16x32_bf16(Bt[n][k], At[m][k], acc[ai][bj][m][n], 0, 0, 0); __builtin_amdgcn_s_setprio(0); } while (0)
; #define PG8_WAIT_V(n) asm volatile("s_waitcnt vmcnt(" #n ")" ::: "memory")
; #define PG8_BAR __builtin_amdgcn_s_barrier()
; template <class Epi, class Sched, bool ALIGN_EPI = false, bool SP2 = false>
; __device__ __forceinline__ void gemm_phase(PG8_LAS unsigned char* lds, const Gemm g, const Sched& S, const Epi& E) {
;     ...
;         for (int t = 0; t < nt; t += 2) {
;             const bool last = (t == nt - 2);
;             const char* a1 = cA + (size_t)(t + 1) * kstep;
;             const char* a2 = last ? nA : cA + (size_t)(t + 2) * kstep; const char* b2 = last ? nB : cB + (size_t)(t + 2) * kstep;
;             const char* a3 = a2 + kstep; const char* b3 = b2 + kstep;
;             if (last && has_next) S.a_ready(nxt);
;             if constexpr (SP2) {
;             PG8_LDB(B0, 0, 0); PG8_LDB(B1, 0, 1); PG8_SCHED; PG8_LDA(At, 0, 0); PG8_STAGE(PG8_SA(1, 1), a1 + hstep, voffA);
;             PG8_WAIT_V(8); PG8_WAIT_L(0); PG8_BAR; PG8_MMA(0, 0, At, B0); PG8_MMA(0, 1, At, B1); PG8_BAR; PG8_SCHED;
;             PG8_LDA(At, 0, 1); PG8_STAGE(PG8_SB(0, 0), b2, voffB); PG8_STAGE(PG8_SB(0, 1), b2 + hstep, voffB); PG8_STAGE(PG8_SA(0, 0), a2, voffA);
;             PG8_WAIT_V(8); PG8_WAIT_L(0); PG8_BAR; PG8_MMA(1, 0, At, B0); PG8_MMA(1, 1, At, B1); PG8_BAR; PG8_SCHED;
.LBB0_722:
	v_add_u32_e32 v144, s59, v183
	v_add_u32_e32 v170, s60, v183
	ds_read_b128 v[116:119], v144
	ds_read_b128 v[136:139], v144 offset:1024
	ds_read_b128 v[140:143], v144 offset:2048
	ds_read_b128 v[144:147], v144 offset:3072
	ds_read_b128 v[148:151], v170
	ds_read_b128 v[188:191], v170 offset:1024
	ds_read_b128 v[192:195], v170 offset:2048
	ds_read_b128 v[198:201], v170 offset:3072
	s_cmp_eq_u32 s53, s8
	v_lshl_add_u64 v[204:205], v[114:115], 0, s[18:19]
	s_cselect_b64 vcc, -1, 0
	s_add_i32 s8, s8, 2
	v_cndmask_b32_e32 v213, v205, v185, vcc
	v_cndmask_b32_e32 v212, v204, v184, vcc
	v_cndmask_b32_e32 v215, v113, v187, vcc
	v_cndmask_b32_e32 v214, v112, v186, vcc
	v_lshl_add_u64 v[240:241], v[114:115], 0, v[178:179]
	s_add_i32 m0, s34, 0xc000
	ds_read_b128 v[204:207], v202
	ds_read_b128 v[208:211], v202 offset:1024
	ds_read_b128 v[216:219], v202 offset:2048
	ds_read_b128 v[220:223], v202 offset:3072
	ds_read_b128 v[224:227], v202 offset:4096
	ds_read_b128 v[228:231], v202 offset:5120
	ds_read_b128 v[232:235], v202 offset:6144
	ds_read_b128 v[236:239], v202 offset:7168
	global_load_lds_dwordx4 v[240:241], off
	s_add_i32 m0, s34, 0xe000
	v_lshl_add_u64 v[240:241], v[114:115], 0, v[176:177]
	global_load_lds_dwordx4 v[240:241], off
	s_waitcnt vmcnt(8) lgkmcnt(0)
	s_setprio 1
	s_barrier
	v_mfma_f32_16x16x32_bf16 v[132:135], v[116:119], v[204:207], v[132:135]
	v_mfma_f32_16x16x32_bf16 v[128:131], v[140:143], v[204:207], v[128:131]
	v_mfma_f32_16x16x32_bf16 v[108:111], v[116:119], v[216:219], v[108:111]
	v_mfma_f32_16x16x32_bf16 v[104:107], v[140:143], v[216:219], v[104:107]
	v_mfma_f32_16x16x32_bf16 v[92:95], v[116:119], v[224:227], v[92:95]
	v_mfma_f32_16x16x32_bf16 v[88:91], v[140:143], v[224:227], v[88:91]
	v_mfma_f32_16x16x32_bf16 v[76:79], v[116:119], v[232:235], v[76:79]
	v_mfma_f32_16x16x32_bf16 v[72:75], v[140:143], v[232:235], v[72:75]
	v_mfma_f32_16x16x32_bf16 v[132:135], v[136:139], v[208:211], v[132:135]
	v_mfma_f32_16x16x32_bf16 v[128:131], v[144:147], v[208:211], v[128:131]
	v_mfma_f32_16x16x32_bf16 v[108:111], v[136:139], v[220:223], v[108:111]
	v_mfma_f32_16x16x32_bf16 v[104:107], v[144:147], v[220:223], v[104:107]
	v_mfma_f32_16x16x32_bf16 v[92:95], v[136:139], v[228:231], v[92:95]
	v_mfma_f32_16x16x32_bf16 v[88:91], v[144:147], v[228:231], v[88:91]
	v_mfma_f32_16x16x32_bf16 v[76:79], v[136:139], v[236:239], v[76:79]
	v_mfma_f32_16x16x32_bf16 v[72:75], v[144:147], v[236:239], v[72:75]
	v_mfma_f32_16x16x32_bf16 v[124:127], v[148:151], v[204:207], v[124:127]
	v_mfma_f32_16x16x32_bf16 v[120:123], v[192:195], v[204:207], v[120:123]
	v_mfma_f32_16x16x32_bf16 v[100:103], v[148:151], v[216:219], v[100:103]
	v_mfma_f32_16x16x32_bf16 v[96:99], v[192:195], v[216:219], v[96:99]
	v_mfma_f32_16x16x32_bf16 v[84:87], v[148:151], v[224:227], v[84:87]
	v_mfma_f32_16x16x32_bf16 v[80:83], v[192:195], v[224:227], v[80:83]
	v_mfma_f32_16x16x32_bf16 v[68:71], v[148:151], v[232:235], v[68:71]
	v_mfma_f32_16x16x32_bf16 v[64:67], v[192:195], v[232:235], v[64:67]
	v_mfma_f32_16x16x32_bf16 v[124:127], v[188:191], v[208:211], v[124:127]
	v_mfma_f32_16x16x32_bf16 v[120:123], v[198:201], v[208:211], v[120:123]
	v_mfma_f32_16x16x32_bf16 v[100:103], v[188:191], v[220:223], v[100:103]
	v_mfma_f32_16x16x32_bf16 v[96:99], v[198:201], v[220:223], v[96:99]
	v_mfma_f32_16x16x32_bf16 v[84:87], v[188:191], v[228:231], v[84:87]
	v_mfma_f32_16x16x32_bf16 v[80:83], v[198:201], v[228:231], v[80:83]
	v_mfma_f32_16x16x32_bf16 v[68:71], v[188:191], v[236:239], v[68:71]
	v_mfma_f32_16x16x32_bf16 v[64:67], v[198:201], v[236:239], v[64:67]
	s_setprio 0
	s_barrier
	s_add_i32 s9, s59, s29
	v_lshl_add_u64 v[240:241], v[214:215], 0, v[164:165]
	s_mov_b32 m0, s9
	ds_read_b128 v[204:207], v202 offset:16384
	ds_read_b128 v[208:211], v202 offset:17408
	ds_read_b128 v[216:219], v202 offset:18432
	ds_read_b128 v[220:223], v202 offset:19456
	ds_read_b128 v[224:227], v202 offset:20480
	ds_read_b128 v[228:231], v202 offset:21504
	ds_read_b128 v[232:235], v202 offset:22528
	ds_read_b128 v[236:239], v202 offset:23552
	global_load_lds_dwordx4 v[240:241], off
	v_lshl_add_u64 v[242:243], v[214:215], 0, v[168:169]
	s_add_i32 m0, s9, 0x2000
	v_lshl_add_u64 v[214:215], v[214:215], 0, s[12:13]
	s_add_i32 s9, s60, s29
	global_load_lds_dwordx4 v[242:243], off
	v_lshl_add_u64 v[244:245], v[214:215], 0, v[164:165]
	s_mov_b32 m0, s9
	v_lshl_add_u64 v[214:215], v[214:215], 0, v[168:169]
	global_load_lds_dwordx4 v[244:245], off
	s_add_i32 m0, s9, 0x2000
	v_lshl_add_u64 v[246:247], v[212:213], 0, v[162:163]
	global_load_lds_dwordx4 v[214:215], off
	s_mov_b32 m0, s34
	v_lshl_add_u64 v[248:249], v[212:213], 0, v[166:167]
	global_load_lds_dwordx4 v[246:247], off
	s_mov_b32 m0, s36
	s_nop 0
	global_load_lds_dwordx4 v[248:249], off
	s_waitcnt vmcnt(8) lgkmcnt(0)
	s_setprio 1
	s_barrier
; #define PG8_STAGE(bufoff, gbase, voff) do { _Pragma("unroll") for (int _i = 0; _i < 2; ++_i) \
;         __builtin_amdgcn_global_load_lds((const unsigned*)((const char*)(gbase) + (voff)[_i]), (PG8_LAS unsigned*)(lds + (bufoff) + ldsw + _i * 8192), 16, 0, 0); } while (0)
; #define PG8_LDA(dst, b, h) do { _Pragma("unroll") for (int m = 0; m < 4; ++m) _Pragma("unroll") for (int k = 0; k < 2; ++k) dst[m][k] = *(const PG8_LAS bf16x8*)(lds + PG8_SA(b, h) + aoff + m * 2048 + k * 1024); } while (0)
; #define PG8_LDB(dst, b, h) do { _Pragma("unroll") for (int n = 0; n < 2; ++n) _Pragma("unroll") for (int k = 0; k < 2; ++k) dst[n][k] = *(const PG8_LAS bf16x8*)(lds + PG8_SB(b, h) + boff + n * 2048 + k * 1024); } while (0)
; #define PG8_MMA(ai, bj, At, Bt) do { __builtin_amdgcn_s_setprio(1); _Pragma("unroll") for (int m = 0; m < 4; ++m) _Pragma("unroll") for (int n = 0; n < 2; ++n) _Pragma("unroll") for (int k = 0; k < 2; ++k) \
;         acc[ai][bj][m][n] = __builtin_amdgcn_mfma_f32_16x16x32_bf16(Bt[n][k], At[m][k], acc[ai][bj][m][n], 0, 0, 0); __builtin_amdgcn_s_setprio(0); } while (0)
; #define PG8_WAIT_V(n) asm volatile("s_waitcnt vmcnt(" #n ")" ::: "memory")
; #define PG8_WAIT_L(n) asm volatile("s_waitcnt lgkmcnt(" #n ")" ::: "memory")
; #define PG8_BAR __builtin_amdgcn_s_barrier()
; #define PG8_SCHED __builtin_amdgcn_sched_barrier(0)
; template <class Epi, class Sched, bool ALIGN_EPI = false, bool SP2 = false>
; __device__ __forceinline__ void gemm_phase(PG8_LAS unsigned char* lds, const Gemm g, const Sched& S, const Epi& E) {
;     ...
;             PG8_WAIT_V(8); PG8_WAIT_L(0); PG8_BAR; PG8_MMA(1, 0, At, B0); PG8_MMA(1, 1, At, B1); PG8_BAR; PG8_SCHED;
;             PG8_LDB(B0, 1, 0); PG8_LDB(B1, 1, 1); PG8_SCHED; PG8_LDA(At, 1, 0); PG8_STAGE(PG8_SA(0, 1), a2 + hstep, voffA);
;             PG8_WAIT_V(8); PG8_WAIT_L(0); PG8_BAR; PG8_MMA(0, 0, At, B0); PG8_MMA(0, 1, At, B1); PG8_BAR; PG8_SCHED;
	v_mfma_f32_16x16x32_bf16 v[60:63], v[116:119], v[204:207], v[60:63]
	v_mfma_f32_16x16x32_bf16 v[56:59], v[140:143], v[204:207], v[56:59]
	v_mfma_f32_16x16x32_bf16 v[44:47], v[116:119], v[216:219], v[44:47]
	v_mfma_f32_16x16x32_bf16 v[40:43], v[140:143], v[216:219], v[40:43]
	v_mfma_f32_16x16x32_bf16 v[28:31], v[116:119], v[224:227], v[28:31]
	v_mfma_f32_16x16x32_bf16 v[24:27], v[140:143], v[224:227], v[24:27]
	v_mfma_f32_16x16x32_bf16 v[12:15], v[116:119], v[232:235], v[12:15]
	v_mfma_f32_16x16x32_bf16 v[8:11], v[140:143], v[232:235], v[8:11]
	v_mfma_f32_16x16x32_bf16 v[60:63], v[136:139], v[208:211], v[60:63]
	v_mfma_f32_16x16x32_bf16 v[56:59], v[144:147], v[208:211], v[56:59]
	v_mfma_f32_16x16x32_bf16 v[44:47], v[136:139], v[220:223], v[44:47]
	v_mfma_f32_16x16x32_bf16 v[40:43], v[144:147], v[220:223], v[40:43]
	v_mfma_f32_16x16x32_bf16 v[28:31], v[136:139], v[228:231], v[28:31]
	v_mfma_f32_16x16x32_bf16 v[24:27], v[144:147], v[228:231], v[24:27]
	v_mfma_f32_16x16x32_bf16 v[12:15], v[136:139], v[236:239], v[12:15]
	v_mfma_f32_16x16x32_bf16 v[8:11], v[144:147], v[236:239], v[8:11]
	v_mfma_f32_16x16x32_bf16 v[52:55], v[148:151], v[204:207], v[52:55]
	v_mfma_f32_16x16x32_bf16 v[48:51], v[192:195], v[204:207], v[48:51]
	v_mfma_f32_16x16x32_bf16 v[36:39], v[148:151], v[216:219], v[36:39]
	v_mfma_f32_16x16x32_bf16 v[32:35], v[192:195], v[216:219], v[32:35]
	v_mfma_f32_16x16x32_bf16 v[20:23], v[148:151], v[224:227], v[20:23]
	v_mfma_f32_16x16x32_bf16 v[16:19], v[192:195], v[224:227], v[16:19]
	v_mfma_f32_16x16x32_bf16 v[4:7], v[148:151], v[232:235], v[4:7]
	v_mfma_f32_16x16x32_bf16 v[0:3], v[192:195], v[232:235], v[0:3]
	v_mfma_f32_16x16x32_bf16 v[52:55], v[188:191], v[208:211], v[52:55]
	v_mfma_f32_16x16x32_bf16 v[48:51], v[198:201], v[208:211], v[48:51]
	v_mfma_f32_16x16x32_bf16 v[36:39], v[188:191], v[220:223], v[36:39]
	v_mfma_f32_16x16x32_bf16 v[32:35], v[198:201], v[220:223], v[32:35]
	v_mfma_f32_16x16x32_bf16 v[20:23], v[188:191], v[228:231], v[20:23]
	v_mfma_f32_16x16x32_bf16 v[16:19], v[198:201], v[228:231], v[16:19]
	v_mfma_f32_16x16x32_bf16 v[4:7], v[188:191], v[236:239], v[4:7]
	v_mfma_f32_16x16x32_bf16 v[0:3], v[198:201], v[236:239], v[0:3]
	s_setprio 0
	s_barrier
	s_add_i32 s9, 0, 0x18000
	s_add_i32 s10, 0, 0x1c000
	v_add_u32_e32 v144, s9, v183
	v_add_u32_e32 v170, s10, v183
	ds_read_b128 v[116:119], v144
	ds_read_b128 v[136:139], v144 offset:1024
	ds_read_b128 v[140:143], v144 offset:2048
	ds_read_b128 v[144:147], v144 offset:3072
	ds_read_b128 v[148:151], v170
	ds_read_b128 v[188:191], v170 offset:1024
	ds_read_b128 v[192:195], v170 offset:2048
	ds_read_b128 v[198:201], v170 offset:3072
	v_lshl_add_u64 v[212:213], v[212:213], 0, s[12:13]
	s_mov_b32 m0, s37
	v_lshl_add_u64 v[250:251], v[212:213], 0, v[162:163]
	ds_read_b128 v[204:207], v202 offset:32768
	ds_read_b128 v[208:211], v202 offset:33792
	ds_read_b128 v[216:219], v202 offset:34816
	ds_read_b128 v[220:223], v202 offset:35840
	ds_read_b128 v[224:227], v202 offset:36864
	ds_read_b128 v[228:231], v202 offset:37888
	ds_read_b128 v[232:235], v202 offset:38912
	ds_read_b128 v[236:239], v202 offset:39936
	global_load_lds_dwordx4 v[250:251], off
	s_mov_b32 m0, s41
	v_lshl_add_u64 v[212:213], v[212:213], 0, v[166:167]
	global_load_lds_dwordx4 v[212:213], off
	s_waitcnt vmcnt(8) lgkmcnt(0)
	s_setprio 1
	s_barrier
	v_mfma_f32_16x16x32_bf16 v[132:135], v[116:119], v[204:207], v[132:135]
	v_mfma_f32_16x16x32_bf16 v[128:131], v[140:143], v[204:207], v[128:131]
	v_mfma_f32_16x16x32_bf16 v[108:111], v[116:119], v[216:219], v[108:111]
	v_mfma_f32_16x16x32_bf16 v[104:107], v[140:143], v[216:219], v[104:107]
	v_mfma_f32_16x16x32_bf16 v[92:95], v[116:119], v[224:227], v[92:95]
	v_mfma_f32_16x16x32_bf16 v[88:91], v[140:143], v[224:227], v[88:91]
	v_mfma_f32_16x16x32_bf16 v[76:79], v[116:119], v[232:235], v[76:79]
	v_mfma_f32_16x16x32_bf16 v[72:75], v[140:143], v[232:235], v[72:75]
	v_mfma_f32_16x16x32_bf16 v[132:135], v[136:139], v[208:211], v[132:135]
	v_mfma_f32_16x16x32_bf16 v[128:131], v[144:147], v[208:211], v[128:131]
	v_mfma_f32_16x16x32_bf16 v[108:111], v[136:139], v[220:223], v[108:111]
	v_mfma_f32_16x16x32_bf16 v[104:107], v[144:147], v[220:223], v[104:107]
	v_mfma_f32_16x16x32_bf16 v[92:95], v[136:139], v[228:231], v[92:95]
	v_mfma_f32_16x16x32_bf16 v[88:91], v[144:147], v[228:231], v[88:91]
	v_mfma_f32_16x16x32_bf16 v[76:79], v[136:139], v[236:239], v[76:79]
	v_mfma_f32_16x16x32_bf16 v[72:75], v[144:147], v[236:239], v[72:75]
	v_mfma_f32_16x16x32_bf16 v[124:127], v[148:151], v[204:207], v[124:127]
	v_mfma_f32_16x16x32_bf16 v[120:123], v[192:195], v[204:207], v[120:123]
	v_mfma_f32_16x16x32_bf16 v[100:103], v[148:151], v[216:219], v[100:103]
	v_mfma_f32_16x16x32_bf16 v[96:99], v[192:195], v[216:219], v[96:99]
	v_mfma_f32_16x16x32_bf16 v[84:87], v[148:151], v[224:227], v[84:87]
	v_mfma_f32_16x16x32_bf16 v[80:83], v[192:195], v[224:227], v[80:83]
	v_mfma_f32_16x16x32_bf16 v[68:71], v[148:151], v[232:235], v[68:71]
	v_mfma_f32_16x16x32_bf16 v[64:67], v[192:195], v[232:235], v[64:67]
	v_mfma_f32_16x16x32_bf16 v[124:127], v[188:191], v[208:211], v[124:127]
	v_mfma_f32_16x16x32_bf16 v[120:123], v[198:201], v[208:211], v[120:123]
	v_mfma_f32_16x16x32_bf16 v[100:103], v[188:191], v[220:223], v[100:103]
	v_mfma_f32_16x16x32_bf16 v[96:99], v[198:201], v[220:223], v[96:99]
	v_mfma_f32_16x16x32_bf16 v[84:87], v[188:191], v[228:231], v[84:87]
	v_mfma_f32_16x16x32_bf16 v[80:83], v[198:201], v[228:231], v[80:83]
	v_mfma_f32_16x16x32_bf16 v[68:71], v[188:191], v[236:239], v[68:71]
	v_mfma_f32_16x16x32_bf16 v[64:67], v[198:201], v[236:239], v[64:67]
	s_setprio 0
	s_barrier
; #define PG8_STAGE(bufoff, gbase, voff) do { _Pragma("unroll") for (int _i = 0; _i < 2; ++_i) \
;         __builtin_amdgcn_global_load_lds((const unsigned*)((const char*)(gbase) + (voff)[_i]), (PG8_LAS unsigned*)(lds + (bufoff) + ldsw + _i * 8192), 16, 0, 0); } while (0)
; #define PG8_LDA(dst, b, h) do { _Pragma("unroll") for (int m = 0; m < 4; ++m) _Pragma("unroll") for (int k = 0; k < 2; ++k) dst[m][k] = *(const PG8_LAS bf16x8*)(lds + PG8_SA(b, h) + aoff + m * 2048 + k * 1024); } while (0)
; #define PG8_MMA(ai, bj, At, Bt) do { __builtin_amdgcn_s_setprio(1); _Pragma("unroll") for (int m = 0; m < 4; ++m) _Pragma("unroll") for (int n = 0; n < 2; ++n) _Pragma("unroll") for (int k = 0; k < 2; ++k) \
;         acc[ai][bj][m][n] = __builtin_amdgcn_mfma_f32_16x16x32_bf16(Bt[n][k], At[m][k], acc[ai][bj][m][n], 0, 0, 0); __builtin_amdgcn_s_setprio(0); } while (0)
; #define PG8_WAIT_V(n) asm volatile("s_waitcnt vmcnt(" #n ")" ::: "memory")
; #define PG8_WAIT_L(n) asm volatile("s_waitcnt lgkmcnt(" #n ")" ::: "memory")
; #define PG8_BAR __builtin_amdgcn_s_barrier()
; #define PG8_SCHED __builtin_amdgcn_sched_barrier(0)
; template <class Epi, class Sched, bool ALIGN_EPI = false, bool SP2 = false>
; __device__ __forceinline__ void gemm_phase(PG8_LAS unsigned char* lds, const Gemm g, const Sched& S, const Epi& E) {
;     ...
;             PG8_LDA(At, 1, 1); PG8_STAGE(PG8_SB(1, 0), b3, voffB); PG8_STAGE(PG8_SB(1, 1), b3 + hstep, voffB); PG8_STAGE(PG8_SA(1, 0), a3, voffA);
;             PG8_WAIT_V(8); PG8_WAIT_L(0); PG8_BAR; PG8_MMA(1, 0, At, B0); PG8_MMA(1, 1, At, B1); PG8_BAR; PG8_SCHED;
	s_add_i32 s9, s9, s29
	v_lshl_add_u64 v[212:213], v[240:241], 0, s[18:19]
	s_mov_b32 m0, s9
	ds_read_b128 v[204:207], v202 offset:49152
	ds_read_b128 v[208:211], v202 offset:50176
	ds_read_b128 v[216:219], v202 offset:51200
	ds_read_b128 v[220:223], v202 offset:52224
	ds_read_b128 v[224:227], v202 offset:53248
	ds_read_b128 v[228:231], v202 offset:54272
	ds_read_b128 v[232:235], v202 offset:55296
	ds_read_b128 v[236:239], v202 offset:56320
	global_load_lds_dwordx4 v[212:213], off
	v_lshl_add_u64 v[212:213], v[242:243], 0, s[18:19]
	s_add_i32 m0, s9, 0x2000
	s_add_i32 s9, s10, s29
	global_load_lds_dwordx4 v[212:213], off
	s_mov_b32 m0, s9
	v_lshl_add_u64 v[212:213], v[244:245], 0, s[18:19]
	global_load_lds_dwordx4 v[212:213], off
	s_add_i32 m0, s9, 0x2000
	v_lshl_add_u64 v[212:213], v[214:215], 0, s[18:19]
	global_load_lds_dwordx4 v[212:213], off
	s_mov_b32 m0, s49
	v_lshl_add_u64 v[212:213], v[246:247], 0, s[18:19]
	global_load_lds_dwordx4 v[212:213], off
	s_mov_b32 m0, s50
	v_lshl_add_u64 v[212:213], v[248:249], 0, s[18:19]
	global_load_lds_dwordx4 v[212:213], off
	s_waitcnt vmcnt(8) lgkmcnt(0)
	s_setprio 1
	s_barrier
	v_mfma_f32_16x16x32_bf16 v[60:63], v[116:119], v[204:207], v[60:63]
	v_mfma_f32_16x16x32_bf16 v[56:59], v[140:143], v[204:207], v[56:59]
	v_mfma_f32_16x16x32_bf16 v[44:47], v[116:119], v[216:219], v[44:47]
	v_mfma_f32_16x16x32_bf16 v[40:43], v[140:143], v[216:219], v[40:43]
	v_mfma_f32_16x16x32_bf16 v[28:31], v[116:119], v[224:227], v[28:31]
	v_mfma_f32_16x16x32_bf16 v[24:27], v[140:143], v[224:227], v[24:27]
	v_mfma_f32_16x16x32_bf16 v[12:15], v[116:119], v[232:235], v[12:15]
	v_mfma_f32_16x16x32_bf16 v[8:11], v[140:143], v[232:235], v[8:11]
	v_mfma_f32_16x16x32_bf16 v[60:63], v[136:139], v[208:211], v[60:63]
	v_mfma_f32_16x16x32_bf16 v[56:59], v[144:147], v[208:211], v[56:59]
	v_mfma_f32_16x16x32_bf16 v[44:47], v[136:139], v[220:223], v[44:47]
	v_mfma_f32_16x16x32_bf16 v[40:43], v[144:147], v[220:223], v[40:43]
	v_mfma_f32_16x16x32_bf16 v[28:31], v[136:139], v[228:231], v[28:31]
	v_mfma_f32_16x16x32_bf16 v[24:27], v[144:147], v[228:231], v[24:27]
	v_mfma_f32_16x16x32_bf16 v[12:15], v[136:139], v[236:239], v[12:15]
	v_mfma_f32_16x16x32_bf16 v[8:11], v[144:147], v[236:239], v[8:11]
	v_mfma_f32_16x16x32_bf16 v[52:55], v[148:151], v[204:207], v[52:55]
	v_mfma_f32_16x16x32_bf16 v[48:51], v[192:195], v[204:207], v[48:51]
	v_mfma_f32_16x16x32_bf16 v[36:39], v[148:151], v[216:219], v[36:39]
	v_mfma_f32_16x16x32_bf16 v[32:35], v[192:195], v[216:219], v[32:35]
	v_mfma_f32_16x16x32_bf16 v[20:23], v[148:151], v[224:227], v[20:23]
	v_mfma_f32_16x16x32_bf16 v[16:19], v[192:195], v[224:227], v[16:19]
	v_mfma_f32_16x16x32_bf16 v[4:7], v[148:151], v[232:235], v[4:7]
	v_mfma_f32_16x16x32_bf16 v[0:3], v[192:195], v[232:235], v[0:3]
	v_mfma_f32_16x16x32_bf16 v[52:55], v[188:191], v[208:211], v[52:55]
	v_mfma_f32_16x16x32_bf16 v[48:51], v[198:201], v[208:211], v[48:51]
	v_mfma_f32_16x16x32_bf16 v[36:39], v[188:191], v[220:223], v[36:39]
	v_mfma_f32_16x16x32_bf16 v[32:35], v[198:201], v[220:223], v[32:35]
	v_mfma_f32_16x16x32_bf16 v[20:23], v[188:191], v[228:231], v[20:23]
	v_mfma_f32_16x16x32_bf16 v[16:19], v[198:201], v[228:231], v[16:19]
	v_mfma_f32_16x16x32_bf16 v[4:7], v[188:191], v[236:239], v[4:7]
	v_mfma_f32_16x16x32_bf16 v[0:3], v[198:201], v[236:239], v[0:3]
	s_setprio 0
	s_barrier
	v_lshl_add_u64 v[112:113], v[112:113], 0, s[26:27]
	s_cmp_ge_i32 s8, s51
	v_lshl_add_u64 v[114:115], v[114:115], 0, s[26:27]
	s_cbranch_scc0 .LBB0_722

; #define PG8_STAGE(bufoff, gbase, voff) do { _Pragma("unroll") for (int _i = 0; _i < 2; ++_i) \
;         __builtin_amdgcn_global_load_lds((const unsigned*)((const char*)(gbase) + (voff)[_i]), (PG8_LAS unsigned*)(lds + (bufoff) + ldsw + _i * 8192), 16, 0, 0); } while (0)
; #define PG8_LDA(dst, b, h) do { _Pragma("unroll") for (int m = 0; m < 4; ++m) _Pragma("unroll") for (int k = 0; k < 2; ++k) dst[m][k] = *(const PG8_LAS bf16x8*)(lds + PG8_SA(b, h) + aoff + m * 2048 + k * 1024); } while (0)
; #define PG8_LDB(dst, b, h) do { _Pragma("unroll") for (int n = 0; n < 2; ++n) _Pragma("unroll") for (int k = 0; k < 2; ++k) dst[n][k] = *(const PG8_LAS bf16x8*)(lds + PG8_SB(b, h) + boff + n * 2048 + k * 1024); } while (0)
; #define PG8_MMA(ai, bj, At, Bt) do { __builtin_amdgcn_s_setprio(1); _Pragma("unroll") for (int m = 0; m < 4; ++m) _Pragma("unroll") for (int n = 0; n < 2; ++n) _Pragma("unroll") for (int k = 0; k < 2; ++k) \
;         acc[ai][bj][m][n] = __builtin_amdgcn_mfma_f32_16x16x32_bf16(Bt[n][k], At[m][k], acc[ai][bj][m][n], 0, 0, 0); __builtin_amdgcn_s_setprio(0); } while (0)
; #define PG8_WAIT_V(n) asm volatile("s_waitcnt vmcnt(" #n ")" ::: "memory")
; #define PG8_BAR __builtin_amdgcn_s_barrier()
; template <class Epi, class Sched, bool ALIGN_EPI = false, bool SP2 = false>
; __device__ __forceinline__ void gemm_phase(PG8_LAS unsigned char* lds, const Gemm g, const Sched& S, const Epi& E) {
;     ...
;         for (int t = 0; t < nt; t += 2) {
;             const bool last = (t == nt - 2);
;             const char* a1 = cA + (size_t)(t + 1) * kstep;
;             const char* a2 = last ? nA : cA + (size_t)(t + 2) * kstep; const char* b2 = last ? nB : cB + (size_t)(t + 2) * kstep;
;             const char* a3 = a2 + kstep; const char* b3 = b2 + kstep;
;             if (last && has_next) S.a_ready(nxt);
;             if constexpr (SP2) {
;             PG8_LDB(B0, 0, 0); PG8_LDB(B1, 0, 1); PG8_SCHED; PG8_LDA(At, 0, 0); PG8_STAGE(PG8_SA(1, 1), a1 + hstep, voffA);
;             PG8_WAIT_V(8); PG8_WAIT_L(0); PG8_BAR; PG8_MMA(0, 0, At, B0); PG8_MMA(0, 1, At, B1); PG8_BAR; PG8_SCHED;
;             PG8_LDA(At, 0, 1); PG8_STAGE(PG8_SB(0, 0), b2, voffB); PG8_STAGE(PG8_SB(0, 1), b2 + hstep, voffB); PG8_STAGE(PG8_SA(0, 0), a2, voffA);
;             PG8_WAIT_V(8); PG8_WAIT_L(0); PG8_BAR; PG8_MMA(1, 0, At, B0); PG8_MMA(1, 1, At, B1); PG8_BAR; PG8_SCHED;
.LBB0_940:
	v_add_u32_e32 v188, s55, v199
	ds_read_b128 v[132:135], v201
	ds_read_b128 v[136:139], v201 offset:1024
	ds_read_b128 v[140:143], v201 offset:2048
	ds_read_b128 v[144:147], v201 offset:3072
	ds_read_b128 v[148:151], v188
	ds_read_b128 v[180:183], v188 offset:1024
	ds_read_b128 v[184:187], v188 offset:2048
	ds_read_b128 v[188:191], v188 offset:3072
	s_cmp_eq_u32 s48, s12
	v_lshl_add_u64 v[192:193], v[130:131], 0, s[22:23]
	s_cselect_b64 vcc, -1, 0
	s_add_i32 s12, s12, 2
	v_cndmask_b32_e32 v197, v193, v177, vcc
	v_cndmask_b32_e32 v196, v192, v176, vcc
	v_cndmask_b32_e32 v213, v129, v179, vcc
	v_cndmask_b32_e32 v212, v128, v178, vcc
	s_mov_b32 m0, s56
	v_lshl_add_u64 v[214:215], v[130:131], 0, v[172:173]
	ds_read_b128 v[192:195], v202
	ds_read_b128 v[204:207], v202 offset:1024
	ds_read_b128 v[208:211], v202 offset:2048
	ds_read_b128 v[216:219], v202 offset:3072
	ds_read_b128 v[220:223], v202 offset:4096
	ds_read_b128 v[224:227], v202 offset:5120
	ds_read_b128 v[228:231], v202 offset:6144
	ds_read_b128 v[232:235], v202 offset:7168
	global_load_lds_dwordx4 v[214:215], off
	s_mov_b32 m0, s57
	v_lshl_add_u64 v[214:215], v[130:131], 0, v[170:171]
	global_load_lds_dwordx4 v[214:215], off
	s_waitcnt vmcnt(8) lgkmcnt(0)
	s_setprio 1
	s_barrier
	v_mfma_f32_16x16x32_bf16 v[120:123], v[132:135], v[192:195], v[120:123]
	v_mfma_f32_16x16x32_bf16 v[124:127], v[140:143], v[192:195], v[124:127]
	v_mfma_f32_16x16x32_bf16 v[108:111], v[132:135], v[208:211], v[108:111]
	v_mfma_f32_16x16x32_bf16 v[104:107], v[140:143], v[208:211], v[104:107]
	v_mfma_f32_16x16x32_bf16 v[92:95], v[132:135], v[220:223], v[92:95]
	v_mfma_f32_16x16x32_bf16 v[88:91], v[140:143], v[220:223], v[88:91]
	v_mfma_f32_16x16x32_bf16 v[76:79], v[132:135], v[228:231], v[76:79]
	v_mfma_f32_16x16x32_bf16 v[72:75], v[140:143], v[228:231], v[72:75]
	v_mfma_f32_16x16x32_bf16 v[120:123], v[136:139], v[204:207], v[120:123]
	v_mfma_f32_16x16x32_bf16 v[124:127], v[144:147], v[204:207], v[124:127]
	v_mfma_f32_16x16x32_bf16 v[108:111], v[136:139], v[216:219], v[108:111]
	v_mfma_f32_16x16x32_bf16 v[104:107], v[144:147], v[216:219], v[104:107]
	v_mfma_f32_16x16x32_bf16 v[92:95], v[136:139], v[224:227], v[92:95]
	v_mfma_f32_16x16x32_bf16 v[88:91], v[144:147], v[224:227], v[88:91]
	v_mfma_f32_16x16x32_bf16 v[76:79], v[136:139], v[232:235], v[76:79]
	v_mfma_f32_16x16x32_bf16 v[72:75], v[144:147], v[232:235], v[72:75]
	v_mfma_f32_16x16x32_bf16 v[116:119], v[148:151], v[192:195], v[116:119]
	v_mfma_f32_16x16x32_bf16 v[112:115], v[184:187], v[192:195], v[112:115]
	v_mfma_f32_16x16x32_bf16 v[100:103], v[148:151], v[208:211], v[100:103]
	v_mfma_f32_16x16x32_bf16 v[96:99], v[184:187], v[208:211], v[96:99]
	v_mfma_f32_16x16x32_bf16 v[84:87], v[148:151], v[220:223], v[84:87]
	v_mfma_f32_16x16x32_bf16 v[80:83], v[184:187], v[220:223], v[80:83]
	v_mfma_f32_16x16x32_bf16 v[68:71], v[148:151], v[228:231], v[68:71]
	v_mfma_f32_16x16x32_bf16 v[64:67], v[184:187], v[228:231], v[64:67]
	v_mfma_f32_16x16x32_bf16 v[116:119], v[180:183], v[204:207], v[116:119]
	v_mfma_f32_16x16x32_bf16 v[112:115], v[188:191], v[204:207], v[112:115]
	v_mfma_f32_16x16x32_bf16 v[100:103], v[180:183], v[216:219], v[100:103]
	v_mfma_f32_16x16x32_bf16 v[96:99], v[188:191], v[216:219], v[96:99]
	v_mfma_f32_16x16x32_bf16 v[84:87], v[180:183], v[224:227], v[84:87]
	v_mfma_f32_16x16x32_bf16 v[80:83], v[188:191], v[224:227], v[80:83]
	v_mfma_f32_16x16x32_bf16 v[68:71], v[180:183], v[232:235], v[68:71]
	v_mfma_f32_16x16x32_bf16 v[64:67], v[188:191], v[232:235], v[64:67]
	s_setprio 0
	s_barrier
	s_mov_b32 m0, s58
	v_lshl_add_u64 v[214:215], v[212:213], 0, v[164:165]
	ds_read_b128 v[192:195], v202 offset:16384
	ds_read_b128 v[204:207], v202 offset:17408
	ds_read_b128 v[208:211], v202 offset:18432
	ds_read_b128 v[216:219], v202 offset:19456
	ds_read_b128 v[220:223], v202 offset:20480
	ds_read_b128 v[224:227], v202 offset:21504
	ds_read_b128 v[228:231], v202 offset:22528
	ds_read_b128 v[232:235], v202 offset:23552
	global_load_lds_dwordx4 v[214:215], off
	v_lshl_add_u64 v[236:237], v[212:213], 0, v[168:169]
	s_mov_b32 m0, s59
	v_lshl_add_u64 v[212:213], v[212:213], 0, s[14:15]
	s_add_i32 s13, s55, s30
	global_load_lds_dwordx4 v[236:237], off
	v_lshl_add_u64 v[238:239], v[212:213], 0, v[164:165]
	s_mov_b32 m0, s13
	v_lshl_add_u64 v[212:213], v[212:213], 0, v[168:169]
	global_load_lds_dwordx4 v[238:239], off
	s_add_i32 m0, s13, 0x2000
	v_lshl_add_u64 v[240:241], v[196:197], 0, v[162:163]
	global_load_lds_dwordx4 v[212:213], off
	s_mov_b32 m0, s31
	v_lshl_add_u64 v[242:243], v[196:197], 0, v[166:167]
	global_load_lds_dwordx4 v[240:241], off
	s_mov_b32 m0, s34
	s_nop 0
	global_load_lds_dwordx4 v[242:243], off
	s_waitcnt vmcnt(8) lgkmcnt(0)
	s_setprio 1
	s_barrier
; #define PG8_STAGE(bufoff, gbase, voff) do { _Pragma("unroll") for (int _i = 0; _i < 2; ++_i) \
;         __builtin_amdgcn_global_load_lds((const unsigned*)((const char*)(gbase) + (voff)[_i]), (PG8_LAS unsigned*)(lds + (bufoff) + ldsw + _i * 8192), 16, 0, 0); } while (0)
; #define PG8_LDA(dst, b, h) do { _Pragma("unroll") for (int m = 0; m < 4; ++m) _Pragma("unroll") for (int k = 0; k < 2; ++k) dst[m][k] = *(const PG8_LAS bf16x8*)(lds + PG8_SA(b, h) + aoff + m * 2048 + k * 1024); } while (0)
; #define PG8_LDB(dst, b, h) do { _Pragma("unroll") for (int n = 0; n < 2; ++n) _Pragma("unroll") for (int k = 0; k < 2; ++k) dst[n][k] = *(const PG8_LAS bf16x8*)(lds + PG8_SB(b, h) + boff + n * 2048 + k * 1024); } while (0)
; #define PG8_MMA(ai, bj, At, Bt) do { __builtin_amdgcn_s_setprio(1); _Pragma("unroll") for (int m = 0; m < 4; ++m) _Pragma("unroll") for (int n = 0; n < 2; ++n) _Pragma("unroll") for (int k = 0; k < 2; ++k) \
;         acc[ai][bj][m][n] = __builtin_amdgcn_mfma_f32_16x16x32_bf16(Bt[n][k], At[m][k], acc[ai][bj][m][n], 0, 0, 0); __builtin_amdgcn_s_setprio(0); } while (0)
; #define PG8_WAIT_V(n) asm volatile("s_waitcnt vmcnt(" #n ")" ::: "memory")
; #define PG8_WAIT_L(n) asm volatile("s_waitcnt lgkmcnt(" #n ")" ::: "memory")
; #define PG8_BAR __builtin_amdgcn_s_barrier()
; #define PG8_SCHED __builtin_amdgcn_sched_barrier(0)
; template <class Epi, class Sched, bool ALIGN_EPI = false, bool SP2 = false>
; __device__ __forceinline__ void gemm_phase(PG8_LAS unsigned char* lds, const Gemm g, const Sched& S, const Epi& E) {
;     ...
;             PG8_WAIT_V(8); PG8_WAIT_L(0); PG8_BAR; PG8_MMA(1, 0, At, B0); PG8_MMA(1, 1, At, B1); PG8_BAR; PG8_SCHED;
;             PG8_LDB(B0, 1, 0); PG8_LDB(B1, 1, 1); PG8_SCHED; PG8_LDA(At, 1, 0); PG8_STAGE(PG8_SA(0, 1), a2 + hstep, voffA);
;             PG8_WAIT_V(8); PG8_WAIT_L(0); PG8_BAR; PG8_MMA(0, 0, At, B0); PG8_MMA(0, 1, At, B1); PG8_BAR; PG8_SCHED;
	v_mfma_f32_16x16x32_bf16 v[60:63], v[132:135], v[192:195], v[60:63]
	v_mfma_f32_16x16x32_bf16 v[56:59], v[140:143], v[192:195], v[56:59]
	v_mfma_f32_16x16x32_bf16 v[44:47], v[132:135], v[208:211], v[44:47]
	v_mfma_f32_16x16x32_bf16 v[40:43], v[140:143], v[208:211], v[40:43]
	v_mfma_f32_16x16x32_bf16 v[28:31], v[132:135], v[220:223], v[28:31]
	v_mfma_f32_16x16x32_bf16 v[24:27], v[140:143], v[220:223], v[24:27]
	v_mfma_f32_16x16x32_bf16 v[12:15], v[132:135], v[228:231], v[12:15]
	v_mfma_f32_16x16x32_bf16 v[8:11], v[140:143], v[228:231], v[8:11]
	v_mfma_f32_16x16x32_bf16 v[60:63], v[136:139], v[204:207], v[60:63]
	v_mfma_f32_16x16x32_bf16 v[56:59], v[144:147], v[204:207], v[56:59]
	v_mfma_f32_16x16x32_bf16 v[44:47], v[136:139], v[216:219], v[44:47]
	v_mfma_f32_16x16x32_bf16 v[40:43], v[144:147], v[216:219], v[40:43]
	v_mfma_f32_16x16x32_bf16 v[28:31], v[136:139], v[224:227], v[28:31]
	v_mfma_f32_16x16x32_bf16 v[24:27], v[144:147], v[224:227], v[24:27]
	v_mfma_f32_16x16x32_bf16 v[12:15], v[136:139], v[232:235], v[12:15]
	v_mfma_f32_16x16x32_bf16 v[8:11], v[144:147], v[232:235], v[8:11]
	v_mfma_f32_16x16x32_bf16 v[52:55], v[148:151], v[192:195], v[52:55]
	v_mfma_f32_16x16x32_bf16 v[48:51], v[184:187], v[192:195], v[48:51]
	v_mfma_f32_16x16x32_bf16 v[36:39], v[148:151], v[208:211], v[36:39]
	v_mfma_f32_16x16x32_bf16 v[32:35], v[184:187], v[208:211], v[32:35]
	v_mfma_f32_16x16x32_bf16 v[20:23], v[148:151], v[220:223], v[20:23]
	v_mfma_f32_16x16x32_bf16 v[16:19], v[184:187], v[220:223], v[16:19]
	v_mfma_f32_16x16x32_bf16 v[4:7], v[148:151], v[228:231], v[4:7]
	v_mfma_f32_16x16x32_bf16 v[0:3], v[184:187], v[228:231], v[0:3]
	v_mfma_f32_16x16x32_bf16 v[52:55], v[180:183], v[204:207], v[52:55]
	v_mfma_f32_16x16x32_bf16 v[48:51], v[188:191], v[204:207], v[48:51]
	v_mfma_f32_16x16x32_bf16 v[36:39], v[180:183], v[216:219], v[36:39]
	v_mfma_f32_16x16x32_bf16 v[32:35], v[188:191], v[216:219], v[32:35]
	v_mfma_f32_16x16x32_bf16 v[20:23], v[180:183], v[224:227], v[20:23]
	v_mfma_f32_16x16x32_bf16 v[16:19], v[188:191], v[224:227], v[16:19]
	v_mfma_f32_16x16x32_bf16 v[4:7], v[180:183], v[232:235], v[4:7]
	v_mfma_f32_16x16x32_bf16 v[0:3], v[188:191], v[232:235], v[0:3]
	s_setprio 0
	s_barrier
	s_add_i32 s13, 0, 0x18000
	s_add_i32 s29, 0, 0x1c000
	v_add_u32_e32 v144, s13, v199
	v_add_u32_e32 v188, s29, v199
	ds_read_b128 v[132:135], v144
	ds_read_b128 v[136:139], v144 offset:1024
	ds_read_b128 v[140:143], v144 offset:2048
	ds_read_b128 v[144:147], v144 offset:3072
	ds_read_b128 v[148:151], v188
	ds_read_b128 v[180:183], v188 offset:1024
	ds_read_b128 v[184:187], v188 offset:2048
	ds_read_b128 v[188:191], v188 offset:3072
	v_lshl_add_u64 v[196:197], v[196:197], 0, s[14:15]
	s_mov_b32 m0, s35
	v_lshl_add_u64 v[244:245], v[196:197], 0, v[162:163]
	ds_read_b128 v[192:195], v202 offset:32768
	ds_read_b128 v[204:207], v202 offset:33792
	ds_read_b128 v[208:211], v202 offset:34816
	ds_read_b128 v[216:219], v202 offset:35840
	ds_read_b128 v[220:223], v202 offset:36864
	ds_read_b128 v[224:227], v202 offset:37888
	ds_read_b128 v[228:231], v202 offset:38912
	ds_read_b128 v[232:235], v202 offset:39936
	global_load_lds_dwordx4 v[244:245], off
	s_mov_b32 m0, s36
	v_lshl_add_u64 v[196:197], v[196:197], 0, v[166:167]
	global_load_lds_dwordx4 v[196:197], off
	s_waitcnt vmcnt(8) lgkmcnt(0)
	s_setprio 1
	s_barrier
	v_mfma_f32_16x16x32_bf16 v[120:123], v[132:135], v[192:195], v[120:123]
	v_mfma_f32_16x16x32_bf16 v[124:127], v[140:143], v[192:195], v[124:127]
	v_mfma_f32_16x16x32_bf16 v[108:111], v[132:135], v[208:211], v[108:111]
	v_mfma_f32_16x16x32_bf16 v[104:107], v[140:143], v[208:211], v[104:107]
	v_mfma_f32_16x16x32_bf16 v[92:95], v[132:135], v[220:223], v[92:95]
	v_mfma_f32_16x16x32_bf16 v[88:91], v[140:143], v[220:223], v[88:91]
	v_mfma_f32_16x16x32_bf16 v[76:79], v[132:135], v[228:231], v[76:79]
	v_mfma_f32_16x16x32_bf16 v[72:75], v[140:143], v[228:231], v[72:75]
	v_mfma_f32_16x16x32_bf16 v[120:123], v[136:139], v[204:207], v[120:123]
	v_mfma_f32_16x16x32_bf16 v[124:127], v[144:147], v[204:207], v[124:127]
	v_mfma_f32_16x16x32_bf16 v[108:111], v[136:139], v[216:219], v[108:111]
	v_mfma_f32_16x16x32_bf16 v[104:107], v[144:147], v[216:219], v[104:107]
	v_mfma_f32_16x16x32_bf16 v[92:95], v[136:139], v[224:227], v[92:95]
	v_mfma_f32_16x16x32_bf16 v[88:91], v[144:147], v[224:227], v[88:91]
	v_mfma_f32_16x16x32_bf16 v[76:79], v[136:139], v[232:235], v[76:79]
	v_mfma_f32_16x16x32_bf16 v[72:75], v[144:147], v[232:235], v[72:75]
	v_mfma_f32_16x16x32_bf16 v[116:119], v[148:151], v[192:195], v[116:119]
	v_mfma_f32_16x16x32_bf16 v[112:115], v[184:187], v[192:195], v[112:115]
	v_mfma_f32_16x16x32_bf16 v[100:103], v[148:151], v[208:211], v[100:103]
	v_mfma_f32_16x16x32_bf16 v[96:99], v[184:187], v[208:211], v[96:99]
	v_mfma_f32_16x16x32_bf16 v[84:87], v[148:151], v[220:223], v[84:87]
	v_mfma_f32_16x16x32_bf16 v[80:83], v[184:187], v[220:223], v[80:83]
	v_mfma_f32_16x16x32_bf16 v[68:71], v[148:151], v[228:231], v[68:71]
	v_mfma_f32_16x16x32_bf16 v[64:67], v[184:187], v[228:231], v[64:67]
	v_mfma_f32_16x16x32_bf16 v[116:119], v[180:183], v[204:207], v[116:119]
	v_mfma_f32_16x16x32_bf16 v[112:115], v[188:191], v[204:207], v[112:115]
	v_mfma_f32_16x16x32_bf16 v[100:103], v[180:183], v[216:219], v[100:103]
	v_mfma_f32_16x16x32_bf16 v[96:99], v[188:191], v[216:219], v[96:99]
	v_mfma_f32_16x16x32_bf16 v[84:87], v[180:183], v[224:227], v[84:87]
	v_mfma_f32_16x16x32_bf16 v[80:83], v[188:191], v[224:227], v[80:83]
	v_mfma_f32_16x16x32_bf16 v[68:71], v[180:183], v[232:235], v[68:71]
	v_mfma_f32_16x16x32_bf16 v[64:67], v[188:191], v[232:235], v[64:67]
	s_setprio 0
	s_barrier
; #define PG8_STAGE(bufoff, gbase, voff) do { _Pragma("unroll") for (int _i = 0; _i < 2; ++_i) \
;         __builtin_amdgcn_global_load_lds((const unsigned*)((const char*)(gbase) + (voff)[_i]), (PG8_LAS unsigned*)(lds + (bufoff) + ldsw + _i * 8192), 16, 0, 0); } while (0)
; #define PG8_LDA(dst, b, h) do { _Pragma("unroll") for (int m = 0; m < 4; ++m) _Pragma("unroll") for (int k = 0; k < 2; ++k) dst[m][k] = *(const PG8_LAS bf16x8*)(lds + PG8_SA(b, h) + aoff + m * 2048 + k * 1024); } while (0)
; #define PG8_MMA(ai, bj, At, Bt) do { __builtin_amdgcn_s_setprio(1); _Pragma("unroll") for (int m = 0; m < 4; ++m) _Pragma("unroll") for (int n = 0; n < 2; ++n) _Pragma("unroll") for (int k = 0; k < 2; ++k) \
;         acc[ai][bj][m][n] = __builtin_amdgcn_mfma_f32_16x16x32_bf16(Bt[n][k], At[m][k], acc[ai][bj][m][n], 0, 0, 0); __builtin_amdgcn_s_setprio(0); } while (0)
; #define PG8_WAIT_V(n) asm volatile("s_waitcnt vmcnt(" #n ")" ::: "memory")
; #define PG8_WAIT_L(n) asm volatile("s_waitcnt lgkmcnt(" #n ")" ::: "memory")
; #define PG8_BAR __builtin_amdgcn_s_barrier()
; #define PG8_SCHED __builtin_amdgcn_sched_barrier(0)
; template <class Epi, class Sched, bool ALIGN_EPI = false, bool SP2 = false>
; __device__ __forceinline__ void gemm_phase(PG8_LAS unsigned char* lds, const Gemm g, const Sched& S, const Epi& E) {
;     ...
;             PG8_LDA(At, 1, 1); PG8_STAGE(PG8_SB(1, 0), b3, voffB); PG8_STAGE(PG8_SB(1, 1), b3 + hstep, voffB); PG8_STAGE(PG8_SA(1, 0), a3, voffA);
;             PG8_WAIT_V(8); PG8_WAIT_L(0); PG8_BAR; PG8_MMA(1, 0, At, B0); PG8_MMA(1, 1, At, B1); PG8_BAR; PG8_SCHED;
	s_add_i32 s13, s13, s30
	v_lshl_add_u64 v[196:197], v[214:215], 0, s[22:23]
	s_mov_b32 m0, s13
	ds_read_b128 v[192:195], v202 offset:49152
	ds_read_b128 v[204:207], v202 offset:50176
	ds_read_b128 v[208:211], v202 offset:51200
	ds_read_b128 v[216:219], v202 offset:52224
	ds_read_b128 v[220:223], v202 offset:53248
	ds_read_b128 v[224:227], v202 offset:54272
	ds_read_b128 v[228:231], v202 offset:55296
	ds_read_b128 v[232:235], v202 offset:56320
	global_load_lds_dwordx4 v[196:197], off
	v_lshl_add_u64 v[196:197], v[236:237], 0, s[22:23]
	s_add_i32 m0, s13, 0x2000
	s_add_i32 s13, s29, s30
	global_load_lds_dwordx4 v[196:197], off
	s_mov_b32 m0, s13
	v_lshl_add_u64 v[196:197], v[238:239], 0, s[22:23]
	global_load_lds_dwordx4 v[196:197], off
	s_add_i32 m0, s13, 0x2000
	v_lshl_add_u64 v[196:197], v[212:213], 0, s[22:23]
	global_load_lds_dwordx4 v[196:197], off
	s_mov_b32 m0, s37
	v_lshl_add_u64 v[196:197], v[240:241], 0, s[22:23]
	global_load_lds_dwordx4 v[196:197], off
	s_mov_b32 m0, s41
	v_lshl_add_u64 v[196:197], v[242:243], 0, s[22:23]
	global_load_lds_dwordx4 v[196:197], off
	s_waitcnt vmcnt(8) lgkmcnt(0)
	s_setprio 1
	s_barrier
	v_mfma_f32_16x16x32_bf16 v[60:63], v[132:135], v[192:195], v[60:63]
	v_mfma_f32_16x16x32_bf16 v[56:59], v[140:143], v[192:195], v[56:59]
	v_mfma_f32_16x16x32_bf16 v[44:47], v[132:135], v[208:211], v[44:47]
	v_mfma_f32_16x16x32_bf16 v[40:43], v[140:143], v[208:211], v[40:43]
	v_mfma_f32_16x16x32_bf16 v[28:31], v[132:135], v[220:223], v[28:31]
	v_mfma_f32_16x16x32_bf16 v[24:27], v[140:143], v[220:223], v[24:27]
	v_mfma_f32_16x16x32_bf16 v[12:15], v[132:135], v[228:231], v[12:15]
	v_mfma_f32_16x16x32_bf16 v[8:11], v[140:143], v[228:231], v[8:11]
	v_mfma_f32_16x16x32_bf16 v[60:63], v[136:139], v[204:207], v[60:63]
	v_mfma_f32_16x16x32_bf16 v[56:59], v[144:147], v[204:207], v[56:59]
	v_mfma_f32_16x16x32_bf16 v[44:47], v[136:139], v[216:219], v[44:47]
	v_mfma_f32_16x16x32_bf16 v[40:43], v[144:147], v[216:219], v[40:43]
	v_mfma_f32_16x16x32_bf16 v[28:31], v[136:139], v[224:227], v[28:31]
	v_mfma_f32_16x16x32_bf16 v[24:27], v[144:147], v[224:227], v[24:27]
	v_mfma_f32_16x16x32_bf16 v[12:15], v[136:139], v[232:235], v[12:15]
	v_mfma_f32_16x16x32_bf16 v[8:11], v[144:147], v[232:235], v[8:11]
	v_mfma_f32_16x16x32_bf16 v[52:55], v[148:151], v[192:195], v[52:55]
	v_mfma_f32_16x16x32_bf16 v[48:51], v[184:187], v[192:195], v[48:51]
	v_mfma_f32_16x16x32_bf16 v[36:39], v[148:151], v[208:211], v[36:39]
	v_mfma_f32_16x16x32_bf16 v[32:35], v[184:187], v[208:211], v[32:35]
	v_mfma_f32_16x16x32_bf16 v[20:23], v[148:151], v[220:223], v[20:23]
	v_mfma_f32_16x16x32_bf16 v[16:19], v[184:187], v[220:223], v[16:19]
	v_mfma_f32_16x16x32_bf16 v[4:7], v[148:151], v[228:231], v[4:7]
	v_mfma_f32_16x16x32_bf16 v[0:3], v[184:187], v[228:231], v[0:3]
	v_mfma_f32_16x16x32_bf16 v[52:55], v[180:183], v[204:207], v[52:55]
	v_mfma_f32_16x16x32_bf16 v[48:51], v[188:191], v[204:207], v[48:51]
	v_mfma_f32_16x16x32_bf16 v[36:39], v[180:183], v[216:219], v[36:39]
	v_mfma_f32_16x16x32_bf16 v[32:35], v[188:191], v[216:219], v[32:35]
	v_mfma_f32_16x16x32_bf16 v[20:23], v[180:183], v[224:227], v[20:23]
	v_mfma_f32_16x16x32_bf16 v[16:19], v[188:191], v[224:227], v[16:19]
	v_mfma_f32_16x16x32_bf16 v[4:7], v[180:183], v[232:235], v[4:7]
	v_mfma_f32_16x16x32_bf16 v[0:3], v[188:191], v[232:235], v[0:3]
	s_setprio 0
	s_barrier
	v_lshl_add_u64 v[128:129], v[128:129], 0, s[26:27]
	s_cmp_ge_i32 s12, s47
	v_lshl_add_u64 v[130:131], v[130:131], 0, s[26:27]
	s_cbranch_scc0 .LBB0_940

; #define PG8_STAGE(bufoff, gbase, voff) do { _Pragma("unroll") for (int _i = 0; _i < 2; ++_i) \
;         __builtin_amdgcn_global_load_lds((const unsigned*)((const char*)(gbase) + (voff)[_i]), (PG8_LAS unsigned*)(lds + (bufoff) + ldsw + _i * 8192), 16, 0, 0); } while (0)
; #define PG8_LDA(dst, b, h) do { _Pragma("unroll") for (int m = 0; m < 4; ++m) _Pragma("unroll") for (int k = 0; k < 2; ++k) dst[m][k] = *(const PG8_LAS bf16x8*)(lds + PG8_SA(b, h) + aoff + m * 2048 + k * 1024); } while (0)
; #define PG8_LDB(dst, b, h) do { _Pragma("unroll") for (int n = 0; n < 2; ++n) _Pragma("unroll") for (int k = 0; k < 2; ++k) dst[n][k] = *(const PG8_LAS bf16x8*)(lds + PG8_SB(b, h) + boff + n * 2048 + k * 1024); } while (0)
; #define PG8_MMA(ai, bj, At, Bt) do { __builtin_amdgcn_s_setprio(1); _Pragma("unroll") for (int m = 0; m < 4; ++m) _Pragma("unroll") for (int n = 0; n < 2; ++n) _Pragma("unroll") for (int k = 0; k < 2; ++k) \
;         acc[ai][bj][m][n] = __builtin_amdgcn_mfma_f32_16x16x32_bf16(Bt[n][k], At[m][k], acc[ai][bj][m][n], 0, 0, 0); __builtin_amdgcn_s_setprio(0); } while (0)
; #define PG8_WAIT_V(n) asm volatile("s_waitcnt vmcnt(" #n ")" ::: "memory")
; #define PG8_BAR __builtin_amdgcn_s_barrier()
; template <class Epi, class Sched, bool ALIGN_EPI = false, bool SP2 = false>
; __device__ __forceinline__ void gemm_phase(PG8_LAS unsigned char* lds, const Gemm g, const Sched& S, const Epi& E) {
;     ...
;         for (int t = 0; t < nt; t += 2) {
;             const bool last = (t == nt - 2);
;             const char* a1 = cA + (size_t)(t + 1) * kstep;
;             const char* a2 = last ? nA : cA + (size_t)(t + 2) * kstep; const char* b2 = last ? nB : cB + (size_t)(t + 2) * kstep;
;             const char* a3 = a2 + kstep; const char* b3 = b2 + kstep;
;             if (last && has_next) S.a_ready(nxt);
;             if constexpr (SP2) {
;             PG8_LDB(B0, 0, 0); PG8_LDB(B1, 0, 1); PG8_SCHED; PG8_LDA(At, 0, 0); PG8_STAGE(PG8_SA(1, 1), a1 + hstep, voffA);
;             PG8_WAIT_V(8); PG8_WAIT_L(0); PG8_BAR; PG8_MMA(0, 0, At, B0); PG8_MMA(0, 1, At, B1); PG8_BAR; PG8_SCHED;
;             PG8_LDA(At, 0, 1); PG8_STAGE(PG8_SB(0, 0), b2, voffB); PG8_STAGE(PG8_SB(0, 1), b2 + hstep, voffB); PG8_STAGE(PG8_SA(0, 0), a2, voffA);
;             PG8_WAIT_V(8); PG8_WAIT_L(0); PG8_BAR; PG8_MMA(1, 0, At, B0); PG8_MMA(1, 1, At, B1); PG8_BAR; PG8_SCHED;
.LBB0_1021:
	v_add_u32_e32 v166, s55, v169
	v_add_u32_e32 v168, s56, v169
	ds_read_b128 v[162:165], v166
	ds_read_b128 v[182:185], v166 offset:1024
	ds_read_b128 v[186:189], v166 offset:2048
	ds_read_b128 v[190:193], v166 offset:3072
	ds_read_b128 v[194:197], v168
	ds_read_b128 v[198:201], v168 offset:1024
	ds_read_b128 v[202:205], v168 offset:2048
	ds_read_b128 v[206:209], v168 offset:3072
	s_cmp_eq_u32 s54, s10
	v_lshl_add_u64 v[172:173], v[160:161], 0, s[22:23]
	s_cselect_b64 vcc, -1, 0
	s_add_i32 s10, s10, 2
	v_cndmask_b32_e32 v173, v173, v153, vcc
	v_cndmask_b32_e32 v172, v172, v152, vcc
	v_cndmask_b32_e32 v215, v159, v155, vcc
	v_cndmask_b32_e32 v214, v158, v154, vcc
	s_mov_b32 m0, s57
	v_lshl_add_u64 v[244:245], v[160:161], 0, v[148:149]
	ds_read_b128 v[210:213], v179
	ds_read_b128 v[216:219], v179 offset:1024
	ds_read_b128 v[220:223], v179 offset:2048
	ds_read_b128 v[224:227], v179 offset:3072
	ds_read_b128 v[228:231], v179 offset:4096
	ds_read_b128 v[232:235], v179 offset:5120
	ds_read_b128 v[236:239], v179 offset:6144
	ds_read_b128 v[240:243], v179 offset:7168
	global_load_lds_dwordx4 v[244:245], off
	s_mov_b32 m0, s58
	v_lshl_add_u64 v[244:245], v[160:161], 0, v[146:147]
	global_load_lds_dwordx4 v[244:245], off
	s_waitcnt vmcnt(8) lgkmcnt(0)
	s_setprio 1
	s_barrier
	v_mfma_f32_16x16x32_bf16 v[124:127], v[162:165], v[210:213], v[124:127]
	v_mfma_f32_16x16x32_bf16 v[116:119], v[186:189], v[210:213], v[116:119]
	v_mfma_f32_16x16x32_bf16 v[108:111], v[162:165], v[220:223], v[108:111]
	v_mfma_f32_16x16x32_bf16 v[100:103], v[186:189], v[220:223], v[100:103]
	v_mfma_f32_16x16x32_bf16 v[92:95], v[162:165], v[228:231], v[92:95]
	v_mfma_f32_16x16x32_bf16 v[84:87], v[186:189], v[228:231], v[84:87]
	v_mfma_f32_16x16x32_bf16 v[76:79], v[162:165], v[236:239], v[76:79]
	v_mfma_f32_16x16x32_bf16 v[68:71], v[186:189], v[236:239], v[68:71]
	v_mfma_f32_16x16x32_bf16 v[124:127], v[182:185], v[216:219], v[124:127]
	v_mfma_f32_16x16x32_bf16 v[116:119], v[190:193], v[216:219], v[116:119]
	v_mfma_f32_16x16x32_bf16 v[108:111], v[182:185], v[224:227], v[108:111]
	v_mfma_f32_16x16x32_bf16 v[100:103], v[190:193], v[224:227], v[100:103]
	v_mfma_f32_16x16x32_bf16 v[92:95], v[182:185], v[232:235], v[92:95]
	v_mfma_f32_16x16x32_bf16 v[84:87], v[190:193], v[232:235], v[84:87]
	v_mfma_f32_16x16x32_bf16 v[76:79], v[182:185], v[240:243], v[76:79]
	v_mfma_f32_16x16x32_bf16 v[68:71], v[190:193], v[240:243], v[68:71]
	v_mfma_f32_16x16x32_bf16 v[120:123], v[194:197], v[210:213], v[120:123]
	v_mfma_f32_16x16x32_bf16 v[112:115], v[202:205], v[210:213], v[112:115]
	v_mfma_f32_16x16x32_bf16 v[104:107], v[194:197], v[220:223], v[104:107]
	v_mfma_f32_16x16x32_bf16 v[96:99], v[202:205], v[220:223], v[96:99]
	v_mfma_f32_16x16x32_bf16 v[88:91], v[194:197], v[228:231], v[88:91]
	v_mfma_f32_16x16x32_bf16 v[80:83], v[202:205], v[228:231], v[80:83]
	v_mfma_f32_16x16x32_bf16 v[72:75], v[194:197], v[236:239], v[72:75]
	v_mfma_f32_16x16x32_bf16 v[64:67], v[202:205], v[236:239], v[64:67]
	v_mfma_f32_16x16x32_bf16 v[120:123], v[198:201], v[216:219], v[120:123]
	v_mfma_f32_16x16x32_bf16 v[112:115], v[206:209], v[216:219], v[112:115]
	v_mfma_f32_16x16x32_bf16 v[104:107], v[198:201], v[224:227], v[104:107]
	v_mfma_f32_16x16x32_bf16 v[96:99], v[206:209], v[224:227], v[96:99]
	v_mfma_f32_16x16x32_bf16 v[88:91], v[198:201], v[232:235], v[88:91]
	v_mfma_f32_16x16x32_bf16 v[80:83], v[206:209], v[232:235], v[80:83]
	v_mfma_f32_16x16x32_bf16 v[72:75], v[198:201], v[240:243], v[72:75]
	v_mfma_f32_16x16x32_bf16 v[64:67], v[206:209], v[240:243], v[64:67]
	s_setprio 0
	s_barrier
	s_mov_b32 m0, s61
	v_lshl_add_u64 v[244:245], v[214:215], 0, v[138:139]
	ds_read_b128 v[210:213], v179 offset:16384
	ds_read_b128 v[216:219], v179 offset:17408
	ds_read_b128 v[220:223], v179 offset:18432
	ds_read_b128 v[224:227], v179 offset:19456
	ds_read_b128 v[228:231], v179 offset:20480
	ds_read_b128 v[232:235], v179 offset:21504
	ds_read_b128 v[236:239], v179 offset:22528
	ds_read_b128 v[240:243], v179 offset:23552
	global_load_lds_dwordx4 v[244:245], off
	v_lshl_add_u64 v[246:247], v[214:215], 0, v[134:135]
	s_mov_b32 m0, s62
	v_lshl_add_u64 v[214:215], v[214:215], 0, s[14:15]
	global_load_lds_dwordx4 v[246:247], off
	v_lshl_add_u64 v[248:249], v[214:215], 0, v[138:139]
	s_mov_b32 m0, s63
	v_lshl_add_u64 v[214:215], v[214:215], 0, v[134:135]
	global_load_lds_dwordx4 v[248:249], off
	s_add_i32 m0, s63, 0x2000
	v_lshl_add_u64 v[250:251], v[172:173], 0, v[140:141]
	global_load_lds_dwordx4 v[214:215], off
	s_mov_b32 m0, s46
	v_lshl_add_u64 v[252:253], v[172:173], 0, v[136:137]
	global_load_lds_dwordx4 v[250:251], off
	s_mov_b32 m0, s47
	s_nop 0
	global_load_lds_dwordx4 v[252:253], off
	s_waitcnt vmcnt(8) lgkmcnt(0)
	s_setprio 1
	s_barrier
; #define PG8_STAGE(bufoff, gbase, voff) do { _Pragma("unroll") for (int _i = 0; _i < 2; ++_i) \
;         __builtin_amdgcn_global_load_lds((const unsigned*)((const char*)(gbase) + (voff)[_i]), (PG8_LAS unsigned*)(lds + (bufoff) + ldsw + _i * 8192), 16, 0, 0); } while (0)
; #define PG8_LDA(dst, b, h) do { _Pragma("unroll") for (int m = 0; m < 4; ++m) _Pragma("unroll") for (int k = 0; k < 2; ++k) dst[m][k] = *(const PG8_LAS bf16x8*)(lds + PG8_SA(b, h) + aoff + m * 2048 + k * 1024); } while (0)
; #define PG8_LDB(dst, b, h) do { _Pragma("unroll") for (int n = 0; n < 2; ++n) _Pragma("unroll") for (int k = 0; k < 2; ++k) dst[n][k] = *(const PG8_LAS bf16x8*)(lds + PG8_SB(b, h) + boff + n * 2048 + k * 1024); } while (0)
; #define PG8_MMA(ai, bj, At, Bt) do { __builtin_amdgcn_s_setprio(1); _Pragma("unroll") for (int m = 0; m < 4; ++m) _Pragma("unroll") for (int n = 0; n < 2; ++n) _Pragma("unroll") for (int k = 0; k < 2; ++k) \
;         acc[ai][bj][m][n] = __builtin_amdgcn_mfma_f32_16x16x32_bf16(Bt[n][k], At[m][k], acc[ai][bj][m][n], 0, 0, 0); __builtin_amdgcn_s_setprio(0); } while (0)
; #define PG8_WAIT_V(n) asm volatile("s_waitcnt vmcnt(" #n ")" ::: "memory")
; #define PG8_WAIT_L(n) asm volatile("s_waitcnt lgkmcnt(" #n ")" ::: "memory")
; #define PG8_BAR __builtin_amdgcn_s_barrier()
; #define PG8_SCHED __builtin_amdgcn_sched_barrier(0)
; template <class Epi, class Sched, bool ALIGN_EPI = false, bool SP2 = false>
; __device__ __forceinline__ void gemm_phase(PG8_LAS unsigned char* lds, const Gemm g, const Sched& S, const Epi& E) {
;     ...
;             PG8_WAIT_V(8); PG8_WAIT_L(0); PG8_BAR; PG8_MMA(1, 0, At, B0); PG8_MMA(1, 1, At, B1); PG8_BAR; PG8_SCHED;
;             PG8_LDB(B0, 1, 0); PG8_LDB(B1, 1, 1); PG8_SCHED; PG8_LDA(At, 1, 0); PG8_STAGE(PG8_SA(0, 1), a2 + hstep, voffA);
;             PG8_WAIT_V(8); PG8_WAIT_L(0); PG8_BAR; PG8_MMA(0, 0, At, B0); PG8_MMA(0, 1, At, B1); PG8_BAR; PG8_SCHED;
	v_mfma_f32_16x16x32_bf16 v[60:63], v[162:165], v[210:213], v[60:63]
	v_mfma_f32_16x16x32_bf16 v[52:55], v[186:189], v[210:213], v[52:55]
	v_mfma_f32_16x16x32_bf16 v[44:47], v[162:165], v[220:223], v[44:47]
	v_mfma_f32_16x16x32_bf16 v[36:39], v[186:189], v[220:223], v[36:39]
	v_mfma_f32_16x16x32_bf16 v[28:31], v[162:165], v[228:231], v[28:31]
	v_mfma_f32_16x16x32_bf16 v[20:23], v[186:189], v[228:231], v[20:23]
	v_mfma_f32_16x16x32_bf16 v[12:15], v[162:165], v[236:239], v[12:15]
	v_mfma_f32_16x16x32_bf16 v[4:7], v[186:189], v[236:239], v[4:7]
	v_mfma_f32_16x16x32_bf16 v[60:63], v[182:185], v[216:219], v[60:63]
	v_mfma_f32_16x16x32_bf16 v[52:55], v[190:193], v[216:219], v[52:55]
	v_mfma_f32_16x16x32_bf16 v[44:47], v[182:185], v[224:227], v[44:47]
	v_mfma_f32_16x16x32_bf16 v[36:39], v[190:193], v[224:227], v[36:39]
	v_mfma_f32_16x16x32_bf16 v[28:31], v[182:185], v[232:235], v[28:31]
	v_mfma_f32_16x16x32_bf16 v[20:23], v[190:193], v[232:235], v[20:23]
	v_mfma_f32_16x16x32_bf16 v[12:15], v[182:185], v[240:243], v[12:15]
	v_mfma_f32_16x16x32_bf16 v[4:7], v[190:193], v[240:243], v[4:7]
	v_mfma_f32_16x16x32_bf16 v[56:59], v[194:197], v[210:213], v[56:59]
	v_mfma_f32_16x16x32_bf16 v[48:51], v[202:205], v[210:213], v[48:51]
	v_mfma_f32_16x16x32_bf16 v[40:43], v[194:197], v[220:223], v[40:43]
	v_mfma_f32_16x16x32_bf16 v[32:35], v[202:205], v[220:223], v[32:35]
	v_mfma_f32_16x16x32_bf16 v[24:27], v[194:197], v[228:231], v[24:27]
	v_mfma_f32_16x16x32_bf16 v[16:19], v[202:205], v[228:231], v[16:19]
	v_mfma_f32_16x16x32_bf16 v[8:11], v[194:197], v[236:239], v[8:11]
	v_mfma_f32_16x16x32_bf16 v[0:3], v[202:205], v[236:239], v[0:3]
	v_mfma_f32_16x16x32_bf16 v[56:59], v[198:201], v[216:219], v[56:59]
	v_mfma_f32_16x16x32_bf16 v[48:51], v[206:209], v[216:219], v[48:51]
	v_mfma_f32_16x16x32_bf16 v[40:43], v[198:201], v[224:227], v[40:43]
	v_mfma_f32_16x16x32_bf16 v[32:35], v[206:209], v[224:227], v[32:35]
	v_mfma_f32_16x16x32_bf16 v[24:27], v[198:201], v[232:235], v[24:27]
	v_mfma_f32_16x16x32_bf16 v[16:19], v[206:209], v[232:235], v[16:19]
	v_mfma_f32_16x16x32_bf16 v[8:11], v[198:201], v[240:243], v[8:11]
	v_mfma_f32_16x16x32_bf16 v[0:3], v[206:209], v[240:243], v[0:3]
	s_setprio 0
	s_barrier
	s_add_i32 s11, 0, 0x18000
	v_add_u32_e32 v166, s11, v169
	s_add_i32 s13, 0, 0x1c000
	ds_read_b128 v[162:165], v166
	ds_read_b128 v[182:185], v166 offset:1024
	ds_read_b128 v[186:189], v166 offset:2048
	ds_read_b128 v[190:193], v166 offset:3072
	v_add_u32_e32 v166, s13, v169
	ds_read_b128 v[194:197], v166
	ds_read_b128 v[198:201], v166 offset:1024
	ds_read_b128 v[202:205], v166 offset:2048
	ds_read_b128 v[206:209], v166 offset:3072
	v_lshl_add_u64 v[172:173], v[172:173], 0, s[14:15]
	s_mov_b32 m0, s48
	v_lshl_add_u64 v[170:171], v[172:173], 0, v[140:141]
	ds_read_b128 v[210:213], v179 offset:32768
	ds_read_b128 v[216:219], v179 offset:33792
	ds_read_b128 v[220:223], v179 offset:34816
	ds_read_b128 v[224:227], v179 offset:35840
	ds_read_b128 v[228:231], v179 offset:36864
	ds_read_b128 v[232:235], v179 offset:37888
	ds_read_b128 v[236:239], v179 offset:38912
	ds_read_b128 v[240:243], v179 offset:39936
	global_load_lds_dwordx4 v[170:171], off
	s_mov_b32 m0, s49
	v_lshl_add_u64 v[170:171], v[172:173], 0, v[136:137]
	global_load_lds_dwordx4 v[170:171], off
	s_waitcnt vmcnt(8) lgkmcnt(0)
	s_setprio 1
	s_barrier
	v_mfma_f32_16x16x32_bf16 v[124:127], v[162:165], v[210:213], v[124:127]
	v_mfma_f32_16x16x32_bf16 v[116:119], v[186:189], v[210:213], v[116:119]
	v_mfma_f32_16x16x32_bf16 v[108:111], v[162:165], v[220:223], v[108:111]
	v_mfma_f32_16x16x32_bf16 v[100:103], v[186:189], v[220:223], v[100:103]
	v_mfma_f32_16x16x32_bf16 v[92:95], v[162:165], v[228:231], v[92:95]
	v_mfma_f32_16x16x32_bf16 v[84:87], v[186:189], v[228:231], v[84:87]
	v_mfma_f32_16x16x32_bf16 v[76:79], v[162:165], v[236:239], v[76:79]
	v_mfma_f32_16x16x32_bf16 v[68:71], v[186:189], v[236:239], v[68:71]
	v_mfma_f32_16x16x32_bf16 v[124:127], v[182:185], v[216:219], v[124:127]
	v_mfma_f32_16x16x32_bf16 v[116:119], v[190:193], v[216:219], v[116:119]
	v_mfma_f32_16x16x32_bf16 v[108:111], v[182:185], v[224:227], v[108:111]
	v_mfma_f32_16x16x32_bf16 v[100:103], v[190:193], v[224:227], v[100:103]
	v_mfma_f32_16x16x32_bf16 v[92:95], v[182:185], v[232:235], v[92:95]
	v_mfma_f32_16x16x32_bf16 v[84:87], v[190:193], v[232:235], v[84:87]
	v_mfma_f32_16x16x32_bf16 v[76:79], v[182:185], v[240:243], v[76:79]
	v_mfma_f32_16x16x32_bf16 v[68:71], v[190:193], v[240:243], v[68:71]
	v_mfma_f32_16x16x32_bf16 v[120:123], v[194:197], v[210:213], v[120:123]
	v_mfma_f32_16x16x32_bf16 v[112:115], v[202:205], v[210:213], v[112:115]
	v_mfma_f32_16x16x32_bf16 v[104:107], v[194:197], v[220:223], v[104:107]
	v_mfma_f32_16x16x32_bf16 v[96:99], v[202:205], v[220:223], v[96:99]
	v_mfma_f32_16x16x32_bf16 v[88:91], v[194:197], v[228:231], v[88:91]
	v_mfma_f32_16x16x32_bf16 v[80:83], v[202:205], v[228:231], v[80:83]
	v_mfma_f32_16x16x32_bf16 v[72:75], v[194:197], v[236:239], v[72:75]
	v_mfma_f32_16x16x32_bf16 v[64:67], v[202:205], v[236:239], v[64:67]
	v_mfma_f32_16x16x32_bf16 v[120:123], v[198:201], v[216:219], v[120:123]
	v_mfma_f32_16x16x32_bf16 v[112:115], v[206:209], v[216:219], v[112:115]
	v_mfma_f32_16x16x32_bf16 v[104:107], v[198:201], v[224:227], v[104:107]
	v_mfma_f32_16x16x32_bf16 v[96:99], v[206:209], v[224:227], v[96:99]
	v_mfma_f32_16x16x32_bf16 v[88:91], v[198:201], v[232:235], v[88:91]
	v_mfma_f32_16x16x32_bf16 v[80:83], v[206:209], v[232:235], v[80:83]
	v_mfma_f32_16x16x32_bf16 v[72:75], v[198:201], v[240:243], v[72:75]
	v_mfma_f32_16x16x32_bf16 v[64:67], v[206:209], v[240:243], v[64:67]
	s_setprio 0
	s_barrier
; #define PG8_STAGE(bufoff, gbase, voff) do { _Pragma("unroll") for (int _i = 0; _i < 2; ++_i) \
;         __builtin_amdgcn_global_load_lds((const unsigned*)((const char*)(gbase) + (voff)[_i]), (PG8_LAS unsigned*)(lds + (bufoff) + ldsw + _i * 8192), 16, 0, 0); } while (0)
; #define PG8_LDA(dst, b, h) do { _Pragma("unroll") for (int m = 0; m < 4; ++m) _Pragma("unroll") for (int k = 0; k < 2; ++k) dst[m][k] = *(const PG8_LAS bf16x8*)(lds + PG8_SA(b, h) + aoff + m * 2048 + k * 1024); } while (0)
; #define PG8_MMA(ai, bj, At, Bt) do { __builtin_amdgcn_s_setprio(1); _Pragma("unroll") for (int m = 0; m < 4; ++m) _Pragma("unroll") for (int n = 0; n < 2; ++n) _Pragma("unroll") for (int k = 0; k < 2; ++k) \
;         acc[ai][bj][m][n] = __builtin_amdgcn_mfma_f32_16x16x32_bf16(Bt[n][k], At[m][k], acc[ai][bj][m][n], 0, 0, 0); __builtin_amdgcn_s_setprio(0); } while (0)
; #define PG8_WAIT_V(n) asm volatile("s_waitcnt vmcnt(" #n ")" ::: "memory")
; #define PG8_WAIT_L(n) asm volatile("s_waitcnt lgkmcnt(" #n ")" ::: "memory")
; #define PG8_BAR __builtin_amdgcn_s_barrier()
; #define PG8_SCHED __builtin_amdgcn_sched_barrier(0)
; template <class Epi, class Sched, bool ALIGN_EPI = false, bool SP2 = false>
; __device__ __forceinline__ void gemm_phase(PG8_LAS unsigned char* lds, const Gemm g, const Sched& S, const Epi& E) {
;     ...
;             PG8_LDA(At, 1, 1); PG8_STAGE(PG8_SB(1, 0), b3, voffB); PG8_STAGE(PG8_SB(1, 1), b3 + hstep, voffB); PG8_STAGE(PG8_SA(1, 0), a3, voffA);
;             PG8_WAIT_V(8); PG8_WAIT_L(0); PG8_BAR; PG8_MMA(1, 0, At, B0); PG8_MMA(1, 1, At, B1); PG8_BAR; PG8_SCHED;
	s_add_i32 s11, s11, s29
	v_lshl_add_u64 v[170:171], v[244:245], 0, s[22:23]
	s_mov_b32 m0, s11
	ds_read_b128 v[210:213], v179 offset:49152
	ds_read_b128 v[216:219], v179 offset:50176
	ds_read_b128 v[220:223], v179 offset:51200
	ds_read_b128 v[224:227], v179 offset:52224
	ds_read_b128 v[228:231], v179 offset:53248
	ds_read_b128 v[232:235], v179 offset:54272
	ds_read_b128 v[236:239], v179 offset:55296
	ds_read_b128 v[240:243], v179 offset:56320
	global_load_lds_dwordx4 v[170:171], off
	v_lshl_add_u64 v[170:171], v[246:247], 0, s[22:23]
	s_add_i32 m0, s11, 0x2000
	s_add_i32 s11, s13, s29
	global_load_lds_dwordx4 v[170:171], off
	s_mov_b32 m0, s11
	v_lshl_add_u64 v[170:171], v[248:249], 0, s[22:23]
	global_load_lds_dwordx4 v[170:171], off
	s_add_i32 m0, s11, 0x2000
	v_lshl_add_u64 v[170:171], v[214:215], 0, s[22:23]
	global_load_lds_dwordx4 v[170:171], off
	s_mov_b32 m0, s50
	v_lshl_add_u64 v[170:171], v[250:251], 0, s[22:23]
	global_load_lds_dwordx4 v[170:171], off
	s_mov_b32 m0, s51
	v_lshl_add_u64 v[170:171], v[252:253], 0, s[22:23]
	global_load_lds_dwordx4 v[170:171], off
	s_waitcnt vmcnt(8) lgkmcnt(0)
	s_setprio 1
	s_barrier
	v_mfma_f32_16x16x32_bf16 v[60:63], v[162:165], v[210:213], v[60:63]
	v_mfma_f32_16x16x32_bf16 v[52:55], v[186:189], v[210:213], v[52:55]
	v_mfma_f32_16x16x32_bf16 v[44:47], v[162:165], v[220:223], v[44:47]
	v_mfma_f32_16x16x32_bf16 v[36:39], v[186:189], v[220:223], v[36:39]
	v_mfma_f32_16x16x32_bf16 v[28:31], v[162:165], v[228:231], v[28:31]
	v_mfma_f32_16x16x32_bf16 v[20:23], v[186:189], v[228:231], v[20:23]
	v_mfma_f32_16x16x32_bf16 v[12:15], v[162:165], v[236:239], v[12:15]
	v_mfma_f32_16x16x32_bf16 v[4:7], v[186:189], v[236:239], v[4:7]
	v_mfma_f32_16x16x32_bf16 v[60:63], v[182:185], v[216:219], v[60:63]
	v_mfma_f32_16x16x32_bf16 v[52:55], v[190:193], v[216:219], v[52:55]
	v_mfma_f32_16x16x32_bf16 v[44:47], v[182:185], v[224:227], v[44:47]
	v_mfma_f32_16x16x32_bf16 v[36:39], v[190:193], v[224:227], v[36:39]
	v_mfma_f32_16x16x32_bf16 v[28:31], v[182:185], v[232:235], v[28:31]
	v_mfma_f32_16x16x32_bf16 v[20:23], v[190:193], v[232:235], v[20:23]
	v_mfma_f32_16x16x32_bf16 v[12:15], v[182:185], v[240:243], v[12:15]
	v_mfma_f32_16x16x32_bf16 v[4:7], v[190:193], v[240:243], v[4:7]
	v_mfma_f32_16x16x32_bf16 v[56:59], v[194:197], v[210:213], v[56:59]
	v_mfma_f32_16x16x32_bf16 v[48:51], v[202:205], v[210:213], v[48:51]
	v_mfma_f32_16x16x32_bf16 v[40:43], v[194:197], v[220:223], v[40:43]
	v_mfma_f32_16x16x32_bf16 v[32:35], v[202:205], v[220:223], v[32:35]
	v_mfma_f32_16x16x32_bf16 v[24:27], v[194:197], v[228:231], v[24:27]
	v_mfma_f32_16x16x32_bf16 v[16:19], v[202:205], v[228:231], v[16:19]
	v_mfma_f32_16x16x32_bf16 v[8:11], v[194:197], v[236:239], v[8:11]
	v_mfma_f32_16x16x32_bf16 v[0:3], v[202:205], v[236:239], v[0:3]
	v_mfma_f32_16x16x32_bf16 v[56:59], v[198:201], v[216:219], v[56:59]
	v_mfma_f32_16x16x32_bf16 v[48:51], v[206:209], v[216:219], v[48:51]
	v_mfma_f32_16x16x32_bf16 v[40:43], v[198:201], v[224:227], v[40:43]
	v_mfma_f32_16x16x32_bf16 v[32:35], v[206:209], v[224:227], v[32:35]
	v_mfma_f32_16x16x32_bf16 v[24:27], v[198:201], v[232:235], v[24:27]
	v_mfma_f32_16x16x32_bf16 v[16:19], v[206:209], v[232:235], v[16:19]
	v_mfma_f32_16x16x32_bf16 v[8:11], v[198:201], v[240:243], v[8:11]
	v_mfma_f32_16x16x32_bf16 v[0:3], v[206:209], v[240:243], v[0:3]
	s_setprio 0
	s_barrier
	v_lshl_add_u64 v[158:159], v[158:159], 0, s[26:27]
	s_cmp_ge_i32 s10, s52
	v_lshl_add_u64 v[160:161], v[160:161], 0, s[26:27]
	s_cbranch_scc0 .LBB0_1021

; #define PG8_STAGE(bufoff, gbase, voff) do { _Pragma("unroll") for (int _i = 0; _i < 2; ++_i) \
;         __builtin_amdgcn_global_load_lds((const unsigned*)((const char*)(gbase) + (voff)[_i]), (PG8_LAS unsigned*)(lds + (bufoff) + ldsw + _i * 8192), 16, 0, 0); } while (0)
; #define PG8_LDA(dst, b, h) do { _Pragma("unroll") for (int m = 0; m < 4; ++m) _Pragma("unroll") for (int k = 0; k < 2; ++k) dst[m][k] = *(const PG8_LAS bf16x8*)(lds + PG8_SA(b, h) + aoff + m * 2048 + k * 1024); } while (0)
; #define PG8_LDB(dst, b, h) do { _Pragma("unroll") for (int n = 0; n < 2; ++n) _Pragma("unroll") for (int k = 0; k < 2; ++k) dst[n][k] = *(const PG8_LAS bf16x8*)(lds + PG8_SB(b, h) + boff + n * 2048 + k * 1024); } while (0)
; #define PG8_MMA(ai, bj, At, Bt) do { __builtin_amdgcn_s_setprio(1); _Pragma("unroll") for (int m = 0; m < 4; ++m) _Pragma("unroll") for (int n = 0; n < 2; ++n) _Pragma("unroll") for (int k = 0; k < 2; ++k) \
;         acc[ai][bj][m][n] = __builtin_amdgcn_mfma_f32_16x16x32_bf16(Bt[n][k], At[m][k], acc[ai][bj][m][n], 0, 0, 0); __builtin_amdgcn_s_setprio(0); } while (0)
; #define PG8_WAIT_V(n) asm volatile("s_waitcnt vmcnt(" #n ")" ::: "memory")
; #define PG8_BAR __builtin_amdgcn_s_barrier()
; template <class Epi, class Sched, bool ALIGN_EPI = false, bool SP2 = false>
; __device__ __forceinline__ void gemm_phase(PG8_LAS unsigned char* lds, const Gemm g, const Sched& S, const Epi& E) {
;     ...
;         for (int t = 0; t < nt; t += 2) {
;             const bool last = (t == nt - 2);
;             const char* a1 = cA + (size_t)(t + 1) * kstep;
;             const char* a2 = last ? nA : cA + (size_t)(t + 2) * kstep; const char* b2 = last ? nB : cB + (size_t)(t + 2) * kstep;
;             const char* a3 = a2 + kstep; const char* b3 = b2 + kstep;
;             if (last && has_next) S.a_ready(nxt);
;             if constexpr (SP2) {
;             PG8_LDB(B0, 0, 0); PG8_LDB(B1, 0, 1); PG8_SCHED; PG8_LDA(At, 0, 0); PG8_STAGE(PG8_SA(1, 1), a1 + hstep, voffA);
;             PG8_WAIT_V(8); PG8_WAIT_L(0); PG8_BAR; PG8_MMA(0, 0, At, B0); PG8_MMA(0, 1, At, B1); PG8_BAR; PG8_SCHED;
;             PG8_LDA(At, 0, 1); PG8_STAGE(PG8_SB(0, 0), b2, voffB); PG8_STAGE(PG8_SB(0, 1), b2 + hstep, voffB); PG8_STAGE(PG8_SA(0, 0), a2, voffA);
;             PG8_WAIT_V(8); PG8_WAIT_L(0); PG8_BAR; PG8_MMA(1, 0, At, B0); PG8_MMA(1, 1, At, B1); PG8_BAR; PG8_SCHED;
.LBB0_1169:
	v_add_u32_e32 v192, s52, v161
	ds_read_b128 v[164:167], v162
	ds_read_b128 v[168:171], v162 offset:1024
	ds_read_b128 v[172:175], v162 offset:2048
	ds_read_b128 v[176:179], v162 offset:3072
	ds_read_b128 v[180:183], v192
	ds_read_b128 v[184:187], v192 offset:1024
	ds_read_b128 v[188:191], v192 offset:2048
	ds_read_b128 v[192:195], v192 offset:3072
	s_cmp_eq_u32 s51, s10
	v_lshl_add_u64 v[196:197], v[158:159], 0, s[24:25]
	s_cselect_b64 vcc, -1, 0
	s_add_i32 s10, s10, 2
	v_cndmask_b32_e32 v213, v197, v151, vcc
	v_cndmask_b32_e32 v212, v196, v150, vcc
	v_cndmask_b32_e32 v215, v155, v153, vcc
	v_cndmask_b32_e32 v214, v154, v152, vcc
	s_mov_b32 m0, s54
	v_lshl_add_u64 v[232:233], v[158:159], 0, v[146:147]
	ds_read_b128 v[196:199], v163
	ds_read_b128 v[200:203], v163 offset:1024
	ds_read_b128 v[204:207], v163 offset:2048
	ds_read_b128 v[208:211], v163 offset:3072
	ds_read_b128 v[216:219], v163 offset:4096
	ds_read_b128 v[220:223], v163 offset:5120
	ds_read_b128 v[224:227], v163 offset:6144
	ds_read_b128 v[228:231], v163 offset:7168
	global_load_lds_dwordx4 v[232:233], off
	s_mov_b32 m0, s55
	v_lshl_add_u64 v[232:233], v[158:159], 0, v[144:145]
	global_load_lds_dwordx4 v[232:233], off
	s_waitcnt vmcnt(8) lgkmcnt(0)
	s_setprio 1
	s_barrier
	v_mfma_f32_16x16x32_bf16 v[124:127], v[164:167], v[196:199], v[124:127]
	v_mfma_f32_16x16x32_bf16 v[120:123], v[172:175], v[196:199], v[120:123]
	v_mfma_f32_16x16x32_bf16 v[108:111], v[164:167], v[204:207], v[108:111]
	v_mfma_f32_16x16x32_bf16 v[104:107], v[172:175], v[204:207], v[104:107]
	v_mfma_f32_16x16x32_bf16 v[92:95], v[164:167], v[216:219], v[92:95]
	v_mfma_f32_16x16x32_bf16 v[88:91], v[172:175], v[216:219], v[88:91]
	v_mfma_f32_16x16x32_bf16 v[76:79], v[164:167], v[224:227], v[76:79]
	v_mfma_f32_16x16x32_bf16 v[72:75], v[172:175], v[224:227], v[72:75]
	v_mfma_f32_16x16x32_bf16 v[124:127], v[168:171], v[200:203], v[124:127]
	v_mfma_f32_16x16x32_bf16 v[120:123], v[176:179], v[200:203], v[120:123]
	v_mfma_f32_16x16x32_bf16 v[108:111], v[168:171], v[208:211], v[108:111]
	v_mfma_f32_16x16x32_bf16 v[104:107], v[176:179], v[208:211], v[104:107]
	v_mfma_f32_16x16x32_bf16 v[92:95], v[168:171], v[220:223], v[92:95]
	v_mfma_f32_16x16x32_bf16 v[88:91], v[176:179], v[220:223], v[88:91]
	v_mfma_f32_16x16x32_bf16 v[76:79], v[168:171], v[228:231], v[76:79]
	v_mfma_f32_16x16x32_bf16 v[72:75], v[176:179], v[228:231], v[72:75]
	v_mfma_f32_16x16x32_bf16 v[116:119], v[180:183], v[196:199], v[116:119]
	v_mfma_f32_16x16x32_bf16 v[112:115], v[188:191], v[196:199], v[112:115]
	v_mfma_f32_16x16x32_bf16 v[100:103], v[180:183], v[204:207], v[100:103]
	v_mfma_f32_16x16x32_bf16 v[96:99], v[188:191], v[204:207], v[96:99]
	v_mfma_f32_16x16x32_bf16 v[84:87], v[180:183], v[216:219], v[84:87]
	v_mfma_f32_16x16x32_bf16 v[80:83], v[188:191], v[216:219], v[80:83]
	v_mfma_f32_16x16x32_bf16 v[68:71], v[180:183], v[224:227], v[68:71]
	v_mfma_f32_16x16x32_bf16 v[64:67], v[188:191], v[224:227], v[64:67]
	v_mfma_f32_16x16x32_bf16 v[116:119], v[184:187], v[200:203], v[116:119]
	v_mfma_f32_16x16x32_bf16 v[112:115], v[192:195], v[200:203], v[112:115]
	v_mfma_f32_16x16x32_bf16 v[100:103], v[184:187], v[208:211], v[100:103]
	v_mfma_f32_16x16x32_bf16 v[96:99], v[192:195], v[208:211], v[96:99]
	v_mfma_f32_16x16x32_bf16 v[84:87], v[184:187], v[220:223], v[84:87]
	v_mfma_f32_16x16x32_bf16 v[80:83], v[192:195], v[220:223], v[80:83]
	v_mfma_f32_16x16x32_bf16 v[68:71], v[184:187], v[228:231], v[68:71]
	v_mfma_f32_16x16x32_bf16 v[64:67], v[192:195], v[228:231], v[64:67]
	s_setprio 0
	s_barrier
	s_mov_b32 m0, s56
	v_lshl_add_u64 v[232:233], v[214:215], 0, v[138:139]
	ds_read_b128 v[196:199], v163 offset:16384
	ds_read_b128 v[200:203], v163 offset:17408
	ds_read_b128 v[204:207], v163 offset:18432
	ds_read_b128 v[208:211], v163 offset:19456
	ds_read_b128 v[216:219], v163 offset:20480
	ds_read_b128 v[220:223], v163 offset:21504
	ds_read_b128 v[224:227], v163 offset:22528
	ds_read_b128 v[228:231], v163 offset:23552
	global_load_lds_dwordx4 v[232:233], off
	v_lshl_add_u64 v[234:235], v[214:215], 0, v[134:135]
	s_mov_b32 m0, s57
	v_lshl_add_u64 v[214:215], v[214:215], 0, s[14:15]
	global_load_lds_dwordx4 v[234:235], off
	v_lshl_add_u64 v[236:237], v[214:215], 0, v[138:139]
	s_mov_b32 m0, s58
	v_lshl_add_u64 v[214:215], v[214:215], 0, v[134:135]
	global_load_lds_dwordx4 v[236:237], off
	s_mov_b32 m0, s59
	v_lshl_add_u64 v[238:239], v[212:213], 0, v[140:141]
	global_load_lds_dwordx4 v[214:215], off
	s_mov_b32 m0, s37
	v_lshl_add_u64 v[240:241], v[212:213], 0, v[136:137]
	global_load_lds_dwordx4 v[238:239], off
	s_mov_b32 m0, s41
	s_nop 0
	global_load_lds_dwordx4 v[240:241], off
	s_waitcnt vmcnt(8) lgkmcnt(0)
	s_setprio 1
	s_barrier
; #define PG8_STAGE(bufoff, gbase, voff) do { _Pragma("unroll") for (int _i = 0; _i < 2; ++_i) \
;         __builtin_amdgcn_global_load_lds((const unsigned*)((const char*)(gbase) + (voff)[_i]), (PG8_LAS unsigned*)(lds + (bufoff) + ldsw + _i * 8192), 16, 0, 0); } while (0)
; #define PG8_LDA(dst, b, h) do { _Pragma("unroll") for (int m = 0; m < 4; ++m) _Pragma("unroll") for (int k = 0; k < 2; ++k) dst[m][k] = *(const PG8_LAS bf16x8*)(lds + PG8_SA(b, h) + aoff + m * 2048 + k * 1024); } while (0)
; #define PG8_LDB(dst, b, h) do { _Pragma("unroll") for (int n = 0; n < 2; ++n) _Pragma("unroll") for (int k = 0; k < 2; ++k) dst[n][k] = *(const PG8_LAS bf16x8*)(lds + PG8_SB(b, h) + boff + n * 2048 + k * 1024); } while (0)
; #define PG8_MMA(ai, bj, At, Bt) do { __builtin_amdgcn_s_setprio(1); _Pragma("unroll") for (int m = 0; m < 4; ++m) _Pragma("unroll") for (int n = 0; n < 2; ++n) _Pragma("unroll") for (int k = 0; k < 2; ++k) \
;         acc[ai][bj][m][n] = __builtin_amdgcn_mfma_f32_16x16x32_bf16(Bt[n][k], At[m][k], acc[ai][bj][m][n], 0, 0, 0); __builtin_amdgcn_s_setprio(0); } while (0)
; #define PG8_WAIT_V(n) asm volatile("s_waitcnt vmcnt(" #n ")" ::: "memory")
; #define PG8_WAIT_L(n) asm volatile("s_waitcnt lgkmcnt(" #n ")" ::: "memory")
; #define PG8_BAR __builtin_amdgcn_s_barrier()
; #define PG8_SCHED __builtin_amdgcn_sched_barrier(0)
; template <class Epi, class Sched, bool ALIGN_EPI = false, bool SP2 = false>
; __device__ __forceinline__ void gemm_phase(PG8_LAS unsigned char* lds, const Gemm g, const Sched& S, const Epi& E) {
;     ...
;             PG8_WAIT_V(8); PG8_WAIT_L(0); PG8_BAR; PG8_MMA(1, 0, At, B0); PG8_MMA(1, 1, At, B1); PG8_BAR; PG8_SCHED;
;             PG8_LDB(B0, 1, 0); PG8_LDB(B1, 1, 1); PG8_SCHED; PG8_LDA(At, 1, 0); PG8_STAGE(PG8_SA(0, 1), a2 + hstep, voffA);
;             PG8_WAIT_V(8); PG8_WAIT_L(0); PG8_BAR; PG8_MMA(0, 0, At, B0); PG8_MMA(0, 1, At, B1); PG8_BAR; PG8_SCHED;
	v_mfma_f32_16x16x32_bf16 v[60:63], v[164:167], v[196:199], v[60:63]
	v_mfma_f32_16x16x32_bf16 v[56:59], v[172:175], v[196:199], v[56:59]
	v_mfma_f32_16x16x32_bf16 v[44:47], v[164:167], v[204:207], v[44:47]
	v_mfma_f32_16x16x32_bf16 v[40:43], v[172:175], v[204:207], v[40:43]
	v_mfma_f32_16x16x32_bf16 v[28:31], v[164:167], v[216:219], v[28:31]
	v_mfma_f32_16x16x32_bf16 v[24:27], v[172:175], v[216:219], v[24:27]
	v_mfma_f32_16x16x32_bf16 v[12:15], v[164:167], v[224:227], v[12:15]
	v_mfma_f32_16x16x32_bf16 v[8:11], v[172:175], v[224:227], v[8:11]
	v_mfma_f32_16x16x32_bf16 v[60:63], v[168:171], v[200:203], v[60:63]
	v_mfma_f32_16x16x32_bf16 v[56:59], v[176:179], v[200:203], v[56:59]
	v_mfma_f32_16x16x32_bf16 v[44:47], v[168:171], v[208:211], v[44:47]
	v_mfma_f32_16x16x32_bf16 v[40:43], v[176:179], v[208:211], v[40:43]
	v_mfma_f32_16x16x32_bf16 v[28:31], v[168:171], v[220:223], v[28:31]
	v_mfma_f32_16x16x32_bf16 v[24:27], v[176:179], v[220:223], v[24:27]
	v_mfma_f32_16x16x32_bf16 v[12:15], v[168:171], v[228:231], v[12:15]
	v_mfma_f32_16x16x32_bf16 v[8:11], v[176:179], v[228:231], v[8:11]
	v_mfma_f32_16x16x32_bf16 v[52:55], v[180:183], v[196:199], v[52:55]
	v_mfma_f32_16x16x32_bf16 v[48:51], v[188:191], v[196:199], v[48:51]
	v_mfma_f32_16x16x32_bf16 v[36:39], v[180:183], v[204:207], v[36:39]
	v_mfma_f32_16x16x32_bf16 v[32:35], v[188:191], v[204:207], v[32:35]
	v_mfma_f32_16x16x32_bf16 v[20:23], v[180:183], v[216:219], v[20:23]
	v_mfma_f32_16x16x32_bf16 v[16:19], v[188:191], v[216:219], v[16:19]
	v_mfma_f32_16x16x32_bf16 v[4:7], v[180:183], v[224:227], v[4:7]
	v_mfma_f32_16x16x32_bf16 v[0:3], v[188:191], v[224:227], v[0:3]
	v_mfma_f32_16x16x32_bf16 v[52:55], v[184:187], v[200:203], v[52:55]
	v_mfma_f32_16x16x32_bf16 v[48:51], v[192:195], v[200:203], v[48:51]
	v_mfma_f32_16x16x32_bf16 v[36:39], v[184:187], v[208:211], v[36:39]
	v_mfma_f32_16x16x32_bf16 v[32:35], v[192:195], v[208:211], v[32:35]
	v_mfma_f32_16x16x32_bf16 v[20:23], v[184:187], v[220:223], v[20:23]
	v_mfma_f32_16x16x32_bf16 v[16:19], v[192:195], v[220:223], v[16:19]
	v_mfma_f32_16x16x32_bf16 v[4:7], v[184:187], v[228:231], v[4:7]
	v_mfma_f32_16x16x32_bf16 v[0:3], v[192:195], v[228:231], v[0:3]
	s_setprio 0
	s_barrier
	v_add_u32_e32 v176, s60, v161
	v_add_u32_e32 v192, s61, v161
	ds_read_b128 v[164:167], v176
	ds_read_b128 v[168:171], v176 offset:1024
	ds_read_b128 v[172:175], v176 offset:2048
	ds_read_b128 v[176:179], v176 offset:3072
	ds_read_b128 v[180:183], v192
	ds_read_b128 v[184:187], v192 offset:1024
	ds_read_b128 v[188:191], v192 offset:2048
	ds_read_b128 v[192:195], v192 offset:3072
	v_lshl_add_u64 v[212:213], v[212:213], 0, s[14:15]
	s_mov_b32 m0, s46
	v_lshl_add_u64 v[242:243], v[212:213], 0, v[140:141]
	ds_read_b128 v[196:199], v163 offset:32768
	ds_read_b128 v[200:203], v163 offset:33792
	ds_read_b128 v[204:207], v163 offset:34816
	ds_read_b128 v[208:211], v163 offset:35840
	ds_read_b128 v[216:219], v163 offset:36864
	ds_read_b128 v[220:223], v163 offset:37888
	ds_read_b128 v[224:227], v163 offset:38912
	ds_read_b128 v[228:231], v163 offset:39936
	global_load_lds_dwordx4 v[242:243], off
	s_mov_b32 m0, s47
	v_lshl_add_u64 v[212:213], v[212:213], 0, v[136:137]
	global_load_lds_dwordx4 v[212:213], off
	s_waitcnt vmcnt(8) lgkmcnt(0)
	s_setprio 1
	s_barrier
	v_mfma_f32_16x16x32_bf16 v[124:127], v[164:167], v[196:199], v[124:127]
	v_mfma_f32_16x16x32_bf16 v[120:123], v[172:175], v[196:199], v[120:123]
	v_mfma_f32_16x16x32_bf16 v[108:111], v[164:167], v[204:207], v[108:111]
	v_mfma_f32_16x16x32_bf16 v[104:107], v[172:175], v[204:207], v[104:107]
	v_mfma_f32_16x16x32_bf16 v[92:95], v[164:167], v[216:219], v[92:95]
	v_mfma_f32_16x16x32_bf16 v[88:91], v[172:175], v[216:219], v[88:91]
	v_mfma_f32_16x16x32_bf16 v[76:79], v[164:167], v[224:227], v[76:79]
	v_mfma_f32_16x16x32_bf16 v[72:75], v[172:175], v[224:227], v[72:75]
	v_mfma_f32_16x16x32_bf16 v[124:127], v[168:171], v[200:203], v[124:127]
	v_mfma_f32_16x16x32_bf16 v[120:123], v[176:179], v[200:203], v[120:123]
	v_mfma_f32_16x16x32_bf16 v[108:111], v[168:171], v[208:211], v[108:111]
	v_mfma_f32_16x16x32_bf16 v[104:107], v[176:179], v[208:211], v[104:107]
	v_mfma_f32_16x16x32_bf16 v[92:95], v[168:171], v[220:223], v[92:95]
	v_mfma_f32_16x16x32_bf16 v[88:91], v[176:179], v[220:223], v[88:91]
	v_mfma_f32_16x16x32_bf16 v[76:79], v[168:171], v[228:231], v[76:79]
	v_mfma_f32_16x16x32_bf16 v[72:75], v[176:179], v[228:231], v[72:75]
	v_mfma_f32_16x16x32_bf16 v[116:119], v[180:183], v[196:199], v[116:119]
	v_mfma_f32_16x16x32_bf16 v[112:115], v[188:191], v[196:199], v[112:115]
	v_mfma_f32_16x16x32_bf16 v[100:103], v[180:183], v[204:207], v[100:103]
	v_mfma_f32_16x16x32_bf16 v[96:99], v[188:191], v[204:207], v[96:99]
	v_mfma_f32_16x16x32_bf16 v[84:87], v[180:183], v[216:219], v[84:87]
	v_mfma_f32_16x16x32_bf16 v[80:83], v[188:191], v[216:219], v[80:83]
	v_mfma_f32_16x16x32_bf16 v[68:71], v[180:183], v[224:227], v[68:71]
	v_mfma_f32_16x16x32_bf16 v[64:67], v[188:191], v[224:227], v[64:67]
	v_mfma_f32_16x16x32_bf16 v[116:119], v[184:187], v[200:203], v[116:119]
	v_mfma_f32_16x16x32_bf16 v[112:115], v[192:195], v[200:203], v[112:115]
	v_mfma_f32_16x16x32_bf16 v[100:103], v[184:187], v[208:211], v[100:103]
	v_mfma_f32_16x16x32_bf16 v[96:99], v[192:195], v[208:211], v[96:99]
	v_mfma_f32_16x16x32_bf16 v[84:87], v[184:187], v[220:223], v[84:87]
	v_mfma_f32_16x16x32_bf16 v[80:83], v[192:195], v[220:223], v[80:83]
	v_mfma_f32_16x16x32_bf16 v[68:71], v[184:187], v[228:231], v[68:71]
	v_mfma_f32_16x16x32_bf16 v[64:67], v[192:195], v[228:231], v[64:67]
	s_setprio 0
	s_barrier
; #define PG8_STAGE(bufoff, gbase, voff) do { _Pragma("unroll") for (int _i = 0; _i < 2; ++_i) \
;         __builtin_amdgcn_global_load_lds((const unsigned*)((const char*)(gbase) + (voff)[_i]), (PG8_LAS unsigned*)(lds + (bufoff) + ldsw + _i * 8192), 16, 0, 0); } while (0)
; #define PG8_LDA(dst, b, h) do { _Pragma("unroll") for (int m = 0; m < 4; ++m) _Pragma("unroll") for (int k = 0; k < 2; ++k) dst[m][k] = *(const PG8_LAS bf16x8*)(lds + PG8_SA(b, h) + aoff + m * 2048 + k * 1024); } while (0)
; #define PG8_MMA(ai, bj, At, Bt) do { __builtin_amdgcn_s_setprio(1); _Pragma("unroll") for (int m = 0; m < 4; ++m) _Pragma("unroll") for (int n = 0; n < 2; ++n) _Pragma("unroll") for (int k = 0; k < 2; ++k) \
;         acc[ai][bj][m][n] = __builtin_amdgcn_mfma_f32_16x16x32_bf16(Bt[n][k], At[m][k], acc[ai][bj][m][n], 0, 0, 0); __builtin_amdgcn_s_setprio(0); } while (0)
; #define PG8_WAIT_V(n) asm volatile("s_waitcnt vmcnt(" #n ")" ::: "memory")
; #define PG8_WAIT_L(n) asm volatile("s_waitcnt lgkmcnt(" #n ")" ::: "memory")
; #define PG8_BAR __builtin_amdgcn_s_barrier()
; #define PG8_SCHED __builtin_amdgcn_sched_barrier(0)
; template <class Epi, class Sched, bool ALIGN_EPI = false, bool SP2 = false>
; __device__ __forceinline__ void gemm_phase(PG8_LAS unsigned char* lds, const Gemm g, const Sched& S, const Epi& E) {
;     ...
;             PG8_LDA(At, 1, 1); PG8_STAGE(PG8_SB(1, 0), b3, voffB); PG8_STAGE(PG8_SB(1, 1), b3 + hstep, voffB); PG8_STAGE(PG8_SA(1, 0), a3, voffA);
;             PG8_WAIT_V(8); PG8_WAIT_L(0); PG8_BAR; PG8_MMA(1, 0, At, B0); PG8_MMA(1, 1, At, B1); PG8_BAR; PG8_SCHED;
	s_mov_b32 m0, s62
	v_lshl_add_u64 v[212:213], v[232:233], 0, s[24:25]
	ds_read_b128 v[196:199], v163 offset:49152
	ds_read_b128 v[200:203], v163 offset:50176
	ds_read_b128 v[204:207], v163 offset:51200
	ds_read_b128 v[208:211], v163 offset:52224
	ds_read_b128 v[216:219], v163 offset:53248
	ds_read_b128 v[220:223], v163 offset:54272
	ds_read_b128 v[224:227], v163 offset:55296
	ds_read_b128 v[228:231], v163 offset:56320
	global_load_lds_dwordx4 v[212:213], off
	s_mov_b32 m0, s63
	v_lshl_add_u64 v[212:213], v[234:235], 0, s[24:25]
	global_load_lds_dwordx4 v[212:213], off
	s_mov_b32 m0, s64
	v_lshl_add_u64 v[212:213], v[236:237], 0, s[24:25]
	global_load_lds_dwordx4 v[212:213], off
	s_mov_b32 m0, s65
	v_lshl_add_u64 v[212:213], v[214:215], 0, s[24:25]
	global_load_lds_dwordx4 v[212:213], off
	s_mov_b32 m0, s48
	v_lshl_add_u64 v[212:213], v[238:239], 0, s[24:25]
	global_load_lds_dwordx4 v[212:213], off
	s_mov_b32 m0, s49
	v_lshl_add_u64 v[212:213], v[240:241], 0, s[24:25]
	global_load_lds_dwordx4 v[212:213], off
	s_waitcnt vmcnt(8) lgkmcnt(0)
	s_setprio 1
	s_barrier
	v_mfma_f32_16x16x32_bf16 v[60:63], v[164:167], v[196:199], v[60:63]
	v_mfma_f32_16x16x32_bf16 v[56:59], v[172:175], v[196:199], v[56:59]
	v_mfma_f32_16x16x32_bf16 v[44:47], v[164:167], v[204:207], v[44:47]
	v_mfma_f32_16x16x32_bf16 v[40:43], v[172:175], v[204:207], v[40:43]
	v_mfma_f32_16x16x32_bf16 v[28:31], v[164:167], v[216:219], v[28:31]
	v_mfma_f32_16x16x32_bf16 v[24:27], v[172:175], v[216:219], v[24:27]
	v_mfma_f32_16x16x32_bf16 v[12:15], v[164:167], v[224:227], v[12:15]
	v_mfma_f32_16x16x32_bf16 v[8:11], v[172:175], v[224:227], v[8:11]
	v_mfma_f32_16x16x32_bf16 v[60:63], v[168:171], v[200:203], v[60:63]
	v_mfma_f32_16x16x32_bf16 v[56:59], v[176:179], v[200:203], v[56:59]
	v_mfma_f32_16x16x32_bf16 v[44:47], v[168:171], v[208:211], v[44:47]
	v_mfma_f32_16x16x32_bf16 v[40:43], v[176:179], v[208:211], v[40:43]
	v_mfma_f32_16x16x32_bf16 v[28:31], v[168:171], v[220:223], v[28:31]
	v_mfma_f32_16x16x32_bf16 v[24:27], v[176:179], v[220:223], v[24:27]
	v_mfma_f32_16x16x32_bf16 v[12:15], v[168:171], v[228:231], v[12:15]
	v_mfma_f32_16x16x32_bf16 v[8:11], v[176:179], v[228:231], v[8:11]
	v_mfma_f32_16x16x32_bf16 v[52:55], v[180:183], v[196:199], v[52:55]
	v_mfma_f32_16x16x32_bf16 v[48:51], v[188:191], v[196:199], v[48:51]
	v_mfma_f32_16x16x32_bf16 v[36:39], v[180:183], v[204:207], v[36:39]
	v_mfma_f32_16x16x32_bf16 v[32:35], v[188:191], v[204:207], v[32:35]
	v_mfma_f32_16x16x32_bf16 v[20:23], v[180:183], v[216:219], v[20:23]
	v_mfma_f32_16x16x32_bf16 v[16:19], v[188:191], v[216:219], v[16:19]
	v_mfma_f32_16x16x32_bf16 v[4:7], v[180:183], v[224:227], v[4:7]
	v_mfma_f32_16x16x32_bf16 v[0:3], v[188:191], v[224:227], v[0:3]
	v_mfma_f32_16x16x32_bf16 v[52:55], v[184:187], v[200:203], v[52:55]
	v_mfma_f32_16x16x32_bf16 v[48:51], v[192:195], v[200:203], v[48:51]
	v_mfma_f32_16x16x32_bf16 v[36:39], v[184:187], v[208:211], v[36:39]
	v_mfma_f32_16x16x32_bf16 v[32:35], v[192:195], v[208:211], v[32:35]
	v_mfma_f32_16x16x32_bf16 v[20:23], v[184:187], v[220:223], v[20:23]
	v_mfma_f32_16x16x32_bf16 v[16:19], v[192:195], v[220:223], v[16:19]
	v_mfma_f32_16x16x32_bf16 v[4:7], v[184:187], v[228:231], v[4:7]
	v_mfma_f32_16x16x32_bf16 v[0:3], v[192:195], v[228:231], v[0:3]
	s_setprio 0
	s_barrier
	v_lshl_add_u64 v[154:155], v[154:155], 0, s[28:29]
	s_cmp_ge_i32 s10, s50
	v_lshl_add_u64 v[158:159], v[158:159], 0, s[28:29]
	s_cbranch_scc0 .LBB0_1169

; #define PG8_STAGE(bufoff, gbase, voff) do { _Pragma("unroll") for (int _i = 0; _i < 2; ++_i) \
;         __builtin_amdgcn_global_load_lds((const unsigned*)((const char*)(gbase) + (voff)[_i]), (PG8_LAS unsigned*)(lds + (bufoff) + ldsw + _i * 8192), 16, 0, 0); } while (0)
; #define PG8_LDA(dst, b, h) do { _Pragma("unroll") for (int m = 0; m < 4; ++m) _Pragma("unroll") for (int k = 0; k < 2; ++k) dst[m][k] = *(const PG8_LAS bf16x8*)(lds + PG8_SA(b, h) + aoff + m * 2048 + k * 1024); } while (0)
; #define PG8_LDB(dst, b, h) do { _Pragma("unroll") for (int n = 0; n < 2; ++n) _Pragma("unroll") for (int k = 0; k < 2; ++k) dst[n][k] = *(const PG8_LAS bf16x8*)(lds + PG8_SB(b, h) + boff + n * 2048 + k * 1024); } while (0)
; #define PG8_MMA(ai, bj, At, Bt) do { __builtin_amdgcn_s_setprio(1); _Pragma("unroll") for (int m = 0; m < 4; ++m) _Pragma("unroll") for (int n = 0; n < 2; ++n) _Pragma("unroll") for (int k = 0; k < 2; ++k) \
;         acc[ai][bj][m][n] = __builtin_amdgcn_mfma_f32_16x16x32_bf16(Bt[n][k], At[m][k], acc[ai][bj][m][n], 0, 0, 0); __builtin_amdgcn_s_setprio(0); } while (0)
; #define PG8_WAIT_V(n) asm volatile("s_waitcnt vmcnt(" #n ")" ::: "memory")
; #define PG8_BAR __builtin_amdgcn_s_barrier()
; template <class Epi, class Sched, bool ALIGN_EPI = false, bool SP2 = false>
; __device__ __forceinline__ void gemm_phase(PG8_LAS unsigned char* lds, const Gemm g, const Sched& S, const Epi& E) {
;     ...
;         for (int t = 0; t < nt; t += 2) {
;             const bool last = (t == nt - 2);
;             const char* a1 = cA + (size_t)(t + 1) * kstep;
;             const char* a2 = last ? nA : cA + (size_t)(t + 2) * kstep; const char* b2 = last ? nB : cB + (size_t)(t + 2) * kstep;
;             const char* a3 = a2 + kstep; const char* b3 = b2 + kstep;
;             if (last && has_next) S.a_ready(nxt);
;             if constexpr (SP2) {
;             PG8_LDB(B0, 0, 0); PG8_LDB(B1, 0, 1); PG8_SCHED; PG8_LDA(At, 0, 0); PG8_STAGE(PG8_SA(1, 1), a1 + hstep, voffA);
;             PG8_WAIT_V(8); PG8_WAIT_L(0); PG8_BAR; PG8_MMA(0, 0, At, B0); PG8_MMA(0, 1, At, B1); PG8_BAR; PG8_SCHED;
;             PG8_LDA(At, 0, 1); PG8_STAGE(PG8_SB(0, 0), b2, voffB); PG8_STAGE(PG8_SB(0, 1), b2 + hstep, voffB); PG8_STAGE(PG8_SA(0, 0), a2, voffA);
;             PG8_WAIT_V(8); PG8_WAIT_L(0); PG8_BAR; PG8_MMA(1, 0, At, B0); PG8_MMA(1, 1, At, B1); PG8_BAR; PG8_SCHED;
.LBB0_1192:
	v_add_u32_e32 v178, s56, v216
	v_add_u32_e32 v194, s57, v216
	ds_read_b128 v[138:141], v178
	ds_read_b128 v[142:145], v178 offset:1024
	ds_read_b128 v[146:149], v178 offset:2048
	ds_read_b128 v[178:181], v178 offset:3072
	ds_read_b128 v[182:185], v194
	ds_read_b128 v[186:189], v194 offset:1024
	ds_read_b128 v[190:193], v194 offset:2048
	ds_read_b128 v[194:197], v194 offset:3072
	s_cmp_eq_u32 s49, s10
	v_lshl_add_u64 v[198:199], v[136:137], 0, s[20:21]
	s_cselect_b64 vcc, -1, 0
	s_add_i32 s10, s10, 2
	v_cndmask_b32_e32 v215, v199, v175, vcc
	v_cndmask_b32_e32 v214, v198, v174, vcc
	v_cndmask_b32_e32 v237, v135, v177, vcc
	v_cndmask_b32_e32 v236, v134, v176, vcc
	v_lshl_add_u64 v[238:239], v[136:137], 0, v[168:169]
	s_add_i32 m0, s34, 0xc000
	ds_read_b128 v[198:201], v218
	ds_read_b128 v[202:205], v218 offset:1024
	ds_read_b128 v[206:209], v218 offset:2048
	ds_read_b128 v[210:213], v218 offset:3072
	ds_read_b128 v[220:223], v218 offset:4096
	ds_read_b128 v[224:227], v218 offset:5120
	ds_read_b128 v[228:231], v218 offset:6144
	ds_read_b128 v[232:235], v218 offset:7168
	global_load_lds_dwordx4 v[238:239], off
	s_add_i32 m0, s34, 0xe000
	v_lshl_add_u64 v[238:239], v[136:137], 0, v[166:167]
	global_load_lds_dwordx4 v[238:239], off
	s_waitcnt vmcnt(8) lgkmcnt(0)
	s_setprio 1
	s_barrier
	v_mfma_f32_16x16x32_bf16 v[130:133], v[138:141], v[198:201], v[130:133]
	v_mfma_f32_16x16x32_bf16 v[126:129], v[146:149], v[198:201], v[126:129]
	v_mfma_f32_16x16x32_bf16 v[114:117], v[138:141], v[206:209], v[114:117]
	v_mfma_f32_16x16x32_bf16 v[110:113], v[146:149], v[206:209], v[110:113]
	v_mfma_f32_16x16x32_bf16 v[98:101], v[138:141], v[220:223], v[98:101]
	v_mfma_f32_16x16x32_bf16 v[94:97], v[146:149], v[220:223], v[94:97]
	v_mfma_f32_16x16x32_bf16 v[82:85], v[138:141], v[228:231], v[82:85]
	v_mfma_f32_16x16x32_bf16 v[78:81], v[146:149], v[228:231], v[78:81]
	v_mfma_f32_16x16x32_bf16 v[130:133], v[142:145], v[202:205], v[130:133]
	v_mfma_f32_16x16x32_bf16 v[126:129], v[178:181], v[202:205], v[126:129]
	v_mfma_f32_16x16x32_bf16 v[114:117], v[142:145], v[210:213], v[114:117]
	v_mfma_f32_16x16x32_bf16 v[110:113], v[178:181], v[210:213], v[110:113]
	v_mfma_f32_16x16x32_bf16 v[98:101], v[142:145], v[224:227], v[98:101]
	v_mfma_f32_16x16x32_bf16 v[94:97], v[178:181], v[224:227], v[94:97]
	v_mfma_f32_16x16x32_bf16 v[82:85], v[142:145], v[232:235], v[82:85]
	v_mfma_f32_16x16x32_bf16 v[78:81], v[178:181], v[232:235], v[78:81]
	v_mfma_f32_16x16x32_bf16 v[122:125], v[182:185], v[198:201], v[122:125]
	v_mfma_f32_16x16x32_bf16 v[118:121], v[190:193], v[198:201], v[118:121]
	v_mfma_f32_16x16x32_bf16 v[106:109], v[182:185], v[206:209], v[106:109]
	v_mfma_f32_16x16x32_bf16 v[102:105], v[190:193], v[206:209], v[102:105]
	v_mfma_f32_16x16x32_bf16 v[90:93], v[182:185], v[220:223], v[90:93]
	v_mfma_f32_16x16x32_bf16 v[86:89], v[190:193], v[220:223], v[86:89]
	v_mfma_f32_16x16x32_bf16 v[74:77], v[182:185], v[228:231], v[74:77]
	v_mfma_f32_16x16x32_bf16 v[70:73], v[190:193], v[228:231], v[70:73]
	v_mfma_f32_16x16x32_bf16 v[122:125], v[186:189], v[202:205], v[122:125]
	v_mfma_f32_16x16x32_bf16 v[118:121], v[194:197], v[202:205], v[118:121]
	v_mfma_f32_16x16x32_bf16 v[106:109], v[186:189], v[210:213], v[106:109]
	v_mfma_f32_16x16x32_bf16 v[102:105], v[194:197], v[210:213], v[102:105]
	v_mfma_f32_16x16x32_bf16 v[90:93], v[186:189], v[224:227], v[90:93]
	v_mfma_f32_16x16x32_bf16 v[86:89], v[194:197], v[224:227], v[86:89]
	v_mfma_f32_16x16x32_bf16 v[74:77], v[186:189], v[232:235], v[74:77]
	v_mfma_f32_16x16x32_bf16 v[70:73], v[194:197], v[232:235], v[70:73]
	s_setprio 0
	s_barrier
	s_add_i32 s11, s56, s29
	v_lshl_add_u64 v[238:239], v[236:237], 0, v[158:159]
	s_mov_b32 m0, s11
	ds_read_b128 v[198:201], v218 offset:16384
	ds_read_b128 v[202:205], v218 offset:17408
	ds_read_b128 v[206:209], v218 offset:18432
	ds_read_b128 v[210:213], v218 offset:19456
	ds_read_b128 v[220:223], v218 offset:20480
	ds_read_b128 v[224:227], v218 offset:21504
	ds_read_b128 v[228:231], v218 offset:22528
	ds_read_b128 v[232:235], v218 offset:23552
	global_load_lds_dwordx4 v[238:239], off
	v_lshl_add_u64 v[240:241], v[236:237], 0, v[162:163]
	s_add_i32 m0, s11, 0x2000
	v_lshl_add_u64 v[236:237], v[236:237], 0, s[12:13]
	s_add_i32 s11, s57, s29
	global_load_lds_dwordx4 v[240:241], off
	v_lshl_add_u64 v[242:243], v[236:237], 0, v[158:159]
	s_mov_b32 m0, s11
	v_lshl_add_u64 v[236:237], v[236:237], 0, v[162:163]
	global_load_lds_dwordx4 v[242:243], off
	s_add_i32 m0, s11, 0x2000
	v_lshl_add_u64 v[244:245], v[214:215], 0, v[154:155]
	global_load_lds_dwordx4 v[236:237], off
	s_mov_b32 m0, s34
	v_lshl_add_u64 v[246:247], v[214:215], 0, v[160:161]
	global_load_lds_dwordx4 v[244:245], off
	s_mov_b32 m0, s35
	s_nop 0
	global_load_lds_dwordx4 v[246:247], off
	s_waitcnt vmcnt(8) lgkmcnt(0)
	s_setprio 1
	s_barrier
; #define PG8_STAGE(bufoff, gbase, voff) do { _Pragma("unroll") for (int _i = 0; _i < 2; ++_i) \
;         __builtin_amdgcn_global_load_lds((const unsigned*)((const char*)(gbase) + (voff)[_i]), (PG8_LAS unsigned*)(lds + (bufoff) + ldsw + _i * 8192), 16, 0, 0); } while (0)
; #define PG8_LDA(dst, b, h) do { _Pragma("unroll") for (int m = 0; m < 4; ++m) _Pragma("unroll") for (int k = 0; k < 2; ++k) dst[m][k] = *(const PG8_LAS bf16x8*)(lds + PG8_SA(b, h) + aoff + m * 2048 + k * 1024); } while (0)
; #define PG8_LDB(dst, b, h) do { _Pragma("unroll") for (int n = 0; n < 2; ++n) _Pragma("unroll") for (int k = 0; k < 2; ++k) dst[n][k] = *(const PG8_LAS bf16x8*)(lds + PG8_SB(b, h) + boff + n * 2048 + k * 1024); } while (0)
; #define PG8_MMA(ai, bj, At, Bt) do { __builtin_amdgcn_s_setprio(1); _Pragma("unroll") for (int m = 0; m < 4; ++m) _Pragma("unroll") for (int n = 0; n < 2; ++n) _Pragma("unroll") for (int k = 0; k < 2; ++k) \
;         acc[ai][bj][m][n] = __builtin_amdgcn_mfma_f32_16x16x32_bf16(Bt[n][k], At[m][k], acc[ai][bj][m][n], 0, 0, 0); __builtin_amdgcn_s_setprio(0); } while (0)
; #define PG8_WAIT_V(n) asm volatile("s_waitcnt vmcnt(" #n ")" ::: "memory")
; #define PG8_WAIT_L(n) asm volatile("s_waitcnt lgkmcnt(" #n ")" ::: "memory")
; #define PG8_BAR __builtin_amdgcn_s_barrier()
; #define PG8_SCHED __builtin_amdgcn_sched_barrier(0)
; template <class Epi, class Sched, bool ALIGN_EPI = false, bool SP2 = false>
; __device__ __forceinline__ void gemm_phase(PG8_LAS unsigned char* lds, const Gemm g, const Sched& S, const Epi& E) {
;     ...
;             PG8_WAIT_V(8); PG8_WAIT_L(0); PG8_BAR; PG8_MMA(1, 0, At, B0); PG8_MMA(1, 1, At, B1); PG8_BAR; PG8_SCHED;
;             PG8_LDB(B0, 1, 0); PG8_LDB(B1, 1, 1); PG8_SCHED; PG8_LDA(At, 1, 0); PG8_STAGE(PG8_SA(0, 1), a2 + hstep, voffA);
;             PG8_WAIT_V(8); PG8_WAIT_L(0); PG8_BAR; PG8_MMA(0, 0, At, B0); PG8_MMA(0, 1, At, B1); PG8_BAR; PG8_SCHED;
	v_mfma_f32_16x16x32_bf16 v[66:69], v[138:141], v[198:201], v[66:69]
	v_mfma_f32_16x16x32_bf16 v[62:65], v[146:149], v[198:201], v[62:65]
	v_mfma_f32_16x16x32_bf16 v[50:53], v[138:141], v[206:209], v[50:53]
	v_mfma_f32_16x16x32_bf16 v[46:49], v[146:149], v[206:209], v[46:49]
	v_mfma_f32_16x16x32_bf16 v[34:37], v[138:141], v[220:223], v[34:37]
	v_mfma_f32_16x16x32_bf16 v[30:33], v[146:149], v[220:223], v[30:33]
	v_mfma_f32_16x16x32_bf16 v[18:21], v[138:141], v[228:231], v[18:21]
	v_mfma_f32_16x16x32_bf16 v[14:17], v[146:149], v[228:231], v[14:17]
	v_mfma_f32_16x16x32_bf16 v[66:69], v[142:145], v[202:205], v[66:69]
	v_mfma_f32_16x16x32_bf16 v[62:65], v[178:181], v[202:205], v[62:65]
	v_mfma_f32_16x16x32_bf16 v[50:53], v[142:145], v[210:213], v[50:53]
	v_mfma_f32_16x16x32_bf16 v[46:49], v[178:181], v[210:213], v[46:49]
	v_mfma_f32_16x16x32_bf16 v[34:37], v[142:145], v[224:227], v[34:37]
	v_mfma_f32_16x16x32_bf16 v[30:33], v[178:181], v[224:227], v[30:33]
	v_mfma_f32_16x16x32_bf16 v[18:21], v[142:145], v[232:235], v[18:21]
	v_mfma_f32_16x16x32_bf16 v[14:17], v[178:181], v[232:235], v[14:17]
	v_mfma_f32_16x16x32_bf16 v[58:61], v[182:185], v[198:201], v[58:61]
	v_mfma_f32_16x16x32_bf16 v[54:57], v[190:193], v[198:201], v[54:57]
	v_mfma_f32_16x16x32_bf16 v[42:45], v[182:185], v[206:209], v[42:45]
	v_mfma_f32_16x16x32_bf16 v[38:41], v[190:193], v[206:209], v[38:41]
	v_mfma_f32_16x16x32_bf16 v[26:29], v[182:185], v[220:223], v[26:29]
	v_mfma_f32_16x16x32_bf16 v[22:25], v[190:193], v[220:223], v[22:25]
	v_mfma_f32_16x16x32_bf16 v[10:13], v[182:185], v[228:231], v[10:13]
	v_mfma_f32_16x16x32_bf16 v[6:9], v[190:193], v[228:231], v[6:9]
	v_mfma_f32_16x16x32_bf16 v[58:61], v[186:189], v[202:205], v[58:61]
	v_mfma_f32_16x16x32_bf16 v[54:57], v[194:197], v[202:205], v[54:57]
	v_mfma_f32_16x16x32_bf16 v[42:45], v[186:189], v[210:213], v[42:45]
	v_mfma_f32_16x16x32_bf16 v[38:41], v[194:197], v[210:213], v[38:41]
	v_mfma_f32_16x16x32_bf16 v[26:29], v[186:189], v[224:227], v[26:29]
	v_mfma_f32_16x16x32_bf16 v[22:25], v[194:197], v[224:227], v[22:25]
	v_mfma_f32_16x16x32_bf16 v[10:13], v[186:189], v[232:235], v[10:13]
	v_mfma_f32_16x16x32_bf16 v[6:9], v[194:197], v[232:235], v[6:9]
	s_setprio 0
	s_barrier
	s_add_i32 s11, 0, 0x18000
	s_add_i32 s31, 0, 0x1c000
	v_add_u32_e32 v178, s11, v216
	v_add_u32_e32 v194, s31, v216
	ds_read_b128 v[138:141], v178
	ds_read_b128 v[142:145], v178 offset:1024
	ds_read_b128 v[146:149], v178 offset:2048
	ds_read_b128 v[178:181], v178 offset:3072
	ds_read_b128 v[182:185], v194
	ds_read_b128 v[186:189], v194 offset:1024
	ds_read_b128 v[190:193], v194 offset:2048
	ds_read_b128 v[194:197], v194 offset:3072
	v_lshl_add_u64 v[214:215], v[214:215], 0, s[12:13]
	s_mov_b32 m0, s36
	v_lshl_add_u64 v[248:249], v[214:215], 0, v[154:155]
	ds_read_b128 v[198:201], v218 offset:32768
	ds_read_b128 v[202:205], v218 offset:33792
	ds_read_b128 v[206:209], v218 offset:34816
	ds_read_b128 v[210:213], v218 offset:35840
	ds_read_b128 v[220:223], v218 offset:36864
	ds_read_b128 v[224:227], v218 offset:37888
	ds_read_b128 v[228:231], v218 offset:38912
	ds_read_b128 v[232:235], v218 offset:39936
	global_load_lds_dwordx4 v[248:249], off
	s_mov_b32 m0, s37
	v_lshl_add_u64 v[214:215], v[214:215], 0, v[160:161]
	global_load_lds_dwordx4 v[214:215], off
	s_waitcnt vmcnt(8) lgkmcnt(0)
	s_setprio 1
	s_barrier
	v_mfma_f32_16x16x32_bf16 v[130:133], v[138:141], v[198:201], v[130:133]
	v_mfma_f32_16x16x32_bf16 v[126:129], v[146:149], v[198:201], v[126:129]
	v_mfma_f32_16x16x32_bf16 v[114:117], v[138:141], v[206:209], v[114:117]
	v_mfma_f32_16x16x32_bf16 v[110:113], v[146:149], v[206:209], v[110:113]
	v_mfma_f32_16x16x32_bf16 v[98:101], v[138:141], v[220:223], v[98:101]
	v_mfma_f32_16x16x32_bf16 v[94:97], v[146:149], v[220:223], v[94:97]
	v_mfma_f32_16x16x32_bf16 v[82:85], v[138:141], v[228:231], v[82:85]
	v_mfma_f32_16x16x32_bf16 v[78:81], v[146:149], v[228:231], v[78:81]
	v_mfma_f32_16x16x32_bf16 v[130:133], v[142:145], v[202:205], v[130:133]
	v_mfma_f32_16x16x32_bf16 v[126:129], v[178:181], v[202:205], v[126:129]
	v_mfma_f32_16x16x32_bf16 v[114:117], v[142:145], v[210:213], v[114:117]
	v_mfma_f32_16x16x32_bf16 v[110:113], v[178:181], v[210:213], v[110:113]
	v_mfma_f32_16x16x32_bf16 v[98:101], v[142:145], v[224:227], v[98:101]
	v_mfma_f32_16x16x32_bf16 v[94:97], v[178:181], v[224:227], v[94:97]
	v_mfma_f32_16x16x32_bf16 v[82:85], v[142:145], v[232:235], v[82:85]
	v_mfma_f32_16x16x32_bf16 v[78:81], v[178:181], v[232:235], v[78:81]
	v_mfma_f32_16x16x32_bf16 v[122:125], v[182:185], v[198:201], v[122:125]
	v_mfma_f32_16x16x32_bf16 v[118:121], v[190:193], v[198:201], v[118:121]
	v_mfma_f32_16x16x32_bf16 v[106:109], v[182:185], v[206:209], v[106:109]
	v_mfma_f32_16x16x32_bf16 v[102:105], v[190:193], v[206:209], v[102:105]
	v_mfma_f32_16x16x32_bf16 v[90:93], v[182:185], v[220:223], v[90:93]
	v_mfma_f32_16x16x32_bf16 v[86:89], v[190:193], v[220:223], v[86:89]
	v_mfma_f32_16x16x32_bf16 v[74:77], v[182:185], v[228:231], v[74:77]
	v_mfma_f32_16x16x32_bf16 v[70:73], v[190:193], v[228:231], v[70:73]
	v_mfma_f32_16x16x32_bf16 v[122:125], v[186:189], v[202:205], v[122:125]
	v_mfma_f32_16x16x32_bf16 v[118:121], v[194:197], v[202:205], v[118:121]
	v_mfma_f32_16x16x32_bf16 v[106:109], v[186:189], v[210:213], v[106:109]
	v_mfma_f32_16x16x32_bf16 v[102:105], v[194:197], v[210:213], v[102:105]
	v_mfma_f32_16x16x32_bf16 v[90:93], v[186:189], v[224:227], v[90:93]
	v_mfma_f32_16x16x32_bf16 v[86:89], v[194:197], v[224:227], v[86:89]
	v_mfma_f32_16x16x32_bf16 v[74:77], v[186:189], v[232:235], v[74:77]
	v_mfma_f32_16x16x32_bf16 v[70:73], v[194:197], v[232:235], v[70:73]
	s_setprio 0
	s_barrier
; #define PG8_STAGE(bufoff, gbase, voff) do { _Pragma("unroll") for (int _i = 0; _i < 2; ++_i) \
;         __builtin_amdgcn_global_load_lds((const unsigned*)((const char*)(gbase) + (voff)[_i]), (PG8_LAS unsigned*)(lds + (bufoff) + ldsw + _i * 8192), 16, 0, 0); } while (0)
; #define PG8_LDA(dst, b, h) do { _Pragma("unroll") for (int m = 0; m < 4; ++m) _Pragma("unroll") for (int k = 0; k < 2; ++k) dst[m][k] = *(const PG8_LAS bf16x8*)(lds + PG8_SA(b, h) + aoff + m * 2048 + k * 1024); } while (0)
; #define PG8_MMA(ai, bj, At, Bt) do { __builtin_amdgcn_s_setprio(1); _Pragma("unroll") for (int m = 0; m < 4; ++m) _Pragma("unroll") for (int n = 0; n < 2; ++n) _Pragma("unroll") for (int k = 0; k < 2; ++k) \
;         acc[ai][bj][m][n] = __builtin_amdgcn_mfma_f32_16x16x32_bf16(Bt[n][k], At[m][k], acc[ai][bj][m][n], 0, 0, 0); __builtin_amdgcn_s_setprio(0); } while (0)
; #define PG8_WAIT_V(n) asm volatile("s_waitcnt vmcnt(" #n ")" ::: "memory")
; #define PG8_WAIT_L(n) asm volatile("s_waitcnt lgkmcnt(" #n ")" ::: "memory")
; #define PG8_BAR __builtin_amdgcn_s_barrier()
; #define PG8_SCHED __builtin_amdgcn_sched_barrier(0)
; template <class Epi, class Sched, bool ALIGN_EPI = false, bool SP2 = false>
; __device__ __forceinline__ void gemm_phase(PG8_LAS unsigned char* lds, const Gemm g, const Sched& S, const Epi& E) {
;     ...
;             PG8_LDA(At, 1, 1); PG8_STAGE(PG8_SB(1, 0), b3, voffB); PG8_STAGE(PG8_SB(1, 1), b3 + hstep, voffB); PG8_STAGE(PG8_SA(1, 0), a3, voffA);
;             PG8_WAIT_V(8); PG8_WAIT_L(0); PG8_BAR; PG8_MMA(1, 0, At, B0); PG8_MMA(1, 1, At, B1); PG8_BAR; PG8_SCHED;
	s_add_i32 s11, s11, s29
	v_lshl_add_u64 v[214:215], v[238:239], 0, s[20:21]
	s_mov_b32 m0, s11
	ds_read_b128 v[198:201], v218 offset:49152
	ds_read_b128 v[202:205], v218 offset:50176
	ds_read_b128 v[206:209], v218 offset:51200
	ds_read_b128 v[210:213], v218 offset:52224
	ds_read_b128 v[220:223], v218 offset:53248
	ds_read_b128 v[224:227], v218 offset:54272
	ds_read_b128 v[228:231], v218 offset:55296
	ds_read_b128 v[232:235], v218 offset:56320
	global_load_lds_dwordx4 v[214:215], off
	v_lshl_add_u64 v[214:215], v[240:241], 0, s[20:21]
	s_add_i32 m0, s11, 0x2000
	s_add_i32 s11, s31, s29
	global_load_lds_dwordx4 v[214:215], off
	s_mov_b32 m0, s11
	v_lshl_add_u64 v[214:215], v[242:243], 0, s[20:21]
	global_load_lds_dwordx4 v[214:215], off
	s_add_i32 m0, s11, 0x2000
	v_lshl_add_u64 v[214:215], v[236:237], 0, s[20:21]
	global_load_lds_dwordx4 v[214:215], off
	s_mov_b32 m0, s41
	v_lshl_add_u64 v[214:215], v[244:245], 0, s[20:21]
	global_load_lds_dwordx4 v[214:215], off
	s_mov_b32 m0, s46
	v_lshl_add_u64 v[214:215], v[246:247], 0, s[20:21]
	global_load_lds_dwordx4 v[214:215], off
	s_waitcnt vmcnt(8) lgkmcnt(0)
	s_setprio 1
	s_barrier
	v_mfma_f32_16x16x32_bf16 v[66:69], v[138:141], v[198:201], v[66:69]
	v_mfma_f32_16x16x32_bf16 v[62:65], v[146:149], v[198:201], v[62:65]
	v_mfma_f32_16x16x32_bf16 v[50:53], v[138:141], v[206:209], v[50:53]
	v_mfma_f32_16x16x32_bf16 v[46:49], v[146:149], v[206:209], v[46:49]
	v_mfma_f32_16x16x32_bf16 v[34:37], v[138:141], v[220:223], v[34:37]
	v_mfma_f32_16x16x32_bf16 v[30:33], v[146:149], v[220:223], v[30:33]
	v_mfma_f32_16x16x32_bf16 v[18:21], v[138:141], v[228:231], v[18:21]
	v_mfma_f32_16x16x32_bf16 v[14:17], v[146:149], v[228:231], v[14:17]
	v_mfma_f32_16x16x32_bf16 v[66:69], v[142:145], v[202:205], v[66:69]
	v_mfma_f32_16x16x32_bf16 v[62:65], v[178:181], v[202:205], v[62:65]
	v_mfma_f32_16x16x32_bf16 v[50:53], v[142:145], v[210:213], v[50:53]
	v_mfma_f32_16x16x32_bf16 v[46:49], v[178:181], v[210:213], v[46:49]
	v_mfma_f32_16x16x32_bf16 v[34:37], v[142:145], v[224:227], v[34:37]
	v_mfma_f32_16x16x32_bf16 v[30:33], v[178:181], v[224:227], v[30:33]
	v_mfma_f32_16x16x32_bf16 v[18:21], v[142:145], v[232:235], v[18:21]
	v_mfma_f32_16x16x32_bf16 v[14:17], v[178:181], v[232:235], v[14:17]
	v_mfma_f32_16x16x32_bf16 v[58:61], v[182:185], v[198:201], v[58:61]
	v_mfma_f32_16x16x32_bf16 v[54:57], v[190:193], v[198:201], v[54:57]
	v_mfma_f32_16x16x32_bf16 v[42:45], v[182:185], v[206:209], v[42:45]
	v_mfma_f32_16x16x32_bf16 v[38:41], v[190:193], v[206:209], v[38:41]
	v_mfma_f32_16x16x32_bf16 v[26:29], v[182:185], v[220:223], v[26:29]
	v_mfma_f32_16x16x32_bf16 v[22:25], v[190:193], v[220:223], v[22:25]
	v_mfma_f32_16x16x32_bf16 v[10:13], v[182:185], v[228:231], v[10:13]
	v_mfma_f32_16x16x32_bf16 v[6:9], v[190:193], v[228:231], v[6:9]
	v_mfma_f32_16x16x32_bf16 v[58:61], v[186:189], v[202:205], v[58:61]
	v_mfma_f32_16x16x32_bf16 v[54:57], v[194:197], v[202:205], v[54:57]
	v_mfma_f32_16x16x32_bf16 v[42:45], v[186:189], v[210:213], v[42:45]
	v_mfma_f32_16x16x32_bf16 v[38:41], v[194:197], v[210:213], v[38:41]
	v_mfma_f32_16x16x32_bf16 v[26:29], v[186:189], v[224:227], v[26:29]
	v_mfma_f32_16x16x32_bf16 v[22:25], v[194:197], v[224:227], v[22:25]
	v_mfma_f32_16x16x32_bf16 v[10:13], v[186:189], v[232:235], v[10:13]
	v_mfma_f32_16x16x32_bf16 v[6:9], v[194:197], v[232:235], v[6:9]
	s_setprio 0
	s_barrier
	v_lshl_add_u64 v[134:135], v[134:135], 0, s[26:27]
	s_cmp_ge_i32 s10, s48
	v_lshl_add_u64 v[136:137], v[136:137], 0, s[26:27]
	s_cbranch_scc0 .LBB0_1192

; #define PG8_STAGE(bufoff, gbase, voff) do { _Pragma("unroll") for (int _i = 0; _i < 2; ++_i) \
;         __builtin_amdgcn_global_load_lds((const unsigned*)((const char*)(gbase) + (voff)[_i]), (PG8_LAS unsigned*)(lds + (bufoff) + ldsw + _i * 8192), 16, 0, 0); } while (0)
; #define PG8_LDA(dst, b, h) do { _Pragma("unroll") for (int m = 0; m < 4; ++m) _Pragma("unroll") for (int k = 0; k < 2; ++k) dst[m][k] = *(const PG8_LAS bf16x8*)(lds + PG8_SA(b, h) + aoff + m * 2048 + k * 1024); } while (0)
; #define PG8_LDB(dst, b, h) do { _Pragma("unroll") for (int n = 0; n < 2; ++n) _Pragma("unroll") for (int k = 0; k < 2; ++k) dst[n][k] = *(const PG8_LAS bf16x8*)(lds + PG8_SB(b, h) + boff + n * 2048 + k * 1024); } while (0)
; #define PG8_MMA(ai, bj, At, Bt) do { __builtin_amdgcn_s_setprio(1); _Pragma("unroll") for (int m = 0; m < 4; ++m) _Pragma("unroll") for (int n = 0; n < 2; ++n) _Pragma("unroll") for (int k = 0; k < 2; ++k) \
;         acc[ai][bj][m][n] = __builtin_amdgcn_mfma_f32_16x16x32_bf16(Bt[n][k], At[m][k], acc[ai][bj][m][n], 0, 0, 0); __builtin_amdgcn_s_setprio(0); } while (0)
; #define PG8_WAIT_V(n) asm volatile("s_waitcnt vmcnt(" #n ")" ::: "memory")
; #define PG8_BAR __builtin_amdgcn_s_barrier()
; template <class Epi, class Sched, bool ALIGN_EPI = false, bool SP2 = false>
; __device__ __forceinline__ void gemm_phase(PG8_LAS unsigned char* lds, const Gemm g, const Sched& S, const Epi& E) {
;     ...
;         for (int t = 0; t < nt; t += 2) {
;             const bool last = (t == nt - 2);
;             const char* a1 = cA + (size_t)(t + 1) * kstep;
;             const char* a2 = last ? nA : cA + (size_t)(t + 2) * kstep; const char* b2 = last ? nB : cB + (size_t)(t + 2) * kstep;
;             const char* a3 = a2 + kstep; const char* b3 = b2 + kstep;
;             if (last && has_next) S.a_ready(nxt);
;             if constexpr (SP2) {
;             PG8_LDB(B0, 0, 0); PG8_LDB(B1, 0, 1); PG8_SCHED; PG8_LDA(At, 0, 0); PG8_STAGE(PG8_SA(1, 1), a1 + hstep, voffA);
;             PG8_WAIT_V(8); PG8_WAIT_L(0); PG8_BAR; PG8_MMA(0, 0, At, B0); PG8_MMA(0, 1, At, B1); PG8_BAR; PG8_SCHED;
;             PG8_LDA(At, 0, 1); PG8_STAGE(PG8_SB(0, 0), b2, voffB); PG8_STAGE(PG8_SB(0, 1), b2 + hstep, voffB); PG8_STAGE(PG8_SA(0, 0), a2, voffA);
;             PG8_WAIT_V(8); PG8_WAIT_L(0); PG8_BAR; PG8_MMA(1, 0, At, B0); PG8_MMA(1, 1, At, B1); PG8_BAR; PG8_SCHED;
.LBB0_1340:
	v_add_u32_e32 v148, s55, v201
	v_add_u32_e32 v190, s56, v201
	ds_read_b128 v[136:139], v148
	ds_read_b128 v[140:143], v148 offset:1024
	ds_read_b128 v[144:147], v148 offset:2048
	ds_read_b128 v[148:151], v148 offset:3072
	ds_read_b128 v[152:155], v190
	ds_read_b128 v[182:185], v190 offset:1024
	ds_read_b128 v[186:189], v190 offset:2048
	ds_read_b128 v[190:193], v190 offset:3072
	s_cmp_eq_u32 s48, s12
	v_lshl_add_u64 v[194:195], v[134:135], 0, s[22:23]
	s_cselect_b64 vcc, -1, 0
	s_add_i32 s12, s12, 2
	v_cndmask_b32_e32 v199, v195, v179, vcc
	v_cndmask_b32_e32 v198, v194, v178, vcc
	v_cndmask_b32_e32 v215, v133, v181, vcc
	v_cndmask_b32_e32 v214, v132, v180, vcc
	s_mov_b32 m0, s57
	v_lshl_add_u64 v[236:237], v[134:135], 0, v[174:175]
	ds_read_b128 v[194:197], v203
	ds_read_b128 v[206:209], v203 offset:1024
	ds_read_b128 v[210:213], v203 offset:2048
	ds_read_b128 v[216:219], v203 offset:3072
	ds_read_b128 v[220:223], v203 offset:4096
	ds_read_b128 v[224:227], v203 offset:5120
	ds_read_b128 v[228:231], v203 offset:6144
	ds_read_b128 v[232:235], v203 offset:7168
	global_load_lds_dwordx4 v[236:237], off
	s_mov_b32 m0, s58
	v_lshl_add_u64 v[236:237], v[134:135], 0, v[172:173]
	global_load_lds_dwordx4 v[236:237], off
	s_waitcnt vmcnt(8) lgkmcnt(0)
	s_setprio 1
	s_barrier
	v_mfma_f32_16x16x32_bf16 v[124:127], v[136:139], v[194:197], v[124:127]
	v_mfma_f32_16x16x32_bf16 v[128:131], v[144:147], v[194:197], v[128:131]
	v_mfma_f32_16x16x32_bf16 v[112:115], v[136:139], v[210:213], v[112:115]
	v_mfma_f32_16x16x32_bf16 v[108:111], v[144:147], v[210:213], v[108:111]
	v_mfma_f32_16x16x32_bf16 v[96:99], v[136:139], v[220:223], v[96:99]
	v_mfma_f32_16x16x32_bf16 v[92:95], v[144:147], v[220:223], v[92:95]
	v_mfma_f32_16x16x32_bf16 v[80:83], v[136:139], v[228:231], v[80:83]
	v_mfma_f32_16x16x32_bf16 v[76:79], v[144:147], v[228:231], v[76:79]
	v_mfma_f32_16x16x32_bf16 v[124:127], v[140:143], v[206:209], v[124:127]
	v_mfma_f32_16x16x32_bf16 v[128:131], v[148:151], v[206:209], v[128:131]
	v_mfma_f32_16x16x32_bf16 v[112:115], v[140:143], v[216:219], v[112:115]
	v_mfma_f32_16x16x32_bf16 v[108:111], v[148:151], v[216:219], v[108:111]
	v_mfma_f32_16x16x32_bf16 v[96:99], v[140:143], v[224:227], v[96:99]
	v_mfma_f32_16x16x32_bf16 v[92:95], v[148:151], v[224:227], v[92:95]
	v_mfma_f32_16x16x32_bf16 v[80:83], v[140:143], v[232:235], v[80:83]
	v_mfma_f32_16x16x32_bf16 v[76:79], v[148:151], v[232:235], v[76:79]
	v_mfma_f32_16x16x32_bf16 v[120:123], v[152:155], v[194:197], v[120:123]
	v_mfma_f32_16x16x32_bf16 v[116:119], v[186:189], v[194:197], v[116:119]
	v_mfma_f32_16x16x32_bf16 v[104:107], v[152:155], v[210:213], v[104:107]
	v_mfma_f32_16x16x32_bf16 v[100:103], v[186:189], v[210:213], v[100:103]
	v_mfma_f32_16x16x32_bf16 v[88:91], v[152:155], v[220:223], v[88:91]
	v_mfma_f32_16x16x32_bf16 v[84:87], v[186:189], v[220:223], v[84:87]
	v_mfma_f32_16x16x32_bf16 v[72:75], v[152:155], v[228:231], v[72:75]
	v_mfma_f32_16x16x32_bf16 v[68:71], v[186:189], v[228:231], v[68:71]
	v_mfma_f32_16x16x32_bf16 v[120:123], v[182:185], v[206:209], v[120:123]
	v_mfma_f32_16x16x32_bf16 v[116:119], v[190:193], v[206:209], v[116:119]
	v_mfma_f32_16x16x32_bf16 v[104:107], v[182:185], v[216:219], v[104:107]
	v_mfma_f32_16x16x32_bf16 v[100:103], v[190:193], v[216:219], v[100:103]
	v_mfma_f32_16x16x32_bf16 v[88:91], v[182:185], v[224:227], v[88:91]
	v_mfma_f32_16x16x32_bf16 v[84:87], v[190:193], v[224:227], v[84:87]
	v_mfma_f32_16x16x32_bf16 v[72:75], v[182:185], v[232:235], v[72:75]
	v_mfma_f32_16x16x32_bf16 v[68:71], v[190:193], v[232:235], v[68:71]
	s_setprio 0
	s_barrier
	s_mov_b32 m0, s59
	v_lshl_add_u64 v[236:237], v[214:215], 0, v[166:167]
	ds_read_b128 v[194:197], v203 offset:16384
	ds_read_b128 v[206:209], v203 offset:17408
	ds_read_b128 v[210:213], v203 offset:18432
	ds_read_b128 v[216:219], v203 offset:19456
	ds_read_b128 v[220:223], v203 offset:20480
	ds_read_b128 v[224:227], v203 offset:21504
	ds_read_b128 v[228:231], v203 offset:22528
	ds_read_b128 v[232:235], v203 offset:23552
	global_load_lds_dwordx4 v[236:237], off
	v_lshl_add_u64 v[238:239], v[214:215], 0, v[170:171]
	s_mov_b32 m0, s60
	v_lshl_add_u64 v[214:215], v[214:215], 0, s[14:15]
	s_add_i32 s13, s56, s30
	global_load_lds_dwordx4 v[238:239], off
	v_lshl_add_u64 v[240:241], v[214:215], 0, v[166:167]
	s_mov_b32 m0, s13
	v_lshl_add_u64 v[214:215], v[214:215], 0, v[170:171]
	global_load_lds_dwordx4 v[240:241], off
	s_add_i32 m0, s13, 0x2000
	v_lshl_add_u64 v[242:243], v[198:199], 0, v[164:165]
	global_load_lds_dwordx4 v[214:215], off
	s_mov_b32 m0, s31
	v_lshl_add_u64 v[244:245], v[198:199], 0, v[168:169]
	global_load_lds_dwordx4 v[242:243], off
	s_mov_b32 m0, s34
	s_nop 0
	global_load_lds_dwordx4 v[244:245], off
	s_waitcnt vmcnt(8) lgkmcnt(0)
	s_setprio 1
	s_barrier
; #define PG8_STAGE(bufoff, gbase, voff) do { _Pragma("unroll") for (int _i = 0; _i < 2; ++_i) \
;         __builtin_amdgcn_global_load_lds((const unsigned*)((const char*)(gbase) + (voff)[_i]), (PG8_LAS unsigned*)(lds + (bufoff) + ldsw + _i * 8192), 16, 0, 0); } while (0)
; #define PG8_LDA(dst, b, h) do { _Pragma("unroll") for (int m = 0; m < 4; ++m) _Pragma("unroll") for (int k = 0; k < 2; ++k) dst[m][k] = *(const PG8_LAS bf16x8*)(lds + PG8_SA(b, h) + aoff + m * 2048 + k * 1024); } while (0)
; #define PG8_LDB(dst, b, h) do { _Pragma("unroll") for (int n = 0; n < 2; ++n) _Pragma("unroll") for (int k = 0; k < 2; ++k) dst[n][k] = *(const PG8_LAS bf16x8*)(lds + PG8_SB(b, h) + boff + n * 2048 + k * 1024); } while (0)
; #define PG8_MMA(ai, bj, At, Bt) do { __builtin_amdgcn_s_setprio(1); _Pragma("unroll") for (int m = 0; m < 4; ++m) _Pragma("unroll") for (int n = 0; n < 2; ++n) _Pragma("unroll") for (int k = 0; k < 2; ++k) \
;         acc[ai][bj][m][n] = __builtin_amdgcn_mfma_f32_16x16x32_bf16(Bt[n][k], At[m][k], acc[ai][bj][m][n], 0, 0, 0); __builtin_amdgcn_s_setprio(0); } while (0)
; #define PG8_WAIT_V(n) asm volatile("s_waitcnt vmcnt(" #n ")" ::: "memory")
; #define PG8_WAIT_L(n) asm volatile("s_waitcnt lgkmcnt(" #n ")" ::: "memory")
; #define PG8_BAR __builtin_amdgcn_s_barrier()
; #define PG8_SCHED __builtin_amdgcn_sched_barrier(0)
; template <class Epi, class Sched, bool ALIGN_EPI = false, bool SP2 = false>
; __device__ __forceinline__ void gemm_phase(PG8_LAS unsigned char* lds, const Gemm g, const Sched& S, const Epi& E) {
;     ...
;             PG8_WAIT_V(8); PG8_WAIT_L(0); PG8_BAR; PG8_MMA(1, 0, At, B0); PG8_MMA(1, 1, At, B1); PG8_BAR; PG8_SCHED;
;             PG8_LDB(B0, 1, 0); PG8_LDB(B1, 1, 1); PG8_SCHED; PG8_LDA(At, 1, 0); PG8_STAGE(PG8_SA(0, 1), a2 + hstep, voffA);
;             PG8_WAIT_V(8); PG8_WAIT_L(0); PG8_BAR; PG8_MMA(0, 0, At, B0); PG8_MMA(0, 1, At, B1); PG8_BAR; PG8_SCHED;
	v_mfma_f32_16x16x32_bf16 v[64:67], v[136:139], v[194:197], v[64:67]
	v_mfma_f32_16x16x32_bf16 v[60:63], v[144:147], v[194:197], v[60:63]
	v_mfma_f32_16x16x32_bf16 v[48:51], v[136:139], v[210:213], v[48:51]
	v_mfma_f32_16x16x32_bf16 v[44:47], v[144:147], v[210:213], v[44:47]
	v_mfma_f32_16x16x32_bf16 v[32:35], v[136:139], v[220:223], v[32:35]
	v_mfma_f32_16x16x32_bf16 v[28:31], v[144:147], v[220:223], v[28:31]
	v_mfma_f32_16x16x32_bf16 v[16:19], v[136:139], v[228:231], v[16:19]
	v_mfma_f32_16x16x32_bf16 v[12:15], v[144:147], v[228:231], v[12:15]
	v_mfma_f32_16x16x32_bf16 v[64:67], v[140:143], v[206:209], v[64:67]
	v_mfma_f32_16x16x32_bf16 v[60:63], v[148:151], v[206:209], v[60:63]
	v_mfma_f32_16x16x32_bf16 v[48:51], v[140:143], v[216:219], v[48:51]
	v_mfma_f32_16x16x32_bf16 v[44:47], v[148:151], v[216:219], v[44:47]
	v_mfma_f32_16x16x32_bf16 v[32:35], v[140:143], v[224:227], v[32:35]
	v_mfma_f32_16x16x32_bf16 v[28:31], v[148:151], v[224:227], v[28:31]
	v_mfma_f32_16x16x32_bf16 v[16:19], v[140:143], v[232:235], v[16:19]
	v_mfma_f32_16x16x32_bf16 v[12:15], v[148:151], v[232:235], v[12:15]
	v_mfma_f32_16x16x32_bf16 v[56:59], v[152:155], v[194:197], v[56:59]
	v_mfma_f32_16x16x32_bf16 v[52:55], v[186:189], v[194:197], v[52:55]
	v_mfma_f32_16x16x32_bf16 v[40:43], v[152:155], v[210:213], v[40:43]
	v_mfma_f32_16x16x32_bf16 v[36:39], v[186:189], v[210:213], v[36:39]
	v_mfma_f32_16x16x32_bf16 v[24:27], v[152:155], v[220:223], v[24:27]
	v_mfma_f32_16x16x32_bf16 v[20:23], v[186:189], v[220:223], v[20:23]
	v_mfma_f32_16x16x32_bf16 v[8:11], v[152:155], v[228:231], v[8:11]
	v_mfma_f32_16x16x32_bf16 v[4:7], v[186:189], v[228:231], v[4:7]
	v_mfma_f32_16x16x32_bf16 v[56:59], v[182:185], v[206:209], v[56:59]
	v_mfma_f32_16x16x32_bf16 v[52:55], v[190:193], v[206:209], v[52:55]
	v_mfma_f32_16x16x32_bf16 v[40:43], v[182:185], v[216:219], v[40:43]
	v_mfma_f32_16x16x32_bf16 v[36:39], v[190:193], v[216:219], v[36:39]
	v_mfma_f32_16x16x32_bf16 v[24:27], v[182:185], v[224:227], v[24:27]
	v_mfma_f32_16x16x32_bf16 v[20:23], v[190:193], v[224:227], v[20:23]
	v_mfma_f32_16x16x32_bf16 v[8:11], v[182:185], v[232:235], v[8:11]
	v_mfma_f32_16x16x32_bf16 v[4:7], v[190:193], v[232:235], v[4:7]
	s_setprio 0
	s_barrier
	s_add_i32 s13, 0, 0x18000
	s_add_i32 s29, 0, 0x1c000
	v_add_u32_e32 v148, s13, v201
	v_add_u32_e32 v190, s29, v201
	ds_read_b128 v[136:139], v148
	ds_read_b128 v[140:143], v148 offset:1024
	ds_read_b128 v[144:147], v148 offset:2048
	ds_read_b128 v[148:151], v148 offset:3072
	ds_read_b128 v[152:155], v190
	ds_read_b128 v[182:185], v190 offset:1024
	ds_read_b128 v[186:189], v190 offset:2048
	ds_read_b128 v[190:193], v190 offset:3072
	v_lshl_add_u64 v[198:199], v[198:199], 0, s[14:15]
	s_mov_b32 m0, s35
	v_lshl_add_u64 v[246:247], v[198:199], 0, v[164:165]
	ds_read_b128 v[194:197], v203 offset:32768
	ds_read_b128 v[206:209], v203 offset:33792
	ds_read_b128 v[210:213], v203 offset:34816
	ds_read_b128 v[216:219], v203 offset:35840
	ds_read_b128 v[220:223], v203 offset:36864
	ds_read_b128 v[224:227], v203 offset:37888
	ds_read_b128 v[228:231], v203 offset:38912
	ds_read_b128 v[232:235], v203 offset:39936
	global_load_lds_dwordx4 v[246:247], off
	s_mov_b32 m0, s36
	v_lshl_add_u64 v[198:199], v[198:199], 0, v[168:169]
	global_load_lds_dwordx4 v[198:199], off
	s_waitcnt vmcnt(8) lgkmcnt(0)
	s_setprio 1
	s_barrier
	v_mfma_f32_16x16x32_bf16 v[124:127], v[136:139], v[194:197], v[124:127]
	v_mfma_f32_16x16x32_bf16 v[128:131], v[144:147], v[194:197], v[128:131]
	v_mfma_f32_16x16x32_bf16 v[112:115], v[136:139], v[210:213], v[112:115]
	v_mfma_f32_16x16x32_bf16 v[108:111], v[144:147], v[210:213], v[108:111]
	v_mfma_f32_16x16x32_bf16 v[96:99], v[136:139], v[220:223], v[96:99]
	v_mfma_f32_16x16x32_bf16 v[92:95], v[144:147], v[220:223], v[92:95]
	v_mfma_f32_16x16x32_bf16 v[80:83], v[136:139], v[228:231], v[80:83]
	v_mfma_f32_16x16x32_bf16 v[76:79], v[144:147], v[228:231], v[76:79]
	v_mfma_f32_16x16x32_bf16 v[124:127], v[140:143], v[206:209], v[124:127]
	v_mfma_f32_16x16x32_bf16 v[128:131], v[148:151], v[206:209], v[128:131]
	v_mfma_f32_16x16x32_bf16 v[112:115], v[140:143], v[216:219], v[112:115]
	v_mfma_f32_16x16x32_bf16 v[108:111], v[148:151], v[216:219], v[108:111]
	v_mfma_f32_16x16x32_bf16 v[96:99], v[140:143], v[224:227], v[96:99]
	v_mfma_f32_16x16x32_bf16 v[92:95], v[148:151], v[224:227], v[92:95]
	v_mfma_f32_16x16x32_bf16 v[80:83], v[140:143], v[232:235], v[80:83]
	v_mfma_f32_16x16x32_bf16 v[76:79], v[148:151], v[232:235], v[76:79]
	v_mfma_f32_16x16x32_bf16 v[120:123], v[152:155], v[194:197], v[120:123]
	v_mfma_f32_16x16x32_bf16 v[116:119], v[186:189], v[194:197], v[116:119]
	v_mfma_f32_16x16x32_bf16 v[104:107], v[152:155], v[210:213], v[104:107]
	v_mfma_f32_16x16x32_bf16 v[100:103], v[186:189], v[210:213], v[100:103]
	v_mfma_f32_16x16x32_bf16 v[88:91], v[152:155], v[220:223], v[88:91]
	v_mfma_f32_16x16x32_bf16 v[84:87], v[186:189], v[220:223], v[84:87]
	v_mfma_f32_16x16x32_bf16 v[72:75], v[152:155], v[228:231], v[72:75]
	v_mfma_f32_16x16x32_bf16 v[68:71], v[186:189], v[228:231], v[68:71]
	v_mfma_f32_16x16x32_bf16 v[120:123], v[182:185], v[206:209], v[120:123]
	v_mfma_f32_16x16x32_bf16 v[116:119], v[190:193], v[206:209], v[116:119]
	v_mfma_f32_16x16x32_bf16 v[104:107], v[182:185], v[216:219], v[104:107]
	v_mfma_f32_16x16x32_bf16 v[100:103], v[190:193], v[216:219], v[100:103]
	v_mfma_f32_16x16x32_bf16 v[88:91], v[182:185], v[224:227], v[88:91]
	v_mfma_f32_16x16x32_bf16 v[84:87], v[190:193], v[224:227], v[84:87]
	v_mfma_f32_16x16x32_bf16 v[72:75], v[182:185], v[232:235], v[72:75]
	v_mfma_f32_16x16x32_bf16 v[68:71], v[190:193], v[232:235], v[68:71]
	s_setprio 0
	s_barrier
; #define PG8_STAGE(bufoff, gbase, voff) do { _Pragma("unroll") for (int _i = 0; _i < 2; ++_i) \
;         __builtin_amdgcn_global_load_lds((const unsigned*)((const char*)(gbase) + (voff)[_i]), (PG8_LAS unsigned*)(lds + (bufoff) + ldsw + _i * 8192), 16, 0, 0); } while (0)
; #define PG8_LDA(dst, b, h) do { _Pragma("unroll") for (int m = 0; m < 4; ++m) _Pragma("unroll") for (int k = 0; k < 2; ++k) dst[m][k] = *(const PG8_LAS bf16x8*)(lds + PG8_SA(b, h) + aoff + m * 2048 + k * 1024); } while (0)
; #define PG8_MMA(ai, bj, At, Bt) do { __builtin_amdgcn_s_setprio(1); _Pragma("unroll") for (int m = 0; m < 4; ++m) _Pragma("unroll") for (int n = 0; n < 2; ++n) _Pragma("unroll") for (int k = 0; k < 2; ++k) \
;         acc[ai][bj][m][n] = __builtin_amdgcn_mfma_f32_16x16x32_bf16(Bt[n][k], At[m][k], acc[ai][bj][m][n], 0, 0, 0); __builtin_amdgcn_s_setprio(0); } while (0)
; #define PG8_WAIT_V(n) asm volatile("s_waitcnt vmcnt(" #n ")" ::: "memory")
; #define PG8_WAIT_L(n) asm volatile("s_waitcnt lgkmcnt(" #n ")" ::: "memory")
; #define PG8_BAR __builtin_amdgcn_s_barrier()
; #define PG8_SCHED __builtin_amdgcn_sched_barrier(0)
; template <class Epi, class Sched, bool ALIGN_EPI = false, bool SP2 = false>
; __device__ __forceinline__ void gemm_phase(PG8_LAS unsigned char* lds, const Gemm g, const Sched& S, const Epi& E) {
;     ...
;             PG8_LDA(At, 1, 1); PG8_STAGE(PG8_SB(1, 0), b3, voffB); PG8_STAGE(PG8_SB(1, 1), b3 + hstep, voffB); PG8_STAGE(PG8_SA(1, 0), a3, voffA);
;             PG8_WAIT_V(8); PG8_WAIT_L(0); PG8_BAR; PG8_MMA(1, 0, At, B0); PG8_MMA(1, 1, At, B1); PG8_BAR; PG8_SCHED;
	s_add_i32 s13, s13, s30
	v_lshl_add_u64 v[198:199], v[236:237], 0, s[22:23]
	s_mov_b32 m0, s13
	ds_read_b128 v[194:197], v203 offset:49152
	ds_read_b128 v[206:209], v203 offset:50176
	ds_read_b128 v[210:213], v203 offset:51200
	ds_read_b128 v[216:219], v203 offset:52224
	ds_read_b128 v[220:223], v203 offset:53248
	ds_read_b128 v[224:227], v203 offset:54272
	ds_read_b128 v[228:231], v203 offset:55296
	ds_read_b128 v[232:235], v203 offset:56320
	global_load_lds_dwordx4 v[198:199], off
	v_lshl_add_u64 v[198:199], v[238:239], 0, s[22:23]
	s_add_i32 m0, s13, 0x2000
	s_add_i32 s13, s29, s30
	global_load_lds_dwordx4 v[198:199], off
	s_mov_b32 m0, s13
	v_lshl_add_u64 v[198:199], v[240:241], 0, s[22:23]
	global_load_lds_dwordx4 v[198:199], off
	s_add_i32 m0, s13, 0x2000
	v_lshl_add_u64 v[198:199], v[214:215], 0, s[22:23]
	global_load_lds_dwordx4 v[198:199], off
	s_mov_b32 m0, s37
	v_lshl_add_u64 v[198:199], v[242:243], 0, s[22:23]
	global_load_lds_dwordx4 v[198:199], off
	s_mov_b32 m0, s41
	v_lshl_add_u64 v[198:199], v[244:245], 0, s[22:23]
	global_load_lds_dwordx4 v[198:199], off
	s_waitcnt vmcnt(8) lgkmcnt(0)
	s_setprio 1
	s_barrier
	v_mfma_f32_16x16x32_bf16 v[64:67], v[136:139], v[194:197], v[64:67]
	v_mfma_f32_16x16x32_bf16 v[60:63], v[144:147], v[194:197], v[60:63]
	v_mfma_f32_16x16x32_bf16 v[48:51], v[136:139], v[210:213], v[48:51]
	v_mfma_f32_16x16x32_bf16 v[44:47], v[144:147], v[210:213], v[44:47]
	v_mfma_f32_16x16x32_bf16 v[32:35], v[136:139], v[220:223], v[32:35]
	v_mfma_f32_16x16x32_bf16 v[28:31], v[144:147], v[220:223], v[28:31]
	v_mfma_f32_16x16x32_bf16 v[16:19], v[136:139], v[228:231], v[16:19]
	v_mfma_f32_16x16x32_bf16 v[12:15], v[144:147], v[228:231], v[12:15]
	v_mfma_f32_16x16x32_bf16 v[64:67], v[140:143], v[206:209], v[64:67]
	v_mfma_f32_16x16x32_bf16 v[60:63], v[148:151], v[206:209], v[60:63]
	v_mfma_f32_16x16x32_bf16 v[48:51], v[140:143], v[216:219], v[48:51]
	v_mfma_f32_16x16x32_bf16 v[44:47], v[148:151], v[216:219], v[44:47]
	v_mfma_f32_16x16x32_bf16 v[32:35], v[140:143], v[224:227], v[32:35]
	v_mfma_f32_16x16x32_bf16 v[28:31], v[148:151], v[224:227], v[28:31]
	v_mfma_f32_16x16x32_bf16 v[16:19], v[140:143], v[232:235], v[16:19]
	v_mfma_f32_16x16x32_bf16 v[12:15], v[148:151], v[232:235], v[12:15]
	v_mfma_f32_16x16x32_bf16 v[56:59], v[152:155], v[194:197], v[56:59]
	v_mfma_f32_16x16x32_bf16 v[52:55], v[186:189], v[194:197], v[52:55]
	v_mfma_f32_16x16x32_bf16 v[40:43], v[152:155], v[210:213], v[40:43]
	v_mfma_f32_16x16x32_bf16 v[36:39], v[186:189], v[210:213], v[36:39]
	v_mfma_f32_16x16x32_bf16 v[24:27], v[152:155], v[220:223], v[24:27]
	v_mfma_f32_16x16x32_bf16 v[20:23], v[186:189], v[220:223], v[20:23]
	v_mfma_f32_16x16x32_bf16 v[8:11], v[152:155], v[228:231], v[8:11]
	v_mfma_f32_16x16x32_bf16 v[4:7], v[186:189], v[228:231], v[4:7]
	v_mfma_f32_16x16x32_bf16 v[56:59], v[182:185], v[206:209], v[56:59]
	v_mfma_f32_16x16x32_bf16 v[52:55], v[190:193], v[206:209], v[52:55]
	v_mfma_f32_16x16x32_bf16 v[40:43], v[182:185], v[216:219], v[40:43]
	v_mfma_f32_16x16x32_bf16 v[36:39], v[190:193], v[216:219], v[36:39]
	v_mfma_f32_16x16x32_bf16 v[24:27], v[182:185], v[224:227], v[24:27]
	v_mfma_f32_16x16x32_bf16 v[20:23], v[190:193], v[224:227], v[20:23]
	v_mfma_f32_16x16x32_bf16 v[8:11], v[182:185], v[232:235], v[8:11]
	v_mfma_f32_16x16x32_bf16 v[4:7], v[190:193], v[232:235], v[4:7]
	s_setprio 0
	s_barrier
	v_lshl_add_u64 v[132:133], v[132:133], 0, s[26:27]
	s_cmp_ge_i32 s12, s47
	v_lshl_add_u64 v[134:135], v[134:135], 0, s[26:27]
	s_cbranch_scc0 .LBB0_1340

; #define PG8_STAGE(bufoff, gbase, voff) do { _Pragma("unroll") for (int _i = 0; _i < 2; ++_i) \
;         __builtin_amdgcn_global_load_lds((const unsigned*)((const char*)(gbase) + (voff)[_i]), (PG8_LAS unsigned*)(lds + (bufoff) + ldsw + _i * 8192), 16, 0, 0); } while (0)
; #define PG8_LDA(dst, b, h) do { _Pragma("unroll") for (int m = 0; m < 4; ++m) _Pragma("unroll") for (int k = 0; k < 2; ++k) dst[m][k] = *(const PG8_LAS bf16x8*)(lds + PG8_SA(b, h) + aoff + m * 2048 + k * 1024); } while (0)
; #define PG8_LDB(dst, b, h) do { _Pragma("unroll") for (int n = 0; n < 2; ++n) _Pragma("unroll") for (int k = 0; k < 2; ++k) dst[n][k] = *(const PG8_LAS bf16x8*)(lds + PG8_SB(b, h) + boff + n * 2048 + k * 1024); } while (0)
; #define PG8_MMA(ai, bj, At, Bt) do { __builtin_amdgcn_s_setprio(1); _Pragma("unroll") for (int m = 0; m < 4; ++m) _Pragma("unroll") for (int n = 0; n < 2; ++n) _Pragma("unroll") for (int k = 0; k < 2; ++k) \
;         acc[ai][bj][m][n] = __builtin_amdgcn_mfma_f32_16x16x32_bf16(Bt[n][k], At[m][k], acc[ai][bj][m][n], 0, 0, 0); __builtin_amdgcn_s_setprio(0); } while (0)
; #define PG8_WAIT_V(n) asm volatile("s_waitcnt vmcnt(" #n ")" ::: "memory")
; #define PG8_BAR __builtin_amdgcn_s_barrier()
; template <class Epi, class Sched, bool ALIGN_EPI = false, bool SP2 = false>
; __device__ __forceinline__ void gemm_phase(PG8_LAS unsigned char* lds, const Gemm g, const Sched& S, const Epi& E) {
;     ...
;         for (int t = 0; t < nt; t += 2) {
;             const bool last = (t == nt - 2);
;             const char* a1 = cA + (size_t)(t + 1) * kstep;
;             const char* a2 = last ? nA : cA + (size_t)(t + 2) * kstep; const char* b2 = last ? nB : cB + (size_t)(t + 2) * kstep;
;             const char* a3 = a2 + kstep; const char* b3 = b2 + kstep;
;             if (last && has_next) S.a_ready(nxt);
;             if constexpr (SP2) {
;             PG8_LDB(B0, 0, 0); PG8_LDB(B1, 0, 1); PG8_SCHED; PG8_LDA(At, 0, 0); PG8_STAGE(PG8_SA(1, 1), a1 + hstep, voffA);
;             PG8_WAIT_V(8); PG8_WAIT_L(0); PG8_BAR; PG8_MMA(0, 0, At, B0); PG8_MMA(0, 1, At, B1); PG8_BAR; PG8_SCHED;
;             PG8_LDA(At, 0, 1); PG8_STAGE(PG8_SB(0, 0), b2, voffB); PG8_STAGE(PG8_SB(0, 1), b2 + hstep, voffB); PG8_STAGE(PG8_SA(0, 0), a2, voffA);
;             PG8_WAIT_V(8); PG8_WAIT_L(0); PG8_BAR; PG8_MMA(1, 0, At, B0); PG8_MMA(1, 1, At, B1); PG8_BAR; PG8_SCHED;
.LBB0_1423:
	v_add_u32_e32 v152, s81, v169
	v_add_u32_e32 v165, s82, v169
	ds_read_b128 v[132:135], v152
	ds_read_b128 v[136:139], v152 offset:1024
	ds_read_b128 v[174:177], v152 offset:2048
	ds_read_b128 v[178:181], v152 offset:3072
	ds_read_b128 v[182:185], v165
	ds_read_b128 v[186:189], v165 offset:1024
	ds_read_b128 v[190:193], v165 offset:2048
	ds_read_b128 v[194:197], v165 offset:3072
	s_cmp_eq_u32 s74, s10
	v_lshl_add_u64 v[198:199], v[130:131], 0, s[26:27]
	s_cselect_b64 vcc, -1, 0
	s_add_i32 s10, s10, 2
	v_cndmask_b32_e32 v211, v199, v171, vcc
	v_cndmask_b32_e32 v210, v198, v170, vcc
	v_cndmask_b32_e32 v215, v129, v173, vcc
	v_cndmask_b32_e32 v214, v128, v172, vcc
	v_lshl_add_u64 v[240:241], v[130:131], 0, v[160:161]
	s_add_i32 m0, s47, 0xc000
	ds_read_b128 v[198:201], v213
	ds_read_b128 v[202:205], v213 offset:1024
	ds_read_b128 v[206:209], v213 offset:2048
	ds_read_b128 v[220:223], v213 offset:3072
	ds_read_b128 v[224:227], v213 offset:4096
	ds_read_b128 v[228:231], v213 offset:5120
	ds_read_b128 v[232:235], v213 offset:6144
	ds_read_b128 v[236:239], v213 offset:7168
	global_load_lds_dwordx4 v[240:241], off
	s_add_i32 m0, s47, 0xe000
	v_lshl_add_u64 v[240:241], v[130:131], 0, v[158:159]
	global_load_lds_dwordx4 v[240:241], off
	s_waitcnt vmcnt(8) lgkmcnt(0)
	s_setprio 1
	s_barrier
	v_mfma_f32_16x16x32_bf16 v[124:127], v[132:135], v[198:201], v[124:127]
	v_mfma_f32_16x16x32_bf16 v[120:123], v[174:177], v[198:201], v[120:123]
	v_mfma_f32_16x16x32_bf16 v[108:111], v[132:135], v[206:209], v[108:111]
	v_mfma_f32_16x16x32_bf16 v[104:107], v[174:177], v[206:209], v[104:107]
	v_mfma_f32_16x16x32_bf16 v[92:95], v[132:135], v[224:227], v[92:95]
	v_mfma_f32_16x16x32_bf16 v[88:91], v[174:177], v[224:227], v[88:91]
	v_mfma_f32_16x16x32_bf16 v[76:79], v[132:135], v[232:235], v[76:79]
	v_mfma_f32_16x16x32_bf16 v[72:75], v[174:177], v[232:235], v[72:75]
	v_mfma_f32_16x16x32_bf16 v[124:127], v[136:139], v[202:205], v[124:127]
	v_mfma_f32_16x16x32_bf16 v[120:123], v[178:181], v[202:205], v[120:123]
	v_mfma_f32_16x16x32_bf16 v[108:111], v[136:139], v[220:223], v[108:111]
	v_mfma_f32_16x16x32_bf16 v[104:107], v[178:181], v[220:223], v[104:107]
	v_mfma_f32_16x16x32_bf16 v[92:95], v[136:139], v[228:231], v[92:95]
	v_mfma_f32_16x16x32_bf16 v[88:91], v[178:181], v[228:231], v[88:91]
	v_mfma_f32_16x16x32_bf16 v[76:79], v[136:139], v[236:239], v[76:79]
	v_mfma_f32_16x16x32_bf16 v[72:75], v[178:181], v[236:239], v[72:75]
	s_cmp_eq_u32 s22, 12
	s_cbranch_scc1 .Lio_skipk0
	v_mfma_f32_16x16x32_bf16 v[116:119], v[182:185], v[198:201], v[116:119]
	v_mfma_f32_16x16x32_bf16 v[112:115], v[190:193], v[198:201], v[112:115]
	v_mfma_f32_16x16x32_bf16 v[100:103], v[182:185], v[206:209], v[100:103]
	v_mfma_f32_16x16x32_bf16 v[96:99], v[190:193], v[206:209], v[96:99]
	v_mfma_f32_16x16x32_bf16 v[84:87], v[182:185], v[224:227], v[84:87]
	v_mfma_f32_16x16x32_bf16 v[80:83], v[190:193], v[224:227], v[80:83]
	v_mfma_f32_16x16x32_bf16 v[68:71], v[182:185], v[232:235], v[68:71]
	v_mfma_f32_16x16x32_bf16 v[64:67], v[190:193], v[232:235], v[64:67]
	v_mfma_f32_16x16x32_bf16 v[116:119], v[186:189], v[202:205], v[116:119]
	v_mfma_f32_16x16x32_bf16 v[112:115], v[194:197], v[202:205], v[112:115]
	v_mfma_f32_16x16x32_bf16 v[100:103], v[186:189], v[220:223], v[100:103]
	v_mfma_f32_16x16x32_bf16 v[96:99], v[194:197], v[220:223], v[96:99]
	v_mfma_f32_16x16x32_bf16 v[84:87], v[186:189], v[228:231], v[84:87]
	v_mfma_f32_16x16x32_bf16 v[80:83], v[194:197], v[228:231], v[80:83]
	v_mfma_f32_16x16x32_bf16 v[68:71], v[186:189], v[236:239], v[68:71]
	v_mfma_f32_16x16x32_bf16 v[64:67], v[194:197], v[236:239], v[64:67]
.Lio_skipk0:
	s_setprio 0
	s_barrier
	s_add_i32 s11, s81, s41
	v_lshl_add_u64 v[240:241], v[214:215], 0, v[146:147]
	s_mov_b32 m0, s11
	ds_read_b128 v[198:201], v213 offset:16384
	ds_read_b128 v[202:205], v213 offset:17408
	ds_read_b128 v[206:209], v213 offset:18432
	ds_read_b128 v[220:223], v213 offset:19456
	ds_read_b128 v[224:227], v213 offset:20480
	ds_read_b128 v[228:231], v213 offset:21504
	ds_read_b128 v[232:235], v213 offset:22528
	ds_read_b128 v[236:239], v213 offset:23552
	global_load_lds_dwordx4 v[240:241], off
	v_lshl_add_u64 v[242:243], v[214:215], 0, v[150:151]
	s_add_i32 m0, s11, 0x2000
	v_lshl_add_u64 v[214:215], v[214:215], 0, s[18:19]
	s_add_i32 s11, s82, s41
	global_load_lds_dwordx4 v[242:243], off
	v_lshl_add_u64 v[244:245], v[214:215], 0, v[146:147]
	s_mov_b32 m0, s11
	v_lshl_add_u64 v[214:215], v[214:215], 0, v[150:151]
	global_load_lds_dwordx4 v[244:245], off
	s_add_i32 m0, s11, 0x2000
	v_lshl_add_u64 v[246:247], v[210:211], 0, v[144:145]
	global_load_lds_dwordx4 v[214:215], off
	s_mov_b32 m0, s47
	v_lshl_add_u64 v[248:249], v[210:211], 0, v[148:149]
	global_load_lds_dwordx4 v[246:247], off
	s_mov_b32 m0, s55
	s_nop 0
	global_load_lds_dwordx4 v[248:249], off
	s_waitcnt vmcnt(8) lgkmcnt(0)
	s_setprio 1
	s_barrier
	v_mfma_f32_16x16x32_bf16 v[60:63], v[132:135], v[198:201], v[60:63]
	v_mfma_f32_16x16x32_bf16 v[56:59], v[174:177], v[198:201], v[56:59]
	v_mfma_f32_16x16x32_bf16 v[44:47], v[132:135], v[206:209], v[44:47]
	v_mfma_f32_16x16x32_bf16 v[40:43], v[174:177], v[206:209], v[40:43]
	v_mfma_f32_16x16x32_bf16 v[28:31], v[132:135], v[224:227], v[28:31]
	v_mfma_f32_16x16x32_bf16 v[24:27], v[174:177], v[224:227], v[24:27]
	v_mfma_f32_16x16x32_bf16 v[12:15], v[132:135], v[232:235], v[12:15]
	v_mfma_f32_16x16x32_bf16 v[8:11], v[174:177], v[232:235], v[8:11]
	v_mfma_f32_16x16x32_bf16 v[60:63], v[136:139], v[202:205], v[60:63]
	v_mfma_f32_16x16x32_bf16 v[56:59], v[178:181], v[202:205], v[56:59]
	v_mfma_f32_16x16x32_bf16 v[44:47], v[136:139], v[220:223], v[44:47]
	v_mfma_f32_16x16x32_bf16 v[40:43], v[178:181], v[220:223], v[40:43]
	v_mfma_f32_16x16x32_bf16 v[28:31], v[136:139], v[228:231], v[28:31]
	v_mfma_f32_16x16x32_bf16 v[24:27], v[178:181], v[228:231], v[24:27]
	v_mfma_f32_16x16x32_bf16 v[12:15], v[136:139], v[236:239], v[12:15]
	v_mfma_f32_16x16x32_bf16 v[8:11], v[178:181], v[236:239], v[8:11]
	s_cmp_eq_u32 s22, 12
	s_cbranch_scc1 .Lio_skipk1
; #define PG8_STAGE(bufoff, gbase, voff) do { _Pragma("unroll") for (int _i = 0; _i < 2; ++_i) \
;         __builtin_amdgcn_global_load_lds((const unsigned*)((const char*)(gbase) + (voff)[_i]), (PG8_LAS unsigned*)(lds + (bufoff) + ldsw + _i * 8192), 16, 0, 0); } while (0)
; #define PG8_LDA(dst, b, h) do { _Pragma("unroll") for (int m = 0; m < 4; ++m) _Pragma("unroll") for (int k = 0; k < 2; ++k) dst[m][k] = *(const PG8_LAS bf16x8*)(lds + PG8_SA(b, h) + aoff + m * 2048 + k * 1024); } while (0)
; #define PG8_LDB(dst, b, h) do { _Pragma("unroll") for (int n = 0; n < 2; ++n) _Pragma("unroll") for (int k = 0; k < 2; ++k) dst[n][k] = *(const PG8_LAS bf16x8*)(lds + PG8_SB(b, h) + boff + n * 2048 + k * 1024); } while (0)
; #define PG8_MMA(ai, bj, At, Bt) do { __builtin_amdgcn_s_setprio(1); _Pragma("unroll") for (int m = 0; m < 4; ++m) _Pragma("unroll") for (int n = 0; n < 2; ++n) _Pragma("unroll") for (int k = 0; k < 2; ++k) \
;         acc[ai][bj][m][n] = __builtin_amdgcn_mfma_f32_16x16x32_bf16(Bt[n][k], At[m][k], acc[ai][bj][m][n], 0, 0, 0); __builtin_amdgcn_s_setprio(0); } while (0)
; #define PG8_WAIT_V(n) asm volatile("s_waitcnt vmcnt(" #n ")" ::: "memory")
; #define PG8_WAIT_L(n) asm volatile("s_waitcnt lgkmcnt(" #n ")" ::: "memory")
; #define PG8_BAR __builtin_amdgcn_s_barrier()
; #define PG8_SCHED __builtin_amdgcn_sched_barrier(0)
; template <class Epi, class Sched, bool ALIGN_EPI = false, bool SP2 = false>
; __device__ __forceinline__ void gemm_phase(PG8_LAS unsigned char* lds, const Gemm g, const Sched& S, const Epi& E) {
;     ...
;             PG8_WAIT_V(8); PG8_WAIT_L(0); PG8_BAR; PG8_MMA(1, 0, At, B0); PG8_MMA(1, 1, At, B1); PG8_BAR; PG8_SCHED;
;             PG8_LDB(B0, 1, 0); PG8_LDB(B1, 1, 1); PG8_SCHED; PG8_LDA(At, 1, 0); PG8_STAGE(PG8_SA(0, 1), a2 + hstep, voffA);
;             PG8_WAIT_V(8); PG8_WAIT_L(0); PG8_BAR; PG8_MMA(0, 0, At, B0); PG8_MMA(0, 1, At, B1); PG8_BAR; PG8_SCHED;
	v_mfma_f32_16x16x32_bf16 v[52:55], v[182:185], v[198:201], v[52:55]
	v_mfma_f32_16x16x32_bf16 v[48:51], v[190:193], v[198:201], v[48:51]
	v_mfma_f32_16x16x32_bf16 v[36:39], v[182:185], v[206:209], v[36:39]
	v_mfma_f32_16x16x32_bf16 v[32:35], v[190:193], v[206:209], v[32:35]
	v_mfma_f32_16x16x32_bf16 v[20:23], v[182:185], v[224:227], v[20:23]
	v_mfma_f32_16x16x32_bf16 v[16:19], v[190:193], v[224:227], v[16:19]
	v_mfma_f32_16x16x32_bf16 v[4:7], v[182:185], v[232:235], v[4:7]
	v_mfma_f32_16x16x32_bf16 v[0:3], v[190:193], v[232:235], v[0:3]
	v_mfma_f32_16x16x32_bf16 v[52:55], v[186:189], v[202:205], v[52:55]
	v_mfma_f32_16x16x32_bf16 v[48:51], v[194:197], v[202:205], v[48:51]
	v_mfma_f32_16x16x32_bf16 v[36:39], v[186:189], v[220:223], v[36:39]
	v_mfma_f32_16x16x32_bf16 v[32:35], v[194:197], v[220:223], v[32:35]
	v_mfma_f32_16x16x32_bf16 v[20:23], v[186:189], v[228:231], v[20:23]
	v_mfma_f32_16x16x32_bf16 v[16:19], v[194:197], v[228:231], v[16:19]
	v_mfma_f32_16x16x32_bf16 v[4:7], v[186:189], v[236:239], v[4:7]
	v_mfma_f32_16x16x32_bf16 v[0:3], v[194:197], v[236:239], v[0:3]
.Lio_skipk1:
	s_setprio 0
	s_barrier
	s_add_i32 s11, 0, 0x18000
	v_add_u32_e32 v152, s11, v169
	s_add_i32 s13, 0, 0x1c000
	ds_read_b128 v[132:135], v152
	ds_read_b128 v[136:139], v152 offset:1024
	ds_read_b128 v[174:177], v152 offset:2048
	ds_read_b128 v[178:181], v152 offset:3072
	v_add_u32_e32 v152, s13, v169
	ds_read_b128 v[182:185], v152
	ds_read_b128 v[186:189], v152 offset:1024
	ds_read_b128 v[190:193], v152 offset:2048
	ds_read_b128 v[194:197], v152 offset:3072
	v_lshl_add_u64 v[210:211], v[210:211], 0, s[18:19]
	s_mov_b32 m0, s57
	v_lshl_add_u64 v[250:251], v[210:211], 0, v[144:145]
	ds_read_b128 v[198:201], v213 offset:32768
	ds_read_b128 v[202:205], v213 offset:33792
	ds_read_b128 v[206:209], v213 offset:34816
	ds_read_b128 v[220:223], v213 offset:35840
	ds_read_b128 v[224:227], v213 offset:36864
	ds_read_b128 v[228:231], v213 offset:37888
	ds_read_b128 v[232:235], v213 offset:38912
	ds_read_b128 v[236:239], v213 offset:39936
	global_load_lds_dwordx4 v[250:251], off
	s_mov_b32 m0, s59
	v_lshl_add_u64 v[210:211], v[210:211], 0, v[148:149]
	global_load_lds_dwordx4 v[210:211], off
	s_waitcnt vmcnt(8) lgkmcnt(0)
	s_setprio 1
	s_barrier
	v_mfma_f32_16x16x32_bf16 v[124:127], v[132:135], v[198:201], v[124:127]
	v_mfma_f32_16x16x32_bf16 v[120:123], v[174:177], v[198:201], v[120:123]
	v_mfma_f32_16x16x32_bf16 v[108:111], v[132:135], v[206:209], v[108:111]
	v_mfma_f32_16x16x32_bf16 v[104:107], v[174:177], v[206:209], v[104:107]
	v_mfma_f32_16x16x32_bf16 v[92:95], v[132:135], v[224:227], v[92:95]
	v_mfma_f32_16x16x32_bf16 v[88:91], v[174:177], v[224:227], v[88:91]
	v_mfma_f32_16x16x32_bf16 v[76:79], v[132:135], v[232:235], v[76:79]
	v_mfma_f32_16x16x32_bf16 v[72:75], v[174:177], v[232:235], v[72:75]
	v_mfma_f32_16x16x32_bf16 v[124:127], v[136:139], v[202:205], v[124:127]
	v_mfma_f32_16x16x32_bf16 v[120:123], v[178:181], v[202:205], v[120:123]
	v_mfma_f32_16x16x32_bf16 v[108:111], v[136:139], v[220:223], v[108:111]
	v_mfma_f32_16x16x32_bf16 v[104:107], v[178:181], v[220:223], v[104:107]
	v_mfma_f32_16x16x32_bf16 v[92:95], v[136:139], v[228:231], v[92:95]
	v_mfma_f32_16x16x32_bf16 v[88:91], v[178:181], v[228:231], v[88:91]
	v_mfma_f32_16x16x32_bf16 v[76:79], v[136:139], v[236:239], v[76:79]
	v_mfma_f32_16x16x32_bf16 v[72:75], v[178:181], v[236:239], v[72:75]
	s_cmp_eq_u32 s22, 12
	s_cbranch_scc1 .Lio_skipk2
	v_mfma_f32_16x16x32_bf16 v[116:119], v[182:185], v[198:201], v[116:119]
	v_mfma_f32_16x16x32_bf16 v[112:115], v[190:193], v[198:201], v[112:115]
	v_mfma_f32_16x16x32_bf16 v[100:103], v[182:185], v[206:209], v[100:103]
	v_mfma_f32_16x16x32_bf16 v[96:99], v[190:193], v[206:209], v[96:99]
	v_mfma_f32_16x16x32_bf16 v[84:87], v[182:185], v[224:227], v[84:87]
	v_mfma_f32_16x16x32_bf16 v[80:83], v[190:193], v[224:227], v[80:83]
	v_mfma_f32_16x16x32_bf16 v[68:71], v[182:185], v[232:235], v[68:71]
	v_mfma_f32_16x16x32_bf16 v[64:67], v[190:193], v[232:235], v[64:67]
	v_mfma_f32_16x16x32_bf16 v[116:119], v[186:189], v[202:205], v[116:119]
	v_mfma_f32_16x16x32_bf16 v[112:115], v[194:197], v[202:205], v[112:115]
	v_mfma_f32_16x16x32_bf16 v[100:103], v[186:189], v[220:223], v[100:103]
	v_mfma_f32_16x16x32_bf16 v[96:99], v[194:197], v[220:223], v[96:99]
	v_mfma_f32_16x16x32_bf16 v[84:87], v[186:189], v[228:231], v[84:87]
	v_mfma_f32_16x16x32_bf16 v[80:83], v[194:197], v[228:231], v[80:83]
	v_mfma_f32_16x16x32_bf16 v[68:71], v[186:189], v[236:239], v[68:71]
	v_mfma_f32_16x16x32_bf16 v[64:67], v[194:197], v[236:239], v[64:67]
; #define PG8_STAGE(bufoff, gbase, voff) do { _Pragma("unroll") for (int _i = 0; _i < 2; ++_i) \
;         __builtin_amdgcn_global_load_lds((const unsigned*)((const char*)(gbase) + (voff)[_i]), (PG8_LAS unsigned*)(lds + (bufoff) + ldsw + _i * 8192), 16, 0, 0); } while (0)
; #define PG8_LDA(dst, b, h) do { _Pragma("unroll") for (int m = 0; m < 4; ++m) _Pragma("unroll") for (int k = 0; k < 2; ++k) dst[m][k] = *(const PG8_LAS bf16x8*)(lds + PG8_SA(b, h) + aoff + m * 2048 + k * 1024); } while (0)
; #define PG8_MMA(ai, bj, At, Bt) do { __builtin_amdgcn_s_setprio(1); _Pragma("unroll") for (int m = 0; m < 4; ++m) _Pragma("unroll") for (int n = 0; n < 2; ++n) _Pragma("unroll") for (int k = 0; k < 2; ++k) \
;         acc[ai][bj][m][n] = __builtin_amdgcn_mfma_f32_16x16x32_bf16(Bt[n][k], At[m][k], acc[ai][bj][m][n], 0, 0, 0); __builtin_amdgcn_s_setprio(0); } while (0)
; #define PG8_WAIT_V(n) asm volatile("s_waitcnt vmcnt(" #n ")" ::: "memory")
; #define PG8_WAIT_L(n) asm volatile("s_waitcnt lgkmcnt(" #n ")" ::: "memory")
; #define PG8_BAR __builtin_amdgcn_s_barrier()
; #define PG8_SCHED __builtin_amdgcn_sched_barrier(0)
; template <class Epi, class Sched, bool ALIGN_EPI = false, bool SP2 = false>
; __device__ __forceinline__ void gemm_phase(PG8_LAS unsigned char* lds, const Gemm g, const Sched& S, const Epi& E) {
;     ...
;             PG8_LDA(At, 1, 1); PG8_STAGE(PG8_SB(1, 0), b3, voffB); PG8_STAGE(PG8_SB(1, 1), b3 + hstep, voffB); PG8_STAGE(PG8_SA(1, 0), a3, voffA);
;             PG8_WAIT_V(8); PG8_WAIT_L(0); PG8_BAR; PG8_MMA(1, 0, At, B0); PG8_MMA(1, 1, At, B1); PG8_BAR; PG8_SCHED;
.Lio_skipk2:
	s_setprio 0
	s_barrier
	s_add_i32 s11, s11, s41
	v_lshl_add_u64 v[210:211], v[240:241], 0, s[26:27]
	s_mov_b32 m0, s11
	ds_read_b128 v[198:201], v213 offset:49152
	ds_read_b128 v[202:205], v213 offset:50176
	ds_read_b128 v[206:209], v213 offset:51200
	ds_read_b128 v[220:223], v213 offset:52224
	ds_read_b128 v[224:227], v213 offset:53248
	ds_read_b128 v[228:231], v213 offset:54272
	ds_read_b128 v[232:235], v213 offset:55296
	ds_read_b128 v[236:239], v213 offset:56320
	global_load_lds_dwordx4 v[210:211], off
	v_lshl_add_u64 v[210:211], v[242:243], 0, s[26:27]
	s_add_i32 m0, s11, 0x2000
	s_add_i32 s11, s13, s41
	global_load_lds_dwordx4 v[210:211], off
	s_mov_b32 m0, s11
	v_lshl_add_u64 v[210:211], v[244:245], 0, s[26:27]
	global_load_lds_dwordx4 v[210:211], off
	s_add_i32 m0, s11, 0x2000
	v_lshl_add_u64 v[210:211], v[214:215], 0, s[26:27]
	global_load_lds_dwordx4 v[210:211], off
	s_mov_b32 m0, s69
	v_lshl_add_u64 v[210:211], v[246:247], 0, s[26:27]
	global_load_lds_dwordx4 v[210:211], off
	s_mov_b32 m0, s70
	v_lshl_add_u64 v[210:211], v[248:249], 0, s[26:27]
	global_load_lds_dwordx4 v[210:211], off
	s_waitcnt vmcnt(8) lgkmcnt(0)
	s_setprio 1
	s_barrier
	v_mfma_f32_16x16x32_bf16 v[60:63], v[132:135], v[198:201], v[60:63]
	v_mfma_f32_16x16x32_bf16 v[56:59], v[174:177], v[198:201], v[56:59]
	v_mfma_f32_16x16x32_bf16 v[44:47], v[132:135], v[206:209], v[44:47]
	v_mfma_f32_16x16x32_bf16 v[40:43], v[174:177], v[206:209], v[40:43]
	v_mfma_f32_16x16x32_bf16 v[28:31], v[132:135], v[224:227], v[28:31]
	v_mfma_f32_16x16x32_bf16 v[24:27], v[174:177], v[224:227], v[24:27]
	v_mfma_f32_16x16x32_bf16 v[12:15], v[132:135], v[232:235], v[12:15]
	v_mfma_f32_16x16x32_bf16 v[8:11], v[174:177], v[232:235], v[8:11]
	v_mfma_f32_16x16x32_bf16 v[60:63], v[136:139], v[202:205], v[60:63]
	v_mfma_f32_16x16x32_bf16 v[56:59], v[178:181], v[202:205], v[56:59]
	v_mfma_f32_16x16x32_bf16 v[44:47], v[136:139], v[220:223], v[44:47]
	v_mfma_f32_16x16x32_bf16 v[40:43], v[178:181], v[220:223], v[40:43]
	v_mfma_f32_16x16x32_bf16 v[28:31], v[136:139], v[228:231], v[28:31]
	v_mfma_f32_16x16x32_bf16 v[24:27], v[178:181], v[228:231], v[24:27]
	v_mfma_f32_16x16x32_bf16 v[12:15], v[136:139], v[236:239], v[12:15]
	v_mfma_f32_16x16x32_bf16 v[8:11], v[178:181], v[236:239], v[8:11]
	s_cmp_eq_u32 s22, 12
	s_cbranch_scc1 .Lio_skipk3
	v_mfma_f32_16x16x32_bf16 v[52:55], v[182:185], v[198:201], v[52:55]
	v_mfma_f32_16x16x32_bf16 v[48:51], v[190:193], v[198:201], v[48:51]
	v_mfma_f32_16x16x32_bf16 v[36:39], v[182:185], v[206:209], v[36:39]
	v_mfma_f32_16x16x32_bf16 v[32:35], v[190:193], v[206:209], v[32:35]
	v_mfma_f32_16x16x32_bf16 v[20:23], v[182:185], v[224:227], v[20:23]
	v_mfma_f32_16x16x32_bf16 v[16:19], v[190:193], v[224:227], v[16:19]
	v_mfma_f32_16x16x32_bf16 v[4:7], v[182:185], v[232:235], v[4:7]
	v_mfma_f32_16x16x32_bf16 v[0:3], v[190:193], v[232:235], v[0:3]
	v_mfma_f32_16x16x32_bf16 v[52:55], v[186:189], v[202:205], v[52:55]
	v_mfma_f32_16x16x32_bf16 v[48:51], v[194:197], v[202:205], v[48:51]
	v_mfma_f32_16x16x32_bf16 v[36:39], v[186:189], v[220:223], v[36:39]
	v_mfma_f32_16x16x32_bf16 v[32:35], v[194:197], v[220:223], v[32:35]
	v_mfma_f32_16x16x32_bf16 v[20:23], v[186:189], v[228:231], v[20:23]
	v_mfma_f32_16x16x32_bf16 v[16:19], v[194:197], v[228:231], v[16:19]
	v_mfma_f32_16x16x32_bf16 v[4:7], v[186:189], v[236:239], v[4:7]
	v_mfma_f32_16x16x32_bf16 v[0:3], v[194:197], v[236:239], v[0:3]

; #define PG8_STAGE(bufoff, gbase, voff) do { _Pragma("unroll") for (int _i = 0; _i < 2; ++_i) \
;         __builtin_amdgcn_global_load_lds((const unsigned*)((const char*)(gbase) + (voff)[_i]), (PG8_LAS unsigned*)(lds + (bufoff) + ldsw + _i * 8192), 16, 0, 0); } while (0)
; #define PG8_LDA(dst, b, h) do { _Pragma("unroll") for (int m = 0; m < 4; ++m) _Pragma("unroll") for (int k = 0; k < 2; ++k) dst[m][k] = *(const PG8_LAS bf16x8*)(lds + PG8_SA(b, h) + aoff + m * 2048 + k * 1024); } while (0)
; #define PG8_LDB(dst, b, h) do { _Pragma("unroll") for (int n = 0; n < 2; ++n) _Pragma("unroll") for (int k = 0; k < 2; ++k) dst[n][k] = *(const PG8_LAS bf16x8*)(lds + PG8_SB(b, h) + boff + n * 2048 + k * 1024); } while (0)
; #define PG8_MMA(ai, bj, At, Bt) do { __builtin_amdgcn_s_setprio(1); _Pragma("unroll") for (int m = 0; m < 4; ++m) _Pragma("unroll") for (int n = 0; n < 2; ++n) _Pragma("unroll") for (int k = 0; k < 2; ++k) \
;         acc[ai][bj][m][n] = __builtin_amdgcn_mfma_f32_16x16x32_bf16(Bt[n][k], At[m][k], acc[ai][bj][m][n], 0, 0, 0); __builtin_amdgcn_s_setprio(0); } while (0)
; #define PG8_WAIT_V(n) asm volatile("s_waitcnt vmcnt(" #n ")" ::: "memory")
; #define PG8_BAR __builtin_amdgcn_s_barrier()
; template <class Epi, class Sched, bool ALIGN_EPI = false, bool SP2 = false>
; __device__ __forceinline__ void gemm_phase(PG8_LAS unsigned char* lds, const Gemm g, const Sched& S, const Epi& E) {
;     ...
;         for (int t = 0; t < nt; t += 2) {
;             const bool last = (t == nt - 2);
;             const char* a1 = cA + (size_t)(t + 1) * kstep;
;             const char* a2 = last ? nA : cA + (size_t)(t + 2) * kstep; const char* b2 = last ? nB : cB + (size_t)(t + 2) * kstep;
;             const char* a3 = a2 + kstep; const char* b3 = b2 + kstep;
;             if (last && has_next) S.a_ready(nxt);
;             if constexpr (SP2) {
;             PG8_LDB(B0, 0, 0); PG8_LDB(B1, 0, 1); PG8_SCHED; PG8_LDA(At, 0, 0); PG8_STAGE(PG8_SA(1, 1), a1 + hstep, voffA);
;             PG8_WAIT_V(8); PG8_WAIT_L(0); PG8_BAR; PG8_MMA(0, 0, At, B0); PG8_MMA(0, 1, At, B1); PG8_BAR; PG8_SCHED;
;             PG8_LDA(At, 0, 1); PG8_STAGE(PG8_SB(0, 0), b2, voffB); PG8_STAGE(PG8_SB(0, 1), b2 + hstep, voffB); PG8_STAGE(PG8_SA(0, 0), a2, voffA);
;             PG8_WAIT_V(8); PG8_WAIT_L(0); PG8_BAR; PG8_MMA(1, 0, At, B0); PG8_MMA(1, 1, At, B1); PG8_BAR; PG8_SCHED;
.LBB0_1695:
	v_add_u32_e32 v188, s54, v199
	ds_read_b128 v[132:135], v201
	ds_read_b128 v[136:139], v201 offset:1024
	ds_read_b128 v[140:143], v201 offset:2048
	ds_read_b128 v[144:147], v201 offset:3072
	ds_read_b128 v[148:151], v188
	ds_read_b128 v[180:183], v188 offset:1024
	ds_read_b128 v[184:187], v188 offset:2048
	ds_read_b128 v[188:191], v188 offset:3072
	s_cmp_eq_u32 s48, s12
	v_lshl_add_u64 v[192:193], v[130:131], 0, s[22:23]
	s_cselect_b64 vcc, -1, 0
	s_add_i32 s12, s12, 2
	v_cndmask_b32_e32 v197, v193, v177, vcc
	v_cndmask_b32_e32 v196, v192, v176, vcc
	v_cndmask_b32_e32 v213, v129, v179, vcc
	v_cndmask_b32_e32 v212, v128, v178, vcc
	s_mov_b32 m0, s55
	v_lshl_add_u64 v[214:215], v[130:131], 0, v[172:173]
	ds_read_b128 v[192:195], v202
	ds_read_b128 v[204:207], v202 offset:1024
	ds_read_b128 v[208:211], v202 offset:2048
	ds_read_b128 v[216:219], v202 offset:3072
	ds_read_b128 v[220:223], v202 offset:4096
	ds_read_b128 v[224:227], v202 offset:5120
	ds_read_b128 v[228:231], v202 offset:6144
	ds_read_b128 v[232:235], v202 offset:7168
	global_load_lds_dwordx4 v[214:215], off
	s_mov_b32 m0, s56
	v_lshl_add_u64 v[214:215], v[130:131], 0, v[170:171]
	global_load_lds_dwordx4 v[214:215], off
	s_waitcnt vmcnt(8) lgkmcnt(0)
	s_setprio 1
	s_barrier
	v_mfma_f32_16x16x32_bf16 v[120:123], v[132:135], v[192:195], v[120:123]
	v_mfma_f32_16x16x32_bf16 v[124:127], v[140:143], v[192:195], v[124:127]
	v_mfma_f32_16x16x32_bf16 v[108:111], v[132:135], v[208:211], v[108:111]
	v_mfma_f32_16x16x32_bf16 v[104:107], v[140:143], v[208:211], v[104:107]
	v_mfma_f32_16x16x32_bf16 v[92:95], v[132:135], v[220:223], v[92:95]
	v_mfma_f32_16x16x32_bf16 v[88:91], v[140:143], v[220:223], v[88:91]
	v_mfma_f32_16x16x32_bf16 v[76:79], v[132:135], v[228:231], v[76:79]
	v_mfma_f32_16x16x32_bf16 v[72:75], v[140:143], v[228:231], v[72:75]
	v_mfma_f32_16x16x32_bf16 v[120:123], v[136:139], v[204:207], v[120:123]
	v_mfma_f32_16x16x32_bf16 v[124:127], v[144:147], v[204:207], v[124:127]
	v_mfma_f32_16x16x32_bf16 v[108:111], v[136:139], v[216:219], v[108:111]
	v_mfma_f32_16x16x32_bf16 v[104:107], v[144:147], v[216:219], v[104:107]
	v_mfma_f32_16x16x32_bf16 v[92:95], v[136:139], v[224:227], v[92:95]
	v_mfma_f32_16x16x32_bf16 v[88:91], v[144:147], v[224:227], v[88:91]
	v_mfma_f32_16x16x32_bf16 v[76:79], v[136:139], v[232:235], v[76:79]
	v_mfma_f32_16x16x32_bf16 v[72:75], v[144:147], v[232:235], v[72:75]
	v_mfma_f32_16x16x32_bf16 v[116:119], v[148:151], v[192:195], v[116:119]
	v_mfma_f32_16x16x32_bf16 v[112:115], v[184:187], v[192:195], v[112:115]
	v_mfma_f32_16x16x32_bf16 v[100:103], v[148:151], v[208:211], v[100:103]
	v_mfma_f32_16x16x32_bf16 v[96:99], v[184:187], v[208:211], v[96:99]
	v_mfma_f32_16x16x32_bf16 v[84:87], v[148:151], v[220:223], v[84:87]
	v_mfma_f32_16x16x32_bf16 v[80:83], v[184:187], v[220:223], v[80:83]
	v_mfma_f32_16x16x32_bf16 v[68:71], v[148:151], v[228:231], v[68:71]
	v_mfma_f32_16x16x32_bf16 v[64:67], v[184:187], v[228:231], v[64:67]
	v_mfma_f32_16x16x32_bf16 v[116:119], v[180:183], v[204:207], v[116:119]
	v_mfma_f32_16x16x32_bf16 v[112:115], v[188:191], v[204:207], v[112:115]
	v_mfma_f32_16x16x32_bf16 v[100:103], v[180:183], v[216:219], v[100:103]
	v_mfma_f32_16x16x32_bf16 v[96:99], v[188:191], v[216:219], v[96:99]
	v_mfma_f32_16x16x32_bf16 v[84:87], v[180:183], v[224:227], v[84:87]
	v_mfma_f32_16x16x32_bf16 v[80:83], v[188:191], v[224:227], v[80:83]
	v_mfma_f32_16x16x32_bf16 v[68:71], v[180:183], v[232:235], v[68:71]
	v_mfma_f32_16x16x32_bf16 v[64:67], v[188:191], v[232:235], v[64:67]
	s_setprio 0
	s_barrier
	s_mov_b32 m0, s57
	v_lshl_add_u64 v[214:215], v[212:213], 0, v[164:165]
	ds_read_b128 v[192:195], v202 offset:16384
	ds_read_b128 v[204:207], v202 offset:17408
	ds_read_b128 v[208:211], v202 offset:18432
	ds_read_b128 v[216:219], v202 offset:19456
	ds_read_b128 v[220:223], v202 offset:20480
	ds_read_b128 v[224:227], v202 offset:21504
	ds_read_b128 v[228:231], v202 offset:22528
	ds_read_b128 v[232:235], v202 offset:23552
	global_load_lds_dwordx4 v[214:215], off
	v_lshl_add_u64 v[236:237], v[212:213], 0, v[168:169]
	s_mov_b32 m0, s58
	v_lshl_add_u64 v[212:213], v[212:213], 0, s[14:15]
	s_add_i32 s13, s54, s30
	global_load_lds_dwordx4 v[236:237], off
	v_lshl_add_u64 v[238:239], v[212:213], 0, v[164:165]
	s_mov_b32 m0, s13
	v_lshl_add_u64 v[212:213], v[212:213], 0, v[168:169]
	global_load_lds_dwordx4 v[238:239], off
	s_add_i32 m0, s13, 0x2000
	v_lshl_add_u64 v[240:241], v[196:197], 0, v[162:163]
	global_load_lds_dwordx4 v[212:213], off
	s_mov_b32 m0, s31
	v_lshl_add_u64 v[242:243], v[196:197], 0, v[166:167]
	global_load_lds_dwordx4 v[240:241], off
	s_mov_b32 m0, s34
	s_nop 0
	global_load_lds_dwordx4 v[242:243], off
	s_waitcnt vmcnt(8) lgkmcnt(0)
	s_setprio 1
	s_barrier
; #define PG8_STAGE(bufoff, gbase, voff) do { _Pragma("unroll") for (int _i = 0; _i < 2; ++_i) \
;         __builtin_amdgcn_global_load_lds((const unsigned*)((const char*)(gbase) + (voff)[_i]), (PG8_LAS unsigned*)(lds + (bufoff) + ldsw + _i * 8192), 16, 0, 0); } while (0)
; #define PG8_LDA(dst, b, h) do { _Pragma("unroll") for (int m = 0; m < 4; ++m) _Pragma("unroll") for (int k = 0; k < 2; ++k) dst[m][k] = *(const PG8_LAS bf16x8*)(lds + PG8_SA(b, h) + aoff + m * 2048 + k * 1024); } while (0)
; #define PG8_LDB(dst, b, h) do { _Pragma("unroll") for (int n = 0; n < 2; ++n) _Pragma("unroll") for (int k = 0; k < 2; ++k) dst[n][k] = *(const PG8_LAS bf16x8*)(lds + PG8_SB(b, h) + boff + n * 2048 + k * 1024); } while (0)
; #define PG8_MMA(ai, bj, At, Bt) do { __builtin_amdgcn_s_setprio(1); _Pragma("unroll") for (int m = 0; m < 4; ++m) _Pragma("unroll") for (int n = 0; n < 2; ++n) _Pragma("unroll") for (int k = 0; k < 2; ++k) \
;         acc[ai][bj][m][n] = __builtin_amdgcn_mfma_f32_16x16x32_bf16(Bt[n][k], At[m][k], acc[ai][bj][m][n], 0, 0, 0); __builtin_amdgcn_s_setprio(0); } while (0)
; #define PG8_WAIT_V(n) asm volatile("s_waitcnt vmcnt(" #n ")" ::: "memory")
; #define PG8_WAIT_L(n) asm volatile("s_waitcnt lgkmcnt(" #n ")" ::: "memory")
; #define PG8_BAR __builtin_amdgcn_s_barrier()
; #define PG8_SCHED __builtin_amdgcn_sched_barrier(0)
; template <class Epi, class Sched, bool ALIGN_EPI = false, bool SP2 = false>
; __device__ __forceinline__ void gemm_phase(PG8_LAS unsigned char* lds, const Gemm g, const Sched& S, const Epi& E) {
;     ...
;             PG8_WAIT_V(8); PG8_WAIT_L(0); PG8_BAR; PG8_MMA(1, 0, At, B0); PG8_MMA(1, 1, At, B1); PG8_BAR; PG8_SCHED;
;             PG8_LDB(B0, 1, 0); PG8_LDB(B1, 1, 1); PG8_SCHED; PG8_LDA(At, 1, 0); PG8_STAGE(PG8_SA(0, 1), a2 + hstep, voffA);
;             PG8_WAIT_V(8); PG8_WAIT_L(0); PG8_BAR; PG8_MMA(0, 0, At, B0); PG8_MMA(0, 1, At, B1); PG8_BAR; PG8_SCHED;
	v_mfma_f32_16x16x32_bf16 v[60:63], v[132:135], v[192:195], v[60:63]
	v_mfma_f32_16x16x32_bf16 v[56:59], v[140:143], v[192:195], v[56:59]
	v_mfma_f32_16x16x32_bf16 v[44:47], v[132:135], v[208:211], v[44:47]
	v_mfma_f32_16x16x32_bf16 v[40:43], v[140:143], v[208:211], v[40:43]
	v_mfma_f32_16x16x32_bf16 v[28:31], v[132:135], v[220:223], v[28:31]
	v_mfma_f32_16x16x32_bf16 v[24:27], v[140:143], v[220:223], v[24:27]
	v_mfma_f32_16x16x32_bf16 v[12:15], v[132:135], v[228:231], v[12:15]
	v_mfma_f32_16x16x32_bf16 v[8:11], v[140:143], v[228:231], v[8:11]
	v_mfma_f32_16x16x32_bf16 v[60:63], v[136:139], v[204:207], v[60:63]
	v_mfma_f32_16x16x32_bf16 v[56:59], v[144:147], v[204:207], v[56:59]
	v_mfma_f32_16x16x32_bf16 v[44:47], v[136:139], v[216:219], v[44:47]
	v_mfma_f32_16x16x32_bf16 v[40:43], v[144:147], v[216:219], v[40:43]
	v_mfma_f32_16x16x32_bf16 v[28:31], v[136:139], v[224:227], v[28:31]
	v_mfma_f32_16x16x32_bf16 v[24:27], v[144:147], v[224:227], v[24:27]
	v_mfma_f32_16x16x32_bf16 v[12:15], v[136:139], v[232:235], v[12:15]
	v_mfma_f32_16x16x32_bf16 v[8:11], v[144:147], v[232:235], v[8:11]
	v_mfma_f32_16x16x32_bf16 v[52:55], v[148:151], v[192:195], v[52:55]
	v_mfma_f32_16x16x32_bf16 v[48:51], v[184:187], v[192:195], v[48:51]
	v_mfma_f32_16x16x32_bf16 v[36:39], v[148:151], v[208:211], v[36:39]
	v_mfma_f32_16x16x32_bf16 v[32:35], v[184:187], v[208:211], v[32:35]
	v_mfma_f32_16x16x32_bf16 v[20:23], v[148:151], v[220:223], v[20:23]
	v_mfma_f32_16x16x32_bf16 v[16:19], v[184:187], v[220:223], v[16:19]
	v_mfma_f32_16x16x32_bf16 v[4:7], v[148:151], v[228:231], v[4:7]
	v_mfma_f32_16x16x32_bf16 v[0:3], v[184:187], v[228:231], v[0:3]
	v_mfma_f32_16x16x32_bf16 v[52:55], v[180:183], v[204:207], v[52:55]
	v_mfma_f32_16x16x32_bf16 v[48:51], v[188:191], v[204:207], v[48:51]
	v_mfma_f32_16x16x32_bf16 v[36:39], v[180:183], v[216:219], v[36:39]
	v_mfma_f32_16x16x32_bf16 v[32:35], v[188:191], v[216:219], v[32:35]
	v_mfma_f32_16x16x32_bf16 v[20:23], v[180:183], v[224:227], v[20:23]
	v_mfma_f32_16x16x32_bf16 v[16:19], v[188:191], v[224:227], v[16:19]
	v_mfma_f32_16x16x32_bf16 v[4:7], v[180:183], v[232:235], v[4:7]
	v_mfma_f32_16x16x32_bf16 v[0:3], v[188:191], v[232:235], v[0:3]
	s_setprio 0
	s_barrier
	s_add_i32 s13, 0, 0x18000
	s_add_i32 s29, 0, 0x1c000
	v_add_u32_e32 v144, s13, v199
	v_add_u32_e32 v188, s29, v199
	ds_read_b128 v[132:135], v144
	ds_read_b128 v[136:139], v144 offset:1024
	ds_read_b128 v[140:143], v144 offset:2048
	ds_read_b128 v[144:147], v144 offset:3072
	ds_read_b128 v[148:151], v188
	ds_read_b128 v[180:183], v188 offset:1024
	ds_read_b128 v[184:187], v188 offset:2048
	ds_read_b128 v[188:191], v188 offset:3072
	v_lshl_add_u64 v[196:197], v[196:197], 0, s[14:15]
	s_mov_b32 m0, s35
	v_lshl_add_u64 v[244:245], v[196:197], 0, v[162:163]
	ds_read_b128 v[192:195], v202 offset:32768
	ds_read_b128 v[204:207], v202 offset:33792
	ds_read_b128 v[208:211], v202 offset:34816
	ds_read_b128 v[216:219], v202 offset:35840
	ds_read_b128 v[220:223], v202 offset:36864
	ds_read_b128 v[224:227], v202 offset:37888
	ds_read_b128 v[228:231], v202 offset:38912
	ds_read_b128 v[232:235], v202 offset:39936
	global_load_lds_dwordx4 v[244:245], off
	s_mov_b32 m0, s36
	v_lshl_add_u64 v[196:197], v[196:197], 0, v[166:167]
	global_load_lds_dwordx4 v[196:197], off
	s_waitcnt vmcnt(8) lgkmcnt(0)
	s_setprio 1
	s_barrier
	v_mfma_f32_16x16x32_bf16 v[120:123], v[132:135], v[192:195], v[120:123]
	v_mfma_f32_16x16x32_bf16 v[124:127], v[140:143], v[192:195], v[124:127]
	v_mfma_f32_16x16x32_bf16 v[108:111], v[132:135], v[208:211], v[108:111]
	v_mfma_f32_16x16x32_bf16 v[104:107], v[140:143], v[208:211], v[104:107]
	v_mfma_f32_16x16x32_bf16 v[92:95], v[132:135], v[220:223], v[92:95]
	v_mfma_f32_16x16x32_bf16 v[88:91], v[140:143], v[220:223], v[88:91]
	v_mfma_f32_16x16x32_bf16 v[76:79], v[132:135], v[228:231], v[76:79]
	v_mfma_f32_16x16x32_bf16 v[72:75], v[140:143], v[228:231], v[72:75]
	v_mfma_f32_16x16x32_bf16 v[120:123], v[136:139], v[204:207], v[120:123]
	v_mfma_f32_16x16x32_bf16 v[124:127], v[144:147], v[204:207], v[124:127]
	v_mfma_f32_16x16x32_bf16 v[108:111], v[136:139], v[216:219], v[108:111]
	v_mfma_f32_16x16x32_bf16 v[104:107], v[144:147], v[216:219], v[104:107]
	v_mfma_f32_16x16x32_bf16 v[92:95], v[136:139], v[224:227], v[92:95]
	v_mfma_f32_16x16x32_bf16 v[88:91], v[144:147], v[224:227], v[88:91]
	v_mfma_f32_16x16x32_bf16 v[76:79], v[136:139], v[232:235], v[76:79]
	v_mfma_f32_16x16x32_bf16 v[72:75], v[144:147], v[232:235], v[72:75]
	v_mfma_f32_16x16x32_bf16 v[116:119], v[148:151], v[192:195], v[116:119]
	v_mfma_f32_16x16x32_bf16 v[112:115], v[184:187], v[192:195], v[112:115]
	v_mfma_f32_16x16x32_bf16 v[100:103], v[148:151], v[208:211], v[100:103]
	v_mfma_f32_16x16x32_bf16 v[96:99], v[184:187], v[208:211], v[96:99]
	v_mfma_f32_16x16x32_bf16 v[84:87], v[148:151], v[220:223], v[84:87]
	v_mfma_f32_16x16x32_bf16 v[80:83], v[184:187], v[220:223], v[80:83]
	v_mfma_f32_16x16x32_bf16 v[68:71], v[148:151], v[228:231], v[68:71]
	v_mfma_f32_16x16x32_bf16 v[64:67], v[184:187], v[228:231], v[64:67]
	v_mfma_f32_16x16x32_bf16 v[116:119], v[180:183], v[204:207], v[116:119]
	v_mfma_f32_16x16x32_bf16 v[112:115], v[188:191], v[204:207], v[112:115]
	v_mfma_f32_16x16x32_bf16 v[100:103], v[180:183], v[216:219], v[100:103]
	v_mfma_f32_16x16x32_bf16 v[96:99], v[188:191], v[216:219], v[96:99]
	v_mfma_f32_16x16x32_bf16 v[84:87], v[180:183], v[224:227], v[84:87]
	v_mfma_f32_16x16x32_bf16 v[80:83], v[188:191], v[224:227], v[80:83]
	v_mfma_f32_16x16x32_bf16 v[68:71], v[180:183], v[232:235], v[68:71]
	v_mfma_f32_16x16x32_bf16 v[64:67], v[188:191], v[232:235], v[64:67]
	s_setprio 0
	s_barrier
; #define PG8_STAGE(bufoff, gbase, voff) do { _Pragma("unroll") for (int _i = 0; _i < 2; ++_i) \
;         __builtin_amdgcn_global_load_lds((const unsigned*)((const char*)(gbase) + (voff)[_i]), (PG8_LAS unsigned*)(lds + (bufoff) + ldsw + _i * 8192), 16, 0, 0); } while (0)
; #define PG8_LDA(dst, b, h) do { _Pragma("unroll") for (int m = 0; m < 4; ++m) _Pragma("unroll") for (int k = 0; k < 2; ++k) dst[m][k] = *(const PG8_LAS bf16x8*)(lds + PG8_SA(b, h) + aoff + m * 2048 + k * 1024); } while (0)
; #define PG8_MMA(ai, bj, At, Bt) do { __builtin_amdgcn_s_setprio(1); _Pragma("unroll") for (int m = 0; m < 4; ++m) _Pragma("unroll") for (int n = 0; n < 2; ++n) _Pragma("unroll") for (int k = 0; k < 2; ++k) \
;         acc[ai][bj][m][n] = __builtin_amdgcn_mfma_f32_16x16x32_bf16(Bt[n][k], At[m][k], acc[ai][bj][m][n], 0, 0, 0); __builtin_amdgcn_s_setprio(0); } while (0)
; #define PG8_WAIT_V(n) asm volatile("s_waitcnt vmcnt(" #n ")" ::: "memory")
; #define PG8_WAIT_L(n) asm volatile("s_waitcnt lgkmcnt(" #n ")" ::: "memory")
; #define PG8_BAR __builtin_amdgcn_s_barrier()
; #define PG8_SCHED __builtin_amdgcn_sched_barrier(0)
; template <class Epi, class Sched, bool ALIGN_EPI = false, bool SP2 = false>
; __device__ __forceinline__ void gemm_phase(PG8_LAS unsigned char* lds, const Gemm g, const Sched& S, const Epi& E) {
;     ...
;             PG8_LDA(At, 1, 1); PG8_STAGE(PG8_SB(1, 0), b3, voffB); PG8_STAGE(PG8_SB(1, 1), b3 + hstep, voffB); PG8_STAGE(PG8_SA(1, 0), a3, voffA);
;             PG8_WAIT_V(8); PG8_WAIT_L(0); PG8_BAR; PG8_MMA(1, 0, At, B0); PG8_MMA(1, 1, At, B1); PG8_BAR; PG8_SCHED;
	s_add_i32 s13, s13, s30
	v_lshl_add_u64 v[196:197], v[214:215], 0, s[22:23]
	s_mov_b32 m0, s13
	ds_read_b128 v[192:195], v202 offset:49152
	ds_read_b128 v[204:207], v202 offset:50176
	ds_read_b128 v[208:211], v202 offset:51200
	ds_read_b128 v[216:219], v202 offset:52224
	ds_read_b128 v[220:223], v202 offset:53248
	ds_read_b128 v[224:227], v202 offset:54272
	ds_read_b128 v[228:231], v202 offset:55296
	ds_read_b128 v[232:235], v202 offset:56320
	global_load_lds_dwordx4 v[196:197], off
	v_lshl_add_u64 v[196:197], v[236:237], 0, s[22:23]
	s_add_i32 m0, s13, 0x2000
	s_add_i32 s13, s29, s30
	global_load_lds_dwordx4 v[196:197], off
	s_mov_b32 m0, s13
	v_lshl_add_u64 v[196:197], v[238:239], 0, s[22:23]
	global_load_lds_dwordx4 v[196:197], off
	s_add_i32 m0, s13, 0x2000
	v_lshl_add_u64 v[196:197], v[212:213], 0, s[22:23]
	global_load_lds_dwordx4 v[196:197], off
	s_mov_b32 m0, s37
	v_lshl_add_u64 v[196:197], v[240:241], 0, s[22:23]
	global_load_lds_dwordx4 v[196:197], off
	s_mov_b32 m0, s41
	v_lshl_add_u64 v[196:197], v[242:243], 0, s[22:23]
	global_load_lds_dwordx4 v[196:197], off
	s_waitcnt vmcnt(8) lgkmcnt(0)
	s_setprio 1
	s_barrier
	v_mfma_f32_16x16x32_bf16 v[60:63], v[132:135], v[192:195], v[60:63]
	v_mfma_f32_16x16x32_bf16 v[56:59], v[140:143], v[192:195], v[56:59]
	v_mfma_f32_16x16x32_bf16 v[44:47], v[132:135], v[208:211], v[44:47]
	v_mfma_f32_16x16x32_bf16 v[40:43], v[140:143], v[208:211], v[40:43]
	v_mfma_f32_16x16x32_bf16 v[28:31], v[132:135], v[220:223], v[28:31]
	v_mfma_f32_16x16x32_bf16 v[24:27], v[140:143], v[220:223], v[24:27]
	v_mfma_f32_16x16x32_bf16 v[12:15], v[132:135], v[228:231], v[12:15]
	v_mfma_f32_16x16x32_bf16 v[8:11], v[140:143], v[228:231], v[8:11]
	v_mfma_f32_16x16x32_bf16 v[60:63], v[136:139], v[204:207], v[60:63]
	v_mfma_f32_16x16x32_bf16 v[56:59], v[144:147], v[204:207], v[56:59]
	v_mfma_f32_16x16x32_bf16 v[44:47], v[136:139], v[216:219], v[44:47]
	v_mfma_f32_16x16x32_bf16 v[40:43], v[144:147], v[216:219], v[40:43]
	v_mfma_f32_16x16x32_bf16 v[28:31], v[136:139], v[224:227], v[28:31]
	v_mfma_f32_16x16x32_bf16 v[24:27], v[144:147], v[224:227], v[24:27]
	v_mfma_f32_16x16x32_bf16 v[12:15], v[136:139], v[232:235], v[12:15]
	v_mfma_f32_16x16x32_bf16 v[8:11], v[144:147], v[232:235], v[8:11]
	v_mfma_f32_16x16x32_bf16 v[52:55], v[148:151], v[192:195], v[52:55]
	v_mfma_f32_16x16x32_bf16 v[48:51], v[184:187], v[192:195], v[48:51]
	v_mfma_f32_16x16x32_bf16 v[36:39], v[148:151], v[208:211], v[36:39]
	v_mfma_f32_16x16x32_bf16 v[32:35], v[184:187], v[208:211], v[32:35]
	v_mfma_f32_16x16x32_bf16 v[20:23], v[148:151], v[220:223], v[20:23]
	v_mfma_f32_16x16x32_bf16 v[16:19], v[184:187], v[220:223], v[16:19]
	v_mfma_f32_16x16x32_bf16 v[4:7], v[148:151], v[228:231], v[4:7]
	v_mfma_f32_16x16x32_bf16 v[0:3], v[184:187], v[228:231], v[0:3]
	v_mfma_f32_16x16x32_bf16 v[52:55], v[180:183], v[204:207], v[52:55]
	v_mfma_f32_16x16x32_bf16 v[48:51], v[188:191], v[204:207], v[48:51]
	v_mfma_f32_16x16x32_bf16 v[36:39], v[180:183], v[216:219], v[36:39]
	v_mfma_f32_16x16x32_bf16 v[32:35], v[188:191], v[216:219], v[32:35]
	v_mfma_f32_16x16x32_bf16 v[20:23], v[180:183], v[224:227], v[20:23]
	v_mfma_f32_16x16x32_bf16 v[16:19], v[188:191], v[224:227], v[16:19]
	v_mfma_f32_16x16x32_bf16 v[4:7], v[180:183], v[232:235], v[4:7]
	v_mfma_f32_16x16x32_bf16 v[0:3], v[188:191], v[232:235], v[0:3]
	s_setprio 0
	s_barrier
	v_lshl_add_u64 v[128:129], v[128:129], 0, s[26:27]
	s_cmp_ge_i32 s12, s47
	v_lshl_add_u64 v[130:131], v[130:131], 0, s[26:27]
	s_cbranch_scc0 .LBB0_1695

; #define PG8_STAGE(bufoff, gbase, voff) do { _Pragma("unroll") for (int _i = 0; _i < 2; ++_i) \
;         __builtin_amdgcn_global_load_lds((const unsigned*)((const char*)(gbase) + (voff)[_i]), (PG8_LAS unsigned*)(lds + (bufoff) + ldsw + _i * 8192), 16, 0, 0); } while (0)
; #define PG8_LDA(dst, b, h) do { _Pragma("unroll") for (int m = 0; m < 4; ++m) _Pragma("unroll") for (int k = 0; k < 2; ++k) dst[m][k] = *(const PG8_LAS bf16x8*)(lds + PG8_SA(b, h) + aoff + m * 2048 + k * 1024); } while (0)
; #define PG8_LDB(dst, b, h) do { _Pragma("unroll") for (int n = 0; n < 2; ++n) _Pragma("unroll") for (int k = 0; k < 2; ++k) dst[n][k] = *(const PG8_LAS bf16x8*)(lds + PG8_SB(b, h) + boff + n * 2048 + k * 1024); } while (0)
; #define PG8_MMA(ai, bj, At, Bt) do { __builtin_amdgcn_s_setprio(1); _Pragma("unroll") for (int m = 0; m < 4; ++m) _Pragma("unroll") for (int n = 0; n < 2; ++n) _Pragma("unroll") for (int k = 0; k < 2; ++k) \
;         acc[ai][bj][m][n] = __builtin_amdgcn_mfma_f32_16x16x32_bf16(Bt[n][k], At[m][k], acc[ai][bj][m][n], 0, 0, 0); __builtin_amdgcn_s_setprio(0); } while (0)
; #define PG8_WAIT_V(n) asm volatile("s_waitcnt vmcnt(" #n ")" ::: "memory")
; #define PG8_BAR __builtin_amdgcn_s_barrier()
; template <class Epi, class Sched, bool ALIGN_EPI = false, bool SP2 = false>
; __device__ __forceinline__ void gemm_phase(PG8_LAS unsigned char* lds, const Gemm g, const Sched& S, const Epi& E) {
;     ...
;         for (int t = 0; t < nt; t += 2) {
;             const bool last = (t == nt - 2);
;             const char* a1 = cA + (size_t)(t + 1) * kstep;
;             const char* a2 = last ? nA : cA + (size_t)(t + 2) * kstep; const char* b2 = last ? nB : cB + (size_t)(t + 2) * kstep;
;             const char* a3 = a2 + kstep; const char* b3 = b2 + kstep;
;             if (last && has_next) S.a_ready(nxt);
;             if constexpr (SP2) {
;             PG8_LDB(B0, 0, 0); PG8_LDB(B1, 0, 1); PG8_SCHED; PG8_LDA(At, 0, 0); PG8_STAGE(PG8_SA(1, 1), a1 + hstep, voffA);
;             PG8_WAIT_V(8); PG8_WAIT_L(0); PG8_BAR; PG8_MMA(0, 0, At, B0); PG8_MMA(0, 1, At, B1); PG8_BAR; PG8_SCHED;
;             PG8_LDA(At, 0, 1); PG8_STAGE(PG8_SB(0, 0), b2, voffB); PG8_STAGE(PG8_SB(0, 1), b2 + hstep, voffB); PG8_STAGE(PG8_SA(0, 0), a2, voffA);
;             PG8_WAIT_V(8); PG8_WAIT_L(0); PG8_BAR; PG8_MMA(1, 0, At, B0); PG8_MMA(1, 1, At, B1); PG8_BAR; PG8_SCHED;
.LBB0_1776:
	v_add_u32_e32 v166, s54, v169
	v_add_u32_e32 v168, s55, v169
	ds_read_b128 v[162:165], v166
	ds_read_b128 v[182:185], v166 offset:1024
	ds_read_b128 v[186:189], v166 offset:2048
	ds_read_b128 v[190:193], v166 offset:3072
	ds_read_b128 v[194:197], v168
	ds_read_b128 v[198:201], v168 offset:1024
	ds_read_b128 v[202:205], v168 offset:2048
	ds_read_b128 v[206:209], v168 offset:3072
	s_cmp_eq_u32 s53, s10
	v_lshl_add_u64 v[172:173], v[160:161], 0, s[22:23]
	s_cselect_b64 vcc, -1, 0
	s_add_i32 s10, s10, 2
	v_cndmask_b32_e32 v173, v173, v153, vcc
	v_cndmask_b32_e32 v172, v172, v152, vcc
	v_cndmask_b32_e32 v215, v159, v155, vcc
	v_cndmask_b32_e32 v214, v158, v154, vcc
	s_mov_b32 m0, s56
	v_lshl_add_u64 v[244:245], v[160:161], 0, v[148:149]
	ds_read_b128 v[210:213], v179
	ds_read_b128 v[216:219], v179 offset:1024
	ds_read_b128 v[220:223], v179 offset:2048
	ds_read_b128 v[224:227], v179 offset:3072
	ds_read_b128 v[228:231], v179 offset:4096
	ds_read_b128 v[232:235], v179 offset:5120
	ds_read_b128 v[236:239], v179 offset:6144
	ds_read_b128 v[240:243], v179 offset:7168
	global_load_lds_dwordx4 v[244:245], off
	s_mov_b32 m0, s57
	v_lshl_add_u64 v[244:245], v[160:161], 0, v[146:147]
	global_load_lds_dwordx4 v[244:245], off
	s_waitcnt vmcnt(8) lgkmcnt(0)
	s_setprio 1
	s_barrier
	v_mfma_f32_16x16x32_bf16 v[124:127], v[162:165], v[210:213], v[124:127]
	v_mfma_f32_16x16x32_bf16 v[116:119], v[186:189], v[210:213], v[116:119]
	v_mfma_f32_16x16x32_bf16 v[108:111], v[162:165], v[220:223], v[108:111]
	v_mfma_f32_16x16x32_bf16 v[100:103], v[186:189], v[220:223], v[100:103]
	v_mfma_f32_16x16x32_bf16 v[92:95], v[162:165], v[228:231], v[92:95]
	v_mfma_f32_16x16x32_bf16 v[84:87], v[186:189], v[228:231], v[84:87]
	v_mfma_f32_16x16x32_bf16 v[76:79], v[162:165], v[236:239], v[76:79]
	v_mfma_f32_16x16x32_bf16 v[68:71], v[186:189], v[236:239], v[68:71]
	v_mfma_f32_16x16x32_bf16 v[124:127], v[182:185], v[216:219], v[124:127]
	v_mfma_f32_16x16x32_bf16 v[116:119], v[190:193], v[216:219], v[116:119]
	v_mfma_f32_16x16x32_bf16 v[108:111], v[182:185], v[224:227], v[108:111]
	v_mfma_f32_16x16x32_bf16 v[100:103], v[190:193], v[224:227], v[100:103]
	v_mfma_f32_16x16x32_bf16 v[92:95], v[182:185], v[232:235], v[92:95]
	v_mfma_f32_16x16x32_bf16 v[84:87], v[190:193], v[232:235], v[84:87]
	v_mfma_f32_16x16x32_bf16 v[76:79], v[182:185], v[240:243], v[76:79]
	v_mfma_f32_16x16x32_bf16 v[68:71], v[190:193], v[240:243], v[68:71]
	v_mfma_f32_16x16x32_bf16 v[120:123], v[194:197], v[210:213], v[120:123]
	v_mfma_f32_16x16x32_bf16 v[112:115], v[202:205], v[210:213], v[112:115]
	v_mfma_f32_16x16x32_bf16 v[104:107], v[194:197], v[220:223], v[104:107]
	v_mfma_f32_16x16x32_bf16 v[96:99], v[202:205], v[220:223], v[96:99]
	v_mfma_f32_16x16x32_bf16 v[88:91], v[194:197], v[228:231], v[88:91]
	v_mfma_f32_16x16x32_bf16 v[80:83], v[202:205], v[228:231], v[80:83]
	v_mfma_f32_16x16x32_bf16 v[72:75], v[194:197], v[236:239], v[72:75]
	v_mfma_f32_16x16x32_bf16 v[64:67], v[202:205], v[236:239], v[64:67]
	v_mfma_f32_16x16x32_bf16 v[120:123], v[198:201], v[216:219], v[120:123]
	v_mfma_f32_16x16x32_bf16 v[112:115], v[206:209], v[216:219], v[112:115]
	v_mfma_f32_16x16x32_bf16 v[104:107], v[198:201], v[224:227], v[104:107]
	v_mfma_f32_16x16x32_bf16 v[96:99], v[206:209], v[224:227], v[96:99]
	v_mfma_f32_16x16x32_bf16 v[88:91], v[198:201], v[232:235], v[88:91]
	v_mfma_f32_16x16x32_bf16 v[80:83], v[206:209], v[232:235], v[80:83]
	v_mfma_f32_16x16x32_bf16 v[72:75], v[198:201], v[240:243], v[72:75]
	v_mfma_f32_16x16x32_bf16 v[64:67], v[206:209], v[240:243], v[64:67]
	s_setprio 0
	s_barrier
	s_mov_b32 m0, s60
	v_lshl_add_u64 v[244:245], v[214:215], 0, v[138:139]
	ds_read_b128 v[210:213], v179 offset:16384
	ds_read_b128 v[216:219], v179 offset:17408
	ds_read_b128 v[220:223], v179 offset:18432
	ds_read_b128 v[224:227], v179 offset:19456
	ds_read_b128 v[228:231], v179 offset:20480
	ds_read_b128 v[232:235], v179 offset:21504
	ds_read_b128 v[236:239], v179 offset:22528
	ds_read_b128 v[240:243], v179 offset:23552
	global_load_lds_dwordx4 v[244:245], off
	v_lshl_add_u64 v[246:247], v[214:215], 0, v[134:135]
	s_mov_b32 m0, s61
	v_lshl_add_u64 v[214:215], v[214:215], 0, s[14:15]
	global_load_lds_dwordx4 v[246:247], off
	v_lshl_add_u64 v[248:249], v[214:215], 0, v[138:139]
	s_mov_b32 m0, s62
	v_lshl_add_u64 v[214:215], v[214:215], 0, v[134:135]
	global_load_lds_dwordx4 v[248:249], off
	s_add_i32 m0, s62, 0x2000
	v_lshl_add_u64 v[250:251], v[172:173], 0, v[140:141]
	global_load_lds_dwordx4 v[214:215], off
	s_mov_b32 m0, s46
	v_lshl_add_u64 v[252:253], v[172:173], 0, v[136:137]
	global_load_lds_dwordx4 v[250:251], off
	s_mov_b32 m0, s47
	s_nop 0
	global_load_lds_dwordx4 v[252:253], off
	s_waitcnt vmcnt(8) lgkmcnt(0)
	s_setprio 1
	s_barrier
; #define PG8_STAGE(bufoff, gbase, voff) do { _Pragma("unroll") for (int _i = 0; _i < 2; ++_i) \
;         __builtin_amdgcn_global_load_lds((const unsigned*)((const char*)(gbase) + (voff)[_i]), (PG8_LAS unsigned*)(lds + (bufoff) + ldsw + _i * 8192), 16, 0, 0); } while (0)
; #define PG8_LDA(dst, b, h) do { _Pragma("unroll") for (int m = 0; m < 4; ++m) _Pragma("unroll") for (int k = 0; k < 2; ++k) dst[m][k] = *(const PG8_LAS bf16x8*)(lds + PG8_SA(b, h) + aoff + m * 2048 + k * 1024); } while (0)
; #define PG8_LDB(dst, b, h) do { _Pragma("unroll") for (int n = 0; n < 2; ++n) _Pragma("unroll") for (int k = 0; k < 2; ++k) dst[n][k] = *(const PG8_LAS bf16x8*)(lds + PG8_SB(b, h) + boff + n * 2048 + k * 1024); } while (0)
; #define PG8_MMA(ai, bj, At, Bt) do { __builtin_amdgcn_s_setprio(1); _Pragma("unroll") for (int m = 0; m < 4; ++m) _Pragma("unroll") for (int n = 0; n < 2; ++n) _Pragma("unroll") for (int k = 0; k < 2; ++k) \
;         acc[ai][bj][m][n] = __builtin_amdgcn_mfma_f32_16x16x32_bf16(Bt[n][k], At[m][k], acc[ai][bj][m][n], 0, 0, 0); __builtin_amdgcn_s_setprio(0); } while (0)
; #define PG8_WAIT_V(n) asm volatile("s_waitcnt vmcnt(" #n ")" ::: "memory")
; #define PG8_WAIT_L(n) asm volatile("s_waitcnt lgkmcnt(" #n ")" ::: "memory")
; #define PG8_BAR __builtin_amdgcn_s_barrier()
; #define PG8_SCHED __builtin_amdgcn_sched_barrier(0)
; template <class Epi, class Sched, bool ALIGN_EPI = false, bool SP2 = false>
; __device__ __forceinline__ void gemm_phase(PG8_LAS unsigned char* lds, const Gemm g, const Sched& S, const Epi& E) {
;     ...
;             PG8_WAIT_V(8); PG8_WAIT_L(0); PG8_BAR; PG8_MMA(1, 0, At, B0); PG8_MMA(1, 1, At, B1); PG8_BAR; PG8_SCHED;
;             PG8_LDB(B0, 1, 0); PG8_LDB(B1, 1, 1); PG8_SCHED; PG8_LDA(At, 1, 0); PG8_STAGE(PG8_SA(0, 1), a2 + hstep, voffA);
;             PG8_WAIT_V(8); PG8_WAIT_L(0); PG8_BAR; PG8_MMA(0, 0, At, B0); PG8_MMA(0, 1, At, B1); PG8_BAR; PG8_SCHED;
	v_mfma_f32_16x16x32_bf16 v[60:63], v[162:165], v[210:213], v[60:63]
	v_mfma_f32_16x16x32_bf16 v[52:55], v[186:189], v[210:213], v[52:55]
	v_mfma_f32_16x16x32_bf16 v[44:47], v[162:165], v[220:223], v[44:47]
	v_mfma_f32_16x16x32_bf16 v[36:39], v[186:189], v[220:223], v[36:39]
	v_mfma_f32_16x16x32_bf16 v[28:31], v[162:165], v[228:231], v[28:31]
	v_mfma_f32_16x16x32_bf16 v[20:23], v[186:189], v[228:231], v[20:23]
	v_mfma_f32_16x16x32_bf16 v[12:15], v[162:165], v[236:239], v[12:15]
	v_mfma_f32_16x16x32_bf16 v[4:7], v[186:189], v[236:239], v[4:7]
	v_mfma_f32_16x16x32_bf16 v[60:63], v[182:185], v[216:219], v[60:63]
	v_mfma_f32_16x16x32_bf16 v[52:55], v[190:193], v[216:219], v[52:55]
	v_mfma_f32_16x16x32_bf16 v[44:47], v[182:185], v[224:227], v[44:47]
	v_mfma_f32_16x16x32_bf16 v[36:39], v[190:193], v[224:227], v[36:39]
	v_mfma_f32_16x16x32_bf16 v[28:31], v[182:185], v[232:235], v[28:31]
	v_mfma_f32_16x16x32_bf16 v[20:23], v[190:193], v[232:235], v[20:23]
	v_mfma_f32_16x16x32_bf16 v[12:15], v[182:185], v[240:243], v[12:15]
	v_mfma_f32_16x16x32_bf16 v[4:7], v[190:193], v[240:243], v[4:7]
	v_mfma_f32_16x16x32_bf16 v[56:59], v[194:197], v[210:213], v[56:59]
	v_mfma_f32_16x16x32_bf16 v[48:51], v[202:205], v[210:213], v[48:51]
	v_mfma_f32_16x16x32_bf16 v[40:43], v[194:197], v[220:223], v[40:43]
	v_mfma_f32_16x16x32_bf16 v[32:35], v[202:205], v[220:223], v[32:35]
	v_mfma_f32_16x16x32_bf16 v[24:27], v[194:197], v[228:231], v[24:27]
	v_mfma_f32_16x16x32_bf16 v[16:19], v[202:205], v[228:231], v[16:19]
	v_mfma_f32_16x16x32_bf16 v[8:11], v[194:197], v[236:239], v[8:11]
	v_mfma_f32_16x16x32_bf16 v[0:3], v[202:205], v[236:239], v[0:3]
	v_mfma_f32_16x16x32_bf16 v[56:59], v[198:201], v[216:219], v[56:59]
	v_mfma_f32_16x16x32_bf16 v[48:51], v[206:209], v[216:219], v[48:51]
	v_mfma_f32_16x16x32_bf16 v[40:43], v[198:201], v[224:227], v[40:43]
	v_mfma_f32_16x16x32_bf16 v[32:35], v[206:209], v[224:227], v[32:35]
	v_mfma_f32_16x16x32_bf16 v[24:27], v[198:201], v[232:235], v[24:27]
	v_mfma_f32_16x16x32_bf16 v[16:19], v[206:209], v[232:235], v[16:19]
	v_mfma_f32_16x16x32_bf16 v[8:11], v[198:201], v[240:243], v[8:11]
	v_mfma_f32_16x16x32_bf16 v[0:3], v[206:209], v[240:243], v[0:3]
	s_setprio 0
	s_barrier
	s_add_i32 s11, 0, 0x18000
	v_add_u32_e32 v166, s11, v169
	s_add_i32 s13, 0, 0x1c000
	ds_read_b128 v[162:165], v166
	ds_read_b128 v[182:185], v166 offset:1024
	ds_read_b128 v[186:189], v166 offset:2048
	ds_read_b128 v[190:193], v166 offset:3072
	v_add_u32_e32 v166, s13, v169
	ds_read_b128 v[194:197], v166
	ds_read_b128 v[198:201], v166 offset:1024
	ds_read_b128 v[202:205], v166 offset:2048
	ds_read_b128 v[206:209], v166 offset:3072
	v_lshl_add_u64 v[172:173], v[172:173], 0, s[14:15]
	s_mov_b32 m0, s48
	v_lshl_add_u64 v[170:171], v[172:173], 0, v[140:141]
	ds_read_b128 v[210:213], v179 offset:32768
	ds_read_b128 v[216:219], v179 offset:33792
	ds_read_b128 v[220:223], v179 offset:34816
	ds_read_b128 v[224:227], v179 offset:35840
	ds_read_b128 v[228:231], v179 offset:36864
	ds_read_b128 v[232:235], v179 offset:37888
	ds_read_b128 v[236:239], v179 offset:38912
	ds_read_b128 v[240:243], v179 offset:39936
	global_load_lds_dwordx4 v[170:171], off
	s_mov_b32 m0, s49
	v_lshl_add_u64 v[170:171], v[172:173], 0, v[136:137]
	global_load_lds_dwordx4 v[170:171], off
	s_waitcnt vmcnt(8) lgkmcnt(0)
	s_setprio 1
	s_barrier
	v_mfma_f32_16x16x32_bf16 v[124:127], v[162:165], v[210:213], v[124:127]
	v_mfma_f32_16x16x32_bf16 v[116:119], v[186:189], v[210:213], v[116:119]
	v_mfma_f32_16x16x32_bf16 v[108:111], v[162:165], v[220:223], v[108:111]
	v_mfma_f32_16x16x32_bf16 v[100:103], v[186:189], v[220:223], v[100:103]
	v_mfma_f32_16x16x32_bf16 v[92:95], v[162:165], v[228:231], v[92:95]
	v_mfma_f32_16x16x32_bf16 v[84:87], v[186:189], v[228:231], v[84:87]
	v_mfma_f32_16x16x32_bf16 v[76:79], v[162:165], v[236:239], v[76:79]
	v_mfma_f32_16x16x32_bf16 v[68:71], v[186:189], v[236:239], v[68:71]
	v_mfma_f32_16x16x32_bf16 v[124:127], v[182:185], v[216:219], v[124:127]
	v_mfma_f32_16x16x32_bf16 v[116:119], v[190:193], v[216:219], v[116:119]
	v_mfma_f32_16x16x32_bf16 v[108:111], v[182:185], v[224:227], v[108:111]
	v_mfma_f32_16x16x32_bf16 v[100:103], v[190:193], v[224:227], v[100:103]
	v_mfma_f32_16x16x32_bf16 v[92:95], v[182:185], v[232:235], v[92:95]
	v_mfma_f32_16x16x32_bf16 v[84:87], v[190:193], v[232:235], v[84:87]
	v_mfma_f32_16x16x32_bf16 v[76:79], v[182:185], v[240:243], v[76:79]
	v_mfma_f32_16x16x32_bf16 v[68:71], v[190:193], v[240:243], v[68:71]
	v_mfma_f32_16x16x32_bf16 v[120:123], v[194:197], v[210:213], v[120:123]
	v_mfma_f32_16x16x32_bf16 v[112:115], v[202:205], v[210:213], v[112:115]
	v_mfma_f32_16x16x32_bf16 v[104:107], v[194:197], v[220:223], v[104:107]
	v_mfma_f32_16x16x32_bf16 v[96:99], v[202:205], v[220:223], v[96:99]
	v_mfma_f32_16x16x32_bf16 v[88:91], v[194:197], v[228:231], v[88:91]
	v_mfma_f32_16x16x32_bf16 v[80:83], v[202:205], v[228:231], v[80:83]
	v_mfma_f32_16x16x32_bf16 v[72:75], v[194:197], v[236:239], v[72:75]
	v_mfma_f32_16x16x32_bf16 v[64:67], v[202:205], v[236:239], v[64:67]
	v_mfma_f32_16x16x32_bf16 v[120:123], v[198:201], v[216:219], v[120:123]
	v_mfma_f32_16x16x32_bf16 v[112:115], v[206:209], v[216:219], v[112:115]
	v_mfma_f32_16x16x32_bf16 v[104:107], v[198:201], v[224:227], v[104:107]
	v_mfma_f32_16x16x32_bf16 v[96:99], v[206:209], v[224:227], v[96:99]
	v_mfma_f32_16x16x32_bf16 v[88:91], v[198:201], v[232:235], v[88:91]
	v_mfma_f32_16x16x32_bf16 v[80:83], v[206:209], v[232:235], v[80:83]
	v_mfma_f32_16x16x32_bf16 v[72:75], v[198:201], v[240:243], v[72:75]
	v_mfma_f32_16x16x32_bf16 v[64:67], v[206:209], v[240:243], v[64:67]
	s_setprio 0
	s_barrier
; #define PG8_STAGE(bufoff, gbase, voff) do { _Pragma("unroll") for (int _i = 0; _i < 2; ++_i) \
;         __builtin_amdgcn_global_load_lds((const unsigned*)((const char*)(gbase) + (voff)[_i]), (PG8_LAS unsigned*)(lds + (bufoff) + ldsw + _i * 8192), 16, 0, 0); } while (0)
; #define PG8_LDA(dst, b, h) do { _Pragma("unroll") for (int m = 0; m < 4; ++m) _Pragma("unroll") for (int k = 0; k < 2; ++k) dst[m][k] = *(const PG8_LAS bf16x8*)(lds + PG8_SA(b, h) + aoff + m * 2048 + k * 1024); } while (0)
; #define PG8_MMA(ai, bj, At, Bt) do { __builtin_amdgcn_s_setprio(1); _Pragma("unroll") for (int m = 0; m < 4; ++m) _Pragma("unroll") for (int n = 0; n < 2; ++n) _Pragma("unroll") for (int k = 0; k < 2; ++k) \
;         acc[ai][bj][m][n] = __builtin_amdgcn_mfma_f32_16x16x32_bf16(Bt[n][k], At[m][k], acc[ai][bj][m][n], 0, 0, 0); __builtin_amdgcn_s_setprio(0); } while (0)
; #define PG8_WAIT_V(n) asm volatile("s_waitcnt vmcnt(" #n ")" ::: "memory")
; #define PG8_WAIT_L(n) asm volatile("s_waitcnt lgkmcnt(" #n ")" ::: "memory")
; #define PG8_BAR __builtin_amdgcn_s_barrier()
; #define PG8_SCHED __builtin_amdgcn_sched_barrier(0)
; template <class Epi, class Sched, bool ALIGN_EPI = false, bool SP2 = false>
; __device__ __forceinline__ void gemm_phase(PG8_LAS unsigned char* lds, const Gemm g, const Sched& S, const Epi& E) {
;     ...
;             PG8_LDA(At, 1, 1); PG8_STAGE(PG8_SB(1, 0), b3, voffB); PG8_STAGE(PG8_SB(1, 1), b3 + hstep, voffB); PG8_STAGE(PG8_SA(1, 0), a3, voffA);
;             PG8_WAIT_V(8); PG8_WAIT_L(0); PG8_BAR; PG8_MMA(1, 0, At, B0); PG8_MMA(1, 1, At, B1); PG8_BAR; PG8_SCHED;
	s_add_i32 s11, s11, s29
	v_lshl_add_u64 v[170:171], v[244:245], 0, s[22:23]
	s_mov_b32 m0, s11
	ds_read_b128 v[210:213], v179 offset:49152
	ds_read_b128 v[216:219], v179 offset:50176
	ds_read_b128 v[220:223], v179 offset:51200
	ds_read_b128 v[224:227], v179 offset:52224
	ds_read_b128 v[228:231], v179 offset:53248
	ds_read_b128 v[232:235], v179 offset:54272
	ds_read_b128 v[236:239], v179 offset:55296
	ds_read_b128 v[240:243], v179 offset:56320
	global_load_lds_dwordx4 v[170:171], off
	v_lshl_add_u64 v[170:171], v[246:247], 0, s[22:23]
	s_add_i32 m0, s11, 0x2000
	s_add_i32 s11, s13, s29
	global_load_lds_dwordx4 v[170:171], off
	s_mov_b32 m0, s11
	v_lshl_add_u64 v[170:171], v[248:249], 0, s[22:23]
	global_load_lds_dwordx4 v[170:171], off
	s_add_i32 m0, s11, 0x2000
	v_lshl_add_u64 v[170:171], v[214:215], 0, s[22:23]
	global_load_lds_dwordx4 v[170:171], off
	s_mov_b32 m0, s50
	v_lshl_add_u64 v[170:171], v[250:251], 0, s[22:23]
	global_load_lds_dwordx4 v[170:171], off
	s_mov_b32 m0, s51
	v_lshl_add_u64 v[170:171], v[252:253], 0, s[22:23]
	global_load_lds_dwordx4 v[170:171], off
	s_waitcnt vmcnt(8) lgkmcnt(0)
	s_setprio 1
	s_barrier
	v_mfma_f32_16x16x32_bf16 v[60:63], v[162:165], v[210:213], v[60:63]
	v_mfma_f32_16x16x32_bf16 v[52:55], v[186:189], v[210:213], v[52:55]
	v_mfma_f32_16x16x32_bf16 v[44:47], v[162:165], v[220:223], v[44:47]
	v_mfma_f32_16x16x32_bf16 v[36:39], v[186:189], v[220:223], v[36:39]
	v_mfma_f32_16x16x32_bf16 v[28:31], v[162:165], v[228:231], v[28:31]
	v_mfma_f32_16x16x32_bf16 v[20:23], v[186:189], v[228:231], v[20:23]
	v_mfma_f32_16x16x32_bf16 v[12:15], v[162:165], v[236:239], v[12:15]
	v_mfma_f32_16x16x32_bf16 v[4:7], v[186:189], v[236:239], v[4:7]
	v_mfma_f32_16x16x32_bf16 v[60:63], v[182:185], v[216:219], v[60:63]
	v_mfma_f32_16x16x32_bf16 v[52:55], v[190:193], v[216:219], v[52:55]
	v_mfma_f32_16x16x32_bf16 v[44:47], v[182:185], v[224:227], v[44:47]
	v_mfma_f32_16x16x32_bf16 v[36:39], v[190:193], v[224:227], v[36:39]
	v_mfma_f32_16x16x32_bf16 v[28:31], v[182:185], v[232:235], v[28:31]
	v_mfma_f32_16x16x32_bf16 v[20:23], v[190:193], v[232:235], v[20:23]
	v_mfma_f32_16x16x32_bf16 v[12:15], v[182:185], v[240:243], v[12:15]
	v_mfma_f32_16x16x32_bf16 v[4:7], v[190:193], v[240:243], v[4:7]
	v_mfma_f32_16x16x32_bf16 v[56:59], v[194:197], v[210:213], v[56:59]
	v_mfma_f32_16x16x32_bf16 v[48:51], v[202:205], v[210:213], v[48:51]
	v_mfma_f32_16x16x32_bf16 v[40:43], v[194:197], v[220:223], v[40:43]
	v_mfma_f32_16x16x32_bf16 v[32:35], v[202:205], v[220:223], v[32:35]
	v_mfma_f32_16x16x32_bf16 v[24:27], v[194:197], v[228:231], v[24:27]
	v_mfma_f32_16x16x32_bf16 v[16:19], v[202:205], v[228:231], v[16:19]
	v_mfma_f32_16x16x32_bf16 v[8:11], v[194:197], v[236:239], v[8:11]
	v_mfma_f32_16x16x32_bf16 v[0:3], v[202:205], v[236:239], v[0:3]
	v_mfma_f32_16x16x32_bf16 v[56:59], v[198:201], v[216:219], v[56:59]
	v_mfma_f32_16x16x32_bf16 v[48:51], v[206:209], v[216:219], v[48:51]
	v_mfma_f32_16x16x32_bf16 v[40:43], v[198:201], v[224:227], v[40:43]
	v_mfma_f32_16x16x32_bf16 v[32:35], v[206:209], v[224:227], v[32:35]
	v_mfma_f32_16x16x32_bf16 v[24:27], v[198:201], v[232:235], v[24:27]
	v_mfma_f32_16x16x32_bf16 v[16:19], v[206:209], v[232:235], v[16:19]
	v_mfma_f32_16x16x32_bf16 v[8:11], v[198:201], v[240:243], v[8:11]
	v_mfma_f32_16x16x32_bf16 v[0:3], v[206:209], v[240:243], v[0:3]
	s_setprio 0
	s_barrier
	v_lshl_add_u64 v[158:159], v[158:159], 0, s[26:27]
	s_cmp_ge_i32 s10, s52
	v_lshl_add_u64 v[160:161], v[160:161], 0, s[26:27]
	s_cbranch_scc0 .LBB0_1776

; #define PG8_STAGE(bufoff, gbase, voff) do { _Pragma("unroll") for (int _i = 0; _i < 2; ++_i) \
;         __builtin_amdgcn_global_load_lds((const unsigned*)((const char*)(gbase) + (voff)[_i]), (PG8_LAS unsigned*)(lds + (bufoff) + ldsw + _i * 8192), 16, 0, 0); } while (0)
; #define PG8_LDA(dst, b, h) do { _Pragma("unroll") for (int m = 0; m < 4; ++m) _Pragma("unroll") for (int k = 0; k < 2; ++k) dst[m][k] = *(const PG8_LAS bf16x8*)(lds + PG8_SA(b, h) + aoff + m * 2048 + k * 1024); } while (0)
; #define PG8_LDB(dst, b, h) do { _Pragma("unroll") for (int n = 0; n < 2; ++n) _Pragma("unroll") for (int k = 0; k < 2; ++k) dst[n][k] = *(const PG8_LAS bf16x8*)(lds + PG8_SB(b, h) + boff + n * 2048 + k * 1024); } while (0)
; #define PG8_MMA(ai, bj, At, Bt) do { __builtin_amdgcn_s_setprio(1); _Pragma("unroll") for (int m = 0; m < 4; ++m) _Pragma("unroll") for (int n = 0; n < 2; ++n) _Pragma("unroll") for (int k = 0; k < 2; ++k) \
;         acc[ai][bj][m][n] = __builtin_amdgcn_mfma_f32_16x16x32_bf16(Bt[n][k], At[m][k], acc[ai][bj][m][n], 0, 0, 0); __builtin_amdgcn_s_setprio(0); } while (0)
; #define PG8_WAIT_V(n) asm volatile("s_waitcnt vmcnt(" #n ")" ::: "memory")
; #define PG8_WAIT_L(n) asm volatile("s_waitcnt lgkmcnt(" #n ")" ::: "memory")
; template <class Epi, class Sched, bool ALIGN_EPI = false, bool SP2 = false>
; __device__ __forceinline__ void gemm_phase(PG8_LAS unsigned char* lds, const Gemm g, const Sched& S, const Epi& E) {
;     ...
;             const bool last = (t == nt - 2);
;             const char* a1 = cA + (size_t)(t + 1) * kstep;
;             const char* a2 = last ? nA : cA + (size_t)(t + 2) * kstep; const char* b2 = last ? nB : cB + (size_t)(t + 2) * kstep;
;             const char* a3 = a2 + kstep; const char* b3 = b2 + kstep;
;             if (last && has_next) S.a_ready(nxt);
;             if constexpr (SP2) {
;             PG8_LDB(B0, 0, 0); PG8_LDB(B1, 0, 1); PG8_SCHED; PG8_LDA(At, 0, 0); PG8_STAGE(PG8_SA(1, 1), a1 + hstep, voffA);
;             PG8_WAIT_V(8); PG8_WAIT_L(0); PG8_BAR; PG8_MMA(0, 0, At, B0); PG8_MMA(0, 1, At, B1); PG8_BAR; PG8_SCHED;
;             PG8_LDA(At, 0, 1); PG8_STAGE(PG8_SB(0, 0), b2, voffB); PG8_STAGE(PG8_SB(0, 1), b2 + hstep, voffB); PG8_STAGE(PG8_SA(0, 0), a2, voffA);
;             PG8_WAIT_V(8); PG8_WAIT_L(0); PG8_BAR; PG8_MMA(1, 0, At, B0); PG8_MMA(1, 1, At, B1); PG8_BAR; PG8_SCHED;
.LBB0_1924:
	v_add_u32_e32 v192, s50, v161
	ds_read_b128 v[164:167], v162
	ds_read_b128 v[168:171], v162 offset:1024
	ds_read_b128 v[172:175], v162 offset:2048
	ds_read_b128 v[176:179], v162 offset:3072
	ds_read_b128 v[180:183], v192
	ds_read_b128 v[184:187], v192 offset:1024
	ds_read_b128 v[188:191], v192 offset:2048
	ds_read_b128 v[192:195], v192 offset:3072
	s_cmp_eq_u32 s49, s10
	v_lshl_add_u64 v[196:197], v[158:159], 0, s[24:25]
	s_cselect_b64 vcc, -1, 0
	s_add_i32 s10, s10, 2
	v_cndmask_b32_e32 v213, v197, v151, vcc
	v_cndmask_b32_e32 v212, v196, v150, vcc
	v_cndmask_b32_e32 v215, v155, v153, vcc
	v_cndmask_b32_e32 v214, v154, v152, vcc
	s_mov_b32 m0, s51
	v_lshl_add_u64 v[232:233], v[158:159], 0, v[146:147]
	ds_read_b128 v[196:199], v163
	ds_read_b128 v[200:203], v163 offset:1024
	ds_read_b128 v[204:207], v163 offset:2048
	ds_read_b128 v[208:211], v163 offset:3072
	ds_read_b128 v[216:219], v163 offset:4096
	ds_read_b128 v[220:223], v163 offset:5120
	ds_read_b128 v[224:227], v163 offset:6144
	ds_read_b128 v[228:231], v163 offset:7168
	global_load_lds_dwordx4 v[232:233], off
	s_mov_b32 m0, s52
	v_lshl_add_u64 v[232:233], v[158:159], 0, v[144:145]
	global_load_lds_dwordx4 v[232:233], off
	s_waitcnt vmcnt(8) lgkmcnt(0)
	s_setprio 1
	s_barrier
	v_mfma_f32_16x16x32_bf16 v[124:127], v[164:167], v[196:199], v[124:127]
	v_mfma_f32_16x16x32_bf16 v[120:123], v[172:175], v[196:199], v[120:123]
	v_mfma_f32_16x16x32_bf16 v[108:111], v[164:167], v[204:207], v[108:111]
	v_mfma_f32_16x16x32_bf16 v[104:107], v[172:175], v[204:207], v[104:107]
	v_mfma_f32_16x16x32_bf16 v[92:95], v[164:167], v[216:219], v[92:95]
	v_mfma_f32_16x16x32_bf16 v[88:91], v[172:175], v[216:219], v[88:91]
	v_mfma_f32_16x16x32_bf16 v[76:79], v[164:167], v[224:227], v[76:79]
	v_mfma_f32_16x16x32_bf16 v[72:75], v[172:175], v[224:227], v[72:75]
	v_mfma_f32_16x16x32_bf16 v[124:127], v[168:171], v[200:203], v[124:127]
	v_mfma_f32_16x16x32_bf16 v[120:123], v[176:179], v[200:203], v[120:123]
	v_mfma_f32_16x16x32_bf16 v[108:111], v[168:171], v[208:211], v[108:111]
	v_mfma_f32_16x16x32_bf16 v[104:107], v[176:179], v[208:211], v[104:107]
	v_mfma_f32_16x16x32_bf16 v[92:95], v[168:171], v[220:223], v[92:95]
	v_mfma_f32_16x16x32_bf16 v[88:91], v[176:179], v[220:223], v[88:91]
	v_mfma_f32_16x16x32_bf16 v[76:79], v[168:171], v[228:231], v[76:79]
	v_mfma_f32_16x16x32_bf16 v[72:75], v[176:179], v[228:231], v[72:75]
	v_mfma_f32_16x16x32_bf16 v[116:119], v[180:183], v[196:199], v[116:119]
	v_mfma_f32_16x16x32_bf16 v[112:115], v[188:191], v[196:199], v[112:115]
	v_mfma_f32_16x16x32_bf16 v[100:103], v[180:183], v[204:207], v[100:103]
	v_mfma_f32_16x16x32_bf16 v[96:99], v[188:191], v[204:207], v[96:99]
	v_mfma_f32_16x16x32_bf16 v[84:87], v[180:183], v[216:219], v[84:87]
	v_mfma_f32_16x16x32_bf16 v[80:83], v[188:191], v[216:219], v[80:83]
	v_mfma_f32_16x16x32_bf16 v[68:71], v[180:183], v[224:227], v[68:71]
	v_mfma_f32_16x16x32_bf16 v[64:67], v[188:191], v[224:227], v[64:67]
	v_mfma_f32_16x16x32_bf16 v[116:119], v[184:187], v[200:203], v[116:119]
	v_mfma_f32_16x16x32_bf16 v[112:115], v[192:195], v[200:203], v[112:115]
	v_mfma_f32_16x16x32_bf16 v[100:103], v[184:187], v[208:211], v[100:103]
	v_mfma_f32_16x16x32_bf16 v[96:99], v[192:195], v[208:211], v[96:99]
	v_mfma_f32_16x16x32_bf16 v[84:87], v[184:187], v[220:223], v[84:87]
	v_mfma_f32_16x16x32_bf16 v[80:83], v[192:195], v[220:223], v[80:83]
	v_mfma_f32_16x16x32_bf16 v[68:71], v[184:187], v[228:231], v[68:71]
	v_mfma_f32_16x16x32_bf16 v[64:67], v[192:195], v[228:231], v[64:67]
	s_setprio 0
	s_barrier
	s_mov_b32 m0, s53
	v_lshl_add_u64 v[232:233], v[214:215], 0, v[138:139]
	ds_read_b128 v[196:199], v163 offset:16384
	ds_read_b128 v[200:203], v163 offset:17408
	ds_read_b128 v[204:207], v163 offset:18432
	ds_read_b128 v[208:211], v163 offset:19456
	ds_read_b128 v[216:219], v163 offset:20480
	ds_read_b128 v[220:223], v163 offset:21504
	ds_read_b128 v[224:227], v163 offset:22528
	ds_read_b128 v[228:231], v163 offset:23552
	global_load_lds_dwordx4 v[232:233], off
	v_lshl_add_u64 v[234:235], v[214:215], 0, v[134:135]
	s_mov_b32 m0, s54
	v_lshl_add_u64 v[214:215], v[214:215], 0, s[14:15]
	global_load_lds_dwordx4 v[234:235], off
	v_lshl_add_u64 v[236:237], v[214:215], 0, v[138:139]
	s_mov_b32 m0, s55
	v_lshl_add_u64 v[214:215], v[214:215], 0, v[134:135]
	global_load_lds_dwordx4 v[236:237], off
	s_mov_b32 m0, s56
	v_lshl_add_u64 v[238:239], v[212:213], 0, v[140:141]
	global_load_lds_dwordx4 v[214:215], off
	s_mov_b32 m0, s37
	v_lshl_add_u64 v[240:241], v[212:213], 0, v[136:137]
	global_load_lds_dwordx4 v[238:239], off
	s_mov_b32 m0, s41
	s_nop 0
	global_load_lds_dwordx4 v[240:241], off
	s_waitcnt vmcnt(8) lgkmcnt(0)
	s_setprio 1
	s_barrier
; #define PG8_STAGE(bufoff, gbase, voff) do { _Pragma("unroll") for (int _i = 0; _i < 2; ++_i) \
;         __builtin_amdgcn_global_load_lds((const unsigned*)((const char*)(gbase) + (voff)[_i]), (PG8_LAS unsigned*)(lds + (bufoff) + ldsw + _i * 8192), 16, 0, 0); } while (0)
; #define PG8_LDA(dst, b, h) do { _Pragma("unroll") for (int m = 0; m < 4; ++m) _Pragma("unroll") for (int k = 0; k < 2; ++k) dst[m][k] = *(const PG8_LAS bf16x8*)(lds + PG8_SA(b, h) + aoff + m * 2048 + k * 1024); } while (0)
; #define PG8_LDB(dst, b, h) do { _Pragma("unroll") for (int n = 0; n < 2; ++n) _Pragma("unroll") for (int k = 0; k < 2; ++k) dst[n][k] = *(const PG8_LAS bf16x8*)(lds + PG8_SB(b, h) + boff + n * 2048 + k * 1024); } while (0)
; #define PG8_MMA(ai, bj, At, Bt) do { __builtin_amdgcn_s_setprio(1); _Pragma("unroll") for (int m = 0; m < 4; ++m) _Pragma("unroll") for (int n = 0; n < 2; ++n) _Pragma("unroll") for (int k = 0; k < 2; ++k) \
;         acc[ai][bj][m][n] = __builtin_amdgcn_mfma_f32_16x16x32_bf16(Bt[n][k], At[m][k], acc[ai][bj][m][n], 0, 0, 0); __builtin_amdgcn_s_setprio(0); } while (0)
; #define PG8_WAIT_V(n) asm volatile("s_waitcnt vmcnt(" #n ")" ::: "memory")
; #define PG8_WAIT_L(n) asm volatile("s_waitcnt lgkmcnt(" #n ")" ::: "memory")
; #define PG8_BAR __builtin_amdgcn_s_barrier()
; #define PG8_SCHED __builtin_amdgcn_sched_barrier(0)
; template <class Epi, class Sched, bool ALIGN_EPI = false, bool SP2 = false>
; __device__ __forceinline__ void gemm_phase(PG8_LAS unsigned char* lds, const Gemm g, const Sched& S, const Epi& E) {
;     ...
;             PG8_WAIT_V(8); PG8_WAIT_L(0); PG8_BAR; PG8_MMA(1, 0, At, B0); PG8_MMA(1, 1, At, B1); PG8_BAR; PG8_SCHED;
;             PG8_LDB(B0, 1, 0); PG8_LDB(B1, 1, 1); PG8_SCHED; PG8_LDA(At, 1, 0); PG8_STAGE(PG8_SA(0, 1), a2 + hstep, voffA);
;             PG8_WAIT_V(8); PG8_WAIT_L(0); PG8_BAR; PG8_MMA(0, 0, At, B0); PG8_MMA(0, 1, At, B1); PG8_BAR; PG8_SCHED;
	v_mfma_f32_16x16x32_bf16 v[60:63], v[164:167], v[196:199], v[60:63]
	v_mfma_f32_16x16x32_bf16 v[56:59], v[172:175], v[196:199], v[56:59]
	v_mfma_f32_16x16x32_bf16 v[44:47], v[164:167], v[204:207], v[44:47]
	v_mfma_f32_16x16x32_bf16 v[40:43], v[172:175], v[204:207], v[40:43]
	v_mfma_f32_16x16x32_bf16 v[28:31], v[164:167], v[216:219], v[28:31]
	v_mfma_f32_16x16x32_bf16 v[24:27], v[172:175], v[216:219], v[24:27]
	v_mfma_f32_16x16x32_bf16 v[12:15], v[164:167], v[224:227], v[12:15]
	v_mfma_f32_16x16x32_bf16 v[8:11], v[172:175], v[224:227], v[8:11]
	v_mfma_f32_16x16x32_bf16 v[60:63], v[168:171], v[200:203], v[60:63]
	v_mfma_f32_16x16x32_bf16 v[56:59], v[176:179], v[200:203], v[56:59]
	v_mfma_f32_16x16x32_bf16 v[44:47], v[168:171], v[208:211], v[44:47]
	v_mfma_f32_16x16x32_bf16 v[40:43], v[176:179], v[208:211], v[40:43]
	v_mfma_f32_16x16x32_bf16 v[28:31], v[168:171], v[220:223], v[28:31]
	v_mfma_f32_16x16x32_bf16 v[24:27], v[176:179], v[220:223], v[24:27]
	v_mfma_f32_16x16x32_bf16 v[12:15], v[168:171], v[228:231], v[12:15]
	v_mfma_f32_16x16x32_bf16 v[8:11], v[176:179], v[228:231], v[8:11]
	v_mfma_f32_16x16x32_bf16 v[52:55], v[180:183], v[196:199], v[52:55]
	v_mfma_f32_16x16x32_bf16 v[48:51], v[188:191], v[196:199], v[48:51]
	v_mfma_f32_16x16x32_bf16 v[36:39], v[180:183], v[204:207], v[36:39]
	v_mfma_f32_16x16x32_bf16 v[32:35], v[188:191], v[204:207], v[32:35]
	v_mfma_f32_16x16x32_bf16 v[20:23], v[180:183], v[216:219], v[20:23]
	v_mfma_f32_16x16x32_bf16 v[16:19], v[188:191], v[216:219], v[16:19]
	v_mfma_f32_16x16x32_bf16 v[4:7], v[180:183], v[224:227], v[4:7]
	v_mfma_f32_16x16x32_bf16 v[0:3], v[188:191], v[224:227], v[0:3]
	v_mfma_f32_16x16x32_bf16 v[52:55], v[184:187], v[200:203], v[52:55]
	v_mfma_f32_16x16x32_bf16 v[48:51], v[192:195], v[200:203], v[48:51]
	v_mfma_f32_16x16x32_bf16 v[36:39], v[184:187], v[208:211], v[36:39]
	v_mfma_f32_16x16x32_bf16 v[32:35], v[192:195], v[208:211], v[32:35]
	v_mfma_f32_16x16x32_bf16 v[20:23], v[184:187], v[220:223], v[20:23]
	v_mfma_f32_16x16x32_bf16 v[16:19], v[192:195], v[220:223], v[16:19]
	v_mfma_f32_16x16x32_bf16 v[4:7], v[184:187], v[228:231], v[4:7]
	v_mfma_f32_16x16x32_bf16 v[0:3], v[192:195], v[228:231], v[0:3]
	s_setprio 0
	s_barrier
	v_add_u32_e32 v176, s57, v161
	v_add_u32_e32 v192, s58, v161
	ds_read_b128 v[164:167], v176
	ds_read_b128 v[168:171], v176 offset:1024
	ds_read_b128 v[172:175], v176 offset:2048
	ds_read_b128 v[176:179], v176 offset:3072
	ds_read_b128 v[180:183], v192
	ds_read_b128 v[184:187], v192 offset:1024
	ds_read_b128 v[188:191], v192 offset:2048
	ds_read_b128 v[192:195], v192 offset:3072
	v_lshl_add_u64 v[212:213], v[212:213], 0, s[14:15]
	s_mov_b32 m0, s44
	v_lshl_add_u64 v[242:243], v[212:213], 0, v[140:141]
	ds_read_b128 v[196:199], v163 offset:32768
	ds_read_b128 v[200:203], v163 offset:33792
	ds_read_b128 v[204:207], v163 offset:34816
	ds_read_b128 v[208:211], v163 offset:35840
	ds_read_b128 v[216:219], v163 offset:36864
	ds_read_b128 v[220:223], v163 offset:37888
	ds_read_b128 v[224:227], v163 offset:38912
	ds_read_b128 v[228:231], v163 offset:39936
	global_load_lds_dwordx4 v[242:243], off
	s_mov_b32 m0, s45
	v_lshl_add_u64 v[212:213], v[212:213], 0, v[136:137]
	global_load_lds_dwordx4 v[212:213], off
	s_waitcnt vmcnt(8) lgkmcnt(0)
	s_setprio 1
	s_barrier
	v_mfma_f32_16x16x32_bf16 v[124:127], v[164:167], v[196:199], v[124:127]
	v_mfma_f32_16x16x32_bf16 v[120:123], v[172:175], v[196:199], v[120:123]
	v_mfma_f32_16x16x32_bf16 v[108:111], v[164:167], v[204:207], v[108:111]
	v_mfma_f32_16x16x32_bf16 v[104:107], v[172:175], v[204:207], v[104:107]
	v_mfma_f32_16x16x32_bf16 v[92:95], v[164:167], v[216:219], v[92:95]
	v_mfma_f32_16x16x32_bf16 v[88:91], v[172:175], v[216:219], v[88:91]
	v_mfma_f32_16x16x32_bf16 v[76:79], v[164:167], v[224:227], v[76:79]
	v_mfma_f32_16x16x32_bf16 v[72:75], v[172:175], v[224:227], v[72:75]
	v_mfma_f32_16x16x32_bf16 v[124:127], v[168:171], v[200:203], v[124:127]
	v_mfma_f32_16x16x32_bf16 v[120:123], v[176:179], v[200:203], v[120:123]
	v_mfma_f32_16x16x32_bf16 v[108:111], v[168:171], v[208:211], v[108:111]
	v_mfma_f32_16x16x32_bf16 v[104:107], v[176:179], v[208:211], v[104:107]
	v_mfma_f32_16x16x32_bf16 v[92:95], v[168:171], v[220:223], v[92:95]
	v_mfma_f32_16x16x32_bf16 v[88:91], v[176:179], v[220:223], v[88:91]
	v_mfma_f32_16x16x32_bf16 v[76:79], v[168:171], v[228:231], v[76:79]
	v_mfma_f32_16x16x32_bf16 v[72:75], v[176:179], v[228:231], v[72:75]
	v_mfma_f32_16x16x32_bf16 v[116:119], v[180:183], v[196:199], v[116:119]
	v_mfma_f32_16x16x32_bf16 v[112:115], v[188:191], v[196:199], v[112:115]
	v_mfma_f32_16x16x32_bf16 v[100:103], v[180:183], v[204:207], v[100:103]
	v_mfma_f32_16x16x32_bf16 v[96:99], v[188:191], v[204:207], v[96:99]
	v_mfma_f32_16x16x32_bf16 v[84:87], v[180:183], v[216:219], v[84:87]
	v_mfma_f32_16x16x32_bf16 v[80:83], v[188:191], v[216:219], v[80:83]
	v_mfma_f32_16x16x32_bf16 v[68:71], v[180:183], v[224:227], v[68:71]
	v_mfma_f32_16x16x32_bf16 v[64:67], v[188:191], v[224:227], v[64:67]
	v_mfma_f32_16x16x32_bf16 v[116:119], v[184:187], v[200:203], v[116:119]
	v_mfma_f32_16x16x32_bf16 v[112:115], v[192:195], v[200:203], v[112:115]
	v_mfma_f32_16x16x32_bf16 v[100:103], v[184:187], v[208:211], v[100:103]
	v_mfma_f32_16x16x32_bf16 v[96:99], v[192:195], v[208:211], v[96:99]
	v_mfma_f32_16x16x32_bf16 v[84:87], v[184:187], v[220:223], v[84:87]
	v_mfma_f32_16x16x32_bf16 v[80:83], v[192:195], v[220:223], v[80:83]
	v_mfma_f32_16x16x32_bf16 v[68:71], v[184:187], v[228:231], v[68:71]
	v_mfma_f32_16x16x32_bf16 v[64:67], v[192:195], v[228:231], v[64:67]
	s_setprio 0
	s_barrier
; #define PG8_STAGE(bufoff, gbase, voff) do { _Pragma("unroll") for (int _i = 0; _i < 2; ++_i) \
;         __builtin_amdgcn_global_load_lds((const unsigned*)((const char*)(gbase) + (voff)[_i]), (PG8_LAS unsigned*)(lds + (bufoff) + ldsw + _i * 8192), 16, 0, 0); } while (0)
; #define PG8_LDA(dst, b, h) do { _Pragma("unroll") for (int m = 0; m < 4; ++m) _Pragma("unroll") for (int k = 0; k < 2; ++k) dst[m][k] = *(const PG8_LAS bf16x8*)(lds + PG8_SA(b, h) + aoff + m * 2048 + k * 1024); } while (0)
; #define PG8_MMA(ai, bj, At, Bt) do { __builtin_amdgcn_s_setprio(1); _Pragma("unroll") for (int m = 0; m < 4; ++m) _Pragma("unroll") for (int n = 0; n < 2; ++n) _Pragma("unroll") for (int k = 0; k < 2; ++k) \
;         acc[ai][bj][m][n] = __builtin_amdgcn_mfma_f32_16x16x32_bf16(Bt[n][k], At[m][k], acc[ai][bj][m][n], 0, 0, 0); __builtin_amdgcn_s_setprio(0); } while (0)
; #define PG8_WAIT_V(n) asm volatile("s_waitcnt vmcnt(" #n ")" ::: "memory")
; #define PG8_WAIT_L(n) asm volatile("s_waitcnt lgkmcnt(" #n ")" ::: "memory")
; #define PG8_BAR __builtin_amdgcn_s_barrier()
; #define PG8_SCHED __builtin_amdgcn_sched_barrier(0)
; template <class Epi, class Sched, bool ALIGN_EPI = false, bool SP2 = false>
; __device__ __forceinline__ void gemm_phase(PG8_LAS unsigned char* lds, const Gemm g, const Sched& S, const Epi& E) {
;     ...
;             PG8_LDA(At, 1, 1); PG8_STAGE(PG8_SB(1, 0), b3, voffB); PG8_STAGE(PG8_SB(1, 1), b3 + hstep, voffB); PG8_STAGE(PG8_SA(1, 0), a3, voffA);
;             PG8_WAIT_V(8); PG8_WAIT_L(0); PG8_BAR; PG8_MMA(1, 0, At, B0); PG8_MMA(1, 1, At, B1); PG8_BAR; PG8_SCHED;
	s_mov_b32 m0, s59
	v_lshl_add_u64 v[212:213], v[232:233], 0, s[24:25]
	ds_read_b128 v[196:199], v163 offset:49152
	ds_read_b128 v[200:203], v163 offset:50176
	ds_read_b128 v[204:207], v163 offset:51200
	ds_read_b128 v[208:211], v163 offset:52224
	ds_read_b128 v[216:219], v163 offset:53248
	ds_read_b128 v[220:223], v163 offset:54272
	ds_read_b128 v[224:227], v163 offset:55296
	ds_read_b128 v[228:231], v163 offset:56320
	global_load_lds_dwordx4 v[212:213], off
	s_mov_b32 m0, s60
	v_lshl_add_u64 v[212:213], v[234:235], 0, s[24:25]
	global_load_lds_dwordx4 v[212:213], off
	s_mov_b32 m0, s61
	v_lshl_add_u64 v[212:213], v[236:237], 0, s[24:25]
	global_load_lds_dwordx4 v[212:213], off
	s_mov_b32 m0, s62
	v_lshl_add_u64 v[212:213], v[214:215], 0, s[24:25]
	global_load_lds_dwordx4 v[212:213], off
	s_mov_b32 m0, s46
	v_lshl_add_u64 v[212:213], v[238:239], 0, s[24:25]
	global_load_lds_dwordx4 v[212:213], off
	s_mov_b32 m0, s47
	v_lshl_add_u64 v[212:213], v[240:241], 0, s[24:25]
	global_load_lds_dwordx4 v[212:213], off
	s_waitcnt vmcnt(8) lgkmcnt(0)
	s_setprio 1
	s_barrier
	v_mfma_f32_16x16x32_bf16 v[60:63], v[164:167], v[196:199], v[60:63]
	v_mfma_f32_16x16x32_bf16 v[56:59], v[172:175], v[196:199], v[56:59]
	v_mfma_f32_16x16x32_bf16 v[44:47], v[164:167], v[204:207], v[44:47]
	v_mfma_f32_16x16x32_bf16 v[40:43], v[172:175], v[204:207], v[40:43]
	v_mfma_f32_16x16x32_bf16 v[28:31], v[164:167], v[216:219], v[28:31]
	v_mfma_f32_16x16x32_bf16 v[24:27], v[172:175], v[216:219], v[24:27]
	v_mfma_f32_16x16x32_bf16 v[12:15], v[164:167], v[224:227], v[12:15]
	v_mfma_f32_16x16x32_bf16 v[8:11], v[172:175], v[224:227], v[8:11]
	v_mfma_f32_16x16x32_bf16 v[60:63], v[168:171], v[200:203], v[60:63]
	v_mfma_f32_16x16x32_bf16 v[56:59], v[176:179], v[200:203], v[56:59]
	v_mfma_f32_16x16x32_bf16 v[44:47], v[168:171], v[208:211], v[44:47]
	v_mfma_f32_16x16x32_bf16 v[40:43], v[176:179], v[208:211], v[40:43]
	v_mfma_f32_16x16x32_bf16 v[28:31], v[168:171], v[220:223], v[28:31]
	v_mfma_f32_16x16x32_bf16 v[24:27], v[176:179], v[220:223], v[24:27]
	v_mfma_f32_16x16x32_bf16 v[12:15], v[168:171], v[228:231], v[12:15]
	v_mfma_f32_16x16x32_bf16 v[8:11], v[176:179], v[228:231], v[8:11]
	v_mfma_f32_16x16x32_bf16 v[52:55], v[180:183], v[196:199], v[52:55]
	v_mfma_f32_16x16x32_bf16 v[48:51], v[188:191], v[196:199], v[48:51]
	v_mfma_f32_16x16x32_bf16 v[36:39], v[180:183], v[204:207], v[36:39]
	v_mfma_f32_16x16x32_bf16 v[32:35], v[188:191], v[204:207], v[32:35]
	v_mfma_f32_16x16x32_bf16 v[20:23], v[180:183], v[216:219], v[20:23]
	v_mfma_f32_16x16x32_bf16 v[16:19], v[188:191], v[216:219], v[16:19]
	v_mfma_f32_16x16x32_bf16 v[4:7], v[180:183], v[224:227], v[4:7]
	v_mfma_f32_16x16x32_bf16 v[0:3], v[188:191], v[224:227], v[0:3]
	v_mfma_f32_16x16x32_bf16 v[52:55], v[184:187], v[200:203], v[52:55]
	v_mfma_f32_16x16x32_bf16 v[48:51], v[192:195], v[200:203], v[48:51]
	v_mfma_f32_16x16x32_bf16 v[36:39], v[184:187], v[208:211], v[36:39]
	v_mfma_f32_16x16x32_bf16 v[32:35], v[192:195], v[208:211], v[32:35]
	v_mfma_f32_16x16x32_bf16 v[20:23], v[184:187], v[220:223], v[20:23]
	v_mfma_f32_16x16x32_bf16 v[16:19], v[192:195], v[220:223], v[16:19]
	v_mfma_f32_16x16x32_bf16 v[4:7], v[184:187], v[228:231], v[4:7]
	v_mfma_f32_16x16x32_bf16 v[0:3], v[192:195], v[228:231], v[0:3]
	s_setprio 0
	s_barrier
	v_lshl_add_u64 v[154:155], v[154:155], 0, s[28:29]
	s_cmp_ge_i32 s10, s48
	v_lshl_add_u64 v[158:159], v[158:159], 0, s[28:29]
	s_cbranch_scc0 .LBB0_1924

; #define PG8_STAGE(bufoff, gbase, voff) do { _Pragma("unroll") for (int _i = 0; _i < 2; ++_i) \
;         __builtin_amdgcn_global_load_lds((const unsigned*)((const char*)(gbase) + (voff)[_i]), (PG8_LAS unsigned*)(lds + (bufoff) + ldsw + _i * 8192), 16, 0, 0); } while (0)
; #define PG8_LDA(dst, b, h) do { _Pragma("unroll") for (int m = 0; m < 4; ++m) _Pragma("unroll") for (int k = 0; k < 2; ++k) dst[m][k] = *(const PG8_LAS bf16x8*)(lds + PG8_SA(b, h) + aoff + m * 2048 + k * 1024); } while (0)
; #define PG8_LDB(dst, b, h) do { _Pragma("unroll") for (int n = 0; n < 2; ++n) _Pragma("unroll") for (int k = 0; k < 2; ++k) dst[n][k] = *(const PG8_LAS bf16x8*)(lds + PG8_SB(b, h) + boff + n * 2048 + k * 1024); } while (0)
; #define PG8_MMA(ai, bj, At, Bt) do { __builtin_amdgcn_s_setprio(1); _Pragma("unroll") for (int m = 0; m < 4; ++m) _Pragma("unroll") for (int n = 0; n < 2; ++n) _Pragma("unroll") for (int k = 0; k < 2; ++k) \
;         acc[ai][bj][m][n] = __builtin_amdgcn_mfma_f32_16x16x32_bf16(Bt[n][k], At[m][k], acc[ai][bj][m][n], 0, 0, 0); __builtin_amdgcn_s_setprio(0); } while (0)
; #define PG8_WAIT_V(n) asm volatile("s_waitcnt vmcnt(" #n ")" ::: "memory")
; #define PG8_WAIT_L(n) asm volatile("s_waitcnt lgkmcnt(" #n ")" ::: "memory")
; template <class Epi, class Sched, bool ALIGN_EPI = false, bool SP2 = false>
; __device__ __forceinline__ void gemm_phase(PG8_LAS unsigned char* lds, const Gemm g, const Sched& S, const Epi& E) {
;     ...
;             const bool last = (t == nt - 2);
;             const char* a1 = cA + (size_t)(t + 1) * kstep;
;             const char* a2 = last ? nA : cA + (size_t)(t + 2) * kstep; const char* b2 = last ? nB : cB + (size_t)(t + 2) * kstep;
;             const char* a3 = a2 + kstep; const char* b3 = b2 + kstep;
;             if (last && has_next) S.a_ready(nxt);
;             if constexpr (SP2) {
;             PG8_LDB(B0, 0, 0); PG8_LDB(B1, 0, 1); PG8_SCHED; PG8_LDA(At, 0, 0); PG8_STAGE(PG8_SA(1, 1), a1 + hstep, voffA);
;             PG8_WAIT_V(8); PG8_WAIT_L(0); PG8_BAR; PG8_MMA(0, 0, At, B0); PG8_MMA(0, 1, At, B1); PG8_BAR; PG8_SCHED;
;             PG8_LDA(At, 0, 1); PG8_STAGE(PG8_SB(0, 0), b2, voffB); PG8_STAGE(PG8_SB(0, 1), b2 + hstep, voffB); PG8_STAGE(PG8_SA(0, 0), a2, voffA);
;             PG8_WAIT_V(8); PG8_WAIT_L(0); PG8_BAR; PG8_MMA(1, 0, At, B0); PG8_MMA(1, 1, At, B1); PG8_BAR; PG8_SCHED;
.LBB0_1947:
	v_add_u32_e32 v178, s53, v216
	v_add_u32_e32 v194, s54, v216
	ds_read_b128 v[138:141], v178
	ds_read_b128 v[142:145], v178 offset:1024
	ds_read_b128 v[146:149], v178 offset:2048
	ds_read_b128 v[178:181], v178 offset:3072
	ds_read_b128 v[182:185], v194
	ds_read_b128 v[186:189], v194 offset:1024
	ds_read_b128 v[190:193], v194 offset:2048
	ds_read_b128 v[194:197], v194 offset:3072
	s_cmp_eq_u32 s47, s10
	v_lshl_add_u64 v[198:199], v[136:137], 0, s[20:21]
	s_cselect_b64 vcc, -1, 0
	s_add_i32 s10, s10, 2
	v_cndmask_b32_e32 v215, v199, v175, vcc
	v_cndmask_b32_e32 v214, v198, v174, vcc
	v_cndmask_b32_e32 v237, v135, v177, vcc
	v_cndmask_b32_e32 v236, v134, v176, vcc
	v_lshl_add_u64 v[238:239], v[136:137], 0, v[168:169]
	s_add_i32 m0, s34, 0xc000
	ds_read_b128 v[198:201], v218
	ds_read_b128 v[202:205], v218 offset:1024
	ds_read_b128 v[206:209], v218 offset:2048
	ds_read_b128 v[210:213], v218 offset:3072
	ds_read_b128 v[220:223], v218 offset:4096
	ds_read_b128 v[224:227], v218 offset:5120
	ds_read_b128 v[228:231], v218 offset:6144
	ds_read_b128 v[232:235], v218 offset:7168
	global_load_lds_dwordx4 v[238:239], off
	s_add_i32 m0, s34, 0xe000
	v_lshl_add_u64 v[238:239], v[136:137], 0, v[166:167]
	global_load_lds_dwordx4 v[238:239], off
	s_waitcnt vmcnt(8) lgkmcnt(0)
	s_setprio 1
	s_barrier
	v_mfma_f32_16x16x32_bf16 v[130:133], v[138:141], v[198:201], v[130:133]
	v_mfma_f32_16x16x32_bf16 v[126:129], v[146:149], v[198:201], v[126:129]
	v_mfma_f32_16x16x32_bf16 v[114:117], v[138:141], v[206:209], v[114:117]
	v_mfma_f32_16x16x32_bf16 v[110:113], v[146:149], v[206:209], v[110:113]
	v_mfma_f32_16x16x32_bf16 v[98:101], v[138:141], v[220:223], v[98:101]
	v_mfma_f32_16x16x32_bf16 v[94:97], v[146:149], v[220:223], v[94:97]
	v_mfma_f32_16x16x32_bf16 v[82:85], v[138:141], v[228:231], v[82:85]
	v_mfma_f32_16x16x32_bf16 v[78:81], v[146:149], v[228:231], v[78:81]
	v_mfma_f32_16x16x32_bf16 v[130:133], v[142:145], v[202:205], v[130:133]
	v_mfma_f32_16x16x32_bf16 v[126:129], v[178:181], v[202:205], v[126:129]
	v_mfma_f32_16x16x32_bf16 v[114:117], v[142:145], v[210:213], v[114:117]
	v_mfma_f32_16x16x32_bf16 v[110:113], v[178:181], v[210:213], v[110:113]
	v_mfma_f32_16x16x32_bf16 v[98:101], v[142:145], v[224:227], v[98:101]
	v_mfma_f32_16x16x32_bf16 v[94:97], v[178:181], v[224:227], v[94:97]
	v_mfma_f32_16x16x32_bf16 v[82:85], v[142:145], v[232:235], v[82:85]
	v_mfma_f32_16x16x32_bf16 v[78:81], v[178:181], v[232:235], v[78:81]
	v_mfma_f32_16x16x32_bf16 v[122:125], v[182:185], v[198:201], v[122:125]
	v_mfma_f32_16x16x32_bf16 v[118:121], v[190:193], v[198:201], v[118:121]
	v_mfma_f32_16x16x32_bf16 v[106:109], v[182:185], v[206:209], v[106:109]
	v_mfma_f32_16x16x32_bf16 v[102:105], v[190:193], v[206:209], v[102:105]
	v_mfma_f32_16x16x32_bf16 v[90:93], v[182:185], v[220:223], v[90:93]
	v_mfma_f32_16x16x32_bf16 v[86:89], v[190:193], v[220:223], v[86:89]
	v_mfma_f32_16x16x32_bf16 v[74:77], v[182:185], v[228:231], v[74:77]
	v_mfma_f32_16x16x32_bf16 v[70:73], v[190:193], v[228:231], v[70:73]
	v_mfma_f32_16x16x32_bf16 v[122:125], v[186:189], v[202:205], v[122:125]
	v_mfma_f32_16x16x32_bf16 v[118:121], v[194:197], v[202:205], v[118:121]
	v_mfma_f32_16x16x32_bf16 v[106:109], v[186:189], v[210:213], v[106:109]
	v_mfma_f32_16x16x32_bf16 v[102:105], v[194:197], v[210:213], v[102:105]
	v_mfma_f32_16x16x32_bf16 v[90:93], v[186:189], v[224:227], v[90:93]
	v_mfma_f32_16x16x32_bf16 v[86:89], v[194:197], v[224:227], v[86:89]
	v_mfma_f32_16x16x32_bf16 v[74:77], v[186:189], v[232:235], v[74:77]
	v_mfma_f32_16x16x32_bf16 v[70:73], v[194:197], v[232:235], v[70:73]
	s_setprio 0
	s_barrier
	s_add_i32 s11, s53, s29
	v_lshl_add_u64 v[238:239], v[236:237], 0, v[158:159]
	s_mov_b32 m0, s11
	ds_read_b128 v[198:201], v218 offset:16384
	ds_read_b128 v[202:205], v218 offset:17408
	ds_read_b128 v[206:209], v218 offset:18432
	ds_read_b128 v[210:213], v218 offset:19456
	ds_read_b128 v[220:223], v218 offset:20480
	ds_read_b128 v[224:227], v218 offset:21504
	ds_read_b128 v[228:231], v218 offset:22528
	ds_read_b128 v[232:235], v218 offset:23552
	global_load_lds_dwordx4 v[238:239], off
	v_lshl_add_u64 v[240:241], v[236:237], 0, v[162:163]
	s_add_i32 m0, s11, 0x2000
	v_lshl_add_u64 v[236:237], v[236:237], 0, s[12:13]
	s_add_i32 s11, s54, s29
	global_load_lds_dwordx4 v[240:241], off
	v_lshl_add_u64 v[242:243], v[236:237], 0, v[158:159]
	s_mov_b32 m0, s11
	v_lshl_add_u64 v[236:237], v[236:237], 0, v[162:163]
	global_load_lds_dwordx4 v[242:243], off
	s_add_i32 m0, s11, 0x2000
	v_lshl_add_u64 v[244:245], v[214:215], 0, v[154:155]
	global_load_lds_dwordx4 v[236:237], off
	s_mov_b32 m0, s34
	v_lshl_add_u64 v[246:247], v[214:215], 0, v[160:161]
	global_load_lds_dwordx4 v[244:245], off
	s_mov_b32 m0, s35
	s_nop 0
	global_load_lds_dwordx4 v[246:247], off
	s_waitcnt vmcnt(8) lgkmcnt(0)
	s_setprio 1
	s_barrier
; #define PG8_STAGE(bufoff, gbase, voff) do { _Pragma("unroll") for (int _i = 0; _i < 2; ++_i) \
;         __builtin_amdgcn_global_load_lds((const unsigned*)((const char*)(gbase) + (voff)[_i]), (PG8_LAS unsigned*)(lds + (bufoff) + ldsw + _i * 8192), 16, 0, 0); } while (0)
; #define PG8_LDA(dst, b, h) do { _Pragma("unroll") for (int m = 0; m < 4; ++m) _Pragma("unroll") for (int k = 0; k < 2; ++k) dst[m][k] = *(const PG8_LAS bf16x8*)(lds + PG8_SA(b, h) + aoff + m * 2048 + k * 1024); } while (0)
; #define PG8_LDB(dst, b, h) do { _Pragma("unroll") for (int n = 0; n < 2; ++n) _Pragma("unroll") for (int k = 0; k < 2; ++k) dst[n][k] = *(const PG8_LAS bf16x8*)(lds + PG8_SB(b, h) + boff + n * 2048 + k * 1024); } while (0)
; #define PG8_MMA(ai, bj, At, Bt) do { __builtin_amdgcn_s_setprio(1); _Pragma("unroll") for (int m = 0; m < 4; ++m) _Pragma("unroll") for (int n = 0; n < 2; ++n) _Pragma("unroll") for (int k = 0; k < 2; ++k) \
;         acc[ai][bj][m][n] = __builtin_amdgcn_mfma_f32_16x16x32_bf16(Bt[n][k], At[m][k], acc[ai][bj][m][n], 0, 0, 0); __builtin_amdgcn_s_setprio(0); } while (0)
; #define PG8_WAIT_V(n) asm volatile("s_waitcnt vmcnt(" #n ")" ::: "memory")
; #define PG8_WAIT_L(n) asm volatile("s_waitcnt lgkmcnt(" #n ")" ::: "memory")
; #define PG8_BAR __builtin_amdgcn_s_barrier()
; #define PG8_SCHED __builtin_amdgcn_sched_barrier(0)
; template <class Epi, class Sched, bool ALIGN_EPI = false, bool SP2 = false>
; __device__ __forceinline__ void gemm_phase(PG8_LAS unsigned char* lds, const Gemm g, const Sched& S, const Epi& E) {
;     ...
;             PG8_WAIT_V(8); PG8_WAIT_L(0); PG8_BAR; PG8_MMA(1, 0, At, B0); PG8_MMA(1, 1, At, B1); PG8_BAR; PG8_SCHED;
;             PG8_LDB(B0, 1, 0); PG8_LDB(B1, 1, 1); PG8_SCHED; PG8_LDA(At, 1, 0); PG8_STAGE(PG8_SA(0, 1), a2 + hstep, voffA);
;             PG8_WAIT_V(8); PG8_WAIT_L(0); PG8_BAR; PG8_MMA(0, 0, At, B0); PG8_MMA(0, 1, At, B1); PG8_BAR; PG8_SCHED;
	v_mfma_f32_16x16x32_bf16 v[66:69], v[138:141], v[198:201], v[66:69]
	v_mfma_f32_16x16x32_bf16 v[62:65], v[146:149], v[198:201], v[62:65]
	v_mfma_f32_16x16x32_bf16 v[50:53], v[138:141], v[206:209], v[50:53]
	v_mfma_f32_16x16x32_bf16 v[46:49], v[146:149], v[206:209], v[46:49]
	v_mfma_f32_16x16x32_bf16 v[34:37], v[138:141], v[220:223], v[34:37]
	v_mfma_f32_16x16x32_bf16 v[30:33], v[146:149], v[220:223], v[30:33]
	v_mfma_f32_16x16x32_bf16 v[18:21], v[138:141], v[228:231], v[18:21]
	v_mfma_f32_16x16x32_bf16 v[14:17], v[146:149], v[228:231], v[14:17]
	v_mfma_f32_16x16x32_bf16 v[66:69], v[142:145], v[202:205], v[66:69]
	v_mfma_f32_16x16x32_bf16 v[62:65], v[178:181], v[202:205], v[62:65]
	v_mfma_f32_16x16x32_bf16 v[50:53], v[142:145], v[210:213], v[50:53]
	v_mfma_f32_16x16x32_bf16 v[46:49], v[178:181], v[210:213], v[46:49]
	v_mfma_f32_16x16x32_bf16 v[34:37], v[142:145], v[224:227], v[34:37]
	v_mfma_f32_16x16x32_bf16 v[30:33], v[178:181], v[224:227], v[30:33]
	v_mfma_f32_16x16x32_bf16 v[18:21], v[142:145], v[232:235], v[18:21]
	v_mfma_f32_16x16x32_bf16 v[14:17], v[178:181], v[232:235], v[14:17]
	v_mfma_f32_16x16x32_bf16 v[58:61], v[182:185], v[198:201], v[58:61]
	v_mfma_f32_16x16x32_bf16 v[54:57], v[190:193], v[198:201], v[54:57]
	v_mfma_f32_16x16x32_bf16 v[42:45], v[182:185], v[206:209], v[42:45]
	v_mfma_f32_16x16x32_bf16 v[38:41], v[190:193], v[206:209], v[38:41]
	v_mfma_f32_16x16x32_bf16 v[26:29], v[182:185], v[220:223], v[26:29]
	v_mfma_f32_16x16x32_bf16 v[22:25], v[190:193], v[220:223], v[22:25]
	v_mfma_f32_16x16x32_bf16 v[10:13], v[182:185], v[228:231], v[10:13]
	v_mfma_f32_16x16x32_bf16 v[6:9], v[190:193], v[228:231], v[6:9]
	v_mfma_f32_16x16x32_bf16 v[58:61], v[186:189], v[202:205], v[58:61]
	v_mfma_f32_16x16x32_bf16 v[54:57], v[194:197], v[202:205], v[54:57]
	v_mfma_f32_16x16x32_bf16 v[42:45], v[186:189], v[210:213], v[42:45]
	v_mfma_f32_16x16x32_bf16 v[38:41], v[194:197], v[210:213], v[38:41]
	v_mfma_f32_16x16x32_bf16 v[26:29], v[186:189], v[224:227], v[26:29]
	v_mfma_f32_16x16x32_bf16 v[22:25], v[194:197], v[224:227], v[22:25]
	v_mfma_f32_16x16x32_bf16 v[10:13], v[186:189], v[232:235], v[10:13]
	v_mfma_f32_16x16x32_bf16 v[6:9], v[194:197], v[232:235], v[6:9]
	s_setprio 0
	s_barrier
	s_add_i32 s11, 0, 0x18000
	s_add_i32 s31, 0, 0x1c000
	v_add_u32_e32 v178, s11, v216
	v_add_u32_e32 v194, s31, v216
	ds_read_b128 v[138:141], v178
	ds_read_b128 v[142:145], v178 offset:1024
	ds_read_b128 v[146:149], v178 offset:2048
	ds_read_b128 v[178:181], v178 offset:3072
	ds_read_b128 v[182:185], v194
	ds_read_b128 v[186:189], v194 offset:1024
	ds_read_b128 v[190:193], v194 offset:2048
	ds_read_b128 v[194:197], v194 offset:3072
	v_lshl_add_u64 v[214:215], v[214:215], 0, s[12:13]
	s_mov_b32 m0, s36
	v_lshl_add_u64 v[248:249], v[214:215], 0, v[154:155]
	ds_read_b128 v[198:201], v218 offset:32768
	ds_read_b128 v[202:205], v218 offset:33792
	ds_read_b128 v[206:209], v218 offset:34816
	ds_read_b128 v[210:213], v218 offset:35840
	ds_read_b128 v[220:223], v218 offset:36864
	ds_read_b128 v[224:227], v218 offset:37888
	ds_read_b128 v[228:231], v218 offset:38912
	ds_read_b128 v[232:235], v218 offset:39936
	global_load_lds_dwordx4 v[248:249], off
	s_mov_b32 m0, s37
	v_lshl_add_u64 v[214:215], v[214:215], 0, v[160:161]
	global_load_lds_dwordx4 v[214:215], off
	s_waitcnt vmcnt(8) lgkmcnt(0)
	s_setprio 1
	s_barrier
	v_mfma_f32_16x16x32_bf16 v[130:133], v[138:141], v[198:201], v[130:133]
	v_mfma_f32_16x16x32_bf16 v[126:129], v[146:149], v[198:201], v[126:129]
	v_mfma_f32_16x16x32_bf16 v[114:117], v[138:141], v[206:209], v[114:117]
	v_mfma_f32_16x16x32_bf16 v[110:113], v[146:149], v[206:209], v[110:113]
	v_mfma_f32_16x16x32_bf16 v[98:101], v[138:141], v[220:223], v[98:101]
	v_mfma_f32_16x16x32_bf16 v[94:97], v[146:149], v[220:223], v[94:97]
	v_mfma_f32_16x16x32_bf16 v[82:85], v[138:141], v[228:231], v[82:85]
	v_mfma_f32_16x16x32_bf16 v[78:81], v[146:149], v[228:231], v[78:81]
	v_mfma_f32_16x16x32_bf16 v[130:133], v[142:145], v[202:205], v[130:133]
	v_mfma_f32_16x16x32_bf16 v[126:129], v[178:181], v[202:205], v[126:129]
	v_mfma_f32_16x16x32_bf16 v[114:117], v[142:145], v[210:213], v[114:117]
	v_mfma_f32_16x16x32_bf16 v[110:113], v[178:181], v[210:213], v[110:113]
	v_mfma_f32_16x16x32_bf16 v[98:101], v[142:145], v[224:227], v[98:101]
	v_mfma_f32_16x16x32_bf16 v[94:97], v[178:181], v[224:227], v[94:97]
	v_mfma_f32_16x16x32_bf16 v[82:85], v[142:145], v[232:235], v[82:85]
	v_mfma_f32_16x16x32_bf16 v[78:81], v[178:181], v[232:235], v[78:81]
	v_mfma_f32_16x16x32_bf16 v[122:125], v[182:185], v[198:201], v[122:125]
	v_mfma_f32_16x16x32_bf16 v[118:121], v[190:193], v[198:201], v[118:121]
	v_mfma_f32_16x16x32_bf16 v[106:109], v[182:185], v[206:209], v[106:109]
	v_mfma_f32_16x16x32_bf16 v[102:105], v[190:193], v[206:209], v[102:105]
	v_mfma_f32_16x16x32_bf16 v[90:93], v[182:185], v[220:223], v[90:93]
	v_mfma_f32_16x16x32_bf16 v[86:89], v[190:193], v[220:223], v[86:89]
	v_mfma_f32_16x16x32_bf16 v[74:77], v[182:185], v[228:231], v[74:77]
	v_mfma_f32_16x16x32_bf16 v[70:73], v[190:193], v[228:231], v[70:73]
	v_mfma_f32_16x16x32_bf16 v[122:125], v[186:189], v[202:205], v[122:125]
	v_mfma_f32_16x16x32_bf16 v[118:121], v[194:197], v[202:205], v[118:121]
	v_mfma_f32_16x16x32_bf16 v[106:109], v[186:189], v[210:213], v[106:109]
	v_mfma_f32_16x16x32_bf16 v[102:105], v[194:197], v[210:213], v[102:105]
	v_mfma_f32_16x16x32_bf16 v[90:93], v[186:189], v[224:227], v[90:93]
	v_mfma_f32_16x16x32_bf16 v[86:89], v[194:197], v[224:227], v[86:89]
	v_mfma_f32_16x16x32_bf16 v[74:77], v[186:189], v[232:235], v[74:77]
	v_mfma_f32_16x16x32_bf16 v[70:73], v[194:197], v[232:235], v[70:73]
	s_setprio 0
	s_barrier
; #define PG8_STAGE(bufoff, gbase, voff) do { _Pragma("unroll") for (int _i = 0; _i < 2; ++_i) \
;         __builtin_amdgcn_global_load_lds((const unsigned*)((const char*)(gbase) + (voff)[_i]), (PG8_LAS unsigned*)(lds + (bufoff) + ldsw + _i * 8192), 16, 0, 0); } while (0)
; #define PG8_LDA(dst, b, h) do { _Pragma("unroll") for (int m = 0; m < 4; ++m) _Pragma("unroll") for (int k = 0; k < 2; ++k) dst[m][k] = *(const PG8_LAS bf16x8*)(lds + PG8_SA(b, h) + aoff + m * 2048 + k * 1024); } while (0)
; #define PG8_MMA(ai, bj, At, Bt) do { __builtin_amdgcn_s_setprio(1); _Pragma("unroll") for (int m = 0; m < 4; ++m) _Pragma("unroll") for (int n = 0; n < 2; ++n) _Pragma("unroll") for (int k = 0; k < 2; ++k) \
;         acc[ai][bj][m][n] = __builtin_amdgcn_mfma_f32_16x16x32_bf16(Bt[n][k], At[m][k], acc[ai][bj][m][n], 0, 0, 0); __builtin_amdgcn_s_setprio(0); } while (0)
; #define PG8_WAIT_V(n) asm volatile("s_waitcnt vmcnt(" #n ")" ::: "memory")
; #define PG8_WAIT_L(n) asm volatile("s_waitcnt lgkmcnt(" #n ")" ::: "memory")
; #define PG8_BAR __builtin_amdgcn_s_barrier()
; #define PG8_SCHED __builtin_amdgcn_sched_barrier(0)
; template <class Epi, class Sched, bool ALIGN_EPI = false, bool SP2 = false>
; __device__ __forceinline__ void gemm_phase(PG8_LAS unsigned char* lds, const Gemm g, const Sched& S, const Epi& E) {
;     ...
;             PG8_LDA(At, 1, 1); PG8_STAGE(PG8_SB(1, 0), b3, voffB); PG8_STAGE(PG8_SB(1, 1), b3 + hstep, voffB); PG8_STAGE(PG8_SA(1, 0), a3, voffA);
;             PG8_WAIT_V(8); PG8_WAIT_L(0); PG8_BAR; PG8_MMA(1, 0, At, B0); PG8_MMA(1, 1, At, B1); PG8_BAR; PG8_SCHED;
	s_add_i32 s11, s11, s29
	v_lshl_add_u64 v[214:215], v[238:239], 0, s[20:21]
	s_mov_b32 m0, s11
	ds_read_b128 v[198:201], v218 offset:49152
	ds_read_b128 v[202:205], v218 offset:50176
	ds_read_b128 v[206:209], v218 offset:51200
	ds_read_b128 v[210:213], v218 offset:52224
	ds_read_b128 v[220:223], v218 offset:53248
	ds_read_b128 v[224:227], v218 offset:54272
	ds_read_b128 v[228:231], v218 offset:55296
	ds_read_b128 v[232:235], v218 offset:56320
	global_load_lds_dwordx4 v[214:215], off
	v_lshl_add_u64 v[214:215], v[240:241], 0, s[20:21]
	s_add_i32 m0, s11, 0x2000
	s_add_i32 s11, s31, s29
	global_load_lds_dwordx4 v[214:215], off
	s_mov_b32 m0, s11
	v_lshl_add_u64 v[214:215], v[242:243], 0, s[20:21]
	global_load_lds_dwordx4 v[214:215], off
	s_add_i32 m0, s11, 0x2000
	v_lshl_add_u64 v[214:215], v[236:237], 0, s[20:21]
	global_load_lds_dwordx4 v[214:215], off
	s_mov_b32 m0, s41
	v_lshl_add_u64 v[214:215], v[244:245], 0, s[20:21]
	global_load_lds_dwordx4 v[214:215], off
	s_mov_b32 m0, s44
	v_lshl_add_u64 v[214:215], v[246:247], 0, s[20:21]
	global_load_lds_dwordx4 v[214:215], off
	s_waitcnt vmcnt(8) lgkmcnt(0)
	s_setprio 1
	s_barrier
	v_mfma_f32_16x16x32_bf16 v[66:69], v[138:141], v[198:201], v[66:69]
	v_mfma_f32_16x16x32_bf16 v[62:65], v[146:149], v[198:201], v[62:65]
	v_mfma_f32_16x16x32_bf16 v[50:53], v[138:141], v[206:209], v[50:53]
	v_mfma_f32_16x16x32_bf16 v[46:49], v[146:149], v[206:209], v[46:49]
	v_mfma_f32_16x16x32_bf16 v[34:37], v[138:141], v[220:223], v[34:37]
	v_mfma_f32_16x16x32_bf16 v[30:33], v[146:149], v[220:223], v[30:33]
	v_mfma_f32_16x16x32_bf16 v[18:21], v[138:141], v[228:231], v[18:21]
	v_mfma_f32_16x16x32_bf16 v[14:17], v[146:149], v[228:231], v[14:17]
	v_mfma_f32_16x16x32_bf16 v[66:69], v[142:145], v[202:205], v[66:69]
	v_mfma_f32_16x16x32_bf16 v[62:65], v[178:181], v[202:205], v[62:65]
	v_mfma_f32_16x16x32_bf16 v[50:53], v[142:145], v[210:213], v[50:53]
	v_mfma_f32_16x16x32_bf16 v[46:49], v[178:181], v[210:213], v[46:49]
	v_mfma_f32_16x16x32_bf16 v[34:37], v[142:145], v[224:227], v[34:37]
	v_mfma_f32_16x16x32_bf16 v[30:33], v[178:181], v[224:227], v[30:33]
	v_mfma_f32_16x16x32_bf16 v[18:21], v[142:145], v[232:235], v[18:21]
	v_mfma_f32_16x16x32_bf16 v[14:17], v[178:181], v[232:235], v[14:17]
	v_mfma_f32_16x16x32_bf16 v[58:61], v[182:185], v[198:201], v[58:61]
	v_mfma_f32_16x16x32_bf16 v[54:57], v[190:193], v[198:201], v[54:57]
	v_mfma_f32_16x16x32_bf16 v[42:45], v[182:185], v[206:209], v[42:45]
	v_mfma_f32_16x16x32_bf16 v[38:41], v[190:193], v[206:209], v[38:41]
	v_mfma_f32_16x16x32_bf16 v[26:29], v[182:185], v[220:223], v[26:29]
	v_mfma_f32_16x16x32_bf16 v[22:25], v[190:193], v[220:223], v[22:25]
	v_mfma_f32_16x16x32_bf16 v[10:13], v[182:185], v[228:231], v[10:13]
	v_mfma_f32_16x16x32_bf16 v[6:9], v[190:193], v[228:231], v[6:9]
	v_mfma_f32_16x16x32_bf16 v[58:61], v[186:189], v[202:205], v[58:61]
	v_mfma_f32_16x16x32_bf16 v[54:57], v[194:197], v[202:205], v[54:57]
	v_mfma_f32_16x16x32_bf16 v[42:45], v[186:189], v[210:213], v[42:45]
	v_mfma_f32_16x16x32_bf16 v[38:41], v[194:197], v[210:213], v[38:41]
	v_mfma_f32_16x16x32_bf16 v[26:29], v[186:189], v[224:227], v[26:29]
	v_mfma_f32_16x16x32_bf16 v[22:25], v[194:197], v[224:227], v[22:25]
	v_mfma_f32_16x16x32_bf16 v[10:13], v[186:189], v[232:235], v[10:13]
	v_mfma_f32_16x16x32_bf16 v[6:9], v[194:197], v[232:235], v[6:9]
	s_setprio 0
	s_barrier
	v_lshl_add_u64 v[134:135], v[134:135], 0, s[26:27]
	s_cmp_ge_i32 s10, s46
	v_lshl_add_u64 v[136:137], v[136:137], 0, s[26:27]
	s_cbranch_scc0 .LBB0_1947
